# v33 plus: hipcc's redundant lgkmcnt waits removed from inside the GEMM MFMA blocks (the explicit lgkmcnt(0) before each segment barrier already covers them)
# speedup vs baseline: 1.0068x; 1.0068x over previous
.LBB0_185:
	ds_read_b128 v[136:139], v149
	ds_read_b128 v[154:157], v149 offset:1024
	ds_read_b128 v[158:161], v149 offset:2048
	ds_read_b128 v[162:165], v149 offset:3072
	ds_read_b128 v[166:169], v150
	ds_read_b128 v[170:173], v150 offset:1024
	ds_read_b128 v[174:177], v150 offset:2048
	ds_read_b128 v[178:181], v150 offset:3072
	s_cmp_eq_u32 s86, 28
	s_cselect_b32 s54, s80, s84
	s_cselect_b32 s55, s25, s85
	s_cselect_b32 s46, s81, s82
	s_cselect_b32 s47, s19, s83
	s_add_u32 s44, s54, 0x80
	s_addc_u32 s45, s55, 0
	ds_read_b128 v[182:185], v151
	ds_read_b128 v[186:189], v151 offset:1024
	ds_read_b128 v[190:193], v151 offset:2048
	ds_read_b128 v[194:197], v151 offset:3072
	ds_read_b128 v[198:201], v151 offset:4096
	ds_read_b128 v[202:205], v151 offset:5120
	ds_read_b128 v[206:209], v151 offset:6144
	ds_read_b128 v[210:213], v151 offset:7168
	s_mov_b32 m0, s75
	s_nop 0
	global_load_lds_dwordx4 v1, s[40:41] offset:0
	s_nop 0
	s_mov_b32 m0, s76
	s_nop 0
	global_load_lds_dwordx4 v143, s[40:41] offset:0
	s_waitcnt vmcnt(8)
	s_waitcnt lgkmcnt(0)
	s_barrier
	s_setprio 1
	v_mfma_f32_16x16x32_bf16 v[126:129], v[136:139], v[182:185], v[126:129]
	v_mfma_f32_16x16x32_bf16 v[126:129], v[154:157], v[186:189], v[126:129]
	v_mfma_f32_16x16x32_bf16 v[122:125], v[158:161], v[182:185], v[122:125]
	v_mfma_f32_16x16x32_bf16 v[122:125], v[162:165], v[186:189], v[122:125]
	v_mfma_f32_16x16x32_bf16 v[114:117], v[136:139], v[190:193], v[114:117]
	v_mfma_f32_16x16x32_bf16 v[114:117], v[154:157], v[194:197], v[114:117]
	v_mfma_f32_16x16x32_bf16 v[106:109], v[158:161], v[190:193], v[106:109]
	v_mfma_f32_16x16x32_bf16 v[106:109], v[162:165], v[194:197], v[106:109]
	v_mfma_f32_16x16x32_bf16 v[98:101], v[136:139], v[198:201], v[98:101]
	v_mfma_f32_16x16x32_bf16 v[98:101], v[154:157], v[202:205], v[98:101]
	v_mfma_f32_16x16x32_bf16 v[90:93], v[158:161], v[198:201], v[90:93]
	v_mfma_f32_16x16x32_bf16 v[90:93], v[162:165], v[202:205], v[90:93]
	v_mfma_f32_16x16x32_bf16 v[82:85], v[136:139], v[206:209], v[82:85]
	v_mfma_f32_16x16x32_bf16 v[82:85], v[154:157], v[210:213], v[82:85]
	v_mfma_f32_16x16x32_bf16 v[74:77], v[158:161], v[206:209], v[74:77]
	v_mfma_f32_16x16x32_bf16 v[74:77], v[162:165], v[210:213], v[74:77]
	s_setprio 0
	s_setprio 1
	v_mfma_f32_16x16x32_bf16 v[118:121], v[166:169], v[182:185], v[118:121]
	v_mfma_f32_16x16x32_bf16 v[118:121], v[170:173], v[186:189], v[118:121]
	v_mfma_f32_16x16x32_bf16 v[110:113], v[174:177], v[182:185], v[110:113]
	v_mfma_f32_16x16x32_bf16 v[110:113], v[178:181], v[186:189], v[110:113]
	v_mfma_f32_16x16x32_bf16 v[102:105], v[166:169], v[190:193], v[102:105]
	v_mfma_f32_16x16x32_bf16 v[102:105], v[170:173], v[194:197], v[102:105]
	v_mfma_f32_16x16x32_bf16 v[94:97], v[174:177], v[190:193], v[94:97]
	v_mfma_f32_16x16x32_bf16 v[94:97], v[178:181], v[194:197], v[94:97]
	v_mfma_f32_16x16x32_bf16 v[86:89], v[166:169], v[198:201], v[86:89]
	v_mfma_f32_16x16x32_bf16 v[86:89], v[170:173], v[202:205], v[86:89]
	v_mfma_f32_16x16x32_bf16 v[78:81], v[174:177], v[198:201], v[78:81]
	v_mfma_f32_16x16x32_bf16 v[78:81], v[178:181], v[202:205], v[78:81]
	v_mfma_f32_16x16x32_bf16 v[70:73], v[166:169], v[206:209], v[70:73]
	v_mfma_f32_16x16x32_bf16 v[70:73], v[170:173], v[210:213], v[70:73]
	v_mfma_f32_16x16x32_bf16 v[66:69], v[174:177], v[206:209], v[66:69]
	v_mfma_f32_16x16x32_bf16 v[66:69], v[178:181], v[210:213], v[66:69]
	s_setprio 0
	s_barrier
	ds_read_b128 v[182:185], v151 offset:16384
	ds_read_b128 v[186:189], v151 offset:17408
	ds_read_b128 v[190:193], v151 offset:18432
	ds_read_b128 v[194:197], v151 offset:19456
	ds_read_b128 v[198:201], v151 offset:20480
	ds_read_b128 v[202:205], v151 offset:21504
	ds_read_b128 v[206:209], v151 offset:22528
	ds_read_b128 v[210:213], v151 offset:23552
	s_mov_b32 m0, s39
	s_nop 0
	global_load_lds_dwordx4 v135, s[46:47] offset:0
	s_add_u32 s30, s46, 0x80000
	s_mov_b32 m0, s58
	s_nop 0
	global_load_lds_dwordx4 v145, s[46:47] offset:0
	s_addc_u32 s31, s47, 0
	s_mov_b32 m0, s59
	s_nop 0
	global_load_lds_dwordx4 v135, s[30:31] offset:0
	s_nop 0
	s_mov_b32 m0, s64
	s_nop 0
	global_load_lds_dwordx4 v145, s[30:31] offset:0
	s_nop 0
	s_mov_b32 m0, s53
	s_nop 0
	global_load_lds_dwordx4 v1, s[54:55] offset:0
	s_nop 0
	s_mov_b32 m0, s65
	s_nop 0
	global_load_lds_dwordx4 v143, s[54:55] offset:0
	s_waitcnt vmcnt(8)
	s_waitcnt lgkmcnt(0)
	s_barrier
	s_setprio 1
	v_mfma_f32_16x16x32_bf16 v[62:65], v[136:139], v[182:185], v[62:65]
	v_mfma_f32_16x16x32_bf16 v[62:65], v[154:157], v[186:189], v[62:65]
	v_mfma_f32_16x16x32_bf16 v[58:61], v[158:161], v[182:185], v[58:61]
	v_mfma_f32_16x16x32_bf16 v[58:61], v[162:165], v[186:189], v[58:61]
	v_mfma_f32_16x16x32_bf16 v[50:53], v[136:139], v[190:193], v[50:53]
	v_mfma_f32_16x16x32_bf16 v[50:53], v[154:157], v[194:197], v[50:53]
	v_mfma_f32_16x16x32_bf16 v[42:45], v[158:161], v[190:193], v[42:45]
	v_mfma_f32_16x16x32_bf16 v[42:45], v[162:165], v[194:197], v[42:45]
	v_mfma_f32_16x16x32_bf16 v[34:37], v[136:139], v[198:201], v[34:37]
	v_mfma_f32_16x16x32_bf16 v[34:37], v[154:157], v[202:205], v[34:37]
	v_mfma_f32_16x16x32_bf16 v[26:29], v[158:161], v[198:201], v[26:29]
	v_mfma_f32_16x16x32_bf16 v[26:29], v[162:165], v[202:205], v[26:29]
	v_mfma_f32_16x16x32_bf16 v[18:21], v[136:139], v[206:209], v[18:21]
	v_mfma_f32_16x16x32_bf16 v[18:21], v[154:157], v[210:213], v[18:21]
	v_mfma_f32_16x16x32_bf16 v[10:13], v[158:161], v[206:209], v[10:13]
	v_mfma_f32_16x16x32_bf16 v[10:13], v[162:165], v[210:213], v[10:13]
	s_setprio 0
	s_setprio 1
	v_mfma_f32_16x16x32_bf16 v[54:57], v[166:169], v[182:185], v[54:57]
	v_mfma_f32_16x16x32_bf16 v[54:57], v[170:173], v[186:189], v[54:57]
	v_mfma_f32_16x16x32_bf16 v[46:49], v[174:177], v[182:185], v[46:49]
	v_mfma_f32_16x16x32_bf16 v[46:49], v[178:181], v[186:189], v[46:49]
	v_mfma_f32_16x16x32_bf16 v[38:41], v[166:169], v[190:193], v[38:41]
	v_mfma_f32_16x16x32_bf16 v[38:41], v[170:173], v[194:197], v[38:41]
	v_mfma_f32_16x16x32_bf16 v[30:33], v[174:177], v[190:193], v[30:33]
	v_mfma_f32_16x16x32_bf16 v[30:33], v[178:181], v[194:197], v[30:33]
	v_mfma_f32_16x16x32_bf16 v[22:25], v[166:169], v[198:201], v[22:25]
	v_mfma_f32_16x16x32_bf16 v[22:25], v[170:173], v[202:205], v[22:25]
	v_mfma_f32_16x16x32_bf16 v[14:17], v[174:177], v[198:201], v[14:17]
	v_mfma_f32_16x16x32_bf16 v[14:17], v[178:181], v[202:205], v[14:17]
	v_mfma_f32_16x16x32_bf16 v[6:9], v[166:169], v[206:209], v[6:9]
	v_mfma_f32_16x16x32_bf16 v[6:9], v[170:173], v[210:213], v[6:9]
	v_mfma_f32_16x16x32_bf16 v[2:5], v[174:177], v[206:209], v[2:5]
	v_mfma_f32_16x16x32_bf16 v[2:5], v[178:181], v[210:213], v[2:5]
	s_setprio 0
	s_barrier
; #define PG8_KSETUP() const bool last = (t == nt - 2); const char* a1 = cA + (size_t)(t + 1) * kstep; \
;             const char* a2 = last ? nA : cA + (size_t)(t + 2) * kstep; const char* b2 = last ? nB : cB + (size_t)(t + 2) * kstep; const char* a3 = a2 + kstep; const char* b3 = b2 + kstep; \
;             if (last && has_next) S.a_ready(nxt)
; template <class Epi, class Sched, bool ALIGN_EPI = false, bool SP2 = false>
; __device__ __forceinline__ void gemm_phase(PG8_LAS unsigned char* lds, const Gemm g, const Sched& S, const Epi& E) {
;     ...
;         int t0 = 0;
;         if constexpr (SP2 && Epi::NVM == 16) { if (ui > 0) { const int t = 0; PG8_KSETUP(); PG8_KITER_SP2(24, 24); t0 = 2; } }
;         if constexpr (SP2 && Epi::NVM == 8) { if (ui > 0) { const int t = 0; PG8_KSETUP(); PG8_KITER_SP2(16, 16); t0 = 2; } }
;         for (int t = t0; t < nt; t += 2) {
	ds_read_b128 v[136:139], v152
	ds_read_b128 v[154:157], v152 offset:1024
	ds_read_b128 v[158:161], v152 offset:2048
	ds_read_b128 v[162:165], v152 offset:3072
	ds_read_b128 v[166:169], v153
	ds_read_b128 v[170:173], v153 offset:1024
	ds_read_b128 v[174:177], v153 offset:2048
	ds_read_b128 v[178:181], v153 offset:3072
	ds_read_b128 v[182:185], v151 offset:32768
	ds_read_b128 v[186:189], v151 offset:33792
	ds_read_b128 v[190:193], v151 offset:34816
	ds_read_b128 v[194:197], v151 offset:35840
	ds_read_b128 v[198:201], v151 offset:36864
	ds_read_b128 v[202:205], v151 offset:37888
	ds_read_b128 v[206:209], v151 offset:38912
	ds_read_b128 v[210:213], v151 offset:39936
	s_add_u32 s30, s54, 0x80000
	s_addc_u32 s31, s55, 0
	s_mov_b32 m0, s66
	s_nop 0
	global_load_lds_dwordx4 v1, s[30:31] offset:0
	s_nop 0
	s_mov_b32 m0, s67
	s_nop 0
	global_load_lds_dwordx4 v143, s[30:31] offset:0
	s_waitcnt vmcnt(8)
	s_waitcnt lgkmcnt(0)
	s_barrier
	s_setprio 1
	v_mfma_f32_16x16x32_bf16 v[126:129], v[136:139], v[182:185], v[126:129]
	v_mfma_f32_16x16x32_bf16 v[126:129], v[154:157], v[186:189], v[126:129]
	v_mfma_f32_16x16x32_bf16 v[122:125], v[158:161], v[182:185], v[122:125]
	v_mfma_f32_16x16x32_bf16 v[122:125], v[162:165], v[186:189], v[122:125]
	v_mfma_f32_16x16x32_bf16 v[114:117], v[136:139], v[190:193], v[114:117]
	v_mfma_f32_16x16x32_bf16 v[114:117], v[154:157], v[194:197], v[114:117]
	v_mfma_f32_16x16x32_bf16 v[106:109], v[158:161], v[190:193], v[106:109]
	v_mfma_f32_16x16x32_bf16 v[106:109], v[162:165], v[194:197], v[106:109]
	v_mfma_f32_16x16x32_bf16 v[98:101], v[136:139], v[198:201], v[98:101]
	v_mfma_f32_16x16x32_bf16 v[98:101], v[154:157], v[202:205], v[98:101]
	v_mfma_f32_16x16x32_bf16 v[90:93], v[158:161], v[198:201], v[90:93]
	v_mfma_f32_16x16x32_bf16 v[90:93], v[162:165], v[202:205], v[90:93]
	v_mfma_f32_16x16x32_bf16 v[82:85], v[136:139], v[206:209], v[82:85]
	v_mfma_f32_16x16x32_bf16 v[82:85], v[154:157], v[210:213], v[82:85]
	v_mfma_f32_16x16x32_bf16 v[74:77], v[158:161], v[206:209], v[74:77]
	v_mfma_f32_16x16x32_bf16 v[74:77], v[162:165], v[210:213], v[74:77]
	s_setprio 0
	s_setprio 1
	v_mfma_f32_16x16x32_bf16 v[118:121], v[166:169], v[182:185], v[118:121]
	v_mfma_f32_16x16x32_bf16 v[118:121], v[170:173], v[186:189], v[118:121]
	v_mfma_f32_16x16x32_bf16 v[110:113], v[174:177], v[182:185], v[110:113]
	v_mfma_f32_16x16x32_bf16 v[110:113], v[178:181], v[186:189], v[110:113]
	v_mfma_f32_16x16x32_bf16 v[102:105], v[166:169], v[190:193], v[102:105]
	v_mfma_f32_16x16x32_bf16 v[102:105], v[170:173], v[194:197], v[102:105]
	v_mfma_f32_16x16x32_bf16 v[94:97], v[174:177], v[190:193], v[94:97]
	v_mfma_f32_16x16x32_bf16 v[94:97], v[178:181], v[194:197], v[94:97]
	v_mfma_f32_16x16x32_bf16 v[86:89], v[166:169], v[198:201], v[86:89]
	v_mfma_f32_16x16x32_bf16 v[86:89], v[170:173], v[202:205], v[86:89]
	v_mfma_f32_16x16x32_bf16 v[78:81], v[174:177], v[198:201], v[78:81]
	v_mfma_f32_16x16x32_bf16 v[78:81], v[178:181], v[202:205], v[78:81]
	v_mfma_f32_16x16x32_bf16 v[70:73], v[166:169], v[206:209], v[70:73]
	v_mfma_f32_16x16x32_bf16 v[70:73], v[170:173], v[210:213], v[70:73]
	v_mfma_f32_16x16x32_bf16 v[66:69], v[174:177], v[206:209], v[66:69]
	v_mfma_f32_16x16x32_bf16 v[66:69], v[178:181], v[210:213], v[66:69]
	s_setprio 0
	s_barrier
	ds_read_b128 v[182:185], v151 offset:49152
	ds_read_b128 v[186:189], v151 offset:50176
	ds_read_b128 v[190:193], v151 offset:51200
	ds_read_b128 v[194:197], v151 offset:52224
	ds_read_b128 v[198:201], v151 offset:53248
	ds_read_b128 v[202:205], v151 offset:54272
	ds_read_b128 v[206:209], v151 offset:55296
	ds_read_b128 v[210:213], v151 offset:56320
	s_add_u32 s30, s46, 0x80
	s_addc_u32 s31, s47, 0
	s_mov_b32 m0, s69
	s_nop 0
	global_load_lds_dwordx4 v135, s[30:31] offset:0
	s_nop 0
	s_mov_b32 m0, s70
	s_nop 0
	global_load_lds_dwordx4 v145, s[30:31] offset:0
	s_add_u32 s30, s46, 0x80080
	s_addc_u32 s31, s47, 0
	s_mov_b32 m0, s73
	s_nop 0
	global_load_lds_dwordx4 v135, s[30:31] offset:0
	s_nop 0
	s_mov_b32 m0, s74
	s_nop 0
	global_load_lds_dwordx4 v145, s[30:31] offset:0
	s_nop 0
	s_mov_b32 m0, s71
	s_nop 0
	global_load_lds_dwordx4 v1, s[44:45] offset:0
	s_nop 0
	s_mov_b32 m0, s72
	s_nop 0
	global_load_lds_dwordx4 v143, s[44:45] offset:0
	s_waitcnt vmcnt(8)
	s_waitcnt lgkmcnt(0)
	s_barrier
	s_setprio 1
	v_mfma_f32_16x16x32_bf16 v[62:65], v[136:139], v[182:185], v[62:65]
	v_mfma_f32_16x16x32_bf16 v[62:65], v[154:157], v[186:189], v[62:65]
	v_mfma_f32_16x16x32_bf16 v[58:61], v[158:161], v[182:185], v[58:61]
	v_mfma_f32_16x16x32_bf16 v[58:61], v[162:165], v[186:189], v[58:61]
	v_mfma_f32_16x16x32_bf16 v[50:53], v[136:139], v[190:193], v[50:53]
	v_mfma_f32_16x16x32_bf16 v[50:53], v[154:157], v[194:197], v[50:53]
	v_mfma_f32_16x16x32_bf16 v[42:45], v[158:161], v[190:193], v[42:45]
	v_mfma_f32_16x16x32_bf16 v[42:45], v[162:165], v[194:197], v[42:45]
	v_mfma_f32_16x16x32_bf16 v[34:37], v[136:139], v[198:201], v[34:37]
	v_mfma_f32_16x16x32_bf16 v[34:37], v[154:157], v[202:205], v[34:37]
	v_mfma_f32_16x16x32_bf16 v[26:29], v[158:161], v[198:201], v[26:29]
	v_mfma_f32_16x16x32_bf16 v[26:29], v[162:165], v[202:205], v[26:29]
	v_mfma_f32_16x16x32_bf16 v[18:21], v[136:139], v[206:209], v[18:21]
	v_mfma_f32_16x16x32_bf16 v[18:21], v[154:157], v[210:213], v[18:21]
	v_mfma_f32_16x16x32_bf16 v[10:13], v[158:161], v[206:209], v[10:13]
	v_mfma_f32_16x16x32_bf16 v[10:13], v[162:165], v[210:213], v[10:13]
	s_setprio 0
	s_setprio 1
	v_mfma_f32_16x16x32_bf16 v[54:57], v[166:169], v[182:185], v[54:57]
	v_mfma_f32_16x16x32_bf16 v[54:57], v[170:173], v[186:189], v[54:57]
	v_mfma_f32_16x16x32_bf16 v[46:49], v[174:177], v[182:185], v[46:49]
	v_mfma_f32_16x16x32_bf16 v[46:49], v[178:181], v[186:189], v[46:49]
	v_mfma_f32_16x16x32_bf16 v[38:41], v[166:169], v[190:193], v[38:41]
	v_mfma_f32_16x16x32_bf16 v[38:41], v[170:173], v[194:197], v[38:41]
	v_mfma_f32_16x16x32_bf16 v[30:33], v[174:177], v[190:193], v[30:33]
	v_mfma_f32_16x16x32_bf16 v[30:33], v[178:181], v[194:197], v[30:33]
	v_mfma_f32_16x16x32_bf16 v[22:25], v[166:169], v[198:201], v[22:25]
	v_mfma_f32_16x16x32_bf16 v[22:25], v[170:173], v[202:205], v[22:25]
	v_mfma_f32_16x16x32_bf16 v[14:17], v[174:177], v[198:201], v[14:17]
	v_mfma_f32_16x16x32_bf16 v[14:17], v[178:181], v[202:205], v[14:17]
	v_mfma_f32_16x16x32_bf16 v[6:9], v[166:169], v[206:209], v[6:9]
	v_mfma_f32_16x16x32_bf16 v[6:9], v[170:173], v[210:213], v[6:9]
	v_mfma_f32_16x16x32_bf16 v[2:5], v[174:177], v[206:209], v[2:5]
	v_mfma_f32_16x16x32_bf16 v[2:5], v[178:181], v[210:213], v[2:5]
	s_setprio 0
	s_barrier
	s_add_i32 s86, s86, 2
	s_add_u32 s82, s82, 0x100
	s_addc_u32 s83, s83, 0
	s_add_u32 s84, s84, 0x100
	s_addc_u32 s85, s85, 0
	s_add_u32 s40, s40, 0x100
	s_addc_u32 s41, s41, 0
	s_cmp_gt_u32 s86, 29
	s_cbranch_scc0 .LBB0_185
	s_and_b64 vcc, exec, s[16:17]
	s_cbranch_vccz .LBB0_188
	s_barrier

; #define PG8_KSETUP() const bool last = (t == nt - 2); const char* a1 = cA + (size_t)(t + 1) * kstep; \
;             const char* a2 = last ? nA : cA + (size_t)(t + 2) * kstep; const char* b2 = last ? nB : cB + (size_t)(t + 2) * kstep; const char* a3 = a2 + kstep; const char* b3 = b2 + kstep; \
;             if (last && has_next) S.a_ready(nxt)
; template <class Epi, class Sched, bool ALIGN_EPI = false, bool SP2 = false>
; __device__ __forceinline__ void gemm_phase(PG8_LAS unsigned char* lds, const Gemm g, const Sched& S, const Epi& E) {
;     ...
;         int t0 = 0;
;         if constexpr (SP2 && Epi::NVM == 16) { if (ui > 0) { const int t = 0; PG8_KSETUP(); PG8_KITER_SP2(24, 24); t0 = 2; } }
;         if constexpr (SP2 && Epi::NVM == 8) { if (ui > 0) { const int t = 0; PG8_KSETUP(); PG8_KITER_SP2(16, 16); t0 = 2; } }
.LBB0_624:
	s_cmp_eq_u32 s37, 0
	s_mov_b32 s64, 0
	s_cbranch_scc1 .LBB0_626
	ds_read_b128 v[4:7], v147
	ds_read_b128 v[8:11], v147 offset:1024
	ds_read_b128 v[12:15], v147 offset:2048
	ds_read_b128 v[16:19], v147 offset:3072
	ds_read_b128 v[20:23], v148
	ds_read_b128 v[24:27], v148 offset:1024
	ds_read_b128 v[28:31], v148 offset:2048
	ds_read_b128 v[32:35], v148 offset:3072
	s_add_u32 s44, s56, 0x100
	s_addc_u32 s45, s57, 0
	s_add_u32 s30, s58, 0x100
	s_addc_u32 s31, s59, 0
	s_add_u32 s40, s56, 0x180
	s_addc_u32 s41, s57, 0
	ds_read_b128 v[36:39], v149
	ds_read_b128 v[40:43], v149 offset:1024
	ds_read_b128 v[44:47], v149 offset:2048
	ds_read_b128 v[48:51], v149 offset:3072
	ds_read_b128 v[52:55], v149 offset:4096
	ds_read_b128 v[56:59], v149 offset:5120
	ds_read_b128 v[60:63], v149 offset:6144
	ds_read_b128 v[64:67], v149 offset:7168
	s_add_u32 s42, s56, 0x80080
	s_addc_u32 s43, s57, 0
	s_mov_b32 m0, s81
	s_nop 0
	global_load_lds_dwordx4 v1, s[42:43] offset:0
	s_nop 0
	s_mov_b32 m0, s82
	s_nop 0
	global_load_lds_dwordx4 v143, s[42:43] offset:0
	s_waitcnt vmcnt(24)
	s_waitcnt lgkmcnt(0)
	s_barrier
	s_setprio 1
	v_mfma_f32_16x16x32_bf16 v[92:95], v[4:7], v[60:63], 0
	v_mfma_f32_16x16x32_bf16 v[68:71], v[4:7], v[36:39], 0
	v_mfma_f32_16x16x32_bf16 v[72:75], v[12:15], v[36:39], 0
	v_mfma_f32_16x16x32_bf16 v[76:79], v[4:7], v[44:47], 0
	v_mfma_f32_16x16x32_bf16 v[80:83], v[12:15], v[44:47], 0
	v_mfma_f32_16x16x32_bf16 v[84:87], v[4:7], v[52:55], 0
	v_mfma_f32_16x16x32_bf16 v[88:91], v[12:15], v[52:55], 0
	v_mfma_f32_16x16x32_bf16 v[102:105], v[8:11], v[64:67], v[92:95]
	v_mfma_f32_16x16x32_bf16 v[92:95], v[12:15], v[60:63], 0
	v_mfma_f32_16x16x32_bf16 v[68:71], v[8:11], v[40:43], v[68:71]
	v_mfma_f32_16x16x32_bf16 v[72:75], v[16:19], v[40:43], v[72:75]
	v_mfma_f32_16x16x32_bf16 v[76:79], v[8:11], v[48:51], v[76:79]
	v_mfma_f32_16x16x32_bf16 v[80:83], v[16:19], v[48:51], v[80:83]
	v_mfma_f32_16x16x32_bf16 v[84:87], v[8:11], v[56:59], v[84:87]
	v_mfma_f32_16x16x32_bf16 v[88:91], v[16:19], v[56:59], v[88:91]
	v_mfma_f32_16x16x32_bf16 v[106:109], v[16:19], v[64:67], v[92:95]
	s_setprio 0
	s_setprio 1
	v_mfma_f32_16x16x32_bf16 v[92:95], v[20:23], v[36:39], 0
	v_mfma_f32_16x16x32_bf16 v[36:39], v[28:31], v[36:39], 0
	v_mfma_f32_16x16x32_bf16 v[118:121], v[24:27], v[40:43], v[92:95]
	v_mfma_f32_16x16x32_bf16 v[36:39], v[32:35], v[40:43], v[36:39]
	v_mfma_f32_16x16x32_bf16 v[40:43], v[20:23], v[44:47], 0
	v_mfma_f32_16x16x32_bf16 v[44:47], v[28:31], v[44:47], 0
	v_mfma_f32_16x16x32_bf16 v[40:43], v[24:27], v[48:51], v[40:43]
	v_mfma_f32_16x16x32_bf16 v[44:47], v[32:35], v[48:51], v[44:47]
	v_mfma_f32_16x16x32_bf16 v[48:51], v[20:23], v[52:55], 0
	v_mfma_f32_16x16x32_bf16 v[52:55], v[28:31], v[52:55], 0
	v_mfma_f32_16x16x32_bf16 v[48:51], v[24:27], v[56:59], v[48:51]
	v_mfma_f32_16x16x32_bf16 v[52:55], v[32:35], v[56:59], v[52:55]
	v_mfma_f32_16x16x32_bf16 v[56:59], v[20:23], v[60:63], 0
	v_mfma_f32_16x16x32_bf16 v[60:63], v[28:31], v[60:63], 0
	v_mfma_f32_16x16x32_bf16 v[56:59], v[24:27], v[64:67], v[56:59]
	v_mfma_f32_16x16x32_bf16 v[60:63], v[32:35], v[64:67], v[60:63]
	s_setprio 0
	s_barrier
	ds_read_b128 v[64:67], v149 offset:16384
	ds_read_b128 v[92:95], v149 offset:17408
	ds_read_b128 v[96:99], v149 offset:18432
	ds_read_b128 v[110:113], v149 offset:19456
	ds_read_b128 v[114:117], v149 offset:20480
	ds_read_b128 v[122:125], v149 offset:21504
	ds_read_b128 v[126:129], v149 offset:22528
	ds_read_b128 v[130:133], v149 offset:23552
	s_mov_b32 m0, s52
	s_nop 0
	global_load_lds_dwordx4 v142, s[30:31] offset:0
	s_nop 0
	s_mov_b32 m0, s53
	s_nop 0
	global_load_lds_dwordx4 v144, s[30:31] offset:0
	s_add_u32 s30, s58, 0x80100
	s_addc_u32 s31, s59, 0
	s_mov_b32 m0, s55
	s_nop 0
	global_load_lds_dwordx4 v142, s[30:31] offset:0
	s_nop 0
	s_mov_b32 m0, s68
	s_nop 0
	global_load_lds_dwordx4 v144, s[30:31] offset:0
	s_nop 0
	s_mov_b32 m0, s33
	s_nop 0
	global_load_lds_dwordx4 v1, s[44:45] offset:0
	s_nop 0
	s_mov_b32 m0, s69
	s_nop 0
	global_load_lds_dwordx4 v143, s[44:45] offset:0
	s_waitcnt vmcnt(24)
	s_waitcnt lgkmcnt(0)
	s_barrier
	s_setprio 1
	v_mfma_f32_16x16x32_bf16 v[138:141], v[4:7], v[64:67], 0
	v_mfma_f32_16x16x32_bf16 v[156:159], v[4:7], v[96:99], 0
	v_mfma_f32_16x16x32_bf16 v[164:167], v[4:7], v[114:117], 0
	v_mfma_f32_16x16x32_bf16 v[4:7], v[4:7], v[126:129], 0
	v_mfma_f32_16x16x32_bf16 v[138:141], v[8:11], v[92:95], v[138:141]
	v_mfma_f32_16x16x32_bf16 v[156:159], v[8:11], v[110:113], v[156:159]
	v_mfma_f32_16x16x32_bf16 v[164:167], v[8:11], v[122:125], v[164:167]
	v_mfma_f32_16x16x32_bf16 v[4:7], v[8:11], v[130:133], v[4:7]
	v_mfma_f32_16x16x32_bf16 v[8:11], v[12:15], v[126:129], 0
	v_mfma_f32_16x16x32_bf16 v[152:155], v[12:15], v[64:67], 0
	v_mfma_f32_16x16x32_bf16 v[160:163], v[12:15], v[96:99], 0
	v_mfma_f32_16x16x32_bf16 v[168:171], v[12:15], v[114:117], 0
	v_mfma_f32_16x16x32_bf16 v[8:11], v[16:19], v[130:133], v[8:11]
	v_mfma_f32_16x16x32_bf16 v[152:155], v[16:19], v[92:95], v[152:155]
	v_mfma_f32_16x16x32_bf16 v[160:163], v[16:19], v[110:113], v[160:163]
	v_mfma_f32_16x16x32_bf16 v[168:171], v[16:19], v[122:125], v[168:171]
	s_setprio 0
	s_setprio 1
	v_mfma_f32_16x16x32_bf16 v[12:15], v[20:23], v[64:67], 0
	v_mfma_f32_16x16x32_bf16 v[172:175], v[24:27], v[92:95], v[12:15]
	v_mfma_f32_16x16x32_bf16 v[12:15], v[28:31], v[64:67], 0
	v_mfma_f32_16x16x32_bf16 v[176:179], v[32:35], v[92:95], v[12:15]
	v_mfma_f32_16x16x32_bf16 v[12:15], v[20:23], v[96:99], 0
	v_mfma_f32_16x16x32_bf16 v[180:183], v[24:27], v[110:113], v[12:15]
	v_mfma_f32_16x16x32_bf16 v[12:15], v[28:31], v[96:99], 0
	v_mfma_f32_16x16x32_bf16 v[184:187], v[32:35], v[110:113], v[12:15]
	v_mfma_f32_16x16x32_bf16 v[12:15], v[20:23], v[114:117], 0
	v_mfma_f32_16x16x32_bf16 v[188:191], v[24:27], v[122:125], v[12:15]
	v_mfma_f32_16x16x32_bf16 v[12:15], v[28:31], v[114:117], 0
	v_mfma_f32_16x16x32_bf16 v[192:195], v[32:35], v[122:125], v[12:15]
	v_mfma_f32_16x16x32_bf16 v[12:15], v[20:23], v[126:129], 0
	v_mfma_f32_16x16x32_bf16 v[196:199], v[24:27], v[130:133], v[12:15]
	v_mfma_f32_16x16x32_bf16 v[12:15], v[28:31], v[126:129], 0
	v_mfma_f32_16x16x32_bf16 v[200:203], v[32:35], v[130:133], v[12:15]
	s_setprio 0
	s_barrier
; #define PG8_KSETUP() const bool last = (t == nt - 2); const char* a1 = cA + (size_t)(t + 1) * kstep; \
;             const char* a2 = last ? nA : cA + (size_t)(t + 2) * kstep; const char* b2 = last ? nB : cB + (size_t)(t + 2) * kstep; const char* a3 = a2 + kstep; const char* b3 = b2 + kstep; \
;             if (last && has_next) S.a_ready(nxt)
; template <class Epi, class Sched, bool ALIGN_EPI = false, bool SP2 = false>
; __device__ __forceinline__ void gemm_phase(PG8_LAS unsigned char* lds, const Gemm g, const Sched& S, const Epi& E) {
;     ...
;         int t0 = 0;
;         if constexpr (SP2 && Epi::NVM == 16) { if (ui > 0) { const int t = 0; PG8_KSETUP(); PG8_KITER_SP2(24, 24); t0 = 2; } }
;         if constexpr (SP2 && Epi::NVM == 8) { if (ui > 0) { const int t = 0; PG8_KSETUP(); PG8_KITER_SP2(16, 16); t0 = 2; } }
	s_nop 4
	ds_read_b128 v[12:15], v150
	ds_read_b128 v[16:19], v150 offset:1024
	ds_read_b128 v[22:25], v150 offset:2048
	ds_read_b128 v[26:29], v150 offset:3072
	ds_read_b128 v[204:207], v151
	ds_read_b128 v[208:211], v151 offset:1024
	ds_read_b128 v[212:215], v151 offset:2048
	ds_read_b128 v[216:219], v151 offset:3072
	ds_read_b128 v[30:33], v149 offset:32768
	ds_read_b128 v[64:67], v149 offset:33792
	ds_read_b128 v[220:223], v149 offset:34816
	ds_read_b128 v[224:227], v149 offset:35840
	ds_read_b128 v[228:231], v149 offset:36864
	ds_read_b128 v[232:235], v149 offset:37888
	ds_read_b128 v[236:239], v149 offset:38912
	ds_read_b128 v[240:243], v149 offset:39936
	s_add_u32 s30, s56, 0x80100
	s_addc_u32 s31, s57, 0
	s_mov_b32 m0, s70
	s_nop 0
	global_load_lds_dwordx4 v1, s[30:31] offset:0
	s_nop 0
	s_mov_b32 m0, s71
	s_nop 0
	global_load_lds_dwordx4 v143, s[30:31] offset:0
	s_waitcnt vmcnt(8)
	s_waitcnt lgkmcnt(0)
	s_barrier
	s_setprio 1
	v_mfma_f32_16x16x32_bf16 v[68:71], v[12:15], v[30:33], v[68:71]
	v_mfma_f32_16x16x32_bf16 v[130:133], v[16:19], v[64:67], v[68:71]
	v_mfma_f32_16x16x32_bf16 v[68:71], v[22:25], v[30:33], v[72:75]
	v_mfma_f32_16x16x32_bf16 v[126:129], v[26:29], v[64:67], v[68:71]
	v_mfma_f32_16x16x32_bf16 v[68:71], v[12:15], v[220:223], v[76:79]
	v_mfma_f32_16x16x32_bf16 v[114:117], v[16:19], v[224:227], v[68:71]
	v_mfma_f32_16x16x32_bf16 v[68:71], v[22:25], v[220:223], v[80:83]
	v_mfma_f32_16x16x32_bf16 v[110:113], v[26:29], v[224:227], v[68:71]
	v_mfma_f32_16x16x32_bf16 v[68:71], v[12:15], v[228:231], v[84:87]
	v_mfma_f32_16x16x32_bf16 v[98:101], v[16:19], v[232:235], v[68:71]
	v_mfma_f32_16x16x32_bf16 v[68:71], v[22:25], v[228:231], v[88:91]
	v_mfma_f32_16x16x32_bf16 v[94:97], v[26:29], v[232:235], v[68:71]
	v_mfma_f32_16x16x32_bf16 v[68:71], v[12:15], v[236:239], v[102:105]
	v_mfma_f32_16x16x32_bf16 v[82:85], v[16:19], v[240:243], v[68:71]
	v_mfma_f32_16x16x32_bf16 v[68:71], v[22:25], v[236:239], v[106:109]
	v_mfma_f32_16x16x32_bf16 v[78:81], v[26:29], v[240:243], v[68:71]
	s_setprio 0
	s_setprio 1
	v_mfma_f32_16x16x32_bf16 v[68:71], v[204:207], v[30:33], v[118:121]
	v_mfma_f32_16x16x32_bf16 v[30:33], v[212:215], v[30:33], v[36:39]
	v_mfma_f32_16x16x32_bf16 v[118:121], v[216:219], v[64:67], v[30:33]
	v_mfma_f32_16x16x32_bf16 v[30:33], v[204:207], v[220:223], v[40:43]
	v_mfma_f32_16x16x32_bf16 v[106:109], v[208:211], v[224:227], v[30:33]
	v_mfma_f32_16x16x32_bf16 v[30:33], v[212:215], v[220:223], v[44:47]
	v_mfma_f32_16x16x32_bf16 v[102:105], v[216:219], v[224:227], v[30:33]
	v_mfma_f32_16x16x32_bf16 v[30:33], v[204:207], v[228:231], v[48:51]
	v_mfma_f32_16x16x32_bf16 v[90:93], v[208:211], v[232:235], v[30:33]
	v_mfma_f32_16x16x32_bf16 v[30:33], v[212:215], v[228:231], v[52:55]
	v_mfma_f32_16x16x32_bf16 v[86:89], v[216:219], v[232:235], v[30:33]
	v_mfma_f32_16x16x32_bf16 v[30:33], v[204:207], v[236:239], v[56:59]
	v_mfma_f32_16x16x32_bf16 v[74:77], v[208:211], v[240:243], v[30:33]
	v_mfma_f32_16x16x32_bf16 v[30:33], v[212:215], v[236:239], v[60:63]
	v_mfma_f32_16x16x32_bf16 v[122:125], v[208:211], v[64:67], v[68:71]
	v_mfma_f32_16x16x32_bf16 v[70:73], v[216:219], v[240:243], v[30:33]
	s_setprio 0
	s_barrier
	ds_read_b128 v[38:41], v149 offset:49152
	ds_read_b128 v[42:45], v149 offset:50176
	ds_read_b128 v[220:223], v149 offset:51200
	ds_read_b128 v[224:227], v149 offset:52224
	ds_read_b128 v[228:231], v149 offset:53248
	ds_read_b128 v[232:235], v149 offset:54272
	ds_read_b128 v[236:239], v149 offset:55296
	ds_read_b128 v[240:243], v149 offset:56320
	s_add_u32 s30, s58, 0x180
	s_addc_u32 s31, s59, 0
	s_mov_b32 m0, s75
	s_nop 0
	global_load_lds_dwordx4 v142, s[30:31] offset:0
	s_nop 0
	s_mov_b32 m0, s76
	s_nop 0
	global_load_lds_dwordx4 v144, s[30:31] offset:0
	s_add_u32 s30, s58, 0x80180
	s_addc_u32 s31, s59, 0
	s_mov_b32 m0, s79
	s_nop 0
	global_load_lds_dwordx4 v142, s[30:31] offset:0
	s_nop 0
	s_mov_b32 m0, s80
	s_nop 0
	global_load_lds_dwordx4 v144, s[30:31] offset:0
	s_nop 0
	s_mov_b32 m0, s77
	s_nop 0
	global_load_lds_dwordx4 v1, s[40:41] offset:0
	s_nop 0
	s_mov_b32 m0, s78
	s_nop 0
	global_load_lds_dwordx4 v143, s[40:41] offset:0
	s_waitcnt vmcnt(8)
	s_waitcnt lgkmcnt(0)
	s_barrier
	s_setprio 1
	v_mfma_f32_16x16x32_bf16 v[30:33], v[12:15], v[38:41], v[138:141]
	v_mfma_f32_16x16x32_bf16 v[66:69], v[16:19], v[42:45], v[30:33]
	v_mfma_f32_16x16x32_bf16 v[30:33], v[22:25], v[38:41], v[152:155]
	v_mfma_f32_16x16x32_bf16 v[62:65], v[26:29], v[42:45], v[30:33]
	v_mfma_f32_16x16x32_bf16 v[30:33], v[12:15], v[220:223], v[156:159]
	v_mfma_f32_16x16x32_bf16 v[50:53], v[16:19], v[224:227], v[30:33]
	v_mfma_f32_16x16x32_bf16 v[30:33], v[22:25], v[220:223], v[160:163]
	v_mfma_f32_16x16x32_bf16 v[46:49], v[26:29], v[224:227], v[30:33]
	v_mfma_f32_16x16x32_bf16 v[30:33], v[12:15], v[228:231], v[164:167]
	v_mfma_f32_16x16x32_bf16 v[4:7], v[12:15], v[236:239], v[4:7]
	v_mfma_f32_16x16x32_bf16 v[34:37], v[16:19], v[232:235], v[30:33]
	v_mfma_f32_16x16x32_bf16 v[30:33], v[22:25], v[228:231], v[168:171]
	v_mfma_f32_16x16x32_bf16 v[18:21], v[16:19], v[240:243], v[4:7]
	v_mfma_f32_16x16x32_bf16 v[4:7], v[22:25], v[236:239], v[8:11]
	v_mfma_f32_16x16x32_bf16 v[30:33], v[26:29], v[232:235], v[30:33]
	v_mfma_f32_16x16x32_bf16 v[14:17], v[26:29], v[240:243], v[4:7]
	s_setprio 0
	s_setprio 1
	v_mfma_f32_16x16x32_bf16 v[4:7], v[204:207], v[38:41], v[172:175]
	v_mfma_f32_16x16x32_bf16 v[58:61], v[208:211], v[42:45], v[4:7]
	v_mfma_f32_16x16x32_bf16 v[4:7], v[212:215], v[38:41], v[176:179]
	v_mfma_f32_16x16x32_bf16 v[54:57], v[216:219], v[42:45], v[4:7]
	v_mfma_f32_16x16x32_bf16 v[4:7], v[204:207], v[220:223], v[180:183]
	v_mfma_f32_16x16x32_bf16 v[42:45], v[208:211], v[224:227], v[4:7]
	v_mfma_f32_16x16x32_bf16 v[4:7], v[212:215], v[220:223], v[184:187]
	v_mfma_f32_16x16x32_bf16 v[38:41], v[216:219], v[224:227], v[4:7]
	v_mfma_f32_16x16x32_bf16 v[4:7], v[204:207], v[228:231], v[188:191]
	v_mfma_f32_16x16x32_bf16 v[26:29], v[208:211], v[232:235], v[4:7]
	v_mfma_f32_16x16x32_bf16 v[4:7], v[212:215], v[228:231], v[192:195]
	v_mfma_f32_16x16x32_bf16 v[22:25], v[216:219], v[232:235], v[4:7]
	v_mfma_f32_16x16x32_bf16 v[4:7], v[204:207], v[236:239], v[196:199]
	v_mfma_f32_16x16x32_bf16 v[10:13], v[208:211], v[240:243], v[4:7]
	v_mfma_f32_16x16x32_bf16 v[4:7], v[212:215], v[236:239], v[200:203]
	v_mfma_f32_16x16x32_bf16 v[6:9], v[216:219], v[240:243], v[4:7]
	s_setprio 0
	s_barrier
	s_mov_b32 s64, 2
	s_branch .LBB0_627

.LBB0_628:
	ds_read_b128 v[138:141], v147
	ds_read_b128 v[152:155], v147 offset:1024
	ds_read_b128 v[156:159], v147 offset:2048
	ds_read_b128 v[160:163], v147 offset:3072
	ds_read_b128 v[164:167], v148
	ds_read_b128 v[168:171], v148 offset:1024
	ds_read_b128 v[172:175], v148 offset:2048
	ds_read_b128 v[176:179], v148 offset:3072
	s_cmp_eq_u32 s88, 28
	s_cselect_b32 s66, s47, s91
	s_cselect_b32 s67, s39, s92
	s_cselect_b32 s64, s87, s89
	s_cselect_b32 s65, s37, s90
	s_add_u32 s58, s66, 0x80
	s_addc_u32 s59, s67, 0
	ds_read_b128 v[180:183], v149
	ds_read_b128 v[184:187], v149 offset:1024
	ds_read_b128 v[188:191], v149 offset:2048
	ds_read_b128 v[192:195], v149 offset:3072
	ds_read_b128 v[196:199], v149 offset:4096
	ds_read_b128 v[200:203], v149 offset:5120
	ds_read_b128 v[204:207], v149 offset:6144
	ds_read_b128 v[208:211], v149 offset:7168
	s_mov_b32 m0, s81
	s_nop 0
	global_load_lds_dwordx4 v1, s[56:57] offset:0
	s_nop 0
	s_mov_b32 m0, s82
	s_nop 0
	global_load_lds_dwordx4 v143, s[56:57] offset:0
	s_waitcnt vmcnt(8)
	s_waitcnt lgkmcnt(0)
	s_barrier
	s_setprio 1
	v_mfma_f32_16x16x32_bf16 v[130:133], v[138:141], v[180:183], v[130:133]
	v_mfma_f32_16x16x32_bf16 v[130:133], v[152:155], v[184:187], v[130:133]
	v_mfma_f32_16x16x32_bf16 v[126:129], v[156:159], v[180:183], v[126:129]
	v_mfma_f32_16x16x32_bf16 v[126:129], v[160:163], v[184:187], v[126:129]
	v_mfma_f32_16x16x32_bf16 v[114:117], v[138:141], v[188:191], v[114:117]
	v_mfma_f32_16x16x32_bf16 v[114:117], v[152:155], v[192:195], v[114:117]
	v_mfma_f32_16x16x32_bf16 v[110:113], v[156:159], v[188:191], v[110:113]
	v_mfma_f32_16x16x32_bf16 v[110:113], v[160:163], v[192:195], v[110:113]
	v_mfma_f32_16x16x32_bf16 v[98:101], v[138:141], v[196:199], v[98:101]
	v_mfma_f32_16x16x32_bf16 v[98:101], v[152:155], v[200:203], v[98:101]
	v_mfma_f32_16x16x32_bf16 v[94:97], v[156:159], v[196:199], v[94:97]
	v_mfma_f32_16x16x32_bf16 v[94:97], v[160:163], v[200:203], v[94:97]
	v_mfma_f32_16x16x32_bf16 v[82:85], v[138:141], v[204:207], v[82:85]
	v_mfma_f32_16x16x32_bf16 v[82:85], v[152:155], v[208:211], v[82:85]
	v_mfma_f32_16x16x32_bf16 v[78:81], v[156:159], v[204:207], v[78:81]
	v_mfma_f32_16x16x32_bf16 v[78:81], v[160:163], v[208:211], v[78:81]
	s_setprio 0
	s_setprio 1
	v_mfma_f32_16x16x32_bf16 v[122:125], v[164:167], v[180:183], v[122:125]
	v_mfma_f32_16x16x32_bf16 v[122:125], v[168:171], v[184:187], v[122:125]
	v_mfma_f32_16x16x32_bf16 v[118:121], v[172:175], v[180:183], v[118:121]
	v_mfma_f32_16x16x32_bf16 v[118:121], v[176:179], v[184:187], v[118:121]
	v_mfma_f32_16x16x32_bf16 v[106:109], v[164:167], v[188:191], v[106:109]
	v_mfma_f32_16x16x32_bf16 v[106:109], v[168:171], v[192:195], v[106:109]
	v_mfma_f32_16x16x32_bf16 v[102:105], v[172:175], v[188:191], v[102:105]
	v_mfma_f32_16x16x32_bf16 v[102:105], v[176:179], v[192:195], v[102:105]
	v_mfma_f32_16x16x32_bf16 v[90:93], v[164:167], v[196:199], v[90:93]
	v_mfma_f32_16x16x32_bf16 v[90:93], v[168:171], v[200:203], v[90:93]
	v_mfma_f32_16x16x32_bf16 v[86:89], v[172:175], v[196:199], v[86:89]
	v_mfma_f32_16x16x32_bf16 v[86:89], v[176:179], v[200:203], v[86:89]
	v_mfma_f32_16x16x32_bf16 v[74:77], v[164:167], v[204:207], v[74:77]
	v_mfma_f32_16x16x32_bf16 v[74:77], v[168:171], v[208:211], v[74:77]
	v_mfma_f32_16x16x32_bf16 v[70:73], v[172:175], v[204:207], v[70:73]
	v_mfma_f32_16x16x32_bf16 v[70:73], v[176:179], v[208:211], v[70:73]
	s_setprio 0
	s_barrier
	ds_read_b128 v[180:183], v149 offset:16384
	ds_read_b128 v[184:187], v149 offset:17408
	ds_read_b128 v[188:191], v149 offset:18432
	ds_read_b128 v[192:195], v149 offset:19456
	ds_read_b128 v[196:199], v149 offset:20480
	ds_read_b128 v[200:203], v149 offset:21504
	ds_read_b128 v[204:207], v149 offset:22528
	ds_read_b128 v[208:211], v149 offset:23552
	s_mov_b32 m0, s52
	s_nop 0
	global_load_lds_dwordx4 v142, s[64:65] offset:0
	s_add_u32 s30, s64, 0x80000
	s_mov_b32 m0, s53
	s_nop 0
	global_load_lds_dwordx4 v144, s[64:65] offset:0
	s_addc_u32 s31, s65, 0
	s_mov_b32 m0, s55
	s_nop 0
	global_load_lds_dwordx4 v142, s[30:31] offset:0
	s_nop 0
	s_mov_b32 m0, s68
	s_nop 0
	global_load_lds_dwordx4 v144, s[30:31] offset:0
	s_nop 0
	s_mov_b32 m0, s33
	s_nop 0
	global_load_lds_dwordx4 v1, s[66:67] offset:0
	s_nop 0
	s_mov_b32 m0, s69
	s_nop 0
	global_load_lds_dwordx4 v143, s[66:67] offset:0
	s_waitcnt vmcnt(8)
	s_waitcnt lgkmcnt(0)
	s_barrier
	s_setprio 1
	v_mfma_f32_16x16x32_bf16 v[66:69], v[138:141], v[180:183], v[66:69]
	v_mfma_f32_16x16x32_bf16 v[66:69], v[152:155], v[184:187], v[66:69]
	v_mfma_f32_16x16x32_bf16 v[62:65], v[156:159], v[180:183], v[62:65]
	v_mfma_f32_16x16x32_bf16 v[62:65], v[160:163], v[184:187], v[62:65]
	v_mfma_f32_16x16x32_bf16 v[50:53], v[138:141], v[188:191], v[50:53]
	v_mfma_f32_16x16x32_bf16 v[50:53], v[152:155], v[192:195], v[50:53]
	v_mfma_f32_16x16x32_bf16 v[46:49], v[156:159], v[188:191], v[46:49]
	v_mfma_f32_16x16x32_bf16 v[46:49], v[160:163], v[192:195], v[46:49]
	v_mfma_f32_16x16x32_bf16 v[34:37], v[138:141], v[196:199], v[34:37]
	v_mfma_f32_16x16x32_bf16 v[34:37], v[152:155], v[200:203], v[34:37]
	v_mfma_f32_16x16x32_bf16 v[30:33], v[156:159], v[196:199], v[30:33]
	v_mfma_f32_16x16x32_bf16 v[30:33], v[160:163], v[200:203], v[30:33]
	v_mfma_f32_16x16x32_bf16 v[18:21], v[138:141], v[204:207], v[18:21]
	v_mfma_f32_16x16x32_bf16 v[18:21], v[152:155], v[208:211], v[18:21]
	v_mfma_f32_16x16x32_bf16 v[14:17], v[156:159], v[204:207], v[14:17]
	v_mfma_f32_16x16x32_bf16 v[14:17], v[160:163], v[208:211], v[14:17]
	s_setprio 0
	s_setprio 1
	v_mfma_f32_16x16x32_bf16 v[58:61], v[164:167], v[180:183], v[58:61]
	v_mfma_f32_16x16x32_bf16 v[54:57], v[172:175], v[180:183], v[54:57]
	v_mfma_f32_16x16x32_bf16 v[42:45], v[164:167], v[188:191], v[42:45]
	v_mfma_f32_16x16x32_bf16 v[38:41], v[172:175], v[188:191], v[38:41]
	v_mfma_f32_16x16x32_bf16 v[26:29], v[164:167], v[196:199], v[26:29]
	v_mfma_f32_16x16x32_bf16 v[22:25], v[172:175], v[196:199], v[22:25]
	v_mfma_f32_16x16x32_bf16 v[10:13], v[164:167], v[204:207], v[10:13]
	v_mfma_f32_16x16x32_bf16 v[4:7], v[172:175], v[204:207], v[6:9]
	v_mfma_f32_16x16x32_bf16 v[58:61], v[168:171], v[184:187], v[58:61]
	v_mfma_f32_16x16x32_bf16 v[54:57], v[176:179], v[184:187], v[54:57]
	v_mfma_f32_16x16x32_bf16 v[42:45], v[168:171], v[192:195], v[42:45]
	v_mfma_f32_16x16x32_bf16 v[38:41], v[176:179], v[192:195], v[38:41]
	v_mfma_f32_16x16x32_bf16 v[26:29], v[168:171], v[200:203], v[26:29]
	v_mfma_f32_16x16x32_bf16 v[22:25], v[176:179], v[200:203], v[22:25]
	v_mfma_f32_16x16x32_bf16 v[10:13], v[168:171], v[208:211], v[10:13]
	v_mfma_f32_16x16x32_bf16 v[4:7], v[176:179], v[208:211], v[4:7]
	s_setprio 0
	s_barrier
; #define PG8_KSETUP() const bool last = (t == nt - 2); const char* a1 = cA + (size_t)(t + 1) * kstep; \
;             const char* a2 = last ? nA : cA + (size_t)(t + 2) * kstep; const char* b2 = last ? nB : cB + (size_t)(t + 2) * kstep; const char* a3 = a2 + kstep; const char* b3 = b2 + kstep; \
;             if (last && has_next) S.a_ready(nxt)
; template <class Epi, class Sched, bool ALIGN_EPI = false, bool SP2 = false>
; __device__ __forceinline__ void gemm_phase(PG8_LAS unsigned char* lds, const Gemm g, const Sched& S, const Epi& E) {
;     ...
;         int t0 = 0;
;         if constexpr (SP2 && Epi::NVM == 16) { if (ui > 0) { const int t = 0; PG8_KSETUP(); PG8_KITER_SP2(24, 24); t0 = 2; } }
;         if constexpr (SP2 && Epi::NVM == 8) { if (ui > 0) { const int t = 0; PG8_KSETUP(); PG8_KITER_SP2(16, 16); t0 = 2; } }
;         for (int t = t0; t < nt; t += 2) {
	ds_read_b128 v[138:141], v150
	ds_read_b128 v[152:155], v150 offset:1024
	ds_read_b128 v[156:159], v150 offset:2048
	ds_read_b128 v[160:163], v150 offset:3072
	ds_read_b128 v[164:167], v151
	ds_read_b128 v[168:171], v151 offset:1024
	ds_read_b128 v[172:175], v151 offset:2048
	ds_read_b128 v[176:179], v151 offset:3072
	ds_read_b128 v[180:183], v149 offset:32768
	ds_read_b128 v[184:187], v149 offset:33792
	ds_read_b128 v[188:191], v149 offset:34816
	ds_read_b128 v[192:195], v149 offset:35840
	ds_read_b128 v[196:199], v149 offset:36864
	ds_read_b128 v[200:203], v149 offset:37888
	ds_read_b128 v[204:207], v149 offset:38912
	ds_read_b128 v[208:211], v149 offset:39936
	s_add_u32 s30, s66, 0x80000
	s_addc_u32 s31, s67, 0
	s_mov_b32 m0, s70
	s_nop 0
	global_load_lds_dwordx4 v1, s[30:31] offset:0
	s_nop 0
	s_mov_b32 m0, s71
	s_nop 0
	global_load_lds_dwordx4 v143, s[30:31] offset:0
	s_waitcnt vmcnt(8)
	s_waitcnt lgkmcnt(0)
	s_barrier
	s_setprio 1
	v_mfma_f32_16x16x32_bf16 v[130:133], v[138:141], v[180:183], v[130:133]
	v_mfma_f32_16x16x32_bf16 v[130:133], v[152:155], v[184:187], v[130:133]
	v_mfma_f32_16x16x32_bf16 v[126:129], v[156:159], v[180:183], v[126:129]
	v_mfma_f32_16x16x32_bf16 v[126:129], v[160:163], v[184:187], v[126:129]
	v_mfma_f32_16x16x32_bf16 v[114:117], v[138:141], v[188:191], v[114:117]
	v_mfma_f32_16x16x32_bf16 v[114:117], v[152:155], v[192:195], v[114:117]
	v_mfma_f32_16x16x32_bf16 v[110:113], v[156:159], v[188:191], v[110:113]
	v_mfma_f32_16x16x32_bf16 v[110:113], v[160:163], v[192:195], v[110:113]
	v_mfma_f32_16x16x32_bf16 v[98:101], v[138:141], v[196:199], v[98:101]
	v_mfma_f32_16x16x32_bf16 v[98:101], v[152:155], v[200:203], v[98:101]
	v_mfma_f32_16x16x32_bf16 v[94:97], v[156:159], v[196:199], v[94:97]
	v_mfma_f32_16x16x32_bf16 v[94:97], v[160:163], v[200:203], v[94:97]
	v_mfma_f32_16x16x32_bf16 v[82:85], v[138:141], v[204:207], v[82:85]
	v_mfma_f32_16x16x32_bf16 v[82:85], v[152:155], v[208:211], v[82:85]
	v_mfma_f32_16x16x32_bf16 v[78:81], v[156:159], v[204:207], v[78:81]
	v_mfma_f32_16x16x32_bf16 v[78:81], v[160:163], v[208:211], v[78:81]
	s_setprio 0
	s_setprio 1
	v_mfma_f32_16x16x32_bf16 v[122:125], v[164:167], v[180:183], v[122:125]
	v_mfma_f32_16x16x32_bf16 v[122:125], v[168:171], v[184:187], v[122:125]
	v_mfma_f32_16x16x32_bf16 v[118:121], v[172:175], v[180:183], v[118:121]
	v_mfma_f32_16x16x32_bf16 v[118:121], v[176:179], v[184:187], v[118:121]
	v_mfma_f32_16x16x32_bf16 v[106:109], v[164:167], v[188:191], v[106:109]
	v_mfma_f32_16x16x32_bf16 v[106:109], v[168:171], v[192:195], v[106:109]
	v_mfma_f32_16x16x32_bf16 v[102:105], v[172:175], v[188:191], v[102:105]
	v_mfma_f32_16x16x32_bf16 v[102:105], v[176:179], v[192:195], v[102:105]
	v_mfma_f32_16x16x32_bf16 v[90:93], v[164:167], v[196:199], v[90:93]
	v_mfma_f32_16x16x32_bf16 v[90:93], v[168:171], v[200:203], v[90:93]
	v_mfma_f32_16x16x32_bf16 v[86:89], v[172:175], v[196:199], v[86:89]
	v_mfma_f32_16x16x32_bf16 v[86:89], v[176:179], v[200:203], v[86:89]
	v_mfma_f32_16x16x32_bf16 v[74:77], v[164:167], v[204:207], v[74:77]
	v_mfma_f32_16x16x32_bf16 v[74:77], v[168:171], v[208:211], v[74:77]
	v_mfma_f32_16x16x32_bf16 v[70:73], v[172:175], v[204:207], v[70:73]
	v_mfma_f32_16x16x32_bf16 v[70:73], v[176:179], v[208:211], v[70:73]
	s_setprio 0
	s_barrier
	ds_read_b128 v[180:183], v149 offset:49152
	ds_read_b128 v[184:187], v149 offset:50176
	ds_read_b128 v[188:191], v149 offset:51200
	ds_read_b128 v[192:195], v149 offset:52224
	ds_read_b128 v[196:199], v149 offset:53248
	ds_read_b128 v[200:203], v149 offset:54272
	ds_read_b128 v[204:207], v149 offset:55296
	ds_read_b128 v[208:211], v149 offset:56320
	s_add_u32 s30, s64, 0x80
	s_addc_u32 s31, s65, 0
	s_mov_b32 m0, s75
	s_nop 0
	global_load_lds_dwordx4 v142, s[30:31] offset:0
	s_nop 0
	s_mov_b32 m0, s76
	s_nop 0
	global_load_lds_dwordx4 v144, s[30:31] offset:0
	s_add_u32 s30, s64, 0x80080
	s_addc_u32 s31, s65, 0
	s_mov_b32 m0, s79
	s_nop 0
	global_load_lds_dwordx4 v142, s[30:31] offset:0
	s_nop 0
	s_mov_b32 m0, s80
	s_nop 0
	global_load_lds_dwordx4 v144, s[30:31] offset:0
	s_nop 0
	s_mov_b32 m0, s77
	s_nop 0
	global_load_lds_dwordx4 v1, s[58:59] offset:0
	s_nop 0
	s_mov_b32 m0, s78
	s_nop 0
	global_load_lds_dwordx4 v143, s[58:59] offset:0
	s_waitcnt vmcnt(8)
	s_waitcnt lgkmcnt(0)
	s_barrier
	s_setprio 1
	v_mfma_f32_16x16x32_bf16 v[66:69], v[138:141], v[180:183], v[66:69]
	v_mfma_f32_16x16x32_bf16 v[66:69], v[152:155], v[184:187], v[66:69]
	v_mfma_f32_16x16x32_bf16 v[62:65], v[156:159], v[180:183], v[62:65]
	v_mfma_f32_16x16x32_bf16 v[62:65], v[160:163], v[184:187], v[62:65]
	v_mfma_f32_16x16x32_bf16 v[50:53], v[138:141], v[188:191], v[50:53]
	v_mfma_f32_16x16x32_bf16 v[50:53], v[152:155], v[192:195], v[50:53]
	v_mfma_f32_16x16x32_bf16 v[46:49], v[156:159], v[188:191], v[46:49]
	v_mfma_f32_16x16x32_bf16 v[46:49], v[160:163], v[192:195], v[46:49]
	v_mfma_f32_16x16x32_bf16 v[34:37], v[138:141], v[196:199], v[34:37]
	v_mfma_f32_16x16x32_bf16 v[34:37], v[152:155], v[200:203], v[34:37]
	v_mfma_f32_16x16x32_bf16 v[30:33], v[156:159], v[196:199], v[30:33]
	v_mfma_f32_16x16x32_bf16 v[30:33], v[160:163], v[200:203], v[30:33]
	v_mfma_f32_16x16x32_bf16 v[18:21], v[138:141], v[204:207], v[18:21]
	v_mfma_f32_16x16x32_bf16 v[18:21], v[152:155], v[208:211], v[18:21]
	v_mfma_f32_16x16x32_bf16 v[14:17], v[156:159], v[204:207], v[14:17]
	v_mfma_f32_16x16x32_bf16 v[14:17], v[160:163], v[208:211], v[14:17]
	s_setprio 0
	s_setprio 1
	v_mfma_f32_16x16x32_bf16 v[58:61], v[164:167], v[180:183], v[58:61]
	v_mfma_f32_16x16x32_bf16 v[54:57], v[172:175], v[180:183], v[54:57]
	v_mfma_f32_16x16x32_bf16 v[42:45], v[164:167], v[188:191], v[42:45]
	v_mfma_f32_16x16x32_bf16 v[38:41], v[172:175], v[188:191], v[38:41]
	v_mfma_f32_16x16x32_bf16 v[26:29], v[164:167], v[196:199], v[26:29]
	v_mfma_f32_16x16x32_bf16 v[22:25], v[172:175], v[196:199], v[22:25]
	v_mfma_f32_16x16x32_bf16 v[8:11], v[164:167], v[204:207], v[10:13]
	v_mfma_f32_16x16x32_bf16 v[4:7], v[172:175], v[204:207], v[4:7]
	v_mfma_f32_16x16x32_bf16 v[58:61], v[168:171], v[184:187], v[58:61]
	v_mfma_f32_16x16x32_bf16 v[54:57], v[176:179], v[184:187], v[54:57]
	v_mfma_f32_16x16x32_bf16 v[42:45], v[168:171], v[192:195], v[42:45]
	v_mfma_f32_16x16x32_bf16 v[38:41], v[176:179], v[192:195], v[38:41]
	v_mfma_f32_16x16x32_bf16 v[26:29], v[168:171], v[200:203], v[26:29]
	v_mfma_f32_16x16x32_bf16 v[22:25], v[176:179], v[200:203], v[22:25]
	v_mfma_f32_16x16x32_bf16 v[10:13], v[168:171], v[208:211], v[8:11]
	v_mfma_f32_16x16x32_bf16 v[6:9], v[176:179], v[208:211], v[4:7]
	s_setprio 0
	s_barrier
	s_add_i32 s88, s88, 2
	s_add_u32 s89, s89, 0x100
	s_addc_u32 s90, s90, 0
	s_add_u32 s91, s91, 0x100
	s_addc_u32 s92, s92, 0
	s_add_u32 s56, s56, 0x100
	s_addc_u32 s57, s57, 0
	s_cmp_gt_u32 s88, 29
	s_cbranch_scc0 .LBB0_628
	s_and_b64 vcc, exec, s[20:21]
	s_cbranch_vccz .LBB0_631
	s_barrier

; #define PG8_KSETUP() const bool last = (t == nt - 2); const char* a1 = cA + (size_t)(t + 1) * kstep; \
;             const char* a2 = last ? nA : cA + (size_t)(t + 2) * kstep; const char* b2 = last ? nB : cB + (size_t)(t + 2) * kstep; const char* a3 = a2 + kstep; const char* b3 = b2 + kstep; \
;             if (last && has_next) S.a_ready(nxt)
; template <class Epi, class Sched, bool ALIGN_EPI = false, bool SP2 = false>
; __device__ __forceinline__ void gemm_phase(PG8_LAS unsigned char* lds, const Gemm g, const Sched& S, const Epi& E) {
;     ...
;         int t0 = 0;
;         if constexpr (SP2 && Epi::NVM == 16) { if (ui > 0) { const int t = 0; PG8_KSETUP(); PG8_KITER_SP2(24, 24); t0 = 2; } }
;         if constexpr (SP2 && Epi::NVM == 8) { if (ui > 0) { const int t = 0; PG8_KSETUP(); PG8_KITER_SP2(16, 16); t0 = 2; } }
.LBB0_783:
	s_cmp_lg_u32 s77, 0
	s_mov_b32 s44, 0
	s_cbranch_scc0 .LBB0_785
	ds_read_b128 v[4:7], v152
	ds_read_b128 v[8:11], v152 offset:1024
	ds_read_b128 v[12:15], v152 offset:2048
	ds_read_b128 v[16:19], v152 offset:3072
	ds_read_b128 v[20:23], v153
	ds_read_b128 v[24:27], v153 offset:1024
	ds_read_b128 v[28:31], v153 offset:2048
	ds_read_b128 v[32:35], v153 offset:3072
	s_add_u32 s28, s38, 0x100
	s_addc_u32 s29, s39, 0
	s_add_u32 s30, s40, 0x100
	s_addc_u32 s31, s41, 0
	s_add_u32 s24, s38, 0x180
	s_addc_u32 s25, s39, 0
	ds_read_b128 v[36:39], v154
	ds_read_b128 v[40:43], v154 offset:1024
	ds_read_b128 v[44:47], v154 offset:2048
	ds_read_b128 v[48:51], v154 offset:3072
	ds_read_b128 v[52:55], v154 offset:4096
	ds_read_b128 v[56:59], v154 offset:5120
	ds_read_b128 v[60:63], v154 offset:6144
	ds_read_b128 v[64:67], v154 offset:7168
	s_add_u32 s42, s38, 0x80080
	s_addc_u32 s43, s39, 0
	s_mov_b32 m0, s68
	s_nop 0
	global_load_lds_dwordx4 v1, s[42:43] offset:0
	s_nop 0
	s_mov_b32 m0, s69
	s_nop 0
	global_load_lds_dwordx4 v147, s[42:43] offset:0
	s_waitcnt vmcnt(16)
	s_waitcnt lgkmcnt(0)
	s_barrier
	s_setprio 1
	v_mfma_f32_16x16x32_bf16 v[92:95], v[4:7], v[60:63], 0
	v_mfma_f32_16x16x32_bf16 v[68:71], v[4:7], v[36:39], 0
	v_mfma_f32_16x16x32_bf16 v[72:75], v[12:15], v[36:39], 0
	v_mfma_f32_16x16x32_bf16 v[76:79], v[4:7], v[44:47], 0
	v_mfma_f32_16x16x32_bf16 v[80:83], v[12:15], v[44:47], 0
	v_mfma_f32_16x16x32_bf16 v[84:87], v[4:7], v[52:55], 0
	v_mfma_f32_16x16x32_bf16 v[88:91], v[12:15], v[52:55], 0
	v_mfma_f32_16x16x32_bf16 v[102:105], v[8:11], v[64:67], v[92:95]
	v_mfma_f32_16x16x32_bf16 v[92:95], v[12:15], v[60:63], 0
	v_mfma_f32_16x16x32_bf16 v[68:71], v[8:11], v[40:43], v[68:71]
	v_mfma_f32_16x16x32_bf16 v[72:75], v[16:19], v[40:43], v[72:75]
	v_mfma_f32_16x16x32_bf16 v[76:79], v[8:11], v[48:51], v[76:79]
	v_mfma_f32_16x16x32_bf16 v[80:83], v[16:19], v[48:51], v[80:83]
	v_mfma_f32_16x16x32_bf16 v[84:87], v[8:11], v[56:59], v[84:87]
	v_mfma_f32_16x16x32_bf16 v[88:91], v[16:19], v[56:59], v[88:91]
	v_mfma_f32_16x16x32_bf16 v[106:109], v[16:19], v[64:67], v[92:95]
	s_setprio 0
	s_setprio 1
	v_mfma_f32_16x16x32_bf16 v[92:95], v[20:23], v[36:39], 0
	v_mfma_f32_16x16x32_bf16 v[36:39], v[28:31], v[36:39], 0
	v_mfma_f32_16x16x32_bf16 v[118:121], v[24:27], v[40:43], v[92:95]
	v_mfma_f32_16x16x32_bf16 v[36:39], v[32:35], v[40:43], v[36:39]
	v_mfma_f32_16x16x32_bf16 v[40:43], v[20:23], v[44:47], 0
	v_mfma_f32_16x16x32_bf16 v[44:47], v[28:31], v[44:47], 0
	v_mfma_f32_16x16x32_bf16 v[40:43], v[24:27], v[48:51], v[40:43]
	v_mfma_f32_16x16x32_bf16 v[44:47], v[32:35], v[48:51], v[44:47]
	v_mfma_f32_16x16x32_bf16 v[48:51], v[20:23], v[52:55], 0
	v_mfma_f32_16x16x32_bf16 v[52:55], v[28:31], v[52:55], 0
	v_mfma_f32_16x16x32_bf16 v[48:51], v[24:27], v[56:59], v[48:51]
	v_mfma_f32_16x16x32_bf16 v[52:55], v[32:35], v[56:59], v[52:55]
	v_mfma_f32_16x16x32_bf16 v[56:59], v[20:23], v[60:63], 0
	v_mfma_f32_16x16x32_bf16 v[60:63], v[28:31], v[60:63], 0
	v_mfma_f32_16x16x32_bf16 v[56:59], v[24:27], v[64:67], v[56:59]
	v_mfma_f32_16x16x32_bf16 v[60:63], v[32:35], v[64:67], v[60:63]
	s_setprio 0
	s_barrier
	ds_read_b128 v[64:67], v154 offset:16384
	ds_read_b128 v[92:95], v154 offset:17408
	ds_read_b128 v[96:99], v154 offset:18432
	ds_read_b128 v[110:113], v154 offset:19456
	ds_read_b128 v[114:117], v154 offset:20480
	ds_read_b128 v[122:125], v154 offset:21504
	ds_read_b128 v[126:129], v154 offset:22528
	ds_read_b128 v[130:133], v154 offset:23552
	s_mov_b32 m0, s37
	s_nop 0
	global_load_lds_dwordx4 v146, s[30:31] offset:0
	s_nop 0
	s_mov_b32 m0, s52
	s_nop 0
	global_load_lds_dwordx4 v148, s[30:31] offset:0
	s_add_u32 s30, s40, 0x80100
	s_addc_u32 s31, s41, 0
	s_mov_b32 m0, s53
	s_nop 0
	global_load_lds_dwordx4 v146, s[30:31] offset:0
	s_nop 0
	s_mov_b32 m0, s54
	s_nop 0
	global_load_lds_dwordx4 v148, s[30:31] offset:0
	s_nop 0
	s_mov_b32 m0, s23
	s_nop 0
	global_load_lds_dwordx4 v1, s[28:29] offset:0
	s_nop 0
	s_mov_b32 m0, s55
	s_nop 0
	global_load_lds_dwordx4 v147, s[28:29] offset:0
	s_waitcnt vmcnt(16)
	s_waitcnt lgkmcnt(0)
	s_barrier
	s_setprio 1
	v_mfma_f32_16x16x32_bf16 v[138:141], v[4:7], v[64:67], 0
	v_mfma_f32_16x16x32_bf16 v[158:161], v[4:7], v[96:99], 0
	v_mfma_f32_16x16x32_bf16 v[166:169], v[4:7], v[114:117], 0
	v_mfma_f32_16x16x32_bf16 v[4:7], v[4:7], v[126:129], 0
	v_mfma_f32_16x16x32_bf16 v[138:141], v[8:11], v[92:95], v[138:141]
	v_mfma_f32_16x16x32_bf16 v[158:161], v[8:11], v[110:113], v[158:161]
	v_mfma_f32_16x16x32_bf16 v[166:169], v[8:11], v[122:125], v[166:169]
	v_mfma_f32_16x16x32_bf16 v[4:7], v[8:11], v[130:133], v[4:7]
	v_mfma_f32_16x16x32_bf16 v[8:11], v[12:15], v[126:129], 0
	v_mfma_f32_16x16x32_bf16 v[142:145], v[12:15], v[64:67], 0
	v_mfma_f32_16x16x32_bf16 v[162:165], v[12:15], v[96:99], 0
	v_mfma_f32_16x16x32_bf16 v[170:173], v[12:15], v[114:117], 0
	v_mfma_f32_16x16x32_bf16 v[8:11], v[16:19], v[130:133], v[8:11]
	v_mfma_f32_16x16x32_bf16 v[142:145], v[16:19], v[92:95], v[142:145]
	v_mfma_f32_16x16x32_bf16 v[162:165], v[16:19], v[110:113], v[162:165]
	v_mfma_f32_16x16x32_bf16 v[170:173], v[16:19], v[122:125], v[170:173]
	s_setprio 0
	s_setprio 1
	v_mfma_f32_16x16x32_bf16 v[12:15], v[20:23], v[64:67], 0
	v_mfma_f32_16x16x32_bf16 v[174:177], v[24:27], v[92:95], v[12:15]
	v_mfma_f32_16x16x32_bf16 v[12:15], v[28:31], v[64:67], 0
	v_mfma_f32_16x16x32_bf16 v[178:181], v[32:35], v[92:95], v[12:15]
	v_mfma_f32_16x16x32_bf16 v[12:15], v[20:23], v[96:99], 0
	v_mfma_f32_16x16x32_bf16 v[182:185], v[24:27], v[110:113], v[12:15]
	v_mfma_f32_16x16x32_bf16 v[12:15], v[28:31], v[96:99], 0
	v_mfma_f32_16x16x32_bf16 v[186:189], v[32:35], v[110:113], v[12:15]
	v_mfma_f32_16x16x32_bf16 v[12:15], v[20:23], v[114:117], 0
	v_mfma_f32_16x16x32_bf16 v[190:193], v[24:27], v[122:125], v[12:15]
	v_mfma_f32_16x16x32_bf16 v[12:15], v[28:31], v[114:117], 0
	v_mfma_f32_16x16x32_bf16 v[194:197], v[32:35], v[122:125], v[12:15]
	v_mfma_f32_16x16x32_bf16 v[12:15], v[20:23], v[126:129], 0
	v_mfma_f32_16x16x32_bf16 v[198:201], v[24:27], v[130:133], v[12:15]
	v_mfma_f32_16x16x32_bf16 v[12:15], v[28:31], v[126:129], 0
	v_mfma_f32_16x16x32_bf16 v[202:205], v[32:35], v[130:133], v[12:15]
	s_setprio 0
	s_barrier
; #define PG8_KSETUP() const bool last = (t == nt - 2); const char* a1 = cA + (size_t)(t + 1) * kstep; \
;             const char* a2 = last ? nA : cA + (size_t)(t + 2) * kstep; const char* b2 = last ? nB : cB + (size_t)(t + 2) * kstep; const char* a3 = a2 + kstep; const char* b3 = b2 + kstep; \
;             if (last && has_next) S.a_ready(nxt)
; template <class Epi, class Sched, bool ALIGN_EPI = false, bool SP2 = false>
; __device__ __forceinline__ void gemm_phase(PG8_LAS unsigned char* lds, const Gemm g, const Sched& S, const Epi& E) {
;     ...
;         int t0 = 0;
;         if constexpr (SP2 && Epi::NVM == 16) { if (ui > 0) { const int t = 0; PG8_KSETUP(); PG8_KITER_SP2(24, 24); t0 = 2; } }
;         if constexpr (SP2 && Epi::NVM == 8) { if (ui > 0) { const int t = 0; PG8_KSETUP(); PG8_KITER_SP2(16, 16); t0 = 2; } }
	s_nop 4
	ds_read_b128 v[12:15], v155
	ds_read_b128 v[16:19], v155 offset:1024
	ds_read_b128 v[22:25], v155 offset:2048
	ds_read_b128 v[26:29], v155 offset:3072
	ds_read_b128 v[206:209], v156
	ds_read_b128 v[210:213], v156 offset:1024
	ds_read_b128 v[214:217], v156 offset:2048
	ds_read_b128 v[218:221], v156 offset:3072
	ds_read_b128 v[30:33], v154 offset:32768
	ds_read_b128 v[64:67], v154 offset:33792
	ds_read_b128 v[222:225], v154 offset:34816
	ds_read_b128 v[226:229], v154 offset:35840
	ds_read_b128 v[230:233], v154 offset:36864
	ds_read_b128 v[234:237], v154 offset:37888
	ds_read_b128 v[238:241], v154 offset:38912
	ds_read_b128 v[242:245], v154 offset:39936
	s_add_u32 s28, s38, 0x80100
	s_addc_u32 s29, s39, 0
	s_mov_b32 m0, s56
	s_nop 0
	global_load_lds_dwordx4 v1, s[28:29] offset:0
	s_nop 0
	s_mov_b32 m0, s57
	s_nop 0
	global_load_lds_dwordx4 v147, s[28:29] offset:0
	s_waitcnt vmcnt(8)
	s_waitcnt lgkmcnt(0)
	s_barrier
	s_setprio 1
	v_mfma_f32_16x16x32_bf16 v[68:71], v[12:15], v[30:33], v[68:71]
	v_mfma_f32_16x16x32_bf16 v[130:133], v[16:19], v[64:67], v[68:71]
	v_mfma_f32_16x16x32_bf16 v[68:71], v[22:25], v[30:33], v[72:75]
	v_mfma_f32_16x16x32_bf16 v[126:129], v[26:29], v[64:67], v[68:71]
	v_mfma_f32_16x16x32_bf16 v[68:71], v[12:15], v[222:225], v[76:79]
	v_mfma_f32_16x16x32_bf16 v[114:117], v[16:19], v[226:229], v[68:71]
	v_mfma_f32_16x16x32_bf16 v[68:71], v[22:25], v[222:225], v[80:83]
	v_mfma_f32_16x16x32_bf16 v[110:113], v[26:29], v[226:229], v[68:71]
	v_mfma_f32_16x16x32_bf16 v[68:71], v[12:15], v[230:233], v[84:87]
	v_mfma_f32_16x16x32_bf16 v[98:101], v[16:19], v[234:237], v[68:71]
	v_mfma_f32_16x16x32_bf16 v[68:71], v[22:25], v[230:233], v[88:91]
	v_mfma_f32_16x16x32_bf16 v[94:97], v[26:29], v[234:237], v[68:71]
	v_mfma_f32_16x16x32_bf16 v[68:71], v[12:15], v[238:241], v[102:105]
	v_mfma_f32_16x16x32_bf16 v[82:85], v[16:19], v[242:245], v[68:71]
	v_mfma_f32_16x16x32_bf16 v[68:71], v[22:25], v[238:241], v[106:109]
	v_mfma_f32_16x16x32_bf16 v[78:81], v[26:29], v[242:245], v[68:71]
	s_setprio 0
	s_setprio 1
	v_mfma_f32_16x16x32_bf16 v[68:71], v[206:209], v[30:33], v[118:121]
	v_mfma_f32_16x16x32_bf16 v[30:33], v[214:217], v[30:33], v[36:39]
	v_mfma_f32_16x16x32_bf16 v[118:121], v[218:221], v[64:67], v[30:33]
	v_mfma_f32_16x16x32_bf16 v[30:33], v[206:209], v[222:225], v[40:43]
	v_mfma_f32_16x16x32_bf16 v[106:109], v[210:213], v[226:229], v[30:33]
	v_mfma_f32_16x16x32_bf16 v[30:33], v[214:217], v[222:225], v[44:47]
	v_mfma_f32_16x16x32_bf16 v[102:105], v[218:221], v[226:229], v[30:33]
	v_mfma_f32_16x16x32_bf16 v[30:33], v[206:209], v[230:233], v[48:51]
	v_mfma_f32_16x16x32_bf16 v[90:93], v[210:213], v[234:237], v[30:33]
	v_mfma_f32_16x16x32_bf16 v[30:33], v[214:217], v[230:233], v[52:55]
	v_mfma_f32_16x16x32_bf16 v[86:89], v[218:221], v[234:237], v[30:33]
	v_mfma_f32_16x16x32_bf16 v[30:33], v[206:209], v[238:241], v[56:59]
	v_mfma_f32_16x16x32_bf16 v[74:77], v[210:213], v[242:245], v[30:33]
	v_mfma_f32_16x16x32_bf16 v[30:33], v[214:217], v[238:241], v[60:63]
	v_mfma_f32_16x16x32_bf16 v[122:125], v[210:213], v[64:67], v[68:71]
	v_mfma_f32_16x16x32_bf16 v[66:69], v[218:221], v[242:245], v[30:33]
	s_setprio 0
	s_barrier
	ds_read_b128 v[38:41], v154 offset:49152
	ds_read_b128 v[42:45], v154 offset:50176
	ds_read_b128 v[222:225], v154 offset:51200
	ds_read_b128 v[226:229], v154 offset:52224
	ds_read_b128 v[230:233], v154 offset:53248
	ds_read_b128 v[234:237], v154 offset:54272
	ds_read_b128 v[238:241], v154 offset:55296
	ds_read_b128 v[242:245], v154 offset:56320
	s_add_u32 s28, s40, 0x180
	s_addc_u32 s29, s41, 0
	s_mov_b32 m0, s58
	s_nop 0
	global_load_lds_dwordx4 v146, s[28:29] offset:0
	s_nop 0
	s_mov_b32 m0, s59
	s_nop 0
	global_load_lds_dwordx4 v148, s[28:29] offset:0
	s_add_u32 s28, s40, 0x80180
	s_addc_u32 s29, s41, 0
	s_mov_b32 m0, s66
	s_nop 0
	global_load_lds_dwordx4 v146, s[28:29] offset:0
	s_nop 0
	s_mov_b32 m0, s67
	s_nop 0
	global_load_lds_dwordx4 v148, s[28:29] offset:0
	s_nop 0
	s_mov_b32 m0, s64
	s_nop 0
	global_load_lds_dwordx4 v1, s[24:25] offset:0
	s_nop 0
	s_mov_b32 m0, s65
	s_nop 0
	global_load_lds_dwordx4 v147, s[24:25] offset:0
	s_waitcnt vmcnt(8)
	s_waitcnt lgkmcnt(0)
	s_barrier
	s_setprio 1
	v_mfma_f32_16x16x32_bf16 v[30:33], v[12:15], v[38:41], v[138:141]
	v_mfma_f32_16x16x32_bf16 v[70:73], v[16:19], v[42:45], v[30:33]
	v_mfma_f32_16x16x32_bf16 v[30:33], v[22:25], v[38:41], v[142:145]
	v_mfma_f32_16x16x32_bf16 v[62:65], v[26:29], v[42:45], v[30:33]
	v_mfma_f32_16x16x32_bf16 v[30:33], v[12:15], v[222:225], v[158:161]
	v_mfma_f32_16x16x32_bf16 v[50:53], v[16:19], v[226:229], v[30:33]
	v_mfma_f32_16x16x32_bf16 v[30:33], v[22:25], v[222:225], v[162:165]
	v_mfma_f32_16x16x32_bf16 v[46:49], v[26:29], v[226:229], v[30:33]
	v_mfma_f32_16x16x32_bf16 v[30:33], v[12:15], v[230:233], v[166:169]
	v_mfma_f32_16x16x32_bf16 v[4:7], v[12:15], v[238:241], v[4:7]
	v_mfma_f32_16x16x32_bf16 v[34:37], v[16:19], v[234:237], v[30:33]
	v_mfma_f32_16x16x32_bf16 v[30:33], v[22:25], v[230:233], v[170:173]
	v_mfma_f32_16x16x32_bf16 v[18:21], v[16:19], v[242:245], v[4:7]
	v_mfma_f32_16x16x32_bf16 v[4:7], v[22:25], v[238:241], v[8:11]
	v_mfma_f32_16x16x32_bf16 v[30:33], v[26:29], v[234:237], v[30:33]
	v_mfma_f32_16x16x32_bf16 v[14:17], v[26:29], v[242:245], v[4:7]
	s_setprio 0
	s_setprio 1
	v_mfma_f32_16x16x32_bf16 v[4:7], v[206:209], v[38:41], v[174:177]
	v_mfma_f32_16x16x32_bf16 v[58:61], v[210:213], v[42:45], v[4:7]
	v_mfma_f32_16x16x32_bf16 v[4:7], v[214:217], v[38:41], v[178:181]
	v_mfma_f32_16x16x32_bf16 v[54:57], v[218:221], v[42:45], v[4:7]
	v_mfma_f32_16x16x32_bf16 v[4:7], v[206:209], v[222:225], v[182:185]
	v_mfma_f32_16x16x32_bf16 v[42:45], v[210:213], v[226:229], v[4:7]
	v_mfma_f32_16x16x32_bf16 v[4:7], v[214:217], v[222:225], v[186:189]
	v_mfma_f32_16x16x32_bf16 v[38:41], v[218:221], v[226:229], v[4:7]
	v_mfma_f32_16x16x32_bf16 v[4:7], v[206:209], v[230:233], v[190:193]
	v_mfma_f32_16x16x32_bf16 v[26:29], v[210:213], v[234:237], v[4:7]
	v_mfma_f32_16x16x32_bf16 v[4:7], v[214:217], v[230:233], v[194:197]
	v_mfma_f32_16x16x32_bf16 v[22:25], v[218:221], v[234:237], v[4:7]
	v_mfma_f32_16x16x32_bf16 v[4:7], v[206:209], v[238:241], v[198:201]
	v_mfma_f32_16x16x32_bf16 v[10:13], v[210:213], v[242:245], v[4:7]
	v_mfma_f32_16x16x32_bf16 v[4:7], v[214:217], v[238:241], v[202:205]
	v_mfma_f32_16x16x32_bf16 v[6:9], v[218:221], v[242:245], v[4:7]
	s_setprio 0
	s_barrier
	s_mov_b32 s44, 2
	s_branch .LBB0_786

.LBB0_787:
	ds_read_b128 v[138:141], v152
	ds_read_b128 v[142:145], v152 offset:1024
	ds_read_b128 v[158:161], v152 offset:2048
	ds_read_b128 v[162:165], v152 offset:3072
	ds_read_b128 v[166:169], v153
	ds_read_b128 v[170:173], v153 offset:1024
	ds_read_b128 v[174:177], v153 offset:2048
	ds_read_b128 v[178:181], v153 offset:3072
	s_cmp_eq_u32 s80, 28
	s_cselect_b32 s44, s78, s83
	s_cselect_b32 s45, s21, s84
	s_cselect_b32 s40, s79, s81
	s_cselect_b32 s41, s19, s82
	s_add_u32 s38, s44, 0x80
	s_addc_u32 s39, s45, 0
	ds_read_b128 v[182:185], v154
	ds_read_b128 v[186:189], v154 offset:1024
	ds_read_b128 v[190:193], v154 offset:2048
	ds_read_b128 v[194:197], v154 offset:3072
	ds_read_b128 v[198:201], v154 offset:4096
	ds_read_b128 v[202:205], v154 offset:5120
	ds_read_b128 v[206:209], v154 offset:6144
	ds_read_b128 v[210:213], v154 offset:7168
	s_add_u32 s30, s83, 0x7ff80
	s_addc_u32 s31, s84, 0
	s_mov_b32 m0, s68
	s_nop 0
	global_load_lds_dwordx4 v1, s[30:31] offset:0
	s_nop 0
	s_mov_b32 m0, s69
	s_nop 0
	global_load_lds_dwordx4 v147, s[30:31] offset:0
	s_waitcnt vmcnt(8)
	s_waitcnt lgkmcnt(0)
	s_barrier
	s_setprio 1
	v_mfma_f32_16x16x32_bf16 v[130:133], v[138:141], v[182:185], v[130:133]
	v_mfma_f32_16x16x32_bf16 v[130:133], v[142:145], v[186:189], v[130:133]
	v_mfma_f32_16x16x32_bf16 v[126:129], v[158:161], v[182:185], v[126:129]
	v_mfma_f32_16x16x32_bf16 v[126:129], v[162:165], v[186:189], v[126:129]
	v_mfma_f32_16x16x32_bf16 v[114:117], v[138:141], v[190:193], v[114:117]
	v_mfma_f32_16x16x32_bf16 v[114:117], v[142:145], v[194:197], v[114:117]
	v_mfma_f32_16x16x32_bf16 v[110:113], v[158:161], v[190:193], v[110:113]
	v_mfma_f32_16x16x32_bf16 v[110:113], v[162:165], v[194:197], v[110:113]
	v_mfma_f32_16x16x32_bf16 v[98:101], v[138:141], v[198:201], v[98:101]
	v_mfma_f32_16x16x32_bf16 v[98:101], v[142:145], v[202:205], v[98:101]
	v_mfma_f32_16x16x32_bf16 v[94:97], v[158:161], v[198:201], v[94:97]
	v_mfma_f32_16x16x32_bf16 v[94:97], v[162:165], v[202:205], v[94:97]
	v_mfma_f32_16x16x32_bf16 v[82:85], v[138:141], v[206:209], v[82:85]
	v_mfma_f32_16x16x32_bf16 v[82:85], v[142:145], v[210:213], v[82:85]
	v_mfma_f32_16x16x32_bf16 v[78:81], v[158:161], v[206:209], v[78:81]
	v_mfma_f32_16x16x32_bf16 v[78:81], v[162:165], v[210:213], v[78:81]
	s_setprio 0
	s_setprio 1
	v_mfma_f32_16x16x32_bf16 v[122:125], v[166:169], v[182:185], v[122:125]
	v_mfma_f32_16x16x32_bf16 v[122:125], v[170:173], v[186:189], v[122:125]
	v_mfma_f32_16x16x32_bf16 v[118:121], v[174:177], v[182:185], v[118:121]
	v_mfma_f32_16x16x32_bf16 v[118:121], v[178:181], v[186:189], v[118:121]
	v_mfma_f32_16x16x32_bf16 v[106:109], v[166:169], v[190:193], v[106:109]
	v_mfma_f32_16x16x32_bf16 v[106:109], v[170:173], v[194:197], v[106:109]
	v_mfma_f32_16x16x32_bf16 v[102:105], v[174:177], v[190:193], v[102:105]
	v_mfma_f32_16x16x32_bf16 v[102:105], v[178:181], v[194:197], v[102:105]
	v_mfma_f32_16x16x32_bf16 v[90:93], v[166:169], v[198:201], v[90:93]
	v_mfma_f32_16x16x32_bf16 v[90:93], v[170:173], v[202:205], v[90:93]
	v_mfma_f32_16x16x32_bf16 v[86:89], v[174:177], v[198:201], v[86:89]
	v_mfma_f32_16x16x32_bf16 v[86:89], v[178:181], v[202:205], v[86:89]
	v_mfma_f32_16x16x32_bf16 v[74:77], v[166:169], v[206:209], v[74:77]
	v_mfma_f32_16x16x32_bf16 v[74:77], v[170:173], v[210:213], v[74:77]
	v_mfma_f32_16x16x32_bf16 v[66:69], v[174:177], v[206:209], v[66:69]
	v_mfma_f32_16x16x32_bf16 v[66:69], v[178:181], v[210:213], v[66:69]
	s_setprio 0
	s_barrier
	ds_read_b128 v[182:185], v154 offset:16384
	ds_read_b128 v[186:189], v154 offset:17408
	ds_read_b128 v[190:193], v154 offset:18432
	ds_read_b128 v[194:197], v154 offset:19456
	ds_read_b128 v[198:201], v154 offset:20480
	ds_read_b128 v[202:205], v154 offset:21504
	ds_read_b128 v[206:209], v154 offset:22528
	ds_read_b128 v[210:213], v154 offset:23552
	s_mov_b32 m0, s37
	s_nop 0
	global_load_lds_dwordx4 v146, s[40:41] offset:0
	s_add_u32 s30, s40, 0x80000
	s_mov_b32 m0, s52
	s_nop 0
	global_load_lds_dwordx4 v148, s[40:41] offset:0
	s_addc_u32 s31, s41, 0
	s_mov_b32 m0, s53
	s_nop 0
	global_load_lds_dwordx4 v146, s[30:31] offset:0
	s_nop 0
	s_mov_b32 m0, s54
	s_nop 0
	global_load_lds_dwordx4 v148, s[30:31] offset:0
	s_nop 0
	s_mov_b32 m0, s23
	s_nop 0
	global_load_lds_dwordx4 v1, s[44:45] offset:0
	s_nop 0
	s_mov_b32 m0, s55
	s_nop 0
	global_load_lds_dwordx4 v147, s[44:45] offset:0
	s_waitcnt vmcnt(8)
	s_waitcnt lgkmcnt(0)
	s_barrier
	s_setprio 1
	v_mfma_f32_16x16x32_bf16 v[70:73], v[138:141], v[182:185], v[70:73]
	v_mfma_f32_16x16x32_bf16 v[70:73], v[142:145], v[186:189], v[70:73]
	v_mfma_f32_16x16x32_bf16 v[62:65], v[158:161], v[182:185], v[62:65]
	v_mfma_f32_16x16x32_bf16 v[62:65], v[162:165], v[186:189], v[62:65]
	v_mfma_f32_16x16x32_bf16 v[50:53], v[138:141], v[190:193], v[50:53]
	v_mfma_f32_16x16x32_bf16 v[50:53], v[142:145], v[194:197], v[50:53]
	v_mfma_f32_16x16x32_bf16 v[46:49], v[158:161], v[190:193], v[46:49]
	v_mfma_f32_16x16x32_bf16 v[46:49], v[162:165], v[194:197], v[46:49]
	v_mfma_f32_16x16x32_bf16 v[34:37], v[138:141], v[198:201], v[34:37]
	v_mfma_f32_16x16x32_bf16 v[34:37], v[142:145], v[202:205], v[34:37]
	v_mfma_f32_16x16x32_bf16 v[30:33], v[158:161], v[198:201], v[30:33]
	v_mfma_f32_16x16x32_bf16 v[30:33], v[162:165], v[202:205], v[30:33]
	v_mfma_f32_16x16x32_bf16 v[18:21], v[138:141], v[206:209], v[18:21]
	v_mfma_f32_16x16x32_bf16 v[18:21], v[142:145], v[210:213], v[18:21]
	v_mfma_f32_16x16x32_bf16 v[14:17], v[158:161], v[206:209], v[14:17]
	v_mfma_f32_16x16x32_bf16 v[14:17], v[162:165], v[210:213], v[14:17]
	s_setprio 0
	s_setprio 1
	v_mfma_f32_16x16x32_bf16 v[58:61], v[166:169], v[182:185], v[58:61]
	v_mfma_f32_16x16x32_bf16 v[54:57], v[174:177], v[182:185], v[54:57]
	v_mfma_f32_16x16x32_bf16 v[42:45], v[166:169], v[190:193], v[42:45]
	v_mfma_f32_16x16x32_bf16 v[38:41], v[174:177], v[190:193], v[38:41]
	v_mfma_f32_16x16x32_bf16 v[26:29], v[166:169], v[198:201], v[26:29]
	v_mfma_f32_16x16x32_bf16 v[22:25], v[174:177], v[198:201], v[22:25]
	v_mfma_f32_16x16x32_bf16 v[10:13], v[166:169], v[206:209], v[10:13]
	v_mfma_f32_16x16x32_bf16 v[4:7], v[174:177], v[206:209], v[6:9]
	v_mfma_f32_16x16x32_bf16 v[58:61], v[170:173], v[186:189], v[58:61]
	v_mfma_f32_16x16x32_bf16 v[54:57], v[178:181], v[186:189], v[54:57]
	v_mfma_f32_16x16x32_bf16 v[42:45], v[170:173], v[194:197], v[42:45]
	v_mfma_f32_16x16x32_bf16 v[38:41], v[178:181], v[194:197], v[38:41]
	v_mfma_f32_16x16x32_bf16 v[26:29], v[170:173], v[202:205], v[26:29]
	v_mfma_f32_16x16x32_bf16 v[22:25], v[178:181], v[202:205], v[22:25]
	v_mfma_f32_16x16x32_bf16 v[10:13], v[170:173], v[210:213], v[10:13]
	v_mfma_f32_16x16x32_bf16 v[4:7], v[178:181], v[210:213], v[4:7]
	s_setprio 0
	s_barrier
; #define PG8_KSETUP() const bool last = (t == nt - 2); const char* a1 = cA + (size_t)(t + 1) * kstep; \
;             const char* a2 = last ? nA : cA + (size_t)(t + 2) * kstep; const char* b2 = last ? nB : cB + (size_t)(t + 2) * kstep; const char* a3 = a2 + kstep; const char* b3 = b2 + kstep; \
;             if (last && has_next) S.a_ready(nxt)
; template <class Epi, class Sched, bool ALIGN_EPI = false, bool SP2 = false>
; __device__ __forceinline__ void gemm_phase(PG8_LAS unsigned char* lds, const Gemm g, const Sched& S, const Epi& E) {
;     ...
;         int t0 = 0;
;         if constexpr (SP2 && Epi::NVM == 16) { if (ui > 0) { const int t = 0; PG8_KSETUP(); PG8_KITER_SP2(24, 24); t0 = 2; } }
;         if constexpr (SP2 && Epi::NVM == 8) { if (ui > 0) { const int t = 0; PG8_KSETUP(); PG8_KITER_SP2(16, 16); t0 = 2; } }
;         for (int t = t0; t < nt; t += 2) {
	ds_read_b128 v[138:141], v155
	ds_read_b128 v[142:145], v155 offset:1024
	ds_read_b128 v[158:161], v155 offset:2048
	ds_read_b128 v[162:165], v155 offset:3072
	ds_read_b128 v[166:169], v156
	ds_read_b128 v[170:173], v156 offset:1024
	ds_read_b128 v[174:177], v156 offset:2048
	ds_read_b128 v[178:181], v156 offset:3072
	ds_read_b128 v[182:185], v154 offset:32768
	ds_read_b128 v[186:189], v154 offset:33792
	ds_read_b128 v[190:193], v154 offset:34816
	ds_read_b128 v[194:197], v154 offset:35840
	ds_read_b128 v[198:201], v154 offset:36864
	ds_read_b128 v[202:205], v154 offset:37888
	ds_read_b128 v[206:209], v154 offset:38912
	ds_read_b128 v[210:213], v154 offset:39936
	s_add_u32 s30, s44, 0x80000
	s_addc_u32 s31, s45, 0
	s_mov_b32 m0, s56
	s_nop 0
	global_load_lds_dwordx4 v1, s[30:31] offset:0
	s_nop 0
	s_mov_b32 m0, s57
	s_nop 0
	global_load_lds_dwordx4 v147, s[30:31] offset:0
	s_waitcnt vmcnt(8)
	s_waitcnt lgkmcnt(0)
	s_barrier
	s_setprio 1
	v_mfma_f32_16x16x32_bf16 v[130:133], v[138:141], v[182:185], v[130:133]
	v_mfma_f32_16x16x32_bf16 v[130:133], v[142:145], v[186:189], v[130:133]
	v_mfma_f32_16x16x32_bf16 v[126:129], v[158:161], v[182:185], v[126:129]
	v_mfma_f32_16x16x32_bf16 v[126:129], v[162:165], v[186:189], v[126:129]
	v_mfma_f32_16x16x32_bf16 v[114:117], v[138:141], v[190:193], v[114:117]
	v_mfma_f32_16x16x32_bf16 v[114:117], v[142:145], v[194:197], v[114:117]
	v_mfma_f32_16x16x32_bf16 v[110:113], v[158:161], v[190:193], v[110:113]
	v_mfma_f32_16x16x32_bf16 v[110:113], v[162:165], v[194:197], v[110:113]
	v_mfma_f32_16x16x32_bf16 v[98:101], v[138:141], v[198:201], v[98:101]
	v_mfma_f32_16x16x32_bf16 v[98:101], v[142:145], v[202:205], v[98:101]
	v_mfma_f32_16x16x32_bf16 v[94:97], v[158:161], v[198:201], v[94:97]
	v_mfma_f32_16x16x32_bf16 v[94:97], v[162:165], v[202:205], v[94:97]
	v_mfma_f32_16x16x32_bf16 v[82:85], v[138:141], v[206:209], v[82:85]
	v_mfma_f32_16x16x32_bf16 v[82:85], v[142:145], v[210:213], v[82:85]
	v_mfma_f32_16x16x32_bf16 v[78:81], v[158:161], v[206:209], v[78:81]
	v_mfma_f32_16x16x32_bf16 v[78:81], v[162:165], v[210:213], v[78:81]
	s_setprio 0
	s_setprio 1
	v_mfma_f32_16x16x32_bf16 v[122:125], v[166:169], v[182:185], v[122:125]
	v_mfma_f32_16x16x32_bf16 v[122:125], v[170:173], v[186:189], v[122:125]
	v_mfma_f32_16x16x32_bf16 v[118:121], v[174:177], v[182:185], v[118:121]
	v_mfma_f32_16x16x32_bf16 v[118:121], v[178:181], v[186:189], v[118:121]
	v_mfma_f32_16x16x32_bf16 v[106:109], v[166:169], v[190:193], v[106:109]
	v_mfma_f32_16x16x32_bf16 v[106:109], v[170:173], v[194:197], v[106:109]
	v_mfma_f32_16x16x32_bf16 v[102:105], v[174:177], v[190:193], v[102:105]
	v_mfma_f32_16x16x32_bf16 v[102:105], v[178:181], v[194:197], v[102:105]
	v_mfma_f32_16x16x32_bf16 v[90:93], v[166:169], v[198:201], v[90:93]
	v_mfma_f32_16x16x32_bf16 v[90:93], v[170:173], v[202:205], v[90:93]
	v_mfma_f32_16x16x32_bf16 v[86:89], v[174:177], v[198:201], v[86:89]
	v_mfma_f32_16x16x32_bf16 v[86:89], v[178:181], v[202:205], v[86:89]
	v_mfma_f32_16x16x32_bf16 v[74:77], v[166:169], v[206:209], v[74:77]
	v_mfma_f32_16x16x32_bf16 v[74:77], v[170:173], v[210:213], v[74:77]
	v_mfma_f32_16x16x32_bf16 v[66:69], v[174:177], v[206:209], v[66:69]
	v_mfma_f32_16x16x32_bf16 v[66:69], v[178:181], v[210:213], v[66:69]
	s_setprio 0
	s_barrier
	ds_read_b128 v[182:185], v154 offset:49152
	ds_read_b128 v[186:189], v154 offset:50176
	ds_read_b128 v[190:193], v154 offset:51200
	ds_read_b128 v[194:197], v154 offset:52224
	ds_read_b128 v[198:201], v154 offset:53248
	ds_read_b128 v[202:205], v154 offset:54272
	ds_read_b128 v[206:209], v154 offset:55296
	ds_read_b128 v[210:213], v154 offset:56320
	s_add_u32 s30, s40, 0x80
	s_addc_u32 s31, s41, 0
	s_mov_b32 m0, s58
	s_nop 0
	global_load_lds_dwordx4 v146, s[30:31] offset:0
	s_nop 0
	s_mov_b32 m0, s59
	s_nop 0
	global_load_lds_dwordx4 v148, s[30:31] offset:0
	s_add_u32 s30, s40, 0x80080
	s_addc_u32 s31, s41, 0
	s_mov_b32 m0, s66
	s_nop 0
	global_load_lds_dwordx4 v146, s[30:31] offset:0
	s_nop 0
	s_mov_b32 m0, s67
	s_nop 0
	global_load_lds_dwordx4 v148, s[30:31] offset:0
	s_nop 0
	s_mov_b32 m0, s64
	s_nop 0
	global_load_lds_dwordx4 v1, s[38:39] offset:0
	s_nop 0
	s_mov_b32 m0, s65
	s_nop 0
	global_load_lds_dwordx4 v147, s[38:39] offset:0
	s_waitcnt vmcnt(8)
	s_waitcnt lgkmcnt(0)
	s_barrier
	s_setprio 1
	v_mfma_f32_16x16x32_bf16 v[70:73], v[138:141], v[182:185], v[70:73]
	v_mfma_f32_16x16x32_bf16 v[70:73], v[142:145], v[186:189], v[70:73]
	v_mfma_f32_16x16x32_bf16 v[62:65], v[158:161], v[182:185], v[62:65]
	v_mfma_f32_16x16x32_bf16 v[62:65], v[162:165], v[186:189], v[62:65]
	v_mfma_f32_16x16x32_bf16 v[50:53], v[138:141], v[190:193], v[50:53]
	v_mfma_f32_16x16x32_bf16 v[50:53], v[142:145], v[194:197], v[50:53]
	v_mfma_f32_16x16x32_bf16 v[46:49], v[158:161], v[190:193], v[46:49]
	v_mfma_f32_16x16x32_bf16 v[46:49], v[162:165], v[194:197], v[46:49]
	v_mfma_f32_16x16x32_bf16 v[34:37], v[138:141], v[198:201], v[34:37]
	v_mfma_f32_16x16x32_bf16 v[34:37], v[142:145], v[202:205], v[34:37]
	v_mfma_f32_16x16x32_bf16 v[30:33], v[158:161], v[198:201], v[30:33]
	v_mfma_f32_16x16x32_bf16 v[30:33], v[162:165], v[202:205], v[30:33]
	v_mfma_f32_16x16x32_bf16 v[18:21], v[138:141], v[206:209], v[18:21]
	v_mfma_f32_16x16x32_bf16 v[18:21], v[142:145], v[210:213], v[18:21]
	v_mfma_f32_16x16x32_bf16 v[14:17], v[158:161], v[206:209], v[14:17]
	v_mfma_f32_16x16x32_bf16 v[14:17], v[162:165], v[210:213], v[14:17]
	s_setprio 0
	s_setprio 1
	v_mfma_f32_16x16x32_bf16 v[58:61], v[166:169], v[182:185], v[58:61]
	v_mfma_f32_16x16x32_bf16 v[54:57], v[174:177], v[182:185], v[54:57]
	v_mfma_f32_16x16x32_bf16 v[42:45], v[166:169], v[190:193], v[42:45]
	v_mfma_f32_16x16x32_bf16 v[38:41], v[174:177], v[190:193], v[38:41]
	v_mfma_f32_16x16x32_bf16 v[26:29], v[166:169], v[198:201], v[26:29]
	v_mfma_f32_16x16x32_bf16 v[22:25], v[174:177], v[198:201], v[22:25]
	v_mfma_f32_16x16x32_bf16 v[8:11], v[166:169], v[206:209], v[10:13]
	v_mfma_f32_16x16x32_bf16 v[4:7], v[174:177], v[206:209], v[4:7]
	v_mfma_f32_16x16x32_bf16 v[58:61], v[170:173], v[186:189], v[58:61]
	v_mfma_f32_16x16x32_bf16 v[54:57], v[178:181], v[186:189], v[54:57]
	v_mfma_f32_16x16x32_bf16 v[42:45], v[170:173], v[194:197], v[42:45]
	v_mfma_f32_16x16x32_bf16 v[38:41], v[178:181], v[194:197], v[38:41]
	v_mfma_f32_16x16x32_bf16 v[26:29], v[170:173], v[202:205], v[26:29]
	v_mfma_f32_16x16x32_bf16 v[22:25], v[178:181], v[202:205], v[22:25]
	v_mfma_f32_16x16x32_bf16 v[10:13], v[170:173], v[210:213], v[8:11]
	v_mfma_f32_16x16x32_bf16 v[6:9], v[178:181], v[210:213], v[4:7]
	s_setprio 0
	s_barrier
	s_add_i32 s80, s80, 2
	s_add_u32 s81, s81, 0x100
	s_addc_u32 s82, s82, 0
	s_add_u32 s83, s83, 0x100
	s_addc_u32 s84, s84, 0
	s_cmp_gt_u32 s80, 29
	s_cbranch_scc0 .LBB0_787
	s_and_b64 vcc, exec, s[16:17]
	s_cbranch_vccz .LBB0_790
	s_barrier

; #define PG8_KSETUP() const bool last = (t == nt - 2); const char* a1 = cA + (size_t)(t + 1) * kstep; \
;             const char* a2 = last ? nA : cA + (size_t)(t + 2) * kstep; const char* b2 = last ? nB : cB + (size_t)(t + 2) * kstep; const char* a3 = a2 + kstep; const char* b3 = b2 + kstep; \
;             if (last && has_next) S.a_ready(nxt)
; template <class Epi, class Sched, bool ALIGN_EPI = false, bool SP2 = false>
; __device__ __forceinline__ void gemm_phase(PG8_LAS unsigned char* lds, const Gemm g, const Sched& S, const Epi& E) {
;     ...
;         int t0 = 0;
;         if constexpr (SP2 && Epi::NVM == 16) { if (ui > 0) { const int t = 0; PG8_KSETUP(); PG8_KITER_SP2(24, 24); t0 = 2; } }
.LBB0_867:
	ds_read_b128 v[4:7], v143
	ds_read_b128 v[8:11], v143 offset:1024
	ds_read_b128 v[12:15], v143 offset:2048
	ds_read_b128 v[16:19], v143 offset:3072
	ds_read_b128 v[20:23], v144
	ds_read_b128 v[24:27], v144 offset:1024
	ds_read_b128 v[28:31], v144 offset:2048
	ds_read_b128 v[32:35], v144 offset:3072
	s_add_u32 s44, s36, 0x100
	s_addc_u32 s45, s37, 0
	s_add_u32 s30, s38, 0x100
	s_addc_u32 s31, s39, 0
	s_add_u32 s40, s36, 0x180
	s_addc_u32 s41, s37, 0
	ds_read_b128 v[36:39], v145
	ds_read_b128 v[40:43], v145 offset:1024
	ds_read_b128 v[44:47], v145 offset:2048
	ds_read_b128 v[48:51], v145 offset:3072
	ds_read_b128 v[52:55], v145 offset:4096
	ds_read_b128 v[56:59], v145 offset:5120
	ds_read_b128 v[60:63], v145 offset:6144
	ds_read_b128 v[64:67], v145 offset:7168
	s_add_u32 s42, s36, 0x160080
	s_addc_u32 s43, s37, 0
	s_mov_b32 m0, s71
	s_nop 0
	global_load_lds_dwordx4 v1, s[42:43] offset:0
	s_nop 0
	s_mov_b32 m0, s72
	s_nop 0
	global_load_lds_dwordx4 v139, s[42:43] offset:0
	s_waitcnt vmcnt(24)
	s_waitcnt lgkmcnt(0)
	s_barrier
	s_setprio 1
	v_mfma_f32_16x16x32_bf16 v[92:95], v[4:7], v[60:63], 0
	v_mfma_f32_16x16x32_bf16 v[68:71], v[4:7], v[36:39], 0
	v_mfma_f32_16x16x32_bf16 v[72:75], v[12:15], v[36:39], 0
	v_mfma_f32_16x16x32_bf16 v[76:79], v[4:7], v[44:47], 0
	v_mfma_f32_16x16x32_bf16 v[80:83], v[12:15], v[44:47], 0
	v_mfma_f32_16x16x32_bf16 v[84:87], v[4:7], v[52:55], 0
	v_mfma_f32_16x16x32_bf16 v[88:91], v[12:15], v[52:55], 0
	v_mfma_f32_16x16x32_bf16 v[102:105], v[8:11], v[64:67], v[92:95]
	v_mfma_f32_16x16x32_bf16 v[92:95], v[12:15], v[60:63], 0
	v_mfma_f32_16x16x32_bf16 v[68:71], v[8:11], v[40:43], v[68:71]
	v_mfma_f32_16x16x32_bf16 v[72:75], v[16:19], v[40:43], v[72:75]
	v_mfma_f32_16x16x32_bf16 v[76:79], v[8:11], v[48:51], v[76:79]
	v_mfma_f32_16x16x32_bf16 v[80:83], v[16:19], v[48:51], v[80:83]
	v_mfma_f32_16x16x32_bf16 v[84:87], v[8:11], v[56:59], v[84:87]
	v_mfma_f32_16x16x32_bf16 v[88:91], v[16:19], v[56:59], v[88:91]
	v_mfma_f32_16x16x32_bf16 v[106:109], v[16:19], v[64:67], v[92:95]
	s_setprio 0
	s_setprio 1
	v_mfma_f32_16x16x32_bf16 v[92:95], v[20:23], v[36:39], 0
	v_mfma_f32_16x16x32_bf16 v[36:39], v[28:31], v[36:39], 0
	v_mfma_f32_16x16x32_bf16 v[118:121], v[24:27], v[40:43], v[92:95]
	v_mfma_f32_16x16x32_bf16 v[36:39], v[32:35], v[40:43], v[36:39]
	v_mfma_f32_16x16x32_bf16 v[40:43], v[20:23], v[44:47], 0
	v_mfma_f32_16x16x32_bf16 v[44:47], v[28:31], v[44:47], 0
	v_mfma_f32_16x16x32_bf16 v[40:43], v[24:27], v[48:51], v[40:43]
	v_mfma_f32_16x16x32_bf16 v[44:47], v[32:35], v[48:51], v[44:47]
	v_mfma_f32_16x16x32_bf16 v[48:51], v[20:23], v[52:55], 0
	v_mfma_f32_16x16x32_bf16 v[52:55], v[28:31], v[52:55], 0
	v_mfma_f32_16x16x32_bf16 v[48:51], v[24:27], v[56:59], v[48:51]
	v_mfma_f32_16x16x32_bf16 v[52:55], v[32:35], v[56:59], v[52:55]
	v_mfma_f32_16x16x32_bf16 v[56:59], v[20:23], v[60:63], 0
	v_mfma_f32_16x16x32_bf16 v[60:63], v[28:31], v[60:63], 0
	v_mfma_f32_16x16x32_bf16 v[56:59], v[24:27], v[64:67], v[56:59]
	v_mfma_f32_16x16x32_bf16 v[60:63], v[32:35], v[64:67], v[60:63]
	s_setprio 0
	s_barrier
	ds_read_b128 v[64:67], v145 offset:16384
	ds_read_b128 v[92:95], v145 offset:17408
	ds_read_b128 v[96:99], v145 offset:18432
	ds_read_b128 v[110:113], v145 offset:19456
	ds_read_b128 v[114:117], v145 offset:20480
	ds_read_b128 v[122:125], v145 offset:21504
	ds_read_b128 v[126:129], v145 offset:22528
	ds_read_b128 v[130:133], v145 offset:23552
	s_mov_b32 m0, s54
	s_nop 0
	global_load_lds_dwordx4 v138, s[30:31] offset:0
	s_nop 0
	s_mov_b32 m0, s55
	s_nop 0
	global_load_lds_dwordx4 v140, s[30:31] offset:0
	s_add_u32 s30, s38, 0x160100
	s_addc_u32 s31, s39, 0
	s_mov_b32 m0, s56
	s_nop 0
	global_load_lds_dwordx4 v138, s[30:31] offset:0
	s_nop 0
	s_mov_b32 m0, s57
	s_nop 0
	global_load_lds_dwordx4 v140, s[30:31] offset:0
	s_nop 0
	s_mov_b32 m0, s47
	s_nop 0
	global_load_lds_dwordx4 v1, s[44:45] offset:0
	s_nop 0
	s_mov_b32 m0, s58
	s_nop 0
	global_load_lds_dwordx4 v139, s[44:45] offset:0
	s_waitcnt vmcnt(24)
	s_waitcnt lgkmcnt(0)
	s_barrier
	s_setprio 1
	v_mfma_f32_16x16x32_bf16 v[148:151], v[4:7], v[64:67], 0
	v_mfma_f32_16x16x32_bf16 v[156:159], v[4:7], v[96:99], 0
	v_mfma_f32_16x16x32_bf16 v[164:167], v[4:7], v[114:117], 0
	v_mfma_f32_16x16x32_bf16 v[4:7], v[4:7], v[126:129], 0
	v_mfma_f32_16x16x32_bf16 v[148:151], v[8:11], v[92:95], v[148:151]
	v_mfma_f32_16x16x32_bf16 v[156:159], v[8:11], v[110:113], v[156:159]
	v_mfma_f32_16x16x32_bf16 v[164:167], v[8:11], v[122:125], v[164:167]
	v_mfma_f32_16x16x32_bf16 v[4:7], v[8:11], v[130:133], v[4:7]
	v_mfma_f32_16x16x32_bf16 v[8:11], v[12:15], v[126:129], 0
	v_mfma_f32_16x16x32_bf16 v[152:155], v[12:15], v[64:67], 0
	v_mfma_f32_16x16x32_bf16 v[160:163], v[12:15], v[96:99], 0
	v_mfma_f32_16x16x32_bf16 v[168:171], v[12:15], v[114:117], 0
	v_mfma_f32_16x16x32_bf16 v[8:11], v[16:19], v[130:133], v[8:11]
	v_mfma_f32_16x16x32_bf16 v[152:155], v[16:19], v[92:95], v[152:155]
	v_mfma_f32_16x16x32_bf16 v[160:163], v[16:19], v[110:113], v[160:163]
	v_mfma_f32_16x16x32_bf16 v[168:171], v[16:19], v[122:125], v[168:171]
	s_setprio 0
	s_setprio 1
	v_mfma_f32_16x16x32_bf16 v[12:15], v[20:23], v[64:67], 0
	v_mfma_f32_16x16x32_bf16 v[172:175], v[24:27], v[92:95], v[12:15]
	v_mfma_f32_16x16x32_bf16 v[12:15], v[28:31], v[64:67], 0
	v_mfma_f32_16x16x32_bf16 v[176:179], v[32:35], v[92:95], v[12:15]
	v_mfma_f32_16x16x32_bf16 v[12:15], v[20:23], v[96:99], 0
	v_mfma_f32_16x16x32_bf16 v[180:183], v[24:27], v[110:113], v[12:15]
	v_mfma_f32_16x16x32_bf16 v[12:15], v[28:31], v[96:99], 0
	v_mfma_f32_16x16x32_bf16 v[184:187], v[32:35], v[110:113], v[12:15]
	v_mfma_f32_16x16x32_bf16 v[12:15], v[20:23], v[114:117], 0
	v_mfma_f32_16x16x32_bf16 v[188:191], v[24:27], v[122:125], v[12:15]
	v_mfma_f32_16x16x32_bf16 v[12:15], v[28:31], v[114:117], 0
	v_mfma_f32_16x16x32_bf16 v[192:195], v[32:35], v[122:125], v[12:15]
	v_mfma_f32_16x16x32_bf16 v[12:15], v[20:23], v[126:129], 0
	v_mfma_f32_16x16x32_bf16 v[196:199], v[24:27], v[130:133], v[12:15]
	v_mfma_f32_16x16x32_bf16 v[12:15], v[28:31], v[126:129], 0
	v_mfma_f32_16x16x32_bf16 v[200:203], v[32:35], v[130:133], v[12:15]
	s_setprio 0
	s_barrier
; #define PG8_KSETUP() const bool last = (t == nt - 2); const char* a1 = cA + (size_t)(t + 1) * kstep; \
;             const char* a2 = last ? nA : cA + (size_t)(t + 2) * kstep; const char* b2 = last ? nB : cB + (size_t)(t + 2) * kstep; const char* a3 = a2 + kstep; const char* b3 = b2 + kstep; \
;             if (last && has_next) S.a_ready(nxt)
; template <class Epi, class Sched, bool ALIGN_EPI = false, bool SP2 = false>
; __device__ __forceinline__ void gemm_phase(PG8_LAS unsigned char* lds, const Gemm g, const Sched& S, const Epi& E) {
;     ...
;         int t0 = 0;
;         if constexpr (SP2 && Epi::NVM == 16) { if (ui > 0) { const int t = 0; PG8_KSETUP(); PG8_KITER_SP2(24, 24); t0 = 2; } }
	s_nop 4
	ds_read_b128 v[12:15], v146
	ds_read_b128 v[16:19], v146 offset:1024
	ds_read_b128 v[22:25], v146 offset:2048
	ds_read_b128 v[26:29], v146 offset:3072
	ds_read_b128 v[204:207], v147
	ds_read_b128 v[208:211], v147 offset:1024
	ds_read_b128 v[212:215], v147 offset:2048
	ds_read_b128 v[216:219], v147 offset:3072
	ds_read_b128 v[30:33], v145 offset:32768
	ds_read_b128 v[64:67], v145 offset:33792
	ds_read_b128 v[220:223], v145 offset:34816
	ds_read_b128 v[224:227], v145 offset:35840
	ds_read_b128 v[228:231], v145 offset:36864
	ds_read_b128 v[232:235], v145 offset:37888
	ds_read_b128 v[236:239], v145 offset:38912
	ds_read_b128 v[240:243], v145 offset:39936
	s_add_u32 s30, s36, 0x160100
	s_addc_u32 s31, s37, 0
	s_mov_b32 m0, s59
	s_nop 0
	global_load_lds_dwordx4 v1, s[30:31] offset:0
	s_nop 0
	s_mov_b32 m0, s64
	s_nop 0
	global_load_lds_dwordx4 v139, s[30:31] offset:0
	s_waitcnt vmcnt(8)
	s_waitcnt lgkmcnt(0)
	s_barrier
	s_setprio 1
	v_mfma_f32_16x16x32_bf16 v[68:71], v[12:15], v[30:33], v[68:71]
	v_mfma_f32_16x16x32_bf16 v[130:133], v[16:19], v[64:67], v[68:71]
	v_mfma_f32_16x16x32_bf16 v[68:71], v[22:25], v[30:33], v[72:75]
	v_mfma_f32_16x16x32_bf16 v[126:129], v[26:29], v[64:67], v[68:71]
	v_mfma_f32_16x16x32_bf16 v[68:71], v[12:15], v[220:223], v[76:79]
	v_mfma_f32_16x16x32_bf16 v[114:117], v[16:19], v[224:227], v[68:71]
	v_mfma_f32_16x16x32_bf16 v[68:71], v[22:25], v[220:223], v[80:83]
	v_mfma_f32_16x16x32_bf16 v[110:113], v[26:29], v[224:227], v[68:71]
	v_mfma_f32_16x16x32_bf16 v[68:71], v[12:15], v[228:231], v[84:87]
	v_mfma_f32_16x16x32_bf16 v[98:101], v[16:19], v[232:235], v[68:71]
	v_mfma_f32_16x16x32_bf16 v[68:71], v[22:25], v[228:231], v[88:91]
	v_mfma_f32_16x16x32_bf16 v[94:97], v[26:29], v[232:235], v[68:71]
	v_mfma_f32_16x16x32_bf16 v[68:71], v[12:15], v[236:239], v[102:105]
	v_mfma_f32_16x16x32_bf16 v[82:85], v[16:19], v[240:243], v[68:71]
	v_mfma_f32_16x16x32_bf16 v[68:71], v[22:25], v[236:239], v[106:109]
	v_mfma_f32_16x16x32_bf16 v[78:81], v[26:29], v[240:243], v[68:71]
	s_setprio 0
	s_setprio 1
	v_mfma_f32_16x16x32_bf16 v[68:71], v[204:207], v[30:33], v[118:121]
	v_mfma_f32_16x16x32_bf16 v[30:33], v[212:215], v[30:33], v[36:39]
	v_mfma_f32_16x16x32_bf16 v[118:121], v[216:219], v[64:67], v[30:33]
	v_mfma_f32_16x16x32_bf16 v[30:33], v[204:207], v[220:223], v[40:43]
	v_mfma_f32_16x16x32_bf16 v[106:109], v[208:211], v[224:227], v[30:33]
	v_mfma_f32_16x16x32_bf16 v[30:33], v[212:215], v[220:223], v[44:47]
	v_mfma_f32_16x16x32_bf16 v[102:105], v[216:219], v[224:227], v[30:33]
	v_mfma_f32_16x16x32_bf16 v[30:33], v[204:207], v[228:231], v[48:51]
	v_mfma_f32_16x16x32_bf16 v[90:93], v[208:211], v[232:235], v[30:33]
	v_mfma_f32_16x16x32_bf16 v[30:33], v[212:215], v[228:231], v[52:55]
	v_mfma_f32_16x16x32_bf16 v[86:89], v[216:219], v[232:235], v[30:33]
	v_mfma_f32_16x16x32_bf16 v[30:33], v[204:207], v[236:239], v[56:59]
	v_mfma_f32_16x16x32_bf16 v[122:125], v[208:211], v[64:67], v[68:71]
	v_mfma_f32_16x16x32_bf16 v[70:73], v[208:211], v[240:243], v[30:33]
	v_mfma_f32_16x16x32_bf16 v[30:33], v[212:215], v[236:239], v[60:63]
	v_mfma_f32_16x16x32_bf16 v[62:65], v[216:219], v[240:243], v[30:33]
	s_setprio 0
	s_barrier
	ds_read_b128 v[38:41], v145 offset:49152
	ds_read_b128 v[42:45], v145 offset:50176
	ds_read_b128 v[220:223], v145 offset:51200
	ds_read_b128 v[224:227], v145 offset:52224
	ds_read_b128 v[228:231], v145 offset:53248
	ds_read_b128 v[232:235], v145 offset:54272
	ds_read_b128 v[236:239], v145 offset:55296
	ds_read_b128 v[240:243], v145 offset:56320
	s_add_u32 s30, s38, 0x180
	s_addc_u32 s31, s39, 0
	s_mov_b32 m0, s65
	s_nop 0
	global_load_lds_dwordx4 v138, s[30:31] offset:0
	s_nop 0
	s_mov_b32 m0, s66
	s_nop 0
	global_load_lds_dwordx4 v140, s[30:31] offset:0
	s_add_u32 s30, s38, 0x160180
	s_addc_u32 s31, s39, 0
	s_mov_b32 m0, s69
	s_nop 0
	global_load_lds_dwordx4 v138, s[30:31] offset:0
	s_nop 0
	s_mov_b32 m0, s70
	s_nop 0
	global_load_lds_dwordx4 v140, s[30:31] offset:0
	s_nop 0
	s_mov_b32 m0, s67
	s_nop 0
	global_load_lds_dwordx4 v1, s[40:41] offset:0
	s_nop 0
	s_mov_b32 m0, s68
	s_nop 0
	global_load_lds_dwordx4 v139, s[40:41] offset:0
	s_waitcnt vmcnt(8)
	s_waitcnt lgkmcnt(0)
	s_barrier
	s_setprio 1
	v_mfma_f32_16x16x32_bf16 v[30:33], v[12:15], v[38:41], v[148:151]
	v_mfma_f32_16x16x32_bf16 v[74:77], v[16:19], v[42:45], v[30:33]
	v_mfma_f32_16x16x32_bf16 v[30:33], v[22:25], v[38:41], v[152:155]
	v_mfma_f32_16x16x32_bf16 v[66:69], v[26:29], v[42:45], v[30:33]
	v_mfma_f32_16x16x32_bf16 v[30:33], v[12:15], v[220:223], v[156:159]
	v_mfma_f32_16x16x32_bf16 v[50:53], v[16:19], v[224:227], v[30:33]
	v_mfma_f32_16x16x32_bf16 v[30:33], v[22:25], v[220:223], v[160:163]
	v_mfma_f32_16x16x32_bf16 v[46:49], v[26:29], v[224:227], v[30:33]
	v_mfma_f32_16x16x32_bf16 v[30:33], v[12:15], v[228:231], v[164:167]
	v_mfma_f32_16x16x32_bf16 v[4:7], v[12:15], v[236:239], v[4:7]
	v_mfma_f32_16x16x32_bf16 v[34:37], v[16:19], v[232:235], v[30:33]
	v_mfma_f32_16x16x32_bf16 v[30:33], v[22:25], v[228:231], v[168:171]
	v_mfma_f32_16x16x32_bf16 v[18:21], v[16:19], v[240:243], v[4:7]
	v_mfma_f32_16x16x32_bf16 v[4:7], v[22:25], v[236:239], v[8:11]
	v_mfma_f32_16x16x32_bf16 v[30:33], v[26:29], v[232:235], v[30:33]
	v_mfma_f32_16x16x32_bf16 v[14:17], v[26:29], v[240:243], v[4:7]
	s_setprio 0
	s_setprio 1
	v_mfma_f32_16x16x32_bf16 v[4:7], v[204:207], v[38:41], v[172:175]
	v_mfma_f32_16x16x32_bf16 v[58:61], v[208:211], v[42:45], v[4:7]
	v_mfma_f32_16x16x32_bf16 v[4:7], v[212:215], v[38:41], v[176:179]
	v_mfma_f32_16x16x32_bf16 v[54:57], v[216:219], v[42:45], v[4:7]
	v_mfma_f32_16x16x32_bf16 v[4:7], v[204:207], v[220:223], v[180:183]
	v_mfma_f32_16x16x32_bf16 v[42:45], v[208:211], v[224:227], v[4:7]
	v_mfma_f32_16x16x32_bf16 v[4:7], v[212:215], v[220:223], v[184:187]
	v_mfma_f32_16x16x32_bf16 v[38:41], v[216:219], v[224:227], v[4:7]
	v_mfma_f32_16x16x32_bf16 v[4:7], v[204:207], v[228:231], v[188:191]
	v_mfma_f32_16x16x32_bf16 v[26:29], v[208:211], v[232:235], v[4:7]
	v_mfma_f32_16x16x32_bf16 v[4:7], v[212:215], v[228:231], v[192:195]
	v_mfma_f32_16x16x32_bf16 v[22:25], v[216:219], v[232:235], v[4:7]
	v_mfma_f32_16x16x32_bf16 v[4:7], v[204:207], v[236:239], v[196:199]
	v_mfma_f32_16x16x32_bf16 v[10:13], v[208:211], v[240:243], v[4:7]
	v_mfma_f32_16x16x32_bf16 v[4:7], v[212:215], v[236:239], v[200:203]
	v_mfma_f32_16x16x32_bf16 v[6:9], v[216:219], v[240:243], v[4:7]
	s_setprio 0
	s_barrier
	s_mov_b32 s40, 2
	s_branch .LBB0_871

; #define PG8_KSETUP() const bool last = (t == nt - 2); const char* a1 = cA + (size_t)(t + 1) * kstep; \
;             const char* a2 = last ? nA : cA + (size_t)(t + 2) * kstep; const char* b2 = last ? nB : cB + (size_t)(t + 2) * kstep; const char* a3 = a2 + kstep; const char* b3 = b2 + kstep; \
;             if (last && has_next) S.a_ready(nxt)
; template <class Epi, class Sched, bool ALIGN_EPI = false, bool SP2 = false>
; __device__ __forceinline__ void gemm_phase(PG8_LAS unsigned char* lds, const Gemm g, const Sched& S, const Epi& E) {
;     ...
;         int t0 = 0;
;         if constexpr (SP2 && Epi::NVM == 16) { if (ui > 0) { const int t = 0; PG8_KSETUP(); PG8_KITER_SP2(24, 24); t0 = 2; } }
;         if constexpr (SP2 && Epi::NVM == 8) { if (ui > 0) { const int t = 0; PG8_KSETUP(); PG8_KITER_SP2(16, 16); t0 = 2; } }
;         for (int t = t0; t < nt; t += 2) {
;             PG8_KSETUP();
;             if constexpr (SP2) {
;             PG8_KITER_SP2(8, 8);
.LBB0_872:
	ds_read_b128 v[148:151], v143
	ds_read_b128 v[152:155], v143 offset:1024
	ds_read_b128 v[156:159], v143 offset:2048
	ds_read_b128 v[160:163], v143 offset:3072
	ds_read_b128 v[164:167], v144
	ds_read_b128 v[168:171], v144 offset:1024
	ds_read_b128 v[172:175], v144 offset:2048
	ds_read_b128 v[176:179], v144 offset:3072
	s_cmpk_eq_i32 s79, 0x54
	s_cselect_b32 s44, s6, s82
	s_cselect_b32 s45, s7, s83
	s_cselect_b32 s40, s28, s80
	s_cselect_b32 s41, s29, s81
	s_add_u32 s38, s44, 0x80
	s_addc_u32 s39, s45, 0
	ds_read_b128 v[180:183], v145
	ds_read_b128 v[184:187], v145 offset:1024
	ds_read_b128 v[188:191], v145 offset:2048
	ds_read_b128 v[192:195], v145 offset:3072
	ds_read_b128 v[196:199], v145 offset:4096
	ds_read_b128 v[200:203], v145 offset:5120
	ds_read_b128 v[204:207], v145 offset:6144
	ds_read_b128 v[208:211], v145 offset:7168
	s_mov_b32 m0, s71
	s_nop 0
	global_load_lds_dwordx4 v1, s[36:37] offset:0
	s_nop 0
	s_mov_b32 m0, s72
	s_nop 0
	global_load_lds_dwordx4 v139, s[36:37] offset:0
	s_waitcnt vmcnt(8)
	s_waitcnt lgkmcnt(0)
	s_barrier
	s_setprio 1
	v_mfma_f32_16x16x32_bf16 v[130:133], v[148:151], v[180:183], v[130:133]
	v_mfma_f32_16x16x32_bf16 v[130:133], v[152:155], v[184:187], v[130:133]
	v_mfma_f32_16x16x32_bf16 v[126:129], v[156:159], v[180:183], v[126:129]
	v_mfma_f32_16x16x32_bf16 v[126:129], v[160:163], v[184:187], v[126:129]
	v_mfma_f32_16x16x32_bf16 v[114:117], v[148:151], v[188:191], v[114:117]
	v_mfma_f32_16x16x32_bf16 v[114:117], v[152:155], v[192:195], v[114:117]
	v_mfma_f32_16x16x32_bf16 v[110:113], v[156:159], v[188:191], v[110:113]
	v_mfma_f32_16x16x32_bf16 v[110:113], v[160:163], v[192:195], v[110:113]
	v_mfma_f32_16x16x32_bf16 v[98:101], v[148:151], v[196:199], v[98:101]
	v_mfma_f32_16x16x32_bf16 v[98:101], v[152:155], v[200:203], v[98:101]
	v_mfma_f32_16x16x32_bf16 v[94:97], v[156:159], v[196:199], v[94:97]
	v_mfma_f32_16x16x32_bf16 v[94:97], v[160:163], v[200:203], v[94:97]
	v_mfma_f32_16x16x32_bf16 v[82:85], v[148:151], v[204:207], v[82:85]
	v_mfma_f32_16x16x32_bf16 v[82:85], v[152:155], v[208:211], v[82:85]
	v_mfma_f32_16x16x32_bf16 v[78:81], v[156:159], v[204:207], v[78:81]
	v_mfma_f32_16x16x32_bf16 v[78:81], v[160:163], v[208:211], v[78:81]
	s_setprio 0
	s_setprio 1
	v_mfma_f32_16x16x32_bf16 v[122:125], v[164:167], v[180:183], v[122:125]
	v_mfma_f32_16x16x32_bf16 v[122:125], v[168:171], v[184:187], v[122:125]
	v_mfma_f32_16x16x32_bf16 v[118:121], v[172:175], v[180:183], v[118:121]
	v_mfma_f32_16x16x32_bf16 v[118:121], v[176:179], v[184:187], v[118:121]
	v_mfma_f32_16x16x32_bf16 v[106:109], v[164:167], v[188:191], v[106:109]
	v_mfma_f32_16x16x32_bf16 v[106:109], v[168:171], v[192:195], v[106:109]
	v_mfma_f32_16x16x32_bf16 v[102:105], v[172:175], v[188:191], v[102:105]
	v_mfma_f32_16x16x32_bf16 v[102:105], v[176:179], v[192:195], v[102:105]
	v_mfma_f32_16x16x32_bf16 v[90:93], v[164:167], v[196:199], v[90:93]
	v_mfma_f32_16x16x32_bf16 v[90:93], v[168:171], v[200:203], v[90:93]
	v_mfma_f32_16x16x32_bf16 v[86:89], v[172:175], v[196:199], v[86:89]
	v_mfma_f32_16x16x32_bf16 v[86:89], v[176:179], v[200:203], v[86:89]
	v_mfma_f32_16x16x32_bf16 v[70:73], v[164:167], v[204:207], v[70:73]
	v_mfma_f32_16x16x32_bf16 v[70:73], v[168:171], v[208:211], v[70:73]
	v_mfma_f32_16x16x32_bf16 v[62:65], v[172:175], v[204:207], v[62:65]
	v_mfma_f32_16x16x32_bf16 v[62:65], v[176:179], v[208:211], v[62:65]
	s_setprio 0
	s_barrier
	ds_read_b128 v[180:183], v145 offset:16384
	ds_read_b128 v[184:187], v145 offset:17408
	ds_read_b128 v[188:191], v145 offset:18432
	ds_read_b128 v[192:195], v145 offset:19456
	ds_read_b128 v[196:199], v145 offset:20480
	ds_read_b128 v[200:203], v145 offset:21504
	ds_read_b128 v[204:207], v145 offset:22528
	ds_read_b128 v[208:211], v145 offset:23552
	s_mov_b32 m0, s54
	s_nop 0
	global_load_lds_dwordx4 v138, s[40:41] offset:0
	s_add_u32 s30, s40, 0x160000
	s_mov_b32 m0, s55
	s_nop 0
	global_load_lds_dwordx4 v140, s[40:41] offset:0
	s_addc_u32 s31, s41, 0
	s_mov_b32 m0, s56
	s_nop 0
	global_load_lds_dwordx4 v138, s[30:31] offset:0
	s_nop 0
	s_mov_b32 m0, s57
	s_nop 0
	global_load_lds_dwordx4 v140, s[30:31] offset:0
	s_nop 0
	s_mov_b32 m0, s47
	s_nop 0
	global_load_lds_dwordx4 v1, s[44:45] offset:0
	s_nop 0
	s_mov_b32 m0, s58
	s_nop 0
	global_load_lds_dwordx4 v139, s[44:45] offset:0
	s_waitcnt vmcnt(8)
	s_waitcnt lgkmcnt(0)
	s_barrier
	s_setprio 1
	v_mfma_f32_16x16x32_bf16 v[74:77], v[148:151], v[180:183], v[74:77]
	v_mfma_f32_16x16x32_bf16 v[74:77], v[152:155], v[184:187], v[74:77]
	v_mfma_f32_16x16x32_bf16 v[66:69], v[156:159], v[180:183], v[66:69]
	v_mfma_f32_16x16x32_bf16 v[66:69], v[160:163], v[184:187], v[66:69]
	v_mfma_f32_16x16x32_bf16 v[50:53], v[148:151], v[188:191], v[50:53]
	v_mfma_f32_16x16x32_bf16 v[50:53], v[152:155], v[192:195], v[50:53]
	v_mfma_f32_16x16x32_bf16 v[46:49], v[156:159], v[188:191], v[46:49]
	v_mfma_f32_16x16x32_bf16 v[46:49], v[160:163], v[192:195], v[46:49]
	v_mfma_f32_16x16x32_bf16 v[34:37], v[148:151], v[196:199], v[34:37]
	v_mfma_f32_16x16x32_bf16 v[34:37], v[152:155], v[200:203], v[34:37]
	v_mfma_f32_16x16x32_bf16 v[30:33], v[156:159], v[196:199], v[30:33]
	v_mfma_f32_16x16x32_bf16 v[30:33], v[160:163], v[200:203], v[30:33]
	v_mfma_f32_16x16x32_bf16 v[18:21], v[148:151], v[204:207], v[18:21]
	v_mfma_f32_16x16x32_bf16 v[18:21], v[152:155], v[208:211], v[18:21]
	v_mfma_f32_16x16x32_bf16 v[14:17], v[156:159], v[204:207], v[14:17]
	v_mfma_f32_16x16x32_bf16 v[14:17], v[160:163], v[208:211], v[14:17]
	s_setprio 0
	s_setprio 1
	v_mfma_f32_16x16x32_bf16 v[58:61], v[164:167], v[180:183], v[58:61]
	v_mfma_f32_16x16x32_bf16 v[54:57], v[172:175], v[180:183], v[54:57]
	v_mfma_f32_16x16x32_bf16 v[42:45], v[164:167], v[188:191], v[42:45]
	v_mfma_f32_16x16x32_bf16 v[38:41], v[172:175], v[188:191], v[38:41]
	v_mfma_f32_16x16x32_bf16 v[26:29], v[164:167], v[196:199], v[26:29]
	v_mfma_f32_16x16x32_bf16 v[22:25], v[172:175], v[196:199], v[22:25]
	v_mfma_f32_16x16x32_bf16 v[10:13], v[164:167], v[204:207], v[10:13]
	v_mfma_f32_16x16x32_bf16 v[4:7], v[172:175], v[204:207], v[6:9]
	v_mfma_f32_16x16x32_bf16 v[58:61], v[168:171], v[184:187], v[58:61]
	v_mfma_f32_16x16x32_bf16 v[54:57], v[176:179], v[184:187], v[54:57]
	v_mfma_f32_16x16x32_bf16 v[42:45], v[168:171], v[192:195], v[42:45]
	v_mfma_f32_16x16x32_bf16 v[38:41], v[176:179], v[192:195], v[38:41]
	v_mfma_f32_16x16x32_bf16 v[26:29], v[168:171], v[200:203], v[26:29]
	v_mfma_f32_16x16x32_bf16 v[22:25], v[176:179], v[200:203], v[22:25]
	v_mfma_f32_16x16x32_bf16 v[10:13], v[168:171], v[208:211], v[10:13]
	v_mfma_f32_16x16x32_bf16 v[4:7], v[176:179], v[208:211], v[4:7]
	s_setprio 0
	s_barrier
; #define PG8_KSETUP() const bool last = (t == nt - 2); const char* a1 = cA + (size_t)(t + 1) * kstep; \
;             const char* a2 = last ? nA : cA + (size_t)(t + 2) * kstep; const char* b2 = last ? nB : cB + (size_t)(t + 2) * kstep; const char* a3 = a2 + kstep; const char* b3 = b2 + kstep; \
;             if (last && has_next) S.a_ready(nxt)
; template <class Epi, class Sched, bool ALIGN_EPI = false, bool SP2 = false>
; __device__ __forceinline__ void gemm_phase(PG8_LAS unsigned char* lds, const Gemm g, const Sched& S, const Epi& E) {
;     ...
;         int t0 = 0;
;         if constexpr (SP2 && Epi::NVM == 16) { if (ui > 0) { const int t = 0; PG8_KSETUP(); PG8_KITER_SP2(24, 24); t0 = 2; } }
;         if constexpr (SP2 && Epi::NVM == 8) { if (ui > 0) { const int t = 0; PG8_KSETUP(); PG8_KITER_SP2(16, 16); t0 = 2; } }
;         for (int t = t0; t < nt; t += 2) {
;             PG8_KSETUP();
;             if constexpr (SP2) {
;             PG8_KITER_SP2(8, 8);
	ds_read_b128 v[148:151], v146
	ds_read_b128 v[152:155], v146 offset:1024
	ds_read_b128 v[156:159], v146 offset:2048
	ds_read_b128 v[160:163], v146 offset:3072
	ds_read_b128 v[164:167], v147
	ds_read_b128 v[168:171], v147 offset:1024
	ds_read_b128 v[172:175], v147 offset:2048
	ds_read_b128 v[176:179], v147 offset:3072
	ds_read_b128 v[180:183], v145 offset:32768
	ds_read_b128 v[184:187], v145 offset:33792
	ds_read_b128 v[188:191], v145 offset:34816
	ds_read_b128 v[192:195], v145 offset:35840
	ds_read_b128 v[196:199], v145 offset:36864
	ds_read_b128 v[200:203], v145 offset:37888
	ds_read_b128 v[204:207], v145 offset:38912
	ds_read_b128 v[208:211], v145 offset:39936
	s_add_u32 s30, s44, 0x160000
	s_addc_u32 s31, s45, 0
	s_mov_b32 m0, s59
	s_nop 0
	global_load_lds_dwordx4 v1, s[30:31] offset:0
	s_nop 0
	s_mov_b32 m0, s64
	s_nop 0
	global_load_lds_dwordx4 v139, s[30:31] offset:0
	s_waitcnt vmcnt(8)
	s_waitcnt lgkmcnt(0)
	s_barrier
	s_setprio 1
	v_mfma_f32_16x16x32_bf16 v[130:133], v[148:151], v[180:183], v[130:133]
	v_mfma_f32_16x16x32_bf16 v[130:133], v[152:155], v[184:187], v[130:133]
	v_mfma_f32_16x16x32_bf16 v[126:129], v[156:159], v[180:183], v[126:129]
	v_mfma_f32_16x16x32_bf16 v[126:129], v[160:163], v[184:187], v[126:129]
	v_mfma_f32_16x16x32_bf16 v[114:117], v[148:151], v[188:191], v[114:117]
	v_mfma_f32_16x16x32_bf16 v[114:117], v[152:155], v[192:195], v[114:117]
	v_mfma_f32_16x16x32_bf16 v[110:113], v[156:159], v[188:191], v[110:113]
	v_mfma_f32_16x16x32_bf16 v[110:113], v[160:163], v[192:195], v[110:113]
	v_mfma_f32_16x16x32_bf16 v[98:101], v[148:151], v[196:199], v[98:101]
	v_mfma_f32_16x16x32_bf16 v[98:101], v[152:155], v[200:203], v[98:101]
	v_mfma_f32_16x16x32_bf16 v[94:97], v[156:159], v[196:199], v[94:97]
	v_mfma_f32_16x16x32_bf16 v[94:97], v[160:163], v[200:203], v[94:97]
	v_mfma_f32_16x16x32_bf16 v[82:85], v[148:151], v[204:207], v[82:85]
	v_mfma_f32_16x16x32_bf16 v[82:85], v[152:155], v[208:211], v[82:85]
	v_mfma_f32_16x16x32_bf16 v[78:81], v[156:159], v[204:207], v[78:81]
	v_mfma_f32_16x16x32_bf16 v[78:81], v[160:163], v[208:211], v[78:81]
	s_setprio 0
	s_setprio 1
	v_mfma_f32_16x16x32_bf16 v[122:125], v[164:167], v[180:183], v[122:125]
	v_mfma_f32_16x16x32_bf16 v[122:125], v[168:171], v[184:187], v[122:125]
	v_mfma_f32_16x16x32_bf16 v[118:121], v[172:175], v[180:183], v[118:121]
	v_mfma_f32_16x16x32_bf16 v[118:121], v[176:179], v[184:187], v[118:121]
	v_mfma_f32_16x16x32_bf16 v[106:109], v[164:167], v[188:191], v[106:109]
	v_mfma_f32_16x16x32_bf16 v[106:109], v[168:171], v[192:195], v[106:109]
	v_mfma_f32_16x16x32_bf16 v[102:105], v[172:175], v[188:191], v[102:105]
	v_mfma_f32_16x16x32_bf16 v[102:105], v[176:179], v[192:195], v[102:105]
	v_mfma_f32_16x16x32_bf16 v[90:93], v[164:167], v[196:199], v[90:93]
	v_mfma_f32_16x16x32_bf16 v[90:93], v[168:171], v[200:203], v[90:93]
	v_mfma_f32_16x16x32_bf16 v[86:89], v[172:175], v[196:199], v[86:89]
	v_mfma_f32_16x16x32_bf16 v[86:89], v[176:179], v[200:203], v[86:89]
	v_mfma_f32_16x16x32_bf16 v[70:73], v[164:167], v[204:207], v[70:73]
	v_mfma_f32_16x16x32_bf16 v[70:73], v[168:171], v[208:211], v[70:73]
	v_mfma_f32_16x16x32_bf16 v[62:65], v[172:175], v[204:207], v[62:65]
	v_mfma_f32_16x16x32_bf16 v[62:65], v[176:179], v[208:211], v[62:65]
	s_setprio 0
	s_barrier
	ds_read_b128 v[180:183], v145 offset:49152
	ds_read_b128 v[184:187], v145 offset:50176
	ds_read_b128 v[188:191], v145 offset:51200
	ds_read_b128 v[192:195], v145 offset:52224
	ds_read_b128 v[196:199], v145 offset:53248
	ds_read_b128 v[200:203], v145 offset:54272
	ds_read_b128 v[204:207], v145 offset:55296
	ds_read_b128 v[208:211], v145 offset:56320
	s_add_u32 s30, s40, 0x80
	s_addc_u32 s31, s41, 0
	s_mov_b32 m0, s65
	s_nop 0
	global_load_lds_dwordx4 v138, s[30:31] offset:0
	s_nop 0
	s_mov_b32 m0, s66
	s_nop 0
	global_load_lds_dwordx4 v140, s[30:31] offset:0
	s_add_u32 s30, s40, 0x160080
	s_addc_u32 s31, s41, 0
	s_mov_b32 m0, s69
	s_nop 0
	global_load_lds_dwordx4 v138, s[30:31] offset:0
	s_nop 0
	s_mov_b32 m0, s70
	s_nop 0
	global_load_lds_dwordx4 v140, s[30:31] offset:0
	s_nop 0
	s_mov_b32 m0, s67
	s_nop 0
	global_load_lds_dwordx4 v1, s[38:39] offset:0
	s_nop 0
	s_mov_b32 m0, s68
	s_nop 0
	global_load_lds_dwordx4 v139, s[38:39] offset:0
	s_waitcnt vmcnt(8)
	s_waitcnt lgkmcnt(0)
	s_barrier
	s_setprio 1
	v_mfma_f32_16x16x32_bf16 v[74:77], v[148:151], v[180:183], v[74:77]
	v_mfma_f32_16x16x32_bf16 v[74:77], v[152:155], v[184:187], v[74:77]
	v_mfma_f32_16x16x32_bf16 v[66:69], v[156:159], v[180:183], v[66:69]
	v_mfma_f32_16x16x32_bf16 v[66:69], v[160:163], v[184:187], v[66:69]
	v_mfma_f32_16x16x32_bf16 v[50:53], v[148:151], v[188:191], v[50:53]
	v_mfma_f32_16x16x32_bf16 v[50:53], v[152:155], v[192:195], v[50:53]
	v_mfma_f32_16x16x32_bf16 v[46:49], v[156:159], v[188:191], v[46:49]
	v_mfma_f32_16x16x32_bf16 v[46:49], v[160:163], v[192:195], v[46:49]
	v_mfma_f32_16x16x32_bf16 v[34:37], v[148:151], v[196:199], v[34:37]
	v_mfma_f32_16x16x32_bf16 v[34:37], v[152:155], v[200:203], v[34:37]
	v_mfma_f32_16x16x32_bf16 v[30:33], v[156:159], v[196:199], v[30:33]
	v_mfma_f32_16x16x32_bf16 v[30:33], v[160:163], v[200:203], v[30:33]
	v_mfma_f32_16x16x32_bf16 v[18:21], v[148:151], v[204:207], v[18:21]
	v_mfma_f32_16x16x32_bf16 v[18:21], v[152:155], v[208:211], v[18:21]
	v_mfma_f32_16x16x32_bf16 v[14:17], v[156:159], v[204:207], v[14:17]
	v_mfma_f32_16x16x32_bf16 v[14:17], v[160:163], v[208:211], v[14:17]
	s_setprio 0
	s_setprio 1
	v_mfma_f32_16x16x32_bf16 v[58:61], v[164:167], v[180:183], v[58:61]
	v_mfma_f32_16x16x32_bf16 v[54:57], v[172:175], v[180:183], v[54:57]
	v_mfma_f32_16x16x32_bf16 v[42:45], v[164:167], v[188:191], v[42:45]
	v_mfma_f32_16x16x32_bf16 v[38:41], v[172:175], v[188:191], v[38:41]
	v_mfma_f32_16x16x32_bf16 v[26:29], v[164:167], v[196:199], v[26:29]
	v_mfma_f32_16x16x32_bf16 v[22:25], v[172:175], v[196:199], v[22:25]
	v_mfma_f32_16x16x32_bf16 v[8:11], v[164:167], v[204:207], v[10:13]
	v_mfma_f32_16x16x32_bf16 v[4:7], v[172:175], v[204:207], v[4:7]
	v_mfma_f32_16x16x32_bf16 v[58:61], v[168:171], v[184:187], v[58:61]
	v_mfma_f32_16x16x32_bf16 v[54:57], v[176:179], v[184:187], v[54:57]
	v_mfma_f32_16x16x32_bf16 v[42:45], v[168:171], v[192:195], v[42:45]
	v_mfma_f32_16x16x32_bf16 v[38:41], v[176:179], v[192:195], v[38:41]
	v_mfma_f32_16x16x32_bf16 v[26:29], v[168:171], v[200:203], v[26:29]
	v_mfma_f32_16x16x32_bf16 v[22:25], v[176:179], v[200:203], v[22:25]
	v_mfma_f32_16x16x32_bf16 v[10:13], v[168:171], v[208:211], v[8:11]
	v_mfma_f32_16x16x32_bf16 v[6:9], v[176:179], v[208:211], v[4:7]
	s_setprio 0
	s_barrier
	s_add_i32 s79, s79, 2
	s_add_u32 s80, s80, 0x100
	s_addc_u32 s81, s81, 0
	s_add_u32 s82, s82, 0x100
	s_addc_u32 s83, s83, 0
	s_add_u32 s36, s36, 0x100
	s_addc_u32 s37, s37, 0
	s_cmpk_gt_u32 s79, 0x55
	s_cbranch_scc0 .LBB0_872
	s_and_b64 vcc, exec, s[16:17]
	s_cbranch_vccz .LBB0_875
	s_barrier

; #define PG8_KSETUP() const bool last = (t == nt - 2); const char* a1 = cA + (size_t)(t + 1) * kstep; \
;             const char* a2 = last ? nA : cA + (size_t)(t + 2) * kstep; const char* b2 = last ? nB : cB + (size_t)(t + 2) * kstep; const char* a3 = a2 + kstep; const char* b3 = b2 + kstep; \
;             if (last && has_next) S.a_ready(nxt)
; template <class Epi, class Sched, bool ALIGN_EPI = false, bool SP2 = false>
; __device__ __forceinline__ void gemm_phase(PG8_LAS unsigned char* lds, const Gemm g, const Sched& S, const Epi& E) {
;     ...
;         int t0 = 0;
;         if constexpr (SP2 && Epi::NVM == 16) { if (ui > 0) { const int t = 0; PG8_KSETUP(); PG8_KITER_SP2(24, 24); t0 = 2; } }
;         if constexpr (SP2 && Epi::NVM == 8) { if (ui > 0) { const int t = 0; PG8_KSETUP(); PG8_KITER_SP2(16, 16); t0 = 2; } }
;         for (int t = t0; t < nt; t += 2) {
;             PG8_KSETUP();
;             if constexpr (SP2) {
;             PG8_KITER_SP2(8, 8);
.LBB0_1013:
	s_add_u32 s30, s40, s58
	s_addc_u32 s31, s41, 0
	s_add_u32 s42, s30, 0x100
	s_addc_u32 s43, s31, 0
	s_and_b64 s[30:31], s[54:55], exec
	s_cselect_b32 s67, s25, s43
	s_cselect_b32 s66, s94, s42
	s_add_u32 s30, s44, s58
	s_addc_u32 s31, s45, 0
	s_add_u32 s42, s30, 0x100
	s_addc_u32 s43, s31, 0
	s_add_u32 s56, s66, 0x80
	s_addc_u32 s57, s67, 0
	s_and_b64 s[30:31], s[54:55], exec
	s_cselect_b32 s69, s23, s43
	s_cselect_b32 s68, s95, s42
	s_add_u32 s30, s96, s58
	s_addc_u32 s31, s97, 0
	ds_read_b128 v[146:149], v141
	ds_read_b128 v[150:153], v141 offset:1024
	ds_read_b128 v[154:157], v141 offset:2048
	ds_read_b128 v[158:161], v141 offset:3072
	ds_read_b128 v[162:165], v142
	ds_read_b128 v[166:169], v142 offset:1024
	ds_read_b128 v[170:173], v142 offset:2048
	ds_read_b128 v[174:177], v142 offset:3072
	s_add_u32 s72, s30, 0x80
	s_addc_u32 s73, s31, 0
	s_add_u32 s70, s68, 0x10000
	s_addc_u32 s71, s69, 0
	s_add_u32 s64, s66, 0x10000
	s_addc_u32 s65, s67, 0
	s_add_u32 s58, s68, 0x80
	s_addc_u32 s59, s69, 0
	s_add_u32 s54, s68, 0x10080
	s_addc_u32 s55, s69, 0
	ds_read_b128 v[178:181], v143
	ds_read_b128 v[182:185], v143 offset:1024
	ds_read_b128 v[186:189], v143 offset:2048
	ds_read_b128 v[190:193], v143 offset:3072
	ds_read_b128 v[194:197], v143 offset:4096
	ds_read_b128 v[198:201], v143 offset:5120
	ds_read_b128 v[202:205], v143 offset:6144
	ds_read_b128 v[206:209], v143 offset:7168
	s_mov_b32 m0, s86
	s_nop 0
	global_load_lds_dwordx4 v1, s[72:73] offset:0
	s_nop 0
	s_mov_b32 m0, s87
	s_nop 0
	global_load_lds_dwordx4 v137, s[72:73] offset:0
	s_waitcnt vmcnt(8)
	s_waitcnt lgkmcnt(0)
	s_barrier
	s_setprio 1
	v_mfma_f32_16x16x32_bf16 v[126:129], v[146:149], v[178:181], v[126:129]
	v_mfma_f32_16x16x32_bf16 v[126:129], v[150:153], v[182:185], v[126:129]
	v_mfma_f32_16x16x32_bf16 v[122:125], v[154:157], v[178:181], v[122:125]
	v_mfma_f32_16x16x32_bf16 v[122:125], v[158:161], v[182:185], v[122:125]
	v_mfma_f32_16x16x32_bf16 v[118:121], v[146:149], v[186:189], v[118:121]
	v_mfma_f32_16x16x32_bf16 v[118:121], v[150:153], v[190:193], v[118:121]
	v_mfma_f32_16x16x32_bf16 v[110:113], v[154:157], v[186:189], v[110:113]
	v_mfma_f32_16x16x32_bf16 v[110:113], v[158:161], v[190:193], v[110:113]
	v_mfma_f32_16x16x32_bf16 v[102:105], v[146:149], v[194:197], v[102:105]
	v_mfma_f32_16x16x32_bf16 v[102:105], v[150:153], v[198:201], v[102:105]
	v_mfma_f32_16x16x32_bf16 v[94:97], v[154:157], v[194:197], v[94:97]
	v_mfma_f32_16x16x32_bf16 v[94:97], v[158:161], v[198:201], v[94:97]
	v_mfma_f32_16x16x32_bf16 v[86:89], v[146:149], v[202:205], v[86:89]
	v_mfma_f32_16x16x32_bf16 v[86:89], v[150:153], v[206:209], v[86:89]
	v_mfma_f32_16x16x32_bf16 v[78:81], v[154:157], v[202:205], v[78:81]
	v_mfma_f32_16x16x32_bf16 v[78:81], v[158:161], v[206:209], v[78:81]
	s_setprio 0
	s_setprio 1
	v_mfma_f32_16x16x32_bf16 v[114:117], v[162:165], v[178:181], v[114:117]
	v_mfma_f32_16x16x32_bf16 v[114:117], v[166:169], v[182:185], v[114:117]
	v_mfma_f32_16x16x32_bf16 v[106:109], v[170:173], v[178:181], v[106:109]
	v_mfma_f32_16x16x32_bf16 v[106:109], v[174:177], v[182:185], v[106:109]
	v_mfma_f32_16x16x32_bf16 v[98:101], v[162:165], v[186:189], v[98:101]
	v_mfma_f32_16x16x32_bf16 v[98:101], v[166:169], v[190:193], v[98:101]
	v_mfma_f32_16x16x32_bf16 v[90:93], v[170:173], v[186:189], v[90:93]
	v_mfma_f32_16x16x32_bf16 v[90:93], v[174:177], v[190:193], v[90:93]
	v_mfma_f32_16x16x32_bf16 v[82:85], v[162:165], v[194:197], v[82:85]
	v_mfma_f32_16x16x32_bf16 v[82:85], v[166:169], v[198:201], v[82:85]
	v_mfma_f32_16x16x32_bf16 v[74:77], v[170:173], v[194:197], v[74:77]
	v_mfma_f32_16x16x32_bf16 v[74:77], v[174:177], v[198:201], v[74:77]
	v_mfma_f32_16x16x32_bf16 v[70:73], v[162:165], v[202:205], v[70:73]
	v_mfma_f32_16x16x32_bf16 v[70:73], v[166:169], v[206:209], v[70:73]
	v_mfma_f32_16x16x32_bf16 v[66:69], v[170:173], v[202:205], v[66:69]
	v_mfma_f32_16x16x32_bf16 v[66:69], v[174:177], v[206:209], v[66:69]
	s_setprio 0
	s_barrier
	ds_read_b128 v[178:181], v143 offset:16384
	ds_read_b128 v[182:185], v143 offset:17408
	ds_read_b128 v[186:189], v143 offset:18432
	ds_read_b128 v[190:193], v143 offset:19456
	ds_read_b128 v[194:197], v143 offset:20480
	ds_read_b128 v[198:201], v143 offset:21504
	ds_read_b128 v[202:205], v143 offset:22528
	ds_read_b128 v[206:209], v143 offset:23552
	s_mov_b32 m0, s39
	s_nop 0
	global_load_lds_dwordx4 v136, s[68:69] offset:0
	s_nop 0
	s_mov_b32 m0, s74
	s_nop 0
	global_load_lds_dwordx4 v138, s[68:69] offset:0
	s_nop 0
	s_mov_b32 m0, s75
	s_nop 0
	global_load_lds_dwordx4 v136, s[70:71] offset:0
	s_nop 0
	s_mov_b32 m0, s76
	s_nop 0
	global_load_lds_dwordx4 v138, s[70:71] offset:0
	s_nop 0
	s_mov_b32 m0, s53
	s_nop 0
	global_load_lds_dwordx4 v1, s[66:67] offset:0
	s_nop 0
	s_mov_b32 m0, s77
	s_nop 0
	global_load_lds_dwordx4 v137, s[66:67] offset:0
	s_waitcnt vmcnt(8)
	s_waitcnt lgkmcnt(0)
	s_barrier
	s_setprio 1
	v_mfma_f32_16x16x32_bf16 v[62:65], v[146:149], v[178:181], v[62:65]
	v_mfma_f32_16x16x32_bf16 v[62:65], v[150:153], v[182:185], v[62:65]
	v_mfma_f32_16x16x32_bf16 v[58:61], v[154:157], v[178:181], v[58:61]
	v_mfma_f32_16x16x32_bf16 v[58:61], v[158:161], v[182:185], v[58:61]
	v_mfma_f32_16x16x32_bf16 v[54:57], v[146:149], v[186:189], v[54:57]
	v_mfma_f32_16x16x32_bf16 v[54:57], v[150:153], v[190:193], v[54:57]
	v_mfma_f32_16x16x32_bf16 v[46:49], v[154:157], v[186:189], v[46:49]
	v_mfma_f32_16x16x32_bf16 v[46:49], v[158:161], v[190:193], v[46:49]
	v_mfma_f32_16x16x32_bf16 v[38:41], v[146:149], v[194:197], v[38:41]
	v_mfma_f32_16x16x32_bf16 v[38:41], v[150:153], v[198:201], v[38:41]
	v_mfma_f32_16x16x32_bf16 v[30:33], v[154:157], v[194:197], v[30:33]
	v_mfma_f32_16x16x32_bf16 v[30:33], v[158:161], v[198:201], v[30:33]
	v_mfma_f32_16x16x32_bf16 v[22:25], v[146:149], v[202:205], v[22:25]
	v_mfma_f32_16x16x32_bf16 v[22:25], v[150:153], v[206:209], v[22:25]
	v_mfma_f32_16x16x32_bf16 v[14:17], v[154:157], v[202:205], v[14:17]
	v_mfma_f32_16x16x32_bf16 v[14:17], v[158:161], v[206:209], v[14:17]
	s_setprio 0
	s_setprio 1
	v_mfma_f32_16x16x32_bf16 v[50:53], v[162:165], v[178:181], v[50:53]
	v_mfma_f32_16x16x32_bf16 v[50:53], v[166:169], v[182:185], v[50:53]
	v_mfma_f32_16x16x32_bf16 v[42:45], v[170:173], v[178:181], v[42:45]
	v_mfma_f32_16x16x32_bf16 v[42:45], v[174:177], v[182:185], v[42:45]
	v_mfma_f32_16x16x32_bf16 v[34:37], v[162:165], v[186:189], v[34:37]
	v_mfma_f32_16x16x32_bf16 v[34:37], v[166:169], v[190:193], v[34:37]
	v_mfma_f32_16x16x32_bf16 v[26:29], v[170:173], v[186:189], v[26:29]
	v_mfma_f32_16x16x32_bf16 v[26:29], v[174:177], v[190:193], v[26:29]
	v_mfma_f32_16x16x32_bf16 v[18:21], v[162:165], v[194:197], v[18:21]
	v_mfma_f32_16x16x32_bf16 v[18:21], v[166:169], v[198:201], v[18:21]
	v_mfma_f32_16x16x32_bf16 v[10:13], v[170:173], v[194:197], v[10:13]
	v_mfma_f32_16x16x32_bf16 v[10:13], v[174:177], v[198:201], v[10:13]
	v_mfma_f32_16x16x32_bf16 v[6:9], v[162:165], v[202:205], v[6:9]
	v_mfma_f32_16x16x32_bf16 v[6:9], v[166:169], v[206:209], v[6:9]
	v_mfma_f32_16x16x32_bf16 v[2:5], v[170:173], v[202:205], v[2:5]
	v_mfma_f32_16x16x32_bf16 v[2:5], v[174:177], v[206:209], v[2:5]
	s_setprio 0
	s_barrier
	ds_read_b128 v[146:149], v144
	ds_read_b128 v[150:153], v144 offset:1024
	ds_read_b128 v[154:157], v144 offset:2048
	ds_read_b128 v[158:161], v144 offset:3072
	ds_read_b128 v[162:165], v145
	ds_read_b128 v[166:169], v145 offset:1024
	ds_read_b128 v[170:173], v145 offset:2048
	ds_read_b128 v[174:177], v145 offset:3072
	ds_read_b128 v[178:181], v143 offset:32768
	ds_read_b128 v[182:185], v143 offset:33792
	ds_read_b128 v[186:189], v143 offset:34816
	ds_read_b128 v[190:193], v143 offset:35840
	ds_read_b128 v[194:197], v143 offset:36864
	ds_read_b128 v[198:201], v143 offset:37888
	ds_read_b128 v[202:205], v143 offset:38912
	ds_read_b128 v[206:209], v143 offset:39936
	s_mov_b32 m0, s78
	s_nop 0
	global_load_lds_dwordx4 v1, s[64:65] offset:0
	s_nop 0
	s_mov_b32 m0, s79
	s_nop 0
	global_load_lds_dwordx4 v137, s[64:65] offset:0
	s_waitcnt vmcnt(8)
	s_waitcnt lgkmcnt(0)
	s_barrier
	s_setprio 1
	v_mfma_f32_16x16x32_bf16 v[126:129], v[146:149], v[178:181], v[126:129]
	v_mfma_f32_16x16x32_bf16 v[126:129], v[150:153], v[182:185], v[126:129]
	v_mfma_f32_16x16x32_bf16 v[122:125], v[154:157], v[178:181], v[122:125]
	v_mfma_f32_16x16x32_bf16 v[122:125], v[158:161], v[182:185], v[122:125]
	v_mfma_f32_16x16x32_bf16 v[118:121], v[146:149], v[186:189], v[118:121]
	v_mfma_f32_16x16x32_bf16 v[118:121], v[150:153], v[190:193], v[118:121]
	v_mfma_f32_16x16x32_bf16 v[110:113], v[154:157], v[186:189], v[110:113]
	v_mfma_f32_16x16x32_bf16 v[110:113], v[158:161], v[190:193], v[110:113]
	v_mfma_f32_16x16x32_bf16 v[102:105], v[146:149], v[194:197], v[102:105]
	v_mfma_f32_16x16x32_bf16 v[102:105], v[150:153], v[198:201], v[102:105]
	v_mfma_f32_16x16x32_bf16 v[94:97], v[154:157], v[194:197], v[94:97]
	v_mfma_f32_16x16x32_bf16 v[94:97], v[158:161], v[198:201], v[94:97]
	v_mfma_f32_16x16x32_bf16 v[86:89], v[146:149], v[202:205], v[86:89]
	v_mfma_f32_16x16x32_bf16 v[86:89], v[150:153], v[206:209], v[86:89]
	v_mfma_f32_16x16x32_bf16 v[78:81], v[154:157], v[202:205], v[78:81]
	v_mfma_f32_16x16x32_bf16 v[78:81], v[158:161], v[206:209], v[78:81]
	s_setprio 0
	s_setprio 1
	v_mfma_f32_16x16x32_bf16 v[114:117], v[162:165], v[178:181], v[114:117]
	v_mfma_f32_16x16x32_bf16 v[114:117], v[166:169], v[182:185], v[114:117]
	v_mfma_f32_16x16x32_bf16 v[106:109], v[170:173], v[178:181], v[106:109]
	v_mfma_f32_16x16x32_bf16 v[106:109], v[174:177], v[182:185], v[106:109]
	v_mfma_f32_16x16x32_bf16 v[98:101], v[162:165], v[186:189], v[98:101]
	v_mfma_f32_16x16x32_bf16 v[98:101], v[166:169], v[190:193], v[98:101]
	v_mfma_f32_16x16x32_bf16 v[90:93], v[170:173], v[186:189], v[90:93]
	v_mfma_f32_16x16x32_bf16 v[90:93], v[174:177], v[190:193], v[90:93]
	v_mfma_f32_16x16x32_bf16 v[82:85], v[162:165], v[194:197], v[82:85]
	v_mfma_f32_16x16x32_bf16 v[82:85], v[166:169], v[198:201], v[82:85]
	v_mfma_f32_16x16x32_bf16 v[74:77], v[170:173], v[194:197], v[74:77]
	v_mfma_f32_16x16x32_bf16 v[74:77], v[174:177], v[198:201], v[74:77]
	v_mfma_f32_16x16x32_bf16 v[70:73], v[162:165], v[202:205], v[70:73]
	v_mfma_f32_16x16x32_bf16 v[70:73], v[166:169], v[206:209], v[70:73]
	v_mfma_f32_16x16x32_bf16 v[66:69], v[170:173], v[202:205], v[66:69]
	v_mfma_f32_16x16x32_bf16 v[66:69], v[174:177], v[206:209], v[66:69]
	s_setprio 0
	s_barrier
; #define PG8_KSETUP() const bool last = (t == nt - 2); const char* a1 = cA + (size_t)(t + 1) * kstep; \
;             const char* a2 = last ? nA : cA + (size_t)(t + 2) * kstep; const char* b2 = last ? nB : cB + (size_t)(t + 2) * kstep; const char* a3 = a2 + kstep; const char* b3 = b2 + kstep; \
;             if (last && has_next) S.a_ready(nxt)
; template <class Epi, class Sched, bool ALIGN_EPI = false, bool SP2 = false>
; __device__ __forceinline__ void gemm_phase(PG8_LAS unsigned char* lds, const Gemm g, const Sched& S, const Epi& E) {
;     ...
;         int t0 = 0;
;         if constexpr (SP2 && Epi::NVM == 16) { if (ui > 0) { const int t = 0; PG8_KSETUP(); PG8_KITER_SP2(24, 24); t0 = 2; } }
;         if constexpr (SP2 && Epi::NVM == 8) { if (ui > 0) { const int t = 0; PG8_KSETUP(); PG8_KITER_SP2(16, 16); t0 = 2; } }
;         for (int t = t0; t < nt; t += 2) {
;             PG8_KSETUP();
;             if constexpr (SP2) {
;             PG8_KITER_SP2(8, 8);
	ds_read_b128 v[178:181], v143 offset:49152
	ds_read_b128 v[182:185], v143 offset:50176
	ds_read_b128 v[186:189], v143 offset:51200
	ds_read_b128 v[190:193], v143 offset:52224
	ds_read_b128 v[194:197], v143 offset:53248
	ds_read_b128 v[198:201], v143 offset:54272
	ds_read_b128 v[202:205], v143 offset:55296
	ds_read_b128 v[206:209], v143 offset:56320
	s_mov_b32 m0, s80
	s_nop 0
	global_load_lds_dwordx4 v136, s[58:59] offset:0
	s_nop 0
	s_mov_b32 m0, s81
	s_nop 0
	global_load_lds_dwordx4 v138, s[58:59] offset:0
	s_nop 0
	s_mov_b32 m0, s84
	s_nop 0
	global_load_lds_dwordx4 v136, s[54:55] offset:0
	s_nop 0
	s_mov_b32 m0, s85
	s_nop 0
	global_load_lds_dwordx4 v138, s[54:55] offset:0
	s_nop 0
	s_mov_b32 m0, s82
	s_nop 0
	global_load_lds_dwordx4 v1, s[56:57] offset:0
	s_nop 0
	s_mov_b32 m0, s83
	s_nop 0
	global_load_lds_dwordx4 v137, s[56:57] offset:0
	s_waitcnt vmcnt(8)
	s_waitcnt lgkmcnt(0)
	s_barrier
	s_setprio 1
	v_mfma_f32_16x16x32_bf16 v[62:65], v[146:149], v[178:181], v[62:65]
	v_mfma_f32_16x16x32_bf16 v[62:65], v[150:153], v[182:185], v[62:65]
	v_mfma_f32_16x16x32_bf16 v[58:61], v[154:157], v[178:181], v[58:61]
	v_mfma_f32_16x16x32_bf16 v[58:61], v[158:161], v[182:185], v[58:61]
	v_mfma_f32_16x16x32_bf16 v[54:57], v[146:149], v[186:189], v[54:57]
	v_mfma_f32_16x16x32_bf16 v[54:57], v[150:153], v[190:193], v[54:57]
	v_mfma_f32_16x16x32_bf16 v[46:49], v[154:157], v[186:189], v[46:49]
	v_mfma_f32_16x16x32_bf16 v[46:49], v[158:161], v[190:193], v[46:49]
	v_mfma_f32_16x16x32_bf16 v[38:41], v[146:149], v[194:197], v[38:41]
	v_mfma_f32_16x16x32_bf16 v[38:41], v[150:153], v[198:201], v[38:41]
	v_mfma_f32_16x16x32_bf16 v[30:33], v[154:157], v[194:197], v[30:33]
	v_mfma_f32_16x16x32_bf16 v[30:33], v[158:161], v[198:201], v[30:33]
	v_mfma_f32_16x16x32_bf16 v[22:25], v[146:149], v[202:205], v[22:25]
	v_mfma_f32_16x16x32_bf16 v[22:25], v[150:153], v[206:209], v[22:25]
	v_mfma_f32_16x16x32_bf16 v[14:17], v[154:157], v[202:205], v[14:17]
	v_mfma_f32_16x16x32_bf16 v[14:17], v[158:161], v[206:209], v[14:17]
	s_setprio 0
	s_setprio 1
	v_mfma_f32_16x16x32_bf16 v[50:53], v[162:165], v[178:181], v[50:53]
	v_mfma_f32_16x16x32_bf16 v[50:53], v[166:169], v[182:185], v[50:53]
	v_mfma_f32_16x16x32_bf16 v[42:45], v[170:173], v[178:181], v[42:45]
	v_mfma_f32_16x16x32_bf16 v[42:45], v[174:177], v[182:185], v[42:45]
	v_mfma_f32_16x16x32_bf16 v[34:37], v[162:165], v[186:189], v[34:37]
	v_mfma_f32_16x16x32_bf16 v[34:37], v[166:169], v[190:193], v[34:37]
	v_mfma_f32_16x16x32_bf16 v[26:29], v[170:173], v[186:189], v[26:29]
	v_mfma_f32_16x16x32_bf16 v[26:29], v[174:177], v[190:193], v[26:29]
	v_mfma_f32_16x16x32_bf16 v[18:21], v[162:165], v[194:197], v[18:21]
	v_mfma_f32_16x16x32_bf16 v[18:21], v[166:169], v[198:201], v[18:21]
	v_mfma_f32_16x16x32_bf16 v[10:13], v[170:173], v[194:197], v[10:13]
	v_mfma_f32_16x16x32_bf16 v[10:13], v[174:177], v[198:201], v[10:13]
	v_mfma_f32_16x16x32_bf16 v[6:9], v[162:165], v[202:205], v[6:9]
	v_mfma_f32_16x16x32_bf16 v[6:9], v[166:169], v[206:209], v[6:9]
	v_mfma_f32_16x16x32_bf16 v[2:5], v[170:173], v[202:205], v[2:5]
	v_mfma_f32_16x16x32_bf16 v[2:5], v[174:177], v[206:209], v[2:5]
	s_setprio 0
	s_barrier
	s_movk_i32 s58, 0x100
	s_andn2_b64 vcc, exec, s[46:47]
	s_mov_b64 s[54:55], -1
	s_mov_b64 s[46:47], 0
	s_cbranch_vccz .LBB0_1013
	s_and_b64 vcc, exec, s[14:15]
	s_cbranch_vccz .LBB0_1016
	s_barrier

; #define PG8_KSETUP() const bool last = (t == nt - 2); const char* a1 = cA + (size_t)(t + 1) * kstep; \
;             const char* a2 = last ? nA : cA + (size_t)(t + 2) * kstep; const char* b2 = last ? nB : cB + (size_t)(t + 2) * kstep; const char* a3 = a2 + kstep; const char* b3 = b2 + kstep; \
;             if (last && has_next) S.a_ready(nxt)
; template <class Epi, class Sched, bool ALIGN_EPI = false, bool SP2 = false>
; __device__ __forceinline__ void gemm_phase(PG8_LAS unsigned char* lds, const Gemm g, const Sched& S, const Epi& E) {
;     ...
;         int t0 = 0;
;         if constexpr (SP2 && Epi::NVM == 16) { if (ui > 0) { const int t = 0; PG8_KSETUP(); PG8_KITER_SP2(24, 24); t0 = 2; } }
.LBB0_2128:
	s_cmp_eq_u32 s29, 0
	s_mov_b32 s58, 0
	s_cbranch_scc1 .LBB0_2130
	ds_read_b128 v[4:7], v147
	ds_read_b128 v[8:11], v147 offset:1024
	ds_read_b128 v[12:15], v147 offset:2048
	ds_read_b128 v[16:19], v147 offset:3072
	ds_read_b128 v[20:23], v148
	ds_read_b128 v[24:27], v148 offset:1024
	ds_read_b128 v[28:31], v148 offset:2048
	ds_read_b128 v[32:35], v148 offset:3072
	s_add_u32 s40, s54, 0x100
	s_addc_u32 s41, s55, 0
	s_add_u32 s30, s56, 0x100
	s_addc_u32 s31, s57, 0
	s_add_u32 s38, s54, 0x180
	s_addc_u32 s39, s55, 0
	ds_read_b128 v[36:39], v149
	ds_read_b128 v[40:43], v149 offset:1024
	ds_read_b128 v[44:47], v149 offset:2048
	ds_read_b128 v[48:51], v149 offset:3072
	ds_read_b128 v[52:55], v149 offset:4096
	ds_read_b128 v[56:59], v149 offset:5120
	ds_read_b128 v[60:63], v149 offset:6144
	ds_read_b128 v[64:67], v149 offset:7168
	s_add_u32 s42, s54, 0x80080
	s_addc_u32 s43, s55, 0
	s_mov_b32 m0, s79
	s_nop 0
	global_load_lds_dwordx4 v1, s[42:43] offset:0
	s_nop 0
	s_mov_b32 m0, s80
	s_nop 0
	global_load_lds_dwordx4 v143, s[42:43] offset:0
	s_waitcnt vmcnt(24)
	s_waitcnt lgkmcnt(0)
	s_barrier
	s_setprio 1
	v_mfma_f32_16x16x32_bf16 v[92:95], v[4:7], v[60:63], 0
	v_mfma_f32_16x16x32_bf16 v[68:71], v[4:7], v[36:39], 0
	v_mfma_f32_16x16x32_bf16 v[72:75], v[12:15], v[36:39], 0
	v_mfma_f32_16x16x32_bf16 v[76:79], v[4:7], v[44:47], 0
	v_mfma_f32_16x16x32_bf16 v[80:83], v[12:15], v[44:47], 0
	v_mfma_f32_16x16x32_bf16 v[84:87], v[4:7], v[52:55], 0
	v_mfma_f32_16x16x32_bf16 v[88:91], v[12:15], v[52:55], 0
	v_mfma_f32_16x16x32_bf16 v[102:105], v[8:11], v[64:67], v[92:95]
	v_mfma_f32_16x16x32_bf16 v[92:95], v[12:15], v[60:63], 0
	v_mfma_f32_16x16x32_bf16 v[68:71], v[8:11], v[40:43], v[68:71]
	v_mfma_f32_16x16x32_bf16 v[72:75], v[16:19], v[40:43], v[72:75]
	v_mfma_f32_16x16x32_bf16 v[76:79], v[8:11], v[48:51], v[76:79]
	v_mfma_f32_16x16x32_bf16 v[80:83], v[16:19], v[48:51], v[80:83]
	v_mfma_f32_16x16x32_bf16 v[84:87], v[8:11], v[56:59], v[84:87]
	v_mfma_f32_16x16x32_bf16 v[88:91], v[16:19], v[56:59], v[88:91]
	v_mfma_f32_16x16x32_bf16 v[106:109], v[16:19], v[64:67], v[92:95]
	s_setprio 0
	s_setprio 1
	v_mfma_f32_16x16x32_bf16 v[92:95], v[20:23], v[36:39], 0
	v_mfma_f32_16x16x32_bf16 v[36:39], v[28:31], v[36:39], 0
	v_mfma_f32_16x16x32_bf16 v[118:121], v[24:27], v[40:43], v[92:95]
	v_mfma_f32_16x16x32_bf16 v[36:39], v[32:35], v[40:43], v[36:39]
	v_mfma_f32_16x16x32_bf16 v[40:43], v[20:23], v[44:47], 0
	v_mfma_f32_16x16x32_bf16 v[44:47], v[28:31], v[44:47], 0
	v_mfma_f32_16x16x32_bf16 v[40:43], v[24:27], v[48:51], v[40:43]
	v_mfma_f32_16x16x32_bf16 v[44:47], v[32:35], v[48:51], v[44:47]
	v_mfma_f32_16x16x32_bf16 v[48:51], v[20:23], v[52:55], 0
	v_mfma_f32_16x16x32_bf16 v[52:55], v[28:31], v[52:55], 0
	v_mfma_f32_16x16x32_bf16 v[48:51], v[24:27], v[56:59], v[48:51]
	v_mfma_f32_16x16x32_bf16 v[52:55], v[32:35], v[56:59], v[52:55]
	v_mfma_f32_16x16x32_bf16 v[56:59], v[20:23], v[60:63], 0
	v_mfma_f32_16x16x32_bf16 v[60:63], v[28:31], v[60:63], 0
	v_mfma_f32_16x16x32_bf16 v[56:59], v[24:27], v[64:67], v[56:59]
	v_mfma_f32_16x16x32_bf16 v[60:63], v[32:35], v[64:67], v[60:63]
	s_setprio 0
	s_barrier
	ds_read_b128 v[64:67], v149 offset:16384
	ds_read_b128 v[92:95], v149 offset:17408
	ds_read_b128 v[96:99], v149 offset:18432
	ds_read_b128 v[110:113], v149 offset:19456
	ds_read_b128 v[114:117], v149 offset:20480
	ds_read_b128 v[122:125], v149 offset:21504
	ds_read_b128 v[126:129], v149 offset:22528
	ds_read_b128 v[130:133], v149 offset:23552
	s_mov_b32 m0, s47
	s_nop 0
	global_load_lds_dwordx4 v142, s[30:31] offset:0
	s_nop 0
	s_mov_b32 m0, s52
	s_nop 0
	global_load_lds_dwordx4 v144, s[30:31] offset:0
	s_add_u32 s30, s56, 0x80100
	s_addc_u32 s31, s57, 0
	s_mov_b32 m0, s53
	s_nop 0
	global_load_lds_dwordx4 v142, s[30:31] offset:0
	s_nop 0
	s_mov_b32 m0, s66
	s_nop 0
	global_load_lds_dwordx4 v144, s[30:31] offset:0
	s_nop 0
	s_mov_b32 m0, s33
	s_nop 0
	global_load_lds_dwordx4 v1, s[40:41] offset:0
	s_nop 0
	s_mov_b32 m0, s67
	s_nop 0
	global_load_lds_dwordx4 v143, s[40:41] offset:0
	s_waitcnt vmcnt(24)
	s_waitcnt lgkmcnt(0)
	s_barrier
	s_setprio 1
	v_mfma_f32_16x16x32_bf16 v[138:141], v[4:7], v[64:67], 0
	v_mfma_f32_16x16x32_bf16 v[156:159], v[4:7], v[96:99], 0
	v_mfma_f32_16x16x32_bf16 v[164:167], v[4:7], v[114:117], 0
	v_mfma_f32_16x16x32_bf16 v[4:7], v[4:7], v[126:129], 0
	v_mfma_f32_16x16x32_bf16 v[138:141], v[8:11], v[92:95], v[138:141]
	v_mfma_f32_16x16x32_bf16 v[156:159], v[8:11], v[110:113], v[156:159]
	v_mfma_f32_16x16x32_bf16 v[164:167], v[8:11], v[122:125], v[164:167]
	v_mfma_f32_16x16x32_bf16 v[4:7], v[8:11], v[130:133], v[4:7]
	v_mfma_f32_16x16x32_bf16 v[8:11], v[12:15], v[126:129], 0
	v_mfma_f32_16x16x32_bf16 v[152:155], v[12:15], v[64:67], 0
	v_mfma_f32_16x16x32_bf16 v[160:163], v[12:15], v[96:99], 0
	v_mfma_f32_16x16x32_bf16 v[168:171], v[12:15], v[114:117], 0
	v_mfma_f32_16x16x32_bf16 v[8:11], v[16:19], v[130:133], v[8:11]
	v_mfma_f32_16x16x32_bf16 v[152:155], v[16:19], v[92:95], v[152:155]
	v_mfma_f32_16x16x32_bf16 v[160:163], v[16:19], v[110:113], v[160:163]
	v_mfma_f32_16x16x32_bf16 v[168:171], v[16:19], v[122:125], v[168:171]
	s_setprio 0
	s_setprio 1
	v_mfma_f32_16x16x32_bf16 v[12:15], v[20:23], v[64:67], 0
	v_mfma_f32_16x16x32_bf16 v[172:175], v[24:27], v[92:95], v[12:15]
	v_mfma_f32_16x16x32_bf16 v[12:15], v[28:31], v[64:67], 0
	v_mfma_f32_16x16x32_bf16 v[176:179], v[32:35], v[92:95], v[12:15]
	v_mfma_f32_16x16x32_bf16 v[12:15], v[20:23], v[96:99], 0
	v_mfma_f32_16x16x32_bf16 v[180:183], v[24:27], v[110:113], v[12:15]
	v_mfma_f32_16x16x32_bf16 v[12:15], v[28:31], v[96:99], 0
	v_mfma_f32_16x16x32_bf16 v[184:187], v[32:35], v[110:113], v[12:15]
	v_mfma_f32_16x16x32_bf16 v[12:15], v[20:23], v[114:117], 0
	v_mfma_f32_16x16x32_bf16 v[188:191], v[24:27], v[122:125], v[12:15]
	v_mfma_f32_16x16x32_bf16 v[12:15], v[28:31], v[114:117], 0
	v_mfma_f32_16x16x32_bf16 v[192:195], v[32:35], v[122:125], v[12:15]
	v_mfma_f32_16x16x32_bf16 v[12:15], v[20:23], v[126:129], 0
	v_mfma_f32_16x16x32_bf16 v[196:199], v[24:27], v[130:133], v[12:15]
	v_mfma_f32_16x16x32_bf16 v[12:15], v[28:31], v[126:129], 0
	v_mfma_f32_16x16x32_bf16 v[200:203], v[32:35], v[130:133], v[12:15]
	s_setprio 0
	s_barrier
; #define PG8_KSETUP() const bool last = (t == nt - 2); const char* a1 = cA + (size_t)(t + 1) * kstep; \
;             const char* a2 = last ? nA : cA + (size_t)(t + 2) * kstep; const char* b2 = last ? nB : cB + (size_t)(t + 2) * kstep; const char* a3 = a2 + kstep; const char* b3 = b2 + kstep; \
;             if (last && has_next) S.a_ready(nxt)
; template <class Epi, class Sched, bool ALIGN_EPI = false, bool SP2 = false>
; __device__ __forceinline__ void gemm_phase(PG8_LAS unsigned char* lds, const Gemm g, const Sched& S, const Epi& E) {
;     ...
;         int t0 = 0;
;         if constexpr (SP2 && Epi::NVM == 16) { if (ui > 0) { const int t = 0; PG8_KSETUP(); PG8_KITER_SP2(24, 24); t0 = 2; } }
	s_nop 4
	ds_read_b128 v[12:15], v150
	ds_read_b128 v[16:19], v150 offset:1024
	ds_read_b128 v[22:25], v150 offset:2048
	ds_read_b128 v[26:29], v150 offset:3072
	ds_read_b128 v[204:207], v151
	ds_read_b128 v[208:211], v151 offset:1024
	ds_read_b128 v[212:215], v151 offset:2048
	ds_read_b128 v[216:219], v151 offset:3072
	ds_read_b128 v[30:33], v149 offset:32768
	ds_read_b128 v[64:67], v149 offset:33792
	ds_read_b128 v[220:223], v149 offset:34816
	ds_read_b128 v[224:227], v149 offset:35840
	ds_read_b128 v[228:231], v149 offset:36864
	ds_read_b128 v[232:235], v149 offset:37888
	ds_read_b128 v[236:239], v149 offset:38912
	ds_read_b128 v[240:243], v149 offset:39936
	s_add_u32 s30, s54, 0x80100
	s_addc_u32 s31, s55, 0
	s_mov_b32 m0, s68
	s_nop 0
	global_load_lds_dwordx4 v1, s[30:31] offset:0
	s_nop 0
	s_mov_b32 m0, s69
	s_nop 0
	global_load_lds_dwordx4 v143, s[30:31] offset:0
	s_waitcnt vmcnt(8)
	s_waitcnt lgkmcnt(0)
	s_barrier
	s_setprio 1
	v_mfma_f32_16x16x32_bf16 v[68:71], v[12:15], v[30:33], v[68:71]
	v_mfma_f32_16x16x32_bf16 v[130:133], v[16:19], v[64:67], v[68:71]
	v_mfma_f32_16x16x32_bf16 v[68:71], v[22:25], v[30:33], v[72:75]
	v_mfma_f32_16x16x32_bf16 v[126:129], v[26:29], v[64:67], v[68:71]
	v_mfma_f32_16x16x32_bf16 v[68:71], v[12:15], v[220:223], v[76:79]
	v_mfma_f32_16x16x32_bf16 v[114:117], v[16:19], v[224:227], v[68:71]
	v_mfma_f32_16x16x32_bf16 v[68:71], v[22:25], v[220:223], v[80:83]
	v_mfma_f32_16x16x32_bf16 v[110:113], v[26:29], v[224:227], v[68:71]
	v_mfma_f32_16x16x32_bf16 v[68:71], v[12:15], v[228:231], v[84:87]
	v_mfma_f32_16x16x32_bf16 v[98:101], v[16:19], v[232:235], v[68:71]
	v_mfma_f32_16x16x32_bf16 v[68:71], v[22:25], v[228:231], v[88:91]
	v_mfma_f32_16x16x32_bf16 v[94:97], v[26:29], v[232:235], v[68:71]
	v_mfma_f32_16x16x32_bf16 v[68:71], v[12:15], v[236:239], v[102:105]
	v_mfma_f32_16x16x32_bf16 v[82:85], v[16:19], v[240:243], v[68:71]
	v_mfma_f32_16x16x32_bf16 v[68:71], v[22:25], v[236:239], v[106:109]
	v_mfma_f32_16x16x32_bf16 v[78:81], v[26:29], v[240:243], v[68:71]
	s_setprio 0
	s_setprio 1
	v_mfma_f32_16x16x32_bf16 v[68:71], v[204:207], v[30:33], v[118:121]
	v_mfma_f32_16x16x32_bf16 v[30:33], v[212:215], v[30:33], v[36:39]
	v_mfma_f32_16x16x32_bf16 v[118:121], v[216:219], v[64:67], v[30:33]
	v_mfma_f32_16x16x32_bf16 v[30:33], v[204:207], v[220:223], v[40:43]
	v_mfma_f32_16x16x32_bf16 v[106:109], v[208:211], v[224:227], v[30:33]
	v_mfma_f32_16x16x32_bf16 v[30:33], v[212:215], v[220:223], v[44:47]
	v_mfma_f32_16x16x32_bf16 v[102:105], v[216:219], v[224:227], v[30:33]
	v_mfma_f32_16x16x32_bf16 v[30:33], v[204:207], v[228:231], v[48:51]
	v_mfma_f32_16x16x32_bf16 v[90:93], v[208:211], v[232:235], v[30:33]
	v_mfma_f32_16x16x32_bf16 v[30:33], v[212:215], v[228:231], v[52:55]
	v_mfma_f32_16x16x32_bf16 v[86:89], v[216:219], v[232:235], v[30:33]
	v_mfma_f32_16x16x32_bf16 v[30:33], v[204:207], v[236:239], v[56:59]
	v_mfma_f32_16x16x32_bf16 v[74:77], v[208:211], v[240:243], v[30:33]
	v_mfma_f32_16x16x32_bf16 v[30:33], v[212:215], v[236:239], v[60:63]
	v_mfma_f32_16x16x32_bf16 v[122:125], v[208:211], v[64:67], v[68:71]
	v_mfma_f32_16x16x32_bf16 v[70:73], v[216:219], v[240:243], v[30:33]
	s_setprio 0
	s_barrier
	ds_read_b128 v[38:41], v149 offset:49152
	ds_read_b128 v[42:45], v149 offset:50176
	ds_read_b128 v[220:223], v149 offset:51200
	ds_read_b128 v[224:227], v149 offset:52224
	ds_read_b128 v[228:231], v149 offset:53248
	ds_read_b128 v[232:235], v149 offset:54272
	ds_read_b128 v[236:239], v149 offset:55296
	ds_read_b128 v[240:243], v149 offset:56320
	s_add_u32 s30, s56, 0x180
	s_addc_u32 s31, s57, 0
	s_mov_b32 m0, s73
	s_nop 0
	global_load_lds_dwordx4 v142, s[30:31] offset:0
	s_nop 0
	s_mov_b32 m0, s74
	s_nop 0
	global_load_lds_dwordx4 v144, s[30:31] offset:0
	s_add_u32 s30, s56, 0x80180
	s_addc_u32 s31, s57, 0
	s_mov_b32 m0, s77
	s_nop 0
	global_load_lds_dwordx4 v142, s[30:31] offset:0
	s_nop 0
	s_mov_b32 m0, s78
	s_nop 0
	global_load_lds_dwordx4 v144, s[30:31] offset:0
	s_nop 0
	s_mov_b32 m0, s75
	s_nop 0
	global_load_lds_dwordx4 v1, s[38:39] offset:0
	s_nop 0
	s_mov_b32 m0, s76
	s_nop 0
	global_load_lds_dwordx4 v143, s[38:39] offset:0
	s_waitcnt vmcnt(8)
	s_waitcnt lgkmcnt(0)
	s_barrier
	s_setprio 1
	v_mfma_f32_16x16x32_bf16 v[30:33], v[12:15], v[38:41], v[138:141]
	v_mfma_f32_16x16x32_bf16 v[66:69], v[16:19], v[42:45], v[30:33]
	v_mfma_f32_16x16x32_bf16 v[30:33], v[22:25], v[38:41], v[152:155]
	v_mfma_f32_16x16x32_bf16 v[62:65], v[26:29], v[42:45], v[30:33]
	v_mfma_f32_16x16x32_bf16 v[30:33], v[12:15], v[220:223], v[156:159]
	v_mfma_f32_16x16x32_bf16 v[50:53], v[16:19], v[224:227], v[30:33]
	v_mfma_f32_16x16x32_bf16 v[30:33], v[22:25], v[220:223], v[160:163]
	v_mfma_f32_16x16x32_bf16 v[46:49], v[26:29], v[224:227], v[30:33]
	v_mfma_f32_16x16x32_bf16 v[30:33], v[12:15], v[228:231], v[164:167]
	v_mfma_f32_16x16x32_bf16 v[4:7], v[12:15], v[236:239], v[4:7]
	v_mfma_f32_16x16x32_bf16 v[34:37], v[16:19], v[232:235], v[30:33]
	v_mfma_f32_16x16x32_bf16 v[30:33], v[22:25], v[228:231], v[168:171]
	v_mfma_f32_16x16x32_bf16 v[18:21], v[16:19], v[240:243], v[4:7]
	v_mfma_f32_16x16x32_bf16 v[4:7], v[22:25], v[236:239], v[8:11]
	v_mfma_f32_16x16x32_bf16 v[30:33], v[26:29], v[232:235], v[30:33]
	v_mfma_f32_16x16x32_bf16 v[14:17], v[26:29], v[240:243], v[4:7]
	s_setprio 0
	s_setprio 1
	v_mfma_f32_16x16x32_bf16 v[4:7], v[204:207], v[38:41], v[172:175]
	v_mfma_f32_16x16x32_bf16 v[58:61], v[208:211], v[42:45], v[4:7]
	v_mfma_f32_16x16x32_bf16 v[4:7], v[212:215], v[38:41], v[176:179]
	v_mfma_f32_16x16x32_bf16 v[54:57], v[216:219], v[42:45], v[4:7]
	v_mfma_f32_16x16x32_bf16 v[4:7], v[204:207], v[220:223], v[180:183]
	v_mfma_f32_16x16x32_bf16 v[42:45], v[208:211], v[224:227], v[4:7]
	v_mfma_f32_16x16x32_bf16 v[4:7], v[212:215], v[220:223], v[184:187]
	v_mfma_f32_16x16x32_bf16 v[38:41], v[216:219], v[224:227], v[4:7]
	v_mfma_f32_16x16x32_bf16 v[4:7], v[204:207], v[228:231], v[188:191]
	v_mfma_f32_16x16x32_bf16 v[26:29], v[208:211], v[232:235], v[4:7]
	v_mfma_f32_16x16x32_bf16 v[4:7], v[212:215], v[228:231], v[192:195]
	v_mfma_f32_16x16x32_bf16 v[22:25], v[216:219], v[232:235], v[4:7]
	v_mfma_f32_16x16x32_bf16 v[4:7], v[204:207], v[236:239], v[196:199]
	v_mfma_f32_16x16x32_bf16 v[10:13], v[208:211], v[240:243], v[4:7]
	v_mfma_f32_16x16x32_bf16 v[4:7], v[212:215], v[236:239], v[200:203]
	v_mfma_f32_16x16x32_bf16 v[6:9], v[216:219], v[240:243], v[4:7]
	s_setprio 0
	s_barrier
	s_mov_b32 s58, 2
	s_branch .LBB0_2131

; #define PG8_KSETUP() const bool last = (t == nt - 2); const char* a1 = cA + (size_t)(t + 1) * kstep; \
;             const char* a2 = last ? nA : cA + (size_t)(t + 2) * kstep; const char* b2 = last ? nB : cB + (size_t)(t + 2) * kstep; const char* a3 = a2 + kstep; const char* b3 = b2 + kstep; \
;             if (last && has_next) S.a_ready(nxt)
; template <class Epi, class Sched, bool ALIGN_EPI = false, bool SP2 = false>
; __device__ __forceinline__ void gemm_phase(PG8_LAS unsigned char* lds, const Gemm g, const Sched& S, const Epi& E) {
;     ...
;         int t0 = 0;
;         if constexpr (SP2 && Epi::NVM == 16) { if (ui > 0) { const int t = 0; PG8_KSETUP(); PG8_KITER_SP2(24, 24); t0 = 2; } }
;         if constexpr (SP2 && Epi::NVM == 8) { if (ui > 0) { const int t = 0; PG8_KSETUP(); PG8_KITER_SP2(16, 16); t0 = 2; } }
;         for (int t = t0; t < nt; t += 2) {
;             PG8_KSETUP();
;             if constexpr (SP2) {
;             PG8_KITER_SP2(8, 8);
.LBB0_2132:
	ds_read_b128 v[138:141], v147
	ds_read_b128 v[152:155], v147 offset:1024
	ds_read_b128 v[156:159], v147 offset:2048
	ds_read_b128 v[160:163], v147 offset:3072
	ds_read_b128 v[164:167], v148
	ds_read_b128 v[168:171], v148 offset:1024
	ds_read_b128 v[172:175], v148 offset:2048
	ds_read_b128 v[176:179], v148 offset:3072
	s_cmp_eq_u32 s86, 28
	s_cselect_b32 s64, s45, s89
	s_cselect_b32 s65, s37, s90
	s_cselect_b32 s58, s85, s87
	s_cselect_b32 s59, s29, s88
	s_add_u32 s56, s64, 0x80
	s_addc_u32 s57, s65, 0
	ds_read_b128 v[180:183], v149
	ds_read_b128 v[184:187], v149 offset:1024
	ds_read_b128 v[188:191], v149 offset:2048
	ds_read_b128 v[192:195], v149 offset:3072
	ds_read_b128 v[196:199], v149 offset:4096
	ds_read_b128 v[200:203], v149 offset:5120
	ds_read_b128 v[204:207], v149 offset:6144
	ds_read_b128 v[208:211], v149 offset:7168
	s_mov_b32 m0, s79
	s_nop 0
	global_load_lds_dwordx4 v1, s[54:55] offset:0
	s_nop 0
	s_mov_b32 m0, s80
	s_nop 0
	global_load_lds_dwordx4 v143, s[54:55] offset:0
	s_waitcnt vmcnt(8)
	s_waitcnt lgkmcnt(0)
	s_barrier
	s_setprio 1
	v_mfma_f32_16x16x32_bf16 v[130:133], v[138:141], v[180:183], v[130:133]
	v_mfma_f32_16x16x32_bf16 v[130:133], v[152:155], v[184:187], v[130:133]
	v_mfma_f32_16x16x32_bf16 v[126:129], v[156:159], v[180:183], v[126:129]
	v_mfma_f32_16x16x32_bf16 v[126:129], v[160:163], v[184:187], v[126:129]
	v_mfma_f32_16x16x32_bf16 v[114:117], v[138:141], v[188:191], v[114:117]
	v_mfma_f32_16x16x32_bf16 v[114:117], v[152:155], v[192:195], v[114:117]
	v_mfma_f32_16x16x32_bf16 v[110:113], v[156:159], v[188:191], v[110:113]
	v_mfma_f32_16x16x32_bf16 v[110:113], v[160:163], v[192:195], v[110:113]
	v_mfma_f32_16x16x32_bf16 v[98:101], v[138:141], v[196:199], v[98:101]
	v_mfma_f32_16x16x32_bf16 v[98:101], v[152:155], v[200:203], v[98:101]
	v_mfma_f32_16x16x32_bf16 v[94:97], v[156:159], v[196:199], v[94:97]
	v_mfma_f32_16x16x32_bf16 v[94:97], v[160:163], v[200:203], v[94:97]
	v_mfma_f32_16x16x32_bf16 v[82:85], v[138:141], v[204:207], v[82:85]
	v_mfma_f32_16x16x32_bf16 v[82:85], v[152:155], v[208:211], v[82:85]
	v_mfma_f32_16x16x32_bf16 v[78:81], v[156:159], v[204:207], v[78:81]
	v_mfma_f32_16x16x32_bf16 v[78:81], v[160:163], v[208:211], v[78:81]
	s_setprio 0
	s_setprio 1
	v_mfma_f32_16x16x32_bf16 v[122:125], v[164:167], v[180:183], v[122:125]
	v_mfma_f32_16x16x32_bf16 v[122:125], v[168:171], v[184:187], v[122:125]
	v_mfma_f32_16x16x32_bf16 v[118:121], v[172:175], v[180:183], v[118:121]
	v_mfma_f32_16x16x32_bf16 v[118:121], v[176:179], v[184:187], v[118:121]
	v_mfma_f32_16x16x32_bf16 v[106:109], v[164:167], v[188:191], v[106:109]
	v_mfma_f32_16x16x32_bf16 v[106:109], v[168:171], v[192:195], v[106:109]
	v_mfma_f32_16x16x32_bf16 v[102:105], v[172:175], v[188:191], v[102:105]
	v_mfma_f32_16x16x32_bf16 v[102:105], v[176:179], v[192:195], v[102:105]
	v_mfma_f32_16x16x32_bf16 v[90:93], v[164:167], v[196:199], v[90:93]
	v_mfma_f32_16x16x32_bf16 v[90:93], v[168:171], v[200:203], v[90:93]
	v_mfma_f32_16x16x32_bf16 v[86:89], v[172:175], v[196:199], v[86:89]
	v_mfma_f32_16x16x32_bf16 v[86:89], v[176:179], v[200:203], v[86:89]
	v_mfma_f32_16x16x32_bf16 v[74:77], v[164:167], v[204:207], v[74:77]
	v_mfma_f32_16x16x32_bf16 v[74:77], v[168:171], v[208:211], v[74:77]
	v_mfma_f32_16x16x32_bf16 v[70:73], v[172:175], v[204:207], v[70:73]
	v_mfma_f32_16x16x32_bf16 v[70:73], v[176:179], v[208:211], v[70:73]
	s_setprio 0
	s_barrier
	ds_read_b128 v[180:183], v149 offset:16384
	ds_read_b128 v[184:187], v149 offset:17408
	ds_read_b128 v[188:191], v149 offset:18432
	ds_read_b128 v[192:195], v149 offset:19456
	ds_read_b128 v[196:199], v149 offset:20480
	ds_read_b128 v[200:203], v149 offset:21504
	ds_read_b128 v[204:207], v149 offset:22528
	ds_read_b128 v[208:211], v149 offset:23552
	s_mov_b32 m0, s47
	s_nop 0
	global_load_lds_dwordx4 v142, s[58:59] offset:0
	s_add_u32 s30, s58, 0x80000
	s_mov_b32 m0, s52
	s_nop 0
	global_load_lds_dwordx4 v144, s[58:59] offset:0
	s_addc_u32 s31, s59, 0
	s_mov_b32 m0, s53
	s_nop 0
	global_load_lds_dwordx4 v142, s[30:31] offset:0
	s_nop 0
	s_mov_b32 m0, s66
	s_nop 0
	global_load_lds_dwordx4 v144, s[30:31] offset:0
	s_nop 0
	s_mov_b32 m0, s33
	s_nop 0
	global_load_lds_dwordx4 v1, s[64:65] offset:0
	s_nop 0
	s_mov_b32 m0, s67
	s_nop 0
	global_load_lds_dwordx4 v143, s[64:65] offset:0
	s_waitcnt vmcnt(8)
	s_waitcnt lgkmcnt(0)
	s_barrier
	s_setprio 1
	v_mfma_f32_16x16x32_bf16 v[66:69], v[138:141], v[180:183], v[66:69]
	v_mfma_f32_16x16x32_bf16 v[66:69], v[152:155], v[184:187], v[66:69]
	v_mfma_f32_16x16x32_bf16 v[62:65], v[156:159], v[180:183], v[62:65]
	v_mfma_f32_16x16x32_bf16 v[62:65], v[160:163], v[184:187], v[62:65]
	v_mfma_f32_16x16x32_bf16 v[50:53], v[138:141], v[188:191], v[50:53]
	v_mfma_f32_16x16x32_bf16 v[50:53], v[152:155], v[192:195], v[50:53]
	v_mfma_f32_16x16x32_bf16 v[46:49], v[156:159], v[188:191], v[46:49]
	v_mfma_f32_16x16x32_bf16 v[46:49], v[160:163], v[192:195], v[46:49]
	v_mfma_f32_16x16x32_bf16 v[34:37], v[138:141], v[196:199], v[34:37]
	v_mfma_f32_16x16x32_bf16 v[34:37], v[152:155], v[200:203], v[34:37]
	v_mfma_f32_16x16x32_bf16 v[30:33], v[156:159], v[196:199], v[30:33]
	v_mfma_f32_16x16x32_bf16 v[30:33], v[160:163], v[200:203], v[30:33]
	v_mfma_f32_16x16x32_bf16 v[18:21], v[138:141], v[204:207], v[18:21]
	v_mfma_f32_16x16x32_bf16 v[18:21], v[152:155], v[208:211], v[18:21]
	v_mfma_f32_16x16x32_bf16 v[14:17], v[156:159], v[204:207], v[14:17]
	v_mfma_f32_16x16x32_bf16 v[14:17], v[160:163], v[208:211], v[14:17]
	s_setprio 0
	s_setprio 1
	v_mfma_f32_16x16x32_bf16 v[58:61], v[164:167], v[180:183], v[58:61]
	v_mfma_f32_16x16x32_bf16 v[54:57], v[172:175], v[180:183], v[54:57]
	v_mfma_f32_16x16x32_bf16 v[42:45], v[164:167], v[188:191], v[42:45]
	v_mfma_f32_16x16x32_bf16 v[38:41], v[172:175], v[188:191], v[38:41]
	v_mfma_f32_16x16x32_bf16 v[26:29], v[164:167], v[196:199], v[26:29]
	v_mfma_f32_16x16x32_bf16 v[22:25], v[172:175], v[196:199], v[22:25]
	v_mfma_f32_16x16x32_bf16 v[10:13], v[164:167], v[204:207], v[10:13]
	v_mfma_f32_16x16x32_bf16 v[4:7], v[172:175], v[204:207], v[6:9]
	v_mfma_f32_16x16x32_bf16 v[58:61], v[168:171], v[184:187], v[58:61]
	v_mfma_f32_16x16x32_bf16 v[54:57], v[176:179], v[184:187], v[54:57]
	v_mfma_f32_16x16x32_bf16 v[42:45], v[168:171], v[192:195], v[42:45]
	v_mfma_f32_16x16x32_bf16 v[38:41], v[176:179], v[192:195], v[38:41]
	v_mfma_f32_16x16x32_bf16 v[26:29], v[168:171], v[200:203], v[26:29]
	v_mfma_f32_16x16x32_bf16 v[22:25], v[176:179], v[200:203], v[22:25]
	v_mfma_f32_16x16x32_bf16 v[10:13], v[168:171], v[208:211], v[10:13]
	v_mfma_f32_16x16x32_bf16 v[4:7], v[176:179], v[208:211], v[4:7]
	s_setprio 0
	s_barrier
; #define PG8_KSETUP() const bool last = (t == nt - 2); const char* a1 = cA + (size_t)(t + 1) * kstep; \
;             const char* a2 = last ? nA : cA + (size_t)(t + 2) * kstep; const char* b2 = last ? nB : cB + (size_t)(t + 2) * kstep; const char* a3 = a2 + kstep; const char* b3 = b2 + kstep; \
;             if (last && has_next) S.a_ready(nxt)
; template <class Epi, class Sched, bool ALIGN_EPI = false, bool SP2 = false>
; __device__ __forceinline__ void gemm_phase(PG8_LAS unsigned char* lds, const Gemm g, const Sched& S, const Epi& E) {
;     ...
;         int t0 = 0;
;         if constexpr (SP2 && Epi::NVM == 16) { if (ui > 0) { const int t = 0; PG8_KSETUP(); PG8_KITER_SP2(24, 24); t0 = 2; } }
;         if constexpr (SP2 && Epi::NVM == 8) { if (ui > 0) { const int t = 0; PG8_KSETUP(); PG8_KITER_SP2(16, 16); t0 = 2; } }
;         for (int t = t0; t < nt; t += 2) {
;             PG8_KSETUP();
;             if constexpr (SP2) {
;             PG8_KITER_SP2(8, 8);
	ds_read_b128 v[138:141], v150
	ds_read_b128 v[152:155], v150 offset:1024
	ds_read_b128 v[156:159], v150 offset:2048
	ds_read_b128 v[160:163], v150 offset:3072
	ds_read_b128 v[164:167], v151
	ds_read_b128 v[168:171], v151 offset:1024
	ds_read_b128 v[172:175], v151 offset:2048
	ds_read_b128 v[176:179], v151 offset:3072
	ds_read_b128 v[180:183], v149 offset:32768
	ds_read_b128 v[184:187], v149 offset:33792
	ds_read_b128 v[188:191], v149 offset:34816
	ds_read_b128 v[192:195], v149 offset:35840
	ds_read_b128 v[196:199], v149 offset:36864
	ds_read_b128 v[200:203], v149 offset:37888
	ds_read_b128 v[204:207], v149 offset:38912
	ds_read_b128 v[208:211], v149 offset:39936
	s_add_u32 s30, s64, 0x80000
	s_addc_u32 s31, s65, 0
	s_mov_b32 m0, s68
	s_nop 0
	global_load_lds_dwordx4 v1, s[30:31] offset:0
	s_nop 0
	s_mov_b32 m0, s69
	s_nop 0
	global_load_lds_dwordx4 v143, s[30:31] offset:0
	s_waitcnt vmcnt(8)
	s_waitcnt lgkmcnt(0)
	s_barrier
	s_setprio 1
	v_mfma_f32_16x16x32_bf16 v[130:133], v[138:141], v[180:183], v[130:133]
	v_mfma_f32_16x16x32_bf16 v[130:133], v[152:155], v[184:187], v[130:133]
	v_mfma_f32_16x16x32_bf16 v[126:129], v[156:159], v[180:183], v[126:129]
	v_mfma_f32_16x16x32_bf16 v[126:129], v[160:163], v[184:187], v[126:129]
	v_mfma_f32_16x16x32_bf16 v[114:117], v[138:141], v[188:191], v[114:117]
	v_mfma_f32_16x16x32_bf16 v[114:117], v[152:155], v[192:195], v[114:117]
	v_mfma_f32_16x16x32_bf16 v[110:113], v[156:159], v[188:191], v[110:113]
	v_mfma_f32_16x16x32_bf16 v[110:113], v[160:163], v[192:195], v[110:113]
	v_mfma_f32_16x16x32_bf16 v[98:101], v[138:141], v[196:199], v[98:101]
	v_mfma_f32_16x16x32_bf16 v[98:101], v[152:155], v[200:203], v[98:101]
	v_mfma_f32_16x16x32_bf16 v[94:97], v[156:159], v[196:199], v[94:97]
	v_mfma_f32_16x16x32_bf16 v[94:97], v[160:163], v[200:203], v[94:97]
	v_mfma_f32_16x16x32_bf16 v[82:85], v[138:141], v[204:207], v[82:85]
	v_mfma_f32_16x16x32_bf16 v[82:85], v[152:155], v[208:211], v[82:85]
	v_mfma_f32_16x16x32_bf16 v[78:81], v[156:159], v[204:207], v[78:81]
	v_mfma_f32_16x16x32_bf16 v[78:81], v[160:163], v[208:211], v[78:81]
	s_setprio 0
	s_setprio 1
	v_mfma_f32_16x16x32_bf16 v[122:125], v[164:167], v[180:183], v[122:125]
	v_mfma_f32_16x16x32_bf16 v[122:125], v[168:171], v[184:187], v[122:125]
	v_mfma_f32_16x16x32_bf16 v[118:121], v[172:175], v[180:183], v[118:121]
	v_mfma_f32_16x16x32_bf16 v[118:121], v[176:179], v[184:187], v[118:121]
	v_mfma_f32_16x16x32_bf16 v[106:109], v[164:167], v[188:191], v[106:109]
	v_mfma_f32_16x16x32_bf16 v[106:109], v[168:171], v[192:195], v[106:109]
	v_mfma_f32_16x16x32_bf16 v[102:105], v[172:175], v[188:191], v[102:105]
	v_mfma_f32_16x16x32_bf16 v[102:105], v[176:179], v[192:195], v[102:105]
	v_mfma_f32_16x16x32_bf16 v[90:93], v[164:167], v[196:199], v[90:93]
	v_mfma_f32_16x16x32_bf16 v[90:93], v[168:171], v[200:203], v[90:93]
	v_mfma_f32_16x16x32_bf16 v[86:89], v[172:175], v[196:199], v[86:89]
	v_mfma_f32_16x16x32_bf16 v[86:89], v[176:179], v[200:203], v[86:89]
	v_mfma_f32_16x16x32_bf16 v[74:77], v[164:167], v[204:207], v[74:77]
	v_mfma_f32_16x16x32_bf16 v[74:77], v[168:171], v[208:211], v[74:77]
	v_mfma_f32_16x16x32_bf16 v[70:73], v[172:175], v[204:207], v[70:73]
	v_mfma_f32_16x16x32_bf16 v[70:73], v[176:179], v[208:211], v[70:73]
	s_setprio 0
	s_barrier
	ds_read_b128 v[180:183], v149 offset:49152
	ds_read_b128 v[184:187], v149 offset:50176
	ds_read_b128 v[188:191], v149 offset:51200
	ds_read_b128 v[192:195], v149 offset:52224
	ds_read_b128 v[196:199], v149 offset:53248
	ds_read_b128 v[200:203], v149 offset:54272
	ds_read_b128 v[204:207], v149 offset:55296
	ds_read_b128 v[208:211], v149 offset:56320
	s_add_u32 s30, s58, 0x80
	s_addc_u32 s31, s59, 0
	s_mov_b32 m0, s73
	s_nop 0
	global_load_lds_dwordx4 v142, s[30:31] offset:0
	s_nop 0
	s_mov_b32 m0, s74
	s_nop 0
	global_load_lds_dwordx4 v144, s[30:31] offset:0
	s_add_u32 s30, s58, 0x80080
	s_addc_u32 s31, s59, 0
	s_mov_b32 m0, s77
	s_nop 0
	global_load_lds_dwordx4 v142, s[30:31] offset:0
	s_nop 0
	s_mov_b32 m0, s78
	s_nop 0
	global_load_lds_dwordx4 v144, s[30:31] offset:0
	s_nop 0
	s_mov_b32 m0, s75
	s_nop 0
	global_load_lds_dwordx4 v1, s[56:57] offset:0
	s_nop 0
	s_mov_b32 m0, s76
	s_nop 0
	global_load_lds_dwordx4 v143, s[56:57] offset:0
	s_waitcnt vmcnt(8)
	s_waitcnt lgkmcnt(0)
	s_barrier
	s_setprio 1
	v_mfma_f32_16x16x32_bf16 v[66:69], v[138:141], v[180:183], v[66:69]
	v_mfma_f32_16x16x32_bf16 v[66:69], v[152:155], v[184:187], v[66:69]
	v_mfma_f32_16x16x32_bf16 v[62:65], v[156:159], v[180:183], v[62:65]
	v_mfma_f32_16x16x32_bf16 v[62:65], v[160:163], v[184:187], v[62:65]
	v_mfma_f32_16x16x32_bf16 v[50:53], v[138:141], v[188:191], v[50:53]
	v_mfma_f32_16x16x32_bf16 v[50:53], v[152:155], v[192:195], v[50:53]
	v_mfma_f32_16x16x32_bf16 v[46:49], v[156:159], v[188:191], v[46:49]
	v_mfma_f32_16x16x32_bf16 v[46:49], v[160:163], v[192:195], v[46:49]
	v_mfma_f32_16x16x32_bf16 v[34:37], v[138:141], v[196:199], v[34:37]
	v_mfma_f32_16x16x32_bf16 v[34:37], v[152:155], v[200:203], v[34:37]
	v_mfma_f32_16x16x32_bf16 v[30:33], v[156:159], v[196:199], v[30:33]
	v_mfma_f32_16x16x32_bf16 v[30:33], v[160:163], v[200:203], v[30:33]
	v_mfma_f32_16x16x32_bf16 v[18:21], v[138:141], v[204:207], v[18:21]
	v_mfma_f32_16x16x32_bf16 v[18:21], v[152:155], v[208:211], v[18:21]
	v_mfma_f32_16x16x32_bf16 v[14:17], v[156:159], v[204:207], v[14:17]
	v_mfma_f32_16x16x32_bf16 v[14:17], v[160:163], v[208:211], v[14:17]
	s_setprio 0
	s_setprio 1
	v_mfma_f32_16x16x32_bf16 v[58:61], v[164:167], v[180:183], v[58:61]
	v_mfma_f32_16x16x32_bf16 v[54:57], v[172:175], v[180:183], v[54:57]
	v_mfma_f32_16x16x32_bf16 v[42:45], v[164:167], v[188:191], v[42:45]
	v_mfma_f32_16x16x32_bf16 v[38:41], v[172:175], v[188:191], v[38:41]
	v_mfma_f32_16x16x32_bf16 v[26:29], v[164:167], v[196:199], v[26:29]
	v_mfma_f32_16x16x32_bf16 v[22:25], v[172:175], v[196:199], v[22:25]
	v_mfma_f32_16x16x32_bf16 v[8:11], v[164:167], v[204:207], v[10:13]
	v_mfma_f32_16x16x32_bf16 v[4:7], v[172:175], v[204:207], v[4:7]
	v_mfma_f32_16x16x32_bf16 v[58:61], v[168:171], v[184:187], v[58:61]
	v_mfma_f32_16x16x32_bf16 v[54:57], v[176:179], v[184:187], v[54:57]
	v_mfma_f32_16x16x32_bf16 v[42:45], v[168:171], v[192:195], v[42:45]
	v_mfma_f32_16x16x32_bf16 v[38:41], v[176:179], v[192:195], v[38:41]
	v_mfma_f32_16x16x32_bf16 v[26:29], v[168:171], v[200:203], v[26:29]
	v_mfma_f32_16x16x32_bf16 v[22:25], v[176:179], v[200:203], v[22:25]
	v_mfma_f32_16x16x32_bf16 v[10:13], v[168:171], v[208:211], v[8:11]
	v_mfma_f32_16x16x32_bf16 v[6:9], v[176:179], v[208:211], v[4:7]
	s_setprio 0
	s_barrier
	s_add_i32 s86, s86, 2
	s_add_u32 s87, s87, 0x100
	s_addc_u32 s88, s88, 0
	s_add_u32 s89, s89, 0x100
	s_addc_u32 s90, s90, 0
	s_add_u32 s54, s54, 0x100
	s_addc_u32 s55, s55, 0
	s_cmp_gt_u32 s86, 29
	s_cbranch_scc0 .LBB0_2132
	s_and_b64 vcc, exec, s[18:19]
	s_cbranch_vccz .LBB0_2135
	s_barrier

; #define PG8_KSETUP() const bool last = (t == nt - 2); const char* a1 = cA + (size_t)(t + 1) * kstep; \
;             const char* a2 = last ? nA : cA + (size_t)(t + 2) * kstep; const char* b2 = last ? nB : cB + (size_t)(t + 2) * kstep; const char* a3 = a2 + kstep; const char* b3 = b2 + kstep; \
;             if (last && has_next) S.a_ready(nxt)
; template <class Epi, class Sched, bool ALIGN_EPI = false, bool SP2 = false>
; __device__ __forceinline__ void gemm_phase(PG8_LAS unsigned char* lds, const Gemm g, const Sched& S, const Epi& E) {
;     ...
;         int t0 = 0;
;         if constexpr (SP2 && Epi::NVM == 16) { if (ui > 0) { const int t = 0; PG8_KSETUP(); PG8_KITER_SP2(24, 24); t0 = 2; } }
;         if constexpr (SP2 && Epi::NVM == 8) { if (ui > 0) { const int t = 0; PG8_KSETUP(); PG8_KITER_SP2(16, 16); t0 = 2; } }
.LBB0_2287:
	s_cmp_lg_u32 s75, 0
	s_mov_b32 s40, 0
	s_cbranch_scc0 .LBB0_2289
	ds_read_b128 v[4:7], v152
	ds_read_b128 v[8:11], v152 offset:1024
	ds_read_b128 v[12:15], v152 offset:2048
	ds_read_b128 v[16:19], v152 offset:3072
	ds_read_b128 v[20:23], v153
	ds_read_b128 v[24:27], v153 offset:1024
	ds_read_b128 v[28:31], v153 offset:2048
	ds_read_b128 v[32:35], v153 offset:3072
	s_add_u32 s24, s36, 0x100
	s_addc_u32 s25, s37, 0
	s_add_u32 s30, s38, 0x100
	s_addc_u32 s31, s39, 0
	s_add_u32 s22, s36, 0x180
	s_addc_u32 s23, s37, 0
	ds_read_b128 v[36:39], v154
	ds_read_b128 v[40:43], v154 offset:1024
	ds_read_b128 v[44:47], v154 offset:2048
	ds_read_b128 v[48:51], v154 offset:3072
	ds_read_b128 v[52:55], v154 offset:4096
	ds_read_b128 v[56:59], v154 offset:5120
	ds_read_b128 v[60:63], v154 offset:6144
	ds_read_b128 v[64:67], v154 offset:7168
	s_add_u32 s40, s36, 0x80080
	s_addc_u32 s41, s37, 0
	s_mov_b32 m0, s66
	s_nop 0
	global_load_lds_dwordx4 v1, s[40:41] offset:0
	s_nop 0
	s_mov_b32 m0, s67
	s_nop 0
	global_load_lds_dwordx4 v147, s[40:41] offset:0
	s_waitcnt vmcnt(16)
	s_waitcnt lgkmcnt(0)
	s_barrier
	s_setprio 1
	v_mfma_f32_16x16x32_bf16 v[92:95], v[4:7], v[60:63], 0
	v_mfma_f32_16x16x32_bf16 v[68:71], v[4:7], v[36:39], 0
	v_mfma_f32_16x16x32_bf16 v[72:75], v[12:15], v[36:39], 0
	v_mfma_f32_16x16x32_bf16 v[76:79], v[4:7], v[44:47], 0
	v_mfma_f32_16x16x32_bf16 v[80:83], v[12:15], v[44:47], 0
	v_mfma_f32_16x16x32_bf16 v[84:87], v[4:7], v[52:55], 0
	v_mfma_f32_16x16x32_bf16 v[88:91], v[12:15], v[52:55], 0
	v_mfma_f32_16x16x32_bf16 v[102:105], v[8:11], v[64:67], v[92:95]
	v_mfma_f32_16x16x32_bf16 v[92:95], v[12:15], v[60:63], 0
	v_mfma_f32_16x16x32_bf16 v[68:71], v[8:11], v[40:43], v[68:71]
	v_mfma_f32_16x16x32_bf16 v[72:75], v[16:19], v[40:43], v[72:75]
	v_mfma_f32_16x16x32_bf16 v[76:79], v[8:11], v[48:51], v[76:79]
	v_mfma_f32_16x16x32_bf16 v[80:83], v[16:19], v[48:51], v[80:83]
	v_mfma_f32_16x16x32_bf16 v[84:87], v[8:11], v[56:59], v[84:87]
	v_mfma_f32_16x16x32_bf16 v[88:91], v[16:19], v[56:59], v[88:91]
	v_mfma_f32_16x16x32_bf16 v[106:109], v[16:19], v[64:67], v[92:95]
	s_setprio 0
	s_setprio 1
	v_mfma_f32_16x16x32_bf16 v[92:95], v[20:23], v[36:39], 0
	v_mfma_f32_16x16x32_bf16 v[36:39], v[28:31], v[36:39], 0
	v_mfma_f32_16x16x32_bf16 v[118:121], v[24:27], v[40:43], v[92:95]
	v_mfma_f32_16x16x32_bf16 v[36:39], v[32:35], v[40:43], v[36:39]
	v_mfma_f32_16x16x32_bf16 v[40:43], v[20:23], v[44:47], 0
	v_mfma_f32_16x16x32_bf16 v[44:47], v[28:31], v[44:47], 0
	v_mfma_f32_16x16x32_bf16 v[40:43], v[24:27], v[48:51], v[40:43]
	v_mfma_f32_16x16x32_bf16 v[44:47], v[32:35], v[48:51], v[44:47]
	v_mfma_f32_16x16x32_bf16 v[48:51], v[20:23], v[52:55], 0
	v_mfma_f32_16x16x32_bf16 v[52:55], v[28:31], v[52:55], 0
	v_mfma_f32_16x16x32_bf16 v[48:51], v[24:27], v[56:59], v[48:51]
	v_mfma_f32_16x16x32_bf16 v[52:55], v[32:35], v[56:59], v[52:55]
	v_mfma_f32_16x16x32_bf16 v[56:59], v[20:23], v[60:63], 0
	v_mfma_f32_16x16x32_bf16 v[60:63], v[28:31], v[60:63], 0
	v_mfma_f32_16x16x32_bf16 v[56:59], v[24:27], v[64:67], v[56:59]
	v_mfma_f32_16x16x32_bf16 v[60:63], v[32:35], v[64:67], v[60:63]
	s_setprio 0
	s_barrier
	ds_read_b128 v[64:67], v154 offset:16384
	ds_read_b128 v[92:95], v154 offset:17408
	ds_read_b128 v[96:99], v154 offset:18432
	ds_read_b128 v[110:113], v154 offset:19456
	ds_read_b128 v[114:117], v154 offset:20480
	ds_read_b128 v[122:125], v154 offset:21504
	ds_read_b128 v[126:129], v154 offset:22528
	ds_read_b128 v[130:133], v154 offset:23552
	s_mov_b32 m0, s29
	s_nop 0
	global_load_lds_dwordx4 v146, s[30:31] offset:0
	s_nop 0
	s_mov_b32 m0, s46
	s_nop 0
	global_load_lds_dwordx4 v148, s[30:31] offset:0
	s_add_u32 s30, s38, 0x80100
	s_addc_u32 s31, s39, 0
	s_mov_b32 m0, s47
	s_nop 0
	global_load_lds_dwordx4 v146, s[30:31] offset:0
	s_nop 0
	s_mov_b32 m0, s52
	s_nop 0
	global_load_lds_dwordx4 v148, s[30:31] offset:0
	s_nop 0
	s_mov_b32 m0, s21
	s_nop 0
	global_load_lds_dwordx4 v1, s[24:25] offset:0
	s_nop 0
	s_mov_b32 m0, s53
	s_nop 0
	global_load_lds_dwordx4 v147, s[24:25] offset:0
	s_waitcnt vmcnt(16)
	s_waitcnt lgkmcnt(0)
	s_barrier
	s_setprio 1
	v_mfma_f32_16x16x32_bf16 v[138:141], v[4:7], v[64:67], 0
	v_mfma_f32_16x16x32_bf16 v[158:161], v[4:7], v[96:99], 0
	v_mfma_f32_16x16x32_bf16 v[166:169], v[4:7], v[114:117], 0
	v_mfma_f32_16x16x32_bf16 v[4:7], v[4:7], v[126:129], 0
	v_mfma_f32_16x16x32_bf16 v[138:141], v[8:11], v[92:95], v[138:141]
	v_mfma_f32_16x16x32_bf16 v[158:161], v[8:11], v[110:113], v[158:161]
	v_mfma_f32_16x16x32_bf16 v[166:169], v[8:11], v[122:125], v[166:169]
	v_mfma_f32_16x16x32_bf16 v[4:7], v[8:11], v[130:133], v[4:7]
	v_mfma_f32_16x16x32_bf16 v[8:11], v[12:15], v[126:129], 0
	v_mfma_f32_16x16x32_bf16 v[142:145], v[12:15], v[64:67], 0
	v_mfma_f32_16x16x32_bf16 v[162:165], v[12:15], v[96:99], 0
	v_mfma_f32_16x16x32_bf16 v[170:173], v[12:15], v[114:117], 0
	v_mfma_f32_16x16x32_bf16 v[8:11], v[16:19], v[130:133], v[8:11]
	v_mfma_f32_16x16x32_bf16 v[142:145], v[16:19], v[92:95], v[142:145]
	v_mfma_f32_16x16x32_bf16 v[162:165], v[16:19], v[110:113], v[162:165]
	v_mfma_f32_16x16x32_bf16 v[170:173], v[16:19], v[122:125], v[170:173]
	s_setprio 0
	s_setprio 1
	v_mfma_f32_16x16x32_bf16 v[12:15], v[20:23], v[64:67], 0
	v_mfma_f32_16x16x32_bf16 v[174:177], v[24:27], v[92:95], v[12:15]
	v_mfma_f32_16x16x32_bf16 v[12:15], v[28:31], v[64:67], 0
	v_mfma_f32_16x16x32_bf16 v[178:181], v[32:35], v[92:95], v[12:15]
	v_mfma_f32_16x16x32_bf16 v[12:15], v[20:23], v[96:99], 0
	v_mfma_f32_16x16x32_bf16 v[182:185], v[24:27], v[110:113], v[12:15]
	v_mfma_f32_16x16x32_bf16 v[12:15], v[28:31], v[96:99], 0
	v_mfma_f32_16x16x32_bf16 v[186:189], v[32:35], v[110:113], v[12:15]
	v_mfma_f32_16x16x32_bf16 v[12:15], v[20:23], v[114:117], 0
	v_mfma_f32_16x16x32_bf16 v[190:193], v[24:27], v[122:125], v[12:15]
	v_mfma_f32_16x16x32_bf16 v[12:15], v[28:31], v[114:117], 0
	v_mfma_f32_16x16x32_bf16 v[194:197], v[32:35], v[122:125], v[12:15]
	v_mfma_f32_16x16x32_bf16 v[12:15], v[20:23], v[126:129], 0
	v_mfma_f32_16x16x32_bf16 v[198:201], v[24:27], v[130:133], v[12:15]
	v_mfma_f32_16x16x32_bf16 v[12:15], v[28:31], v[126:129], 0
	v_mfma_f32_16x16x32_bf16 v[202:205], v[32:35], v[130:133], v[12:15]
	s_setprio 0
	s_barrier
; #define PG8_KSETUP() const bool last = (t == nt - 2); const char* a1 = cA + (size_t)(t + 1) * kstep; \
;             const char* a2 = last ? nA : cA + (size_t)(t + 2) * kstep; const char* b2 = last ? nB : cB + (size_t)(t + 2) * kstep; const char* a3 = a2 + kstep; const char* b3 = b2 + kstep; \
;             if (last && has_next) S.a_ready(nxt)
; template <class Epi, class Sched, bool ALIGN_EPI = false, bool SP2 = false>
; __device__ __forceinline__ void gemm_phase(PG8_LAS unsigned char* lds, const Gemm g, const Sched& S, const Epi& E) {
;     ...
;         int t0 = 0;
;         if constexpr (SP2 && Epi::NVM == 16) { if (ui > 0) { const int t = 0; PG8_KSETUP(); PG8_KITER_SP2(24, 24); t0 = 2; } }
;         if constexpr (SP2 && Epi::NVM == 8) { if (ui > 0) { const int t = 0; PG8_KSETUP(); PG8_KITER_SP2(16, 16); t0 = 2; } }
	s_nop 4
	ds_read_b128 v[12:15], v155
	ds_read_b128 v[16:19], v155 offset:1024
	ds_read_b128 v[22:25], v155 offset:2048
	ds_read_b128 v[26:29], v155 offset:3072
	ds_read_b128 v[206:209], v156
	ds_read_b128 v[210:213], v156 offset:1024
	ds_read_b128 v[214:217], v156 offset:2048
	ds_read_b128 v[218:221], v156 offset:3072
	ds_read_b128 v[30:33], v154 offset:32768
	ds_read_b128 v[64:67], v154 offset:33792
	ds_read_b128 v[222:225], v154 offset:34816
	ds_read_b128 v[226:229], v154 offset:35840
	ds_read_b128 v[230:233], v154 offset:36864
	ds_read_b128 v[234:237], v154 offset:37888
	ds_read_b128 v[238:241], v154 offset:38912
	ds_read_b128 v[242:245], v154 offset:39936
	s_add_u32 s24, s36, 0x80100
	s_addc_u32 s25, s37, 0
	s_mov_b32 m0, s54
	s_nop 0
	global_load_lds_dwordx4 v1, s[24:25] offset:0
	s_nop 0
	s_mov_b32 m0, s55
	s_nop 0
	global_load_lds_dwordx4 v147, s[24:25] offset:0
	s_waitcnt vmcnt(8)
	s_waitcnt lgkmcnt(0)
	s_barrier
	s_setprio 1
	v_mfma_f32_16x16x32_bf16 v[68:71], v[12:15], v[30:33], v[68:71]
	v_mfma_f32_16x16x32_bf16 v[130:133], v[16:19], v[64:67], v[68:71]
	v_mfma_f32_16x16x32_bf16 v[68:71], v[22:25], v[30:33], v[72:75]
	v_mfma_f32_16x16x32_bf16 v[126:129], v[26:29], v[64:67], v[68:71]
	v_mfma_f32_16x16x32_bf16 v[68:71], v[12:15], v[222:225], v[76:79]
	v_mfma_f32_16x16x32_bf16 v[114:117], v[16:19], v[226:229], v[68:71]
	v_mfma_f32_16x16x32_bf16 v[68:71], v[22:25], v[222:225], v[80:83]
	v_mfma_f32_16x16x32_bf16 v[110:113], v[26:29], v[226:229], v[68:71]
	v_mfma_f32_16x16x32_bf16 v[68:71], v[12:15], v[230:233], v[84:87]
	v_mfma_f32_16x16x32_bf16 v[98:101], v[16:19], v[234:237], v[68:71]
	v_mfma_f32_16x16x32_bf16 v[68:71], v[22:25], v[230:233], v[88:91]
	v_mfma_f32_16x16x32_bf16 v[94:97], v[26:29], v[234:237], v[68:71]
	v_mfma_f32_16x16x32_bf16 v[68:71], v[12:15], v[238:241], v[102:105]
	v_mfma_f32_16x16x32_bf16 v[82:85], v[16:19], v[242:245], v[68:71]
	v_mfma_f32_16x16x32_bf16 v[68:71], v[22:25], v[238:241], v[106:109]
	v_mfma_f32_16x16x32_bf16 v[78:81], v[26:29], v[242:245], v[68:71]
	s_setprio 0
	s_setprio 1
	v_mfma_f32_16x16x32_bf16 v[68:71], v[206:209], v[30:33], v[118:121]
	v_mfma_f32_16x16x32_bf16 v[30:33], v[214:217], v[30:33], v[36:39]
	v_mfma_f32_16x16x32_bf16 v[118:121], v[218:221], v[64:67], v[30:33]
	v_mfma_f32_16x16x32_bf16 v[30:33], v[206:209], v[222:225], v[40:43]
	v_mfma_f32_16x16x32_bf16 v[106:109], v[210:213], v[226:229], v[30:33]
	v_mfma_f32_16x16x32_bf16 v[30:33], v[214:217], v[222:225], v[44:47]
	v_mfma_f32_16x16x32_bf16 v[102:105], v[218:221], v[226:229], v[30:33]
	v_mfma_f32_16x16x32_bf16 v[30:33], v[206:209], v[230:233], v[48:51]
	v_mfma_f32_16x16x32_bf16 v[90:93], v[210:213], v[234:237], v[30:33]
	v_mfma_f32_16x16x32_bf16 v[30:33], v[214:217], v[230:233], v[52:55]
	v_mfma_f32_16x16x32_bf16 v[86:89], v[218:221], v[234:237], v[30:33]
	v_mfma_f32_16x16x32_bf16 v[30:33], v[206:209], v[238:241], v[56:59]
	v_mfma_f32_16x16x32_bf16 v[74:77], v[210:213], v[242:245], v[30:33]
	v_mfma_f32_16x16x32_bf16 v[30:33], v[214:217], v[238:241], v[60:63]
	v_mfma_f32_16x16x32_bf16 v[122:125], v[210:213], v[64:67], v[68:71]
	v_mfma_f32_16x16x32_bf16 v[66:69], v[218:221], v[242:245], v[30:33]
	s_setprio 0
	s_barrier
	ds_read_b128 v[38:41], v154 offset:49152
	ds_read_b128 v[42:45], v154 offset:50176
	ds_read_b128 v[222:225], v154 offset:51200
	ds_read_b128 v[226:229], v154 offset:52224
	ds_read_b128 v[230:233], v154 offset:53248
	ds_read_b128 v[234:237], v154 offset:54272
	ds_read_b128 v[238:241], v154 offset:55296
	ds_read_b128 v[242:245], v154 offset:56320
	s_add_u32 s24, s38, 0x180
	s_addc_u32 s25, s39, 0
	s_mov_b32 m0, s56
	s_nop 0
	global_load_lds_dwordx4 v146, s[24:25] offset:0
	s_nop 0
	s_mov_b32 m0, s57
	s_nop 0
	global_load_lds_dwordx4 v148, s[24:25] offset:0
	s_add_u32 s24, s38, 0x80180
	s_addc_u32 s25, s39, 0
	s_mov_b32 m0, s64
	s_nop 0
	global_load_lds_dwordx4 v146, s[24:25] offset:0
	s_nop 0
	s_mov_b32 m0, s65
	s_nop 0
	global_load_lds_dwordx4 v148, s[24:25] offset:0
	s_nop 0
	s_mov_b32 m0, s58
	s_nop 0
	global_load_lds_dwordx4 v1, s[22:23] offset:0
	s_nop 0
	s_mov_b32 m0, s59
	s_nop 0
	global_load_lds_dwordx4 v147, s[22:23] offset:0
	s_waitcnt vmcnt(8)
	s_waitcnt lgkmcnt(0)
	s_barrier
	s_setprio 1
	v_mfma_f32_16x16x32_bf16 v[30:33], v[12:15], v[38:41], v[138:141]
	v_mfma_f32_16x16x32_bf16 v[70:73], v[16:19], v[42:45], v[30:33]
	v_mfma_f32_16x16x32_bf16 v[30:33], v[22:25], v[38:41], v[142:145]
	v_mfma_f32_16x16x32_bf16 v[62:65], v[26:29], v[42:45], v[30:33]
	v_mfma_f32_16x16x32_bf16 v[30:33], v[12:15], v[222:225], v[158:161]
	v_mfma_f32_16x16x32_bf16 v[50:53], v[16:19], v[226:229], v[30:33]
	v_mfma_f32_16x16x32_bf16 v[30:33], v[22:25], v[222:225], v[162:165]
	v_mfma_f32_16x16x32_bf16 v[46:49], v[26:29], v[226:229], v[30:33]
	v_mfma_f32_16x16x32_bf16 v[30:33], v[12:15], v[230:233], v[166:169]
	v_mfma_f32_16x16x32_bf16 v[4:7], v[12:15], v[238:241], v[4:7]
	v_mfma_f32_16x16x32_bf16 v[34:37], v[16:19], v[234:237], v[30:33]
	v_mfma_f32_16x16x32_bf16 v[30:33], v[22:25], v[230:233], v[170:173]
	v_mfma_f32_16x16x32_bf16 v[18:21], v[16:19], v[242:245], v[4:7]
	v_mfma_f32_16x16x32_bf16 v[4:7], v[22:25], v[238:241], v[8:11]
	v_mfma_f32_16x16x32_bf16 v[30:33], v[26:29], v[234:237], v[30:33]
	v_mfma_f32_16x16x32_bf16 v[14:17], v[26:29], v[242:245], v[4:7]
	s_setprio 0
	s_setprio 1
	v_mfma_f32_16x16x32_bf16 v[4:7], v[206:209], v[38:41], v[174:177]
	v_mfma_f32_16x16x32_bf16 v[58:61], v[210:213], v[42:45], v[4:7]
	v_mfma_f32_16x16x32_bf16 v[4:7], v[214:217], v[38:41], v[178:181]
	v_mfma_f32_16x16x32_bf16 v[54:57], v[218:221], v[42:45], v[4:7]
	v_mfma_f32_16x16x32_bf16 v[4:7], v[206:209], v[222:225], v[182:185]
	v_mfma_f32_16x16x32_bf16 v[42:45], v[210:213], v[226:229], v[4:7]
	v_mfma_f32_16x16x32_bf16 v[4:7], v[214:217], v[222:225], v[186:189]
	v_mfma_f32_16x16x32_bf16 v[38:41], v[218:221], v[226:229], v[4:7]
	v_mfma_f32_16x16x32_bf16 v[4:7], v[206:209], v[230:233], v[190:193]
	v_mfma_f32_16x16x32_bf16 v[26:29], v[210:213], v[234:237], v[4:7]
	v_mfma_f32_16x16x32_bf16 v[4:7], v[214:217], v[230:233], v[194:197]
	v_mfma_f32_16x16x32_bf16 v[22:25], v[218:221], v[234:237], v[4:7]
	v_mfma_f32_16x16x32_bf16 v[4:7], v[206:209], v[238:241], v[198:201]
	v_mfma_f32_16x16x32_bf16 v[10:13], v[210:213], v[242:245], v[4:7]
	v_mfma_f32_16x16x32_bf16 v[4:7], v[214:217], v[238:241], v[202:205]
	v_mfma_f32_16x16x32_bf16 v[6:9], v[218:221], v[242:245], v[4:7]
	s_setprio 0
	s_barrier
	s_mov_b32 s40, 2
	s_branch .LBB0_2290

; #define PG8_KSETUP() const bool last = (t == nt - 2); const char* a1 = cA + (size_t)(t + 1) * kstep; \
;             const char* a2 = last ? nA : cA + (size_t)(t + 2) * kstep; const char* b2 = last ? nB : cB + (size_t)(t + 2) * kstep; const char* a3 = a2 + kstep; const char* b3 = b2 + kstep; \
;             if (last && has_next) S.a_ready(nxt)
; template <class Epi, class Sched, bool ALIGN_EPI = false, bool SP2 = false>
; __device__ __forceinline__ void gemm_phase(PG8_LAS unsigned char* lds, const Gemm g, const Sched& S, const Epi& E) {
;     ...
;         int t0 = 0;
;         if constexpr (SP2 && Epi::NVM == 16) { if (ui > 0) { const int t = 0; PG8_KSETUP(); PG8_KITER_SP2(24, 24); t0 = 2; } }
;         if constexpr (SP2 && Epi::NVM == 8) { if (ui > 0) { const int t = 0; PG8_KSETUP(); PG8_KITER_SP2(16, 16); t0 = 2; } }
;         for (int t = t0; t < nt; t += 2) {
;             PG8_KSETUP();
;             if constexpr (SP2) {
;             PG8_KITER_SP2(8, 8);
.LBB0_2291:
	ds_read_b128 v[138:141], v152
	ds_read_b128 v[142:145], v152 offset:1024
	ds_read_b128 v[158:161], v152 offset:2048
	ds_read_b128 v[162:165], v152 offset:3072
	ds_read_b128 v[166:169], v153
	ds_read_b128 v[170:173], v153 offset:1024
	ds_read_b128 v[174:177], v153 offset:2048
	ds_read_b128 v[178:181], v153 offset:3072
	s_cmp_eq_u32 s78, 28
	s_cselect_b32 s40, s76, s81
	s_cselect_b32 s41, s19, s82
	s_cselect_b32 s38, s77, s79
	s_cselect_b32 s39, s17, s80
	s_add_u32 s36, s40, 0x80
	s_addc_u32 s37, s41, 0
	ds_read_b128 v[182:185], v154
	ds_read_b128 v[186:189], v154 offset:1024
	ds_read_b128 v[190:193], v154 offset:2048
	ds_read_b128 v[194:197], v154 offset:3072
	ds_read_b128 v[198:201], v154 offset:4096
	ds_read_b128 v[202:205], v154 offset:5120
	ds_read_b128 v[206:209], v154 offset:6144
	ds_read_b128 v[210:213], v154 offset:7168
	s_add_u32 s30, s81, 0x7ff80
	s_addc_u32 s31, s82, 0
	s_mov_b32 m0, s66
	s_nop 0
	global_load_lds_dwordx4 v1, s[30:31] offset:0
	s_nop 0
	s_mov_b32 m0, s67
	s_nop 0
	global_load_lds_dwordx4 v147, s[30:31] offset:0
	s_waitcnt vmcnt(8)
	s_waitcnt lgkmcnt(0)
	s_barrier
	s_setprio 1
	v_mfma_f32_16x16x32_bf16 v[130:133], v[138:141], v[182:185], v[130:133]
	v_mfma_f32_16x16x32_bf16 v[130:133], v[142:145], v[186:189], v[130:133]
	v_mfma_f32_16x16x32_bf16 v[126:129], v[158:161], v[182:185], v[126:129]
	v_mfma_f32_16x16x32_bf16 v[126:129], v[162:165], v[186:189], v[126:129]
	v_mfma_f32_16x16x32_bf16 v[114:117], v[138:141], v[190:193], v[114:117]
	v_mfma_f32_16x16x32_bf16 v[114:117], v[142:145], v[194:197], v[114:117]
	v_mfma_f32_16x16x32_bf16 v[110:113], v[158:161], v[190:193], v[110:113]
	v_mfma_f32_16x16x32_bf16 v[110:113], v[162:165], v[194:197], v[110:113]
	v_mfma_f32_16x16x32_bf16 v[98:101], v[138:141], v[198:201], v[98:101]
	v_mfma_f32_16x16x32_bf16 v[98:101], v[142:145], v[202:205], v[98:101]
	v_mfma_f32_16x16x32_bf16 v[94:97], v[158:161], v[198:201], v[94:97]
	v_mfma_f32_16x16x32_bf16 v[94:97], v[162:165], v[202:205], v[94:97]
	v_mfma_f32_16x16x32_bf16 v[82:85], v[138:141], v[206:209], v[82:85]
	v_mfma_f32_16x16x32_bf16 v[82:85], v[142:145], v[210:213], v[82:85]
	v_mfma_f32_16x16x32_bf16 v[78:81], v[158:161], v[206:209], v[78:81]
	v_mfma_f32_16x16x32_bf16 v[78:81], v[162:165], v[210:213], v[78:81]
	s_setprio 0
	s_setprio 1
	v_mfma_f32_16x16x32_bf16 v[122:125], v[166:169], v[182:185], v[122:125]
	v_mfma_f32_16x16x32_bf16 v[122:125], v[170:173], v[186:189], v[122:125]
	v_mfma_f32_16x16x32_bf16 v[118:121], v[174:177], v[182:185], v[118:121]
	v_mfma_f32_16x16x32_bf16 v[118:121], v[178:181], v[186:189], v[118:121]
	v_mfma_f32_16x16x32_bf16 v[106:109], v[166:169], v[190:193], v[106:109]
	v_mfma_f32_16x16x32_bf16 v[106:109], v[170:173], v[194:197], v[106:109]
	v_mfma_f32_16x16x32_bf16 v[102:105], v[174:177], v[190:193], v[102:105]
	v_mfma_f32_16x16x32_bf16 v[102:105], v[178:181], v[194:197], v[102:105]
	v_mfma_f32_16x16x32_bf16 v[90:93], v[166:169], v[198:201], v[90:93]
	v_mfma_f32_16x16x32_bf16 v[90:93], v[170:173], v[202:205], v[90:93]
	v_mfma_f32_16x16x32_bf16 v[86:89], v[174:177], v[198:201], v[86:89]
	v_mfma_f32_16x16x32_bf16 v[86:89], v[178:181], v[202:205], v[86:89]
	v_mfma_f32_16x16x32_bf16 v[74:77], v[166:169], v[206:209], v[74:77]
	v_mfma_f32_16x16x32_bf16 v[74:77], v[170:173], v[210:213], v[74:77]
	v_mfma_f32_16x16x32_bf16 v[66:69], v[174:177], v[206:209], v[66:69]
	v_mfma_f32_16x16x32_bf16 v[66:69], v[178:181], v[210:213], v[66:69]
	s_setprio 0
	s_barrier
	ds_read_b128 v[182:185], v154 offset:16384
	ds_read_b128 v[186:189], v154 offset:17408
	ds_read_b128 v[190:193], v154 offset:18432
	ds_read_b128 v[194:197], v154 offset:19456
	ds_read_b128 v[198:201], v154 offset:20480
	ds_read_b128 v[202:205], v154 offset:21504
	ds_read_b128 v[206:209], v154 offset:22528
	ds_read_b128 v[210:213], v154 offset:23552
	s_mov_b32 m0, s29
	s_nop 0
	global_load_lds_dwordx4 v146, s[38:39] offset:0
	s_add_u32 s30, s38, 0x80000
	s_mov_b32 m0, s46
	s_nop 0
	global_load_lds_dwordx4 v148, s[38:39] offset:0
	s_addc_u32 s31, s39, 0
	s_mov_b32 m0, s47
	s_nop 0
	global_load_lds_dwordx4 v146, s[30:31] offset:0
	s_nop 0
	s_mov_b32 m0, s52
	s_nop 0
	global_load_lds_dwordx4 v148, s[30:31] offset:0
	s_nop 0
	s_mov_b32 m0, s21
	s_nop 0
	global_load_lds_dwordx4 v1, s[40:41] offset:0
	s_nop 0
	s_mov_b32 m0, s53
	s_nop 0
	global_load_lds_dwordx4 v147, s[40:41] offset:0
	s_waitcnt vmcnt(8)
	s_waitcnt lgkmcnt(0)
	s_barrier
	s_setprio 1
	v_mfma_f32_16x16x32_bf16 v[70:73], v[138:141], v[182:185], v[70:73]
	v_mfma_f32_16x16x32_bf16 v[70:73], v[142:145], v[186:189], v[70:73]
	v_mfma_f32_16x16x32_bf16 v[62:65], v[158:161], v[182:185], v[62:65]
	v_mfma_f32_16x16x32_bf16 v[62:65], v[162:165], v[186:189], v[62:65]
	v_mfma_f32_16x16x32_bf16 v[50:53], v[138:141], v[190:193], v[50:53]
	v_mfma_f32_16x16x32_bf16 v[50:53], v[142:145], v[194:197], v[50:53]
	v_mfma_f32_16x16x32_bf16 v[46:49], v[158:161], v[190:193], v[46:49]
	v_mfma_f32_16x16x32_bf16 v[46:49], v[162:165], v[194:197], v[46:49]
	v_mfma_f32_16x16x32_bf16 v[34:37], v[138:141], v[198:201], v[34:37]
	v_mfma_f32_16x16x32_bf16 v[34:37], v[142:145], v[202:205], v[34:37]
	v_mfma_f32_16x16x32_bf16 v[30:33], v[158:161], v[198:201], v[30:33]
	v_mfma_f32_16x16x32_bf16 v[30:33], v[162:165], v[202:205], v[30:33]
	v_mfma_f32_16x16x32_bf16 v[18:21], v[138:141], v[206:209], v[18:21]
	v_mfma_f32_16x16x32_bf16 v[18:21], v[142:145], v[210:213], v[18:21]
	v_mfma_f32_16x16x32_bf16 v[14:17], v[158:161], v[206:209], v[14:17]
	v_mfma_f32_16x16x32_bf16 v[14:17], v[162:165], v[210:213], v[14:17]
	s_setprio 0
	s_setprio 1
	v_mfma_f32_16x16x32_bf16 v[58:61], v[166:169], v[182:185], v[58:61]
	v_mfma_f32_16x16x32_bf16 v[54:57], v[174:177], v[182:185], v[54:57]
	v_mfma_f32_16x16x32_bf16 v[42:45], v[166:169], v[190:193], v[42:45]
	v_mfma_f32_16x16x32_bf16 v[38:41], v[174:177], v[190:193], v[38:41]
	v_mfma_f32_16x16x32_bf16 v[26:29], v[166:169], v[198:201], v[26:29]
	v_mfma_f32_16x16x32_bf16 v[22:25], v[174:177], v[198:201], v[22:25]
	v_mfma_f32_16x16x32_bf16 v[10:13], v[166:169], v[206:209], v[10:13]
	v_mfma_f32_16x16x32_bf16 v[4:7], v[174:177], v[206:209], v[6:9]
	v_mfma_f32_16x16x32_bf16 v[58:61], v[170:173], v[186:189], v[58:61]
	v_mfma_f32_16x16x32_bf16 v[54:57], v[178:181], v[186:189], v[54:57]
	v_mfma_f32_16x16x32_bf16 v[42:45], v[170:173], v[194:197], v[42:45]
	v_mfma_f32_16x16x32_bf16 v[38:41], v[178:181], v[194:197], v[38:41]
	v_mfma_f32_16x16x32_bf16 v[26:29], v[170:173], v[202:205], v[26:29]
	v_mfma_f32_16x16x32_bf16 v[22:25], v[178:181], v[202:205], v[22:25]
	v_mfma_f32_16x16x32_bf16 v[10:13], v[170:173], v[210:213], v[10:13]
	v_mfma_f32_16x16x32_bf16 v[4:7], v[178:181], v[210:213], v[4:7]
	s_setprio 0
	s_barrier
; #define PG8_KSETUP() const bool last = (t == nt - 2); const char* a1 = cA + (size_t)(t + 1) * kstep; \
;             const char* a2 = last ? nA : cA + (size_t)(t + 2) * kstep; const char* b2 = last ? nB : cB + (size_t)(t + 2) * kstep; const char* a3 = a2 + kstep; const char* b3 = b2 + kstep; \
;             if (last && has_next) S.a_ready(nxt)
; template <class Epi, class Sched, bool ALIGN_EPI = false, bool SP2 = false>
; __device__ __forceinline__ void gemm_phase(PG8_LAS unsigned char* lds, const Gemm g, const Sched& S, const Epi& E) {
;     ...
;         int t0 = 0;
;         if constexpr (SP2 && Epi::NVM == 16) { if (ui > 0) { const int t = 0; PG8_KSETUP(); PG8_KITER_SP2(24, 24); t0 = 2; } }
;         if constexpr (SP2 && Epi::NVM == 8) { if (ui > 0) { const int t = 0; PG8_KSETUP(); PG8_KITER_SP2(16, 16); t0 = 2; } }
;         for (int t = t0; t < nt; t += 2) {
;             PG8_KSETUP();
;             if constexpr (SP2) {
;             PG8_KITER_SP2(8, 8);
	ds_read_b128 v[138:141], v155
	ds_read_b128 v[142:145], v155 offset:1024
	ds_read_b128 v[158:161], v155 offset:2048
	ds_read_b128 v[162:165], v155 offset:3072
	ds_read_b128 v[166:169], v156
	ds_read_b128 v[170:173], v156 offset:1024
	ds_read_b128 v[174:177], v156 offset:2048
	ds_read_b128 v[178:181], v156 offset:3072
	ds_read_b128 v[182:185], v154 offset:32768
	ds_read_b128 v[186:189], v154 offset:33792
	ds_read_b128 v[190:193], v154 offset:34816
	ds_read_b128 v[194:197], v154 offset:35840
	ds_read_b128 v[198:201], v154 offset:36864
	ds_read_b128 v[202:205], v154 offset:37888
	ds_read_b128 v[206:209], v154 offset:38912
	ds_read_b128 v[210:213], v154 offset:39936
	s_add_u32 s30, s40, 0x80000
	s_addc_u32 s31, s41, 0
	s_mov_b32 m0, s54
	s_nop 0
	global_load_lds_dwordx4 v1, s[30:31] offset:0
	s_nop 0
	s_mov_b32 m0, s55
	s_nop 0
	global_load_lds_dwordx4 v147, s[30:31] offset:0
	s_waitcnt vmcnt(8)
	s_waitcnt lgkmcnt(0)
	s_barrier
	s_setprio 1
	v_mfma_f32_16x16x32_bf16 v[130:133], v[138:141], v[182:185], v[130:133]
	v_mfma_f32_16x16x32_bf16 v[130:133], v[142:145], v[186:189], v[130:133]
	v_mfma_f32_16x16x32_bf16 v[126:129], v[158:161], v[182:185], v[126:129]
	v_mfma_f32_16x16x32_bf16 v[126:129], v[162:165], v[186:189], v[126:129]
	v_mfma_f32_16x16x32_bf16 v[114:117], v[138:141], v[190:193], v[114:117]
	v_mfma_f32_16x16x32_bf16 v[114:117], v[142:145], v[194:197], v[114:117]
	v_mfma_f32_16x16x32_bf16 v[110:113], v[158:161], v[190:193], v[110:113]
	v_mfma_f32_16x16x32_bf16 v[110:113], v[162:165], v[194:197], v[110:113]
	v_mfma_f32_16x16x32_bf16 v[98:101], v[138:141], v[198:201], v[98:101]
	v_mfma_f32_16x16x32_bf16 v[98:101], v[142:145], v[202:205], v[98:101]
	v_mfma_f32_16x16x32_bf16 v[94:97], v[158:161], v[198:201], v[94:97]
	v_mfma_f32_16x16x32_bf16 v[94:97], v[162:165], v[202:205], v[94:97]
	v_mfma_f32_16x16x32_bf16 v[82:85], v[138:141], v[206:209], v[82:85]
	v_mfma_f32_16x16x32_bf16 v[82:85], v[142:145], v[210:213], v[82:85]
	v_mfma_f32_16x16x32_bf16 v[78:81], v[158:161], v[206:209], v[78:81]
	v_mfma_f32_16x16x32_bf16 v[78:81], v[162:165], v[210:213], v[78:81]
	s_setprio 0
	s_setprio 1
	v_mfma_f32_16x16x32_bf16 v[122:125], v[166:169], v[182:185], v[122:125]
	v_mfma_f32_16x16x32_bf16 v[122:125], v[170:173], v[186:189], v[122:125]
	v_mfma_f32_16x16x32_bf16 v[118:121], v[174:177], v[182:185], v[118:121]
	v_mfma_f32_16x16x32_bf16 v[118:121], v[178:181], v[186:189], v[118:121]
	v_mfma_f32_16x16x32_bf16 v[106:109], v[166:169], v[190:193], v[106:109]
	v_mfma_f32_16x16x32_bf16 v[106:109], v[170:173], v[194:197], v[106:109]
	v_mfma_f32_16x16x32_bf16 v[102:105], v[174:177], v[190:193], v[102:105]
	v_mfma_f32_16x16x32_bf16 v[102:105], v[178:181], v[194:197], v[102:105]
	v_mfma_f32_16x16x32_bf16 v[90:93], v[166:169], v[198:201], v[90:93]
	v_mfma_f32_16x16x32_bf16 v[90:93], v[170:173], v[202:205], v[90:93]
	v_mfma_f32_16x16x32_bf16 v[86:89], v[174:177], v[198:201], v[86:89]
	v_mfma_f32_16x16x32_bf16 v[86:89], v[178:181], v[202:205], v[86:89]
	v_mfma_f32_16x16x32_bf16 v[74:77], v[166:169], v[206:209], v[74:77]
	v_mfma_f32_16x16x32_bf16 v[74:77], v[170:173], v[210:213], v[74:77]
	v_mfma_f32_16x16x32_bf16 v[66:69], v[174:177], v[206:209], v[66:69]
	v_mfma_f32_16x16x32_bf16 v[66:69], v[178:181], v[210:213], v[66:69]
	s_setprio 0
	s_barrier
	ds_read_b128 v[182:185], v154 offset:49152
	ds_read_b128 v[186:189], v154 offset:50176
	ds_read_b128 v[190:193], v154 offset:51200
	ds_read_b128 v[194:197], v154 offset:52224
	ds_read_b128 v[198:201], v154 offset:53248
	ds_read_b128 v[202:205], v154 offset:54272
	ds_read_b128 v[206:209], v154 offset:55296
	ds_read_b128 v[210:213], v154 offset:56320
	s_add_u32 s30, s38, 0x80
	s_addc_u32 s31, s39, 0
	s_mov_b32 m0, s56
	s_nop 0
	global_load_lds_dwordx4 v146, s[30:31] offset:0
	s_nop 0
	s_mov_b32 m0, s57
	s_nop 0
	global_load_lds_dwordx4 v148, s[30:31] offset:0
	s_add_u32 s30, s38, 0x80080
	s_addc_u32 s31, s39, 0
	s_mov_b32 m0, s64
	s_nop 0
	global_load_lds_dwordx4 v146, s[30:31] offset:0
	s_nop 0
	s_mov_b32 m0, s65
	s_nop 0
	global_load_lds_dwordx4 v148, s[30:31] offset:0
	s_nop 0
	s_mov_b32 m0, s58
	s_nop 0
	global_load_lds_dwordx4 v1, s[36:37] offset:0
	s_nop 0
	s_mov_b32 m0, s59
	s_nop 0
	global_load_lds_dwordx4 v147, s[36:37] offset:0
	s_waitcnt vmcnt(8)
	s_waitcnt lgkmcnt(0)
	s_barrier
	s_setprio 1
	v_mfma_f32_16x16x32_bf16 v[70:73], v[138:141], v[182:185], v[70:73]
	v_mfma_f32_16x16x32_bf16 v[70:73], v[142:145], v[186:189], v[70:73]
	v_mfma_f32_16x16x32_bf16 v[62:65], v[158:161], v[182:185], v[62:65]
	v_mfma_f32_16x16x32_bf16 v[62:65], v[162:165], v[186:189], v[62:65]
	v_mfma_f32_16x16x32_bf16 v[50:53], v[138:141], v[190:193], v[50:53]
	v_mfma_f32_16x16x32_bf16 v[50:53], v[142:145], v[194:197], v[50:53]
	v_mfma_f32_16x16x32_bf16 v[46:49], v[158:161], v[190:193], v[46:49]
	v_mfma_f32_16x16x32_bf16 v[46:49], v[162:165], v[194:197], v[46:49]
	v_mfma_f32_16x16x32_bf16 v[34:37], v[138:141], v[198:201], v[34:37]
	v_mfma_f32_16x16x32_bf16 v[34:37], v[142:145], v[202:205], v[34:37]
	v_mfma_f32_16x16x32_bf16 v[30:33], v[158:161], v[198:201], v[30:33]
	v_mfma_f32_16x16x32_bf16 v[30:33], v[162:165], v[202:205], v[30:33]
	v_mfma_f32_16x16x32_bf16 v[18:21], v[138:141], v[206:209], v[18:21]
	v_mfma_f32_16x16x32_bf16 v[18:21], v[142:145], v[210:213], v[18:21]
	v_mfma_f32_16x16x32_bf16 v[14:17], v[158:161], v[206:209], v[14:17]
	v_mfma_f32_16x16x32_bf16 v[14:17], v[162:165], v[210:213], v[14:17]
	s_setprio 0
	s_setprio 1
	v_mfma_f32_16x16x32_bf16 v[58:61], v[166:169], v[182:185], v[58:61]
	v_mfma_f32_16x16x32_bf16 v[54:57], v[174:177], v[182:185], v[54:57]
	v_mfma_f32_16x16x32_bf16 v[42:45], v[166:169], v[190:193], v[42:45]
	v_mfma_f32_16x16x32_bf16 v[38:41], v[174:177], v[190:193], v[38:41]
	v_mfma_f32_16x16x32_bf16 v[26:29], v[166:169], v[198:201], v[26:29]
	v_mfma_f32_16x16x32_bf16 v[22:25], v[174:177], v[198:201], v[22:25]
	v_mfma_f32_16x16x32_bf16 v[8:11], v[166:169], v[206:209], v[10:13]
	v_mfma_f32_16x16x32_bf16 v[4:7], v[174:177], v[206:209], v[4:7]
	v_mfma_f32_16x16x32_bf16 v[58:61], v[170:173], v[186:189], v[58:61]
	v_mfma_f32_16x16x32_bf16 v[54:57], v[178:181], v[186:189], v[54:57]
	v_mfma_f32_16x16x32_bf16 v[42:45], v[170:173], v[194:197], v[42:45]
	v_mfma_f32_16x16x32_bf16 v[38:41], v[178:181], v[194:197], v[38:41]
	v_mfma_f32_16x16x32_bf16 v[26:29], v[170:173], v[202:205], v[26:29]
	v_mfma_f32_16x16x32_bf16 v[22:25], v[178:181], v[202:205], v[22:25]
	v_mfma_f32_16x16x32_bf16 v[10:13], v[170:173], v[210:213], v[8:11]
	v_mfma_f32_16x16x32_bf16 v[6:9], v[178:181], v[210:213], v[4:7]
	s_setprio 0
	s_barrier
	s_add_i32 s78, s78, 2
	s_add_u32 s79, s79, 0x100
	s_addc_u32 s80, s80, 0
	s_add_u32 s81, s81, 0x100
	s_addc_u32 s82, s82, 0
	s_cmp_gt_u32 s78, 29
	s_cbranch_scc0 .LBB0_2291
	s_and_b64 vcc, exec, s[14:15]
	s_cbranch_vccz .LBB0_2294
	s_barrier

; #define PG8_KSETUP() const bool last = (t == nt - 2); const char* a1 = cA + (size_t)(t + 1) * kstep; \
;             const char* a2 = last ? nA : cA + (size_t)(t + 2) * kstep; const char* b2 = last ? nB : cB + (size_t)(t + 2) * kstep; const char* a3 = a2 + kstep; const char* b3 = b2 + kstep; \
;             if (last && has_next) S.a_ready(nxt)
; template <class Epi, class Sched, bool ALIGN_EPI = false, bool SP2 = false>
; __device__ __forceinline__ void gemm_phase(PG8_LAS unsigned char* lds, const Gemm g, const Sched& S, const Epi& E) {
;     ...
;         int t0 = 0;
;         if constexpr (SP2 && Epi::NVM == 16) { if (ui > 0) { const int t = 0; PG8_KSETUP(); PG8_KITER_SP2(24, 24); t0 = 2; } }
.LBB0_2373:
	ds_read_b128 v[4:7], v147
	ds_read_b128 v[8:11], v147 offset:1024
	ds_read_b128 v[12:15], v147 offset:2048
	ds_read_b128 v[16:19], v147 offset:3072
	ds_read_b128 v[20:23], v148
	ds_read_b128 v[24:27], v148 offset:1024
	ds_read_b128 v[28:31], v148 offset:2048
	ds_read_b128 v[32:35], v148 offset:3072
	s_add_u32 s44, s36, 0x100
	s_addc_u32 s45, s37, 0
	s_add_u32 s30, s38, 0x100
	s_addc_u32 s31, s39, 0
	s_add_u32 s40, s36, 0x180
	s_addc_u32 s41, s37, 0
	ds_read_b128 v[36:39], v149
	ds_read_b128 v[40:43], v149 offset:1024
	ds_read_b128 v[44:47], v149 offset:2048
	ds_read_b128 v[48:51], v149 offset:3072
	ds_read_b128 v[52:55], v149 offset:4096
	ds_read_b128 v[56:59], v149 offset:5120
	ds_read_b128 v[60:63], v149 offset:6144
	ds_read_b128 v[64:67], v149 offset:7168
	s_add_u32 s42, s36, 0x160080
	s_addc_u32 s43, s37, 0
	s_mov_b32 m0, s72
	s_nop 0
	global_load_lds_dwordx4 v1, s[42:43] offset:0
	s_nop 0
	s_mov_b32 m0, s73
	s_nop 0
	global_load_lds_dwordx4 v143, s[42:43] offset:0
	s_waitcnt vmcnt(24)
	s_waitcnt lgkmcnt(0)
	s_barrier
	s_setprio 1
	v_mfma_f32_16x16x32_bf16 v[92:95], v[4:7], v[60:63], 0
	v_mfma_f32_16x16x32_bf16 v[68:71], v[4:7], v[36:39], 0
	v_mfma_f32_16x16x32_bf16 v[72:75], v[12:15], v[36:39], 0
	v_mfma_f32_16x16x32_bf16 v[76:79], v[4:7], v[44:47], 0
	v_mfma_f32_16x16x32_bf16 v[80:83], v[12:15], v[44:47], 0
	v_mfma_f32_16x16x32_bf16 v[84:87], v[4:7], v[52:55], 0
	v_mfma_f32_16x16x32_bf16 v[88:91], v[12:15], v[52:55], 0
	v_mfma_f32_16x16x32_bf16 v[102:105], v[8:11], v[64:67], v[92:95]
	v_mfma_f32_16x16x32_bf16 v[92:95], v[12:15], v[60:63], 0
	v_mfma_f32_16x16x32_bf16 v[68:71], v[8:11], v[40:43], v[68:71]
	v_mfma_f32_16x16x32_bf16 v[72:75], v[16:19], v[40:43], v[72:75]
	v_mfma_f32_16x16x32_bf16 v[76:79], v[8:11], v[48:51], v[76:79]
	v_mfma_f32_16x16x32_bf16 v[80:83], v[16:19], v[48:51], v[80:83]
	v_mfma_f32_16x16x32_bf16 v[84:87], v[8:11], v[56:59], v[84:87]
	v_mfma_f32_16x16x32_bf16 v[88:91], v[16:19], v[56:59], v[88:91]
	v_mfma_f32_16x16x32_bf16 v[106:109], v[16:19], v[64:67], v[92:95]
	s_setprio 0
	s_setprio 1
	v_mfma_f32_16x16x32_bf16 v[92:95], v[20:23], v[36:39], 0
	v_mfma_f32_16x16x32_bf16 v[36:39], v[28:31], v[36:39], 0
	v_mfma_f32_16x16x32_bf16 v[118:121], v[24:27], v[40:43], v[92:95]
	v_mfma_f32_16x16x32_bf16 v[36:39], v[32:35], v[40:43], v[36:39]
	v_mfma_f32_16x16x32_bf16 v[40:43], v[20:23], v[44:47], 0
	v_mfma_f32_16x16x32_bf16 v[44:47], v[28:31], v[44:47], 0
	v_mfma_f32_16x16x32_bf16 v[40:43], v[24:27], v[48:51], v[40:43]
	v_mfma_f32_16x16x32_bf16 v[44:47], v[32:35], v[48:51], v[44:47]
	v_mfma_f32_16x16x32_bf16 v[48:51], v[20:23], v[52:55], 0
	v_mfma_f32_16x16x32_bf16 v[52:55], v[28:31], v[52:55], 0
	v_mfma_f32_16x16x32_bf16 v[48:51], v[24:27], v[56:59], v[48:51]
	v_mfma_f32_16x16x32_bf16 v[52:55], v[32:35], v[56:59], v[52:55]
	v_mfma_f32_16x16x32_bf16 v[56:59], v[20:23], v[60:63], 0
	v_mfma_f32_16x16x32_bf16 v[60:63], v[28:31], v[60:63], 0
	v_mfma_f32_16x16x32_bf16 v[56:59], v[24:27], v[64:67], v[56:59]
	v_mfma_f32_16x16x32_bf16 v[60:63], v[32:35], v[64:67], v[60:63]
	s_setprio 0
	s_barrier
	ds_read_b128 v[64:67], v149 offset:16384
	ds_read_b128 v[92:95], v149 offset:17408
	ds_read_b128 v[96:99], v149 offset:18432
	ds_read_b128 v[110:113], v149 offset:19456
	ds_read_b128 v[114:117], v149 offset:20480
	ds_read_b128 v[122:125], v149 offset:21504
	ds_read_b128 v[126:129], v149 offset:22528
	ds_read_b128 v[130:133], v149 offset:23552
	s_mov_b32 m0, s52
	s_nop 0
	global_load_lds_dwordx4 v142, s[30:31] offset:0
	s_nop 0
	s_mov_b32 m0, s53
	s_nop 0
	global_load_lds_dwordx4 v144, s[30:31] offset:0
	s_add_u32 s30, s38, 0x160100
	s_addc_u32 s31, s39, 0
	s_mov_b32 m0, s54
	s_nop 0
	global_load_lds_dwordx4 v142, s[30:31] offset:0
	s_nop 0
	s_mov_b32 m0, s55
	s_nop 0
	global_load_lds_dwordx4 v144, s[30:31] offset:0
	s_nop 0
	s_mov_b32 m0, s47
	s_nop 0
	global_load_lds_dwordx4 v1, s[44:45] offset:0
	s_nop 0
	s_mov_b32 m0, s56
	s_nop 0
	global_load_lds_dwordx4 v143, s[44:45] offset:0
	s_waitcnt vmcnt(24)
	s_waitcnt lgkmcnt(0)
	s_barrier
	s_setprio 1
	v_mfma_f32_16x16x32_bf16 v[138:141], v[4:7], v[64:67], 0
	v_mfma_f32_16x16x32_bf16 v[156:159], v[4:7], v[96:99], 0
	v_mfma_f32_16x16x32_bf16 v[164:167], v[4:7], v[114:117], 0
	v_mfma_f32_16x16x32_bf16 v[4:7], v[4:7], v[126:129], 0
	v_mfma_f32_16x16x32_bf16 v[138:141], v[8:11], v[92:95], v[138:141]
	v_mfma_f32_16x16x32_bf16 v[156:159], v[8:11], v[110:113], v[156:159]
	v_mfma_f32_16x16x32_bf16 v[164:167], v[8:11], v[122:125], v[164:167]
	v_mfma_f32_16x16x32_bf16 v[4:7], v[8:11], v[130:133], v[4:7]
	v_mfma_f32_16x16x32_bf16 v[8:11], v[12:15], v[126:129], 0
	v_mfma_f32_16x16x32_bf16 v[152:155], v[12:15], v[64:67], 0
	v_mfma_f32_16x16x32_bf16 v[160:163], v[12:15], v[96:99], 0
	v_mfma_f32_16x16x32_bf16 v[168:171], v[12:15], v[114:117], 0
	v_mfma_f32_16x16x32_bf16 v[8:11], v[16:19], v[130:133], v[8:11]
	v_mfma_f32_16x16x32_bf16 v[152:155], v[16:19], v[92:95], v[152:155]
	v_mfma_f32_16x16x32_bf16 v[160:163], v[16:19], v[110:113], v[160:163]
	v_mfma_f32_16x16x32_bf16 v[168:171], v[16:19], v[122:125], v[168:171]
	s_setprio 0
	s_setprio 1
	v_mfma_f32_16x16x32_bf16 v[12:15], v[20:23], v[64:67], 0
	v_mfma_f32_16x16x32_bf16 v[172:175], v[24:27], v[92:95], v[12:15]
	v_mfma_f32_16x16x32_bf16 v[12:15], v[28:31], v[64:67], 0
	v_mfma_f32_16x16x32_bf16 v[176:179], v[32:35], v[92:95], v[12:15]
	v_mfma_f32_16x16x32_bf16 v[12:15], v[20:23], v[96:99], 0
	v_mfma_f32_16x16x32_bf16 v[180:183], v[24:27], v[110:113], v[12:15]
	v_mfma_f32_16x16x32_bf16 v[12:15], v[28:31], v[96:99], 0
	v_mfma_f32_16x16x32_bf16 v[184:187], v[32:35], v[110:113], v[12:15]
	v_mfma_f32_16x16x32_bf16 v[12:15], v[20:23], v[114:117], 0
	v_mfma_f32_16x16x32_bf16 v[188:191], v[24:27], v[122:125], v[12:15]
	v_mfma_f32_16x16x32_bf16 v[12:15], v[28:31], v[114:117], 0
	v_mfma_f32_16x16x32_bf16 v[192:195], v[32:35], v[122:125], v[12:15]
	v_mfma_f32_16x16x32_bf16 v[12:15], v[20:23], v[126:129], 0
	v_mfma_f32_16x16x32_bf16 v[196:199], v[24:27], v[130:133], v[12:15]
	v_mfma_f32_16x16x32_bf16 v[12:15], v[28:31], v[126:129], 0
	v_mfma_f32_16x16x32_bf16 v[200:203], v[32:35], v[130:133], v[12:15]
	s_setprio 0
	s_barrier
; #define PG8_KSETUP() const bool last = (t == nt - 2); const char* a1 = cA + (size_t)(t + 1) * kstep; \
;             const char* a2 = last ? nA : cA + (size_t)(t + 2) * kstep; const char* b2 = last ? nB : cB + (size_t)(t + 2) * kstep; const char* a3 = a2 + kstep; const char* b3 = b2 + kstep; \
;             if (last && has_next) S.a_ready(nxt)
; template <class Epi, class Sched, bool ALIGN_EPI = false, bool SP2 = false>
; __device__ __forceinline__ void gemm_phase(PG8_LAS unsigned char* lds, const Gemm g, const Sched& S, const Epi& E) {
;     ...
;         int t0 = 0;
;         if constexpr (SP2 && Epi::NVM == 16) { if (ui > 0) { const int t = 0; PG8_KSETUP(); PG8_KITER_SP2(24, 24); t0 = 2; } }
	s_nop 4
	ds_read_b128 v[12:15], v150
	ds_read_b128 v[16:19], v150 offset:1024
	ds_read_b128 v[22:25], v150 offset:2048
	ds_read_b128 v[26:29], v150 offset:3072
	ds_read_b128 v[204:207], v151
	ds_read_b128 v[208:211], v151 offset:1024
	ds_read_b128 v[212:215], v151 offset:2048
	ds_read_b128 v[216:219], v151 offset:3072
	ds_read_b128 v[30:33], v149 offset:32768
	ds_read_b128 v[64:67], v149 offset:33792
	ds_read_b128 v[220:223], v149 offset:34816
	ds_read_b128 v[224:227], v149 offset:35840
	ds_read_b128 v[228:231], v149 offset:36864
	ds_read_b128 v[232:235], v149 offset:37888
	ds_read_b128 v[236:239], v149 offset:38912
	ds_read_b128 v[240:243], v149 offset:39936
	s_add_u32 s30, s36, 0x160100
	s_addc_u32 s31, s37, 0
	s_mov_b32 m0, s57
	s_nop 0
	global_load_lds_dwordx4 v1, s[30:31] offset:0
	s_nop 0
	s_mov_b32 m0, s58
	s_nop 0
	global_load_lds_dwordx4 v143, s[30:31] offset:0
	s_waitcnt vmcnt(8)
	s_waitcnt lgkmcnt(0)
	s_barrier
	s_setprio 1
	v_mfma_f32_16x16x32_bf16 v[68:71], v[12:15], v[30:33], v[68:71]
	v_mfma_f32_16x16x32_bf16 v[130:133], v[16:19], v[64:67], v[68:71]
	v_mfma_f32_16x16x32_bf16 v[68:71], v[22:25], v[30:33], v[72:75]
	v_mfma_f32_16x16x32_bf16 v[126:129], v[26:29], v[64:67], v[68:71]
	v_mfma_f32_16x16x32_bf16 v[68:71], v[12:15], v[220:223], v[76:79]
	v_mfma_f32_16x16x32_bf16 v[114:117], v[16:19], v[224:227], v[68:71]
	v_mfma_f32_16x16x32_bf16 v[68:71], v[22:25], v[220:223], v[80:83]
	v_mfma_f32_16x16x32_bf16 v[110:113], v[26:29], v[224:227], v[68:71]
	v_mfma_f32_16x16x32_bf16 v[68:71], v[12:15], v[228:231], v[84:87]
	v_mfma_f32_16x16x32_bf16 v[98:101], v[16:19], v[232:235], v[68:71]
	v_mfma_f32_16x16x32_bf16 v[68:71], v[22:25], v[228:231], v[88:91]
	v_mfma_f32_16x16x32_bf16 v[94:97], v[26:29], v[232:235], v[68:71]
	v_mfma_f32_16x16x32_bf16 v[68:71], v[12:15], v[236:239], v[102:105]
	v_mfma_f32_16x16x32_bf16 v[82:85], v[16:19], v[240:243], v[68:71]
	v_mfma_f32_16x16x32_bf16 v[68:71], v[22:25], v[236:239], v[106:109]
	v_mfma_f32_16x16x32_bf16 v[78:81], v[26:29], v[240:243], v[68:71]
	s_setprio 0
	s_setprio 1
	v_mfma_f32_16x16x32_bf16 v[68:71], v[204:207], v[30:33], v[118:121]
	v_mfma_f32_16x16x32_bf16 v[30:33], v[212:215], v[30:33], v[36:39]
	v_mfma_f32_16x16x32_bf16 v[118:121], v[216:219], v[64:67], v[30:33]
	v_mfma_f32_16x16x32_bf16 v[30:33], v[204:207], v[220:223], v[40:43]
	v_mfma_f32_16x16x32_bf16 v[106:109], v[208:211], v[224:227], v[30:33]
	v_mfma_f32_16x16x32_bf16 v[30:33], v[212:215], v[220:223], v[44:47]
	v_mfma_f32_16x16x32_bf16 v[102:105], v[216:219], v[224:227], v[30:33]
	v_mfma_f32_16x16x32_bf16 v[30:33], v[204:207], v[228:231], v[48:51]
	v_mfma_f32_16x16x32_bf16 v[90:93], v[208:211], v[232:235], v[30:33]
	v_mfma_f32_16x16x32_bf16 v[30:33], v[212:215], v[228:231], v[52:55]
	v_mfma_f32_16x16x32_bf16 v[86:89], v[216:219], v[232:235], v[30:33]
	v_mfma_f32_16x16x32_bf16 v[30:33], v[204:207], v[236:239], v[56:59]
	v_mfma_f32_16x16x32_bf16 v[74:77], v[208:211], v[240:243], v[30:33]
	v_mfma_f32_16x16x32_bf16 v[30:33], v[212:215], v[236:239], v[60:63]
	v_mfma_f32_16x16x32_bf16 v[122:125], v[208:211], v[64:67], v[68:71]
	v_mfma_f32_16x16x32_bf16 v[70:73], v[216:219], v[240:243], v[30:33]
	s_setprio 0
	s_barrier
	ds_read_b128 v[38:41], v149 offset:49152
	ds_read_b128 v[42:45], v149 offset:50176
	ds_read_b128 v[220:223], v149 offset:51200
	ds_read_b128 v[224:227], v149 offset:52224
	ds_read_b128 v[228:231], v149 offset:53248
	ds_read_b128 v[232:235], v149 offset:54272
	ds_read_b128 v[236:239], v149 offset:55296
	ds_read_b128 v[240:243], v149 offset:56320
	s_add_u32 s30, s38, 0x180
	s_addc_u32 s31, s39, 0
	s_mov_b32 m0, s66
	s_nop 0
	global_load_lds_dwordx4 v142, s[30:31] offset:0
	s_nop 0
	s_mov_b32 m0, s67
	s_nop 0
	global_load_lds_dwordx4 v144, s[30:31] offset:0
	s_add_u32 s30, s38, 0x160180
	s_addc_u32 s31, s39, 0
	s_mov_b32 m0, s70
	s_nop 0
	global_load_lds_dwordx4 v142, s[30:31] offset:0
	s_nop 0
	s_mov_b32 m0, s71
	s_nop 0
	global_load_lds_dwordx4 v144, s[30:31] offset:0
	s_nop 0
	s_mov_b32 m0, s68
	s_nop 0
	global_load_lds_dwordx4 v1, s[40:41] offset:0
	s_nop 0
	s_mov_b32 m0, s69
	s_nop 0
	global_load_lds_dwordx4 v143, s[40:41] offset:0
	s_waitcnt vmcnt(8)
	s_waitcnt lgkmcnt(0)
	s_barrier
	s_setprio 1
	v_mfma_f32_16x16x32_bf16 v[30:33], v[12:15], v[38:41], v[138:141]
	v_mfma_f32_16x16x32_bf16 v[66:69], v[16:19], v[42:45], v[30:33]
	v_mfma_f32_16x16x32_bf16 v[30:33], v[22:25], v[38:41], v[152:155]
	v_mfma_f32_16x16x32_bf16 v[62:65], v[26:29], v[42:45], v[30:33]
	v_mfma_f32_16x16x32_bf16 v[30:33], v[12:15], v[220:223], v[156:159]
	v_mfma_f32_16x16x32_bf16 v[50:53], v[16:19], v[224:227], v[30:33]
	v_mfma_f32_16x16x32_bf16 v[30:33], v[22:25], v[220:223], v[160:163]
	v_mfma_f32_16x16x32_bf16 v[46:49], v[26:29], v[224:227], v[30:33]
	v_mfma_f32_16x16x32_bf16 v[30:33], v[12:15], v[228:231], v[164:167]
	v_mfma_f32_16x16x32_bf16 v[4:7], v[12:15], v[236:239], v[4:7]
	v_mfma_f32_16x16x32_bf16 v[34:37], v[16:19], v[232:235], v[30:33]
	v_mfma_f32_16x16x32_bf16 v[30:33], v[22:25], v[228:231], v[168:171]
	v_mfma_f32_16x16x32_bf16 v[18:21], v[16:19], v[240:243], v[4:7]
	v_mfma_f32_16x16x32_bf16 v[4:7], v[22:25], v[236:239], v[8:11]
	v_mfma_f32_16x16x32_bf16 v[30:33], v[26:29], v[232:235], v[30:33]
	v_mfma_f32_16x16x32_bf16 v[14:17], v[26:29], v[240:243], v[4:7]
	s_setprio 0
	s_setprio 1
	v_mfma_f32_16x16x32_bf16 v[4:7], v[204:207], v[38:41], v[172:175]
	v_mfma_f32_16x16x32_bf16 v[58:61], v[208:211], v[42:45], v[4:7]
	v_mfma_f32_16x16x32_bf16 v[4:7], v[212:215], v[38:41], v[176:179]
	v_mfma_f32_16x16x32_bf16 v[54:57], v[216:219], v[42:45], v[4:7]
	v_mfma_f32_16x16x32_bf16 v[4:7], v[204:207], v[220:223], v[180:183]
	v_mfma_f32_16x16x32_bf16 v[42:45], v[208:211], v[224:227], v[4:7]
	v_mfma_f32_16x16x32_bf16 v[4:7], v[212:215], v[220:223], v[184:187]
	v_mfma_f32_16x16x32_bf16 v[38:41], v[216:219], v[224:227], v[4:7]
	v_mfma_f32_16x16x32_bf16 v[4:7], v[204:207], v[228:231], v[188:191]
	v_mfma_f32_16x16x32_bf16 v[26:29], v[208:211], v[232:235], v[4:7]
	v_mfma_f32_16x16x32_bf16 v[4:7], v[212:215], v[228:231], v[192:195]
	v_mfma_f32_16x16x32_bf16 v[22:25], v[216:219], v[232:235], v[4:7]
	v_mfma_f32_16x16x32_bf16 v[4:7], v[204:207], v[236:239], v[196:199]
	v_mfma_f32_16x16x32_bf16 v[10:13], v[208:211], v[240:243], v[4:7]
	v_mfma_f32_16x16x32_bf16 v[4:7], v[212:215], v[236:239], v[200:203]
	v_mfma_f32_16x16x32_bf16 v[6:9], v[216:219], v[240:243], v[4:7]
	s_setprio 0
	s_barrier
	s_mov_b32 s40, 2
	s_branch .LBB0_2377

; #define PG8_KSETUP() const bool last = (t == nt - 2); const char* a1 = cA + (size_t)(t + 1) * kstep; \
;             const char* a2 = last ? nA : cA + (size_t)(t + 2) * kstep; const char* b2 = last ? nB : cB + (size_t)(t + 2) * kstep; const char* a3 = a2 + kstep; const char* b3 = b2 + kstep; \
;             if (last && has_next) S.a_ready(nxt)
; template <class Epi, class Sched, bool ALIGN_EPI = false, bool SP2 = false>
; __device__ __forceinline__ void gemm_phase(PG8_LAS unsigned char* lds, const Gemm g, const Sched& S, const Epi& E) {
;     ...
;         int t0 = 0;
;         if constexpr (SP2 && Epi::NVM == 16) { if (ui > 0) { const int t = 0; PG8_KSETUP(); PG8_KITER_SP2(24, 24); t0 = 2; } }
;         if constexpr (SP2 && Epi::NVM == 8) { if (ui > 0) { const int t = 0; PG8_KSETUP(); PG8_KITER_SP2(16, 16); t0 = 2; } }
;         for (int t = t0; t < nt; t += 2) {
;             PG8_KSETUP();
;             if constexpr (SP2) {
;             PG8_KITER_SP2(8, 8);
.LBB0_2378:
	ds_read_b128 v[138:141], v147
	ds_read_b128 v[152:155], v147 offset:1024
	ds_read_b128 v[156:159], v147 offset:2048
	ds_read_b128 v[160:163], v147 offset:3072
	ds_read_b128 v[164:167], v148
	ds_read_b128 v[168:171], v148 offset:1024
	ds_read_b128 v[172:175], v148 offset:2048
	ds_read_b128 v[176:179], v148 offset:3072
	s_cmpk_eq_i32 s82, 0x54
	s_cselect_b32 s44, s8, s85
	s_cselect_b32 s45, s9, s86
	s_cselect_b32 s40, s28, s83
	s_cselect_b32 s41, s29, s84
	s_add_u32 s38, s44, 0x80
	s_addc_u32 s39, s45, 0
	ds_read_b128 v[180:183], v149
	ds_read_b128 v[184:187], v149 offset:1024
	ds_read_b128 v[188:191], v149 offset:2048
	ds_read_b128 v[192:195], v149 offset:3072
	ds_read_b128 v[196:199], v149 offset:4096
	ds_read_b128 v[200:203], v149 offset:5120
	ds_read_b128 v[204:207], v149 offset:6144
	ds_read_b128 v[208:211], v149 offset:7168
	s_mov_b32 m0, s72
	s_nop 0
	global_load_lds_dwordx4 v1, s[36:37] offset:0
	s_nop 0
	s_mov_b32 m0, s73
	s_nop 0
	global_load_lds_dwordx4 v143, s[36:37] offset:0
	s_waitcnt vmcnt(8)
	s_waitcnt lgkmcnt(0)
	s_barrier
	s_setprio 1
	v_mfma_f32_16x16x32_bf16 v[130:133], v[138:141], v[180:183], v[130:133]
	v_mfma_f32_16x16x32_bf16 v[130:133], v[152:155], v[184:187], v[130:133]
	v_mfma_f32_16x16x32_bf16 v[126:129], v[156:159], v[180:183], v[126:129]
	v_mfma_f32_16x16x32_bf16 v[126:129], v[160:163], v[184:187], v[126:129]
	v_mfma_f32_16x16x32_bf16 v[114:117], v[138:141], v[188:191], v[114:117]
	v_mfma_f32_16x16x32_bf16 v[114:117], v[152:155], v[192:195], v[114:117]
	v_mfma_f32_16x16x32_bf16 v[110:113], v[156:159], v[188:191], v[110:113]
	v_mfma_f32_16x16x32_bf16 v[110:113], v[160:163], v[192:195], v[110:113]
	v_mfma_f32_16x16x32_bf16 v[98:101], v[138:141], v[196:199], v[98:101]
	v_mfma_f32_16x16x32_bf16 v[98:101], v[152:155], v[200:203], v[98:101]
	v_mfma_f32_16x16x32_bf16 v[94:97], v[156:159], v[196:199], v[94:97]
	v_mfma_f32_16x16x32_bf16 v[94:97], v[160:163], v[200:203], v[94:97]
	v_mfma_f32_16x16x32_bf16 v[82:85], v[138:141], v[204:207], v[82:85]
	v_mfma_f32_16x16x32_bf16 v[82:85], v[152:155], v[208:211], v[82:85]
	v_mfma_f32_16x16x32_bf16 v[78:81], v[156:159], v[204:207], v[78:81]
	v_mfma_f32_16x16x32_bf16 v[78:81], v[160:163], v[208:211], v[78:81]
	s_setprio 0
	s_setprio 1
	v_mfma_f32_16x16x32_bf16 v[122:125], v[164:167], v[180:183], v[122:125]
	v_mfma_f32_16x16x32_bf16 v[122:125], v[168:171], v[184:187], v[122:125]
	v_mfma_f32_16x16x32_bf16 v[118:121], v[172:175], v[180:183], v[118:121]
	v_mfma_f32_16x16x32_bf16 v[118:121], v[176:179], v[184:187], v[118:121]
	v_mfma_f32_16x16x32_bf16 v[106:109], v[164:167], v[188:191], v[106:109]
	v_mfma_f32_16x16x32_bf16 v[106:109], v[168:171], v[192:195], v[106:109]
	v_mfma_f32_16x16x32_bf16 v[102:105], v[172:175], v[188:191], v[102:105]
	v_mfma_f32_16x16x32_bf16 v[102:105], v[176:179], v[192:195], v[102:105]
	v_mfma_f32_16x16x32_bf16 v[90:93], v[164:167], v[196:199], v[90:93]
	v_mfma_f32_16x16x32_bf16 v[90:93], v[168:171], v[200:203], v[90:93]
	v_mfma_f32_16x16x32_bf16 v[86:89], v[172:175], v[196:199], v[86:89]
	v_mfma_f32_16x16x32_bf16 v[86:89], v[176:179], v[200:203], v[86:89]
	v_mfma_f32_16x16x32_bf16 v[74:77], v[164:167], v[204:207], v[74:77]
	v_mfma_f32_16x16x32_bf16 v[74:77], v[168:171], v[208:211], v[74:77]
	v_mfma_f32_16x16x32_bf16 v[70:73], v[172:175], v[204:207], v[70:73]
	v_mfma_f32_16x16x32_bf16 v[70:73], v[176:179], v[208:211], v[70:73]
	s_setprio 0
	s_barrier
	ds_read_b128 v[180:183], v149 offset:16384
	ds_read_b128 v[184:187], v149 offset:17408
	ds_read_b128 v[188:191], v149 offset:18432
	ds_read_b128 v[192:195], v149 offset:19456
	ds_read_b128 v[196:199], v149 offset:20480
	ds_read_b128 v[200:203], v149 offset:21504
	ds_read_b128 v[204:207], v149 offset:22528
	ds_read_b128 v[208:211], v149 offset:23552
	s_mov_b32 m0, s52
	s_nop 0
	global_load_lds_dwordx4 v142, s[40:41] offset:0
	s_add_u32 s30, s40, 0x160000
	s_mov_b32 m0, s53
	s_nop 0
	global_load_lds_dwordx4 v144, s[40:41] offset:0
	s_addc_u32 s31, s41, 0
	s_mov_b32 m0, s54
	s_nop 0
	global_load_lds_dwordx4 v142, s[30:31] offset:0
	s_nop 0
	s_mov_b32 m0, s55
	s_nop 0
	global_load_lds_dwordx4 v144, s[30:31] offset:0
	s_nop 0
	s_mov_b32 m0, s47
	s_nop 0
	global_load_lds_dwordx4 v1, s[44:45] offset:0
	s_nop 0
	s_mov_b32 m0, s56
	s_nop 0
	global_load_lds_dwordx4 v143, s[44:45] offset:0
	s_waitcnt vmcnt(8)
	s_waitcnt lgkmcnt(0)
	s_barrier
	s_setprio 1
	v_mfma_f32_16x16x32_bf16 v[66:69], v[138:141], v[180:183], v[66:69]
	v_mfma_f32_16x16x32_bf16 v[66:69], v[152:155], v[184:187], v[66:69]
	v_mfma_f32_16x16x32_bf16 v[62:65], v[156:159], v[180:183], v[62:65]
	v_mfma_f32_16x16x32_bf16 v[62:65], v[160:163], v[184:187], v[62:65]
	v_mfma_f32_16x16x32_bf16 v[50:53], v[138:141], v[188:191], v[50:53]
	v_mfma_f32_16x16x32_bf16 v[50:53], v[152:155], v[192:195], v[50:53]
	v_mfma_f32_16x16x32_bf16 v[46:49], v[156:159], v[188:191], v[46:49]
	v_mfma_f32_16x16x32_bf16 v[46:49], v[160:163], v[192:195], v[46:49]
	v_mfma_f32_16x16x32_bf16 v[34:37], v[138:141], v[196:199], v[34:37]
	v_mfma_f32_16x16x32_bf16 v[34:37], v[152:155], v[200:203], v[34:37]
	v_mfma_f32_16x16x32_bf16 v[30:33], v[156:159], v[196:199], v[30:33]
	v_mfma_f32_16x16x32_bf16 v[30:33], v[160:163], v[200:203], v[30:33]
	v_mfma_f32_16x16x32_bf16 v[18:21], v[138:141], v[204:207], v[18:21]
	v_mfma_f32_16x16x32_bf16 v[18:21], v[152:155], v[208:211], v[18:21]
	v_mfma_f32_16x16x32_bf16 v[14:17], v[156:159], v[204:207], v[14:17]
	v_mfma_f32_16x16x32_bf16 v[14:17], v[160:163], v[208:211], v[14:17]
	s_setprio 0
	s_setprio 1
	v_mfma_f32_16x16x32_bf16 v[58:61], v[164:167], v[180:183], v[58:61]
	v_mfma_f32_16x16x32_bf16 v[54:57], v[172:175], v[180:183], v[54:57]
	v_mfma_f32_16x16x32_bf16 v[42:45], v[164:167], v[188:191], v[42:45]
	v_mfma_f32_16x16x32_bf16 v[38:41], v[172:175], v[188:191], v[38:41]
	v_mfma_f32_16x16x32_bf16 v[26:29], v[164:167], v[196:199], v[26:29]
	v_mfma_f32_16x16x32_bf16 v[22:25], v[172:175], v[196:199], v[22:25]
	v_mfma_f32_16x16x32_bf16 v[10:13], v[164:167], v[204:207], v[10:13]
	v_mfma_f32_16x16x32_bf16 v[4:7], v[172:175], v[204:207], v[6:9]
	v_mfma_f32_16x16x32_bf16 v[58:61], v[168:171], v[184:187], v[58:61]
	v_mfma_f32_16x16x32_bf16 v[54:57], v[176:179], v[184:187], v[54:57]
	v_mfma_f32_16x16x32_bf16 v[42:45], v[168:171], v[192:195], v[42:45]
	v_mfma_f32_16x16x32_bf16 v[38:41], v[176:179], v[192:195], v[38:41]
	v_mfma_f32_16x16x32_bf16 v[26:29], v[168:171], v[200:203], v[26:29]
	v_mfma_f32_16x16x32_bf16 v[22:25], v[176:179], v[200:203], v[22:25]
	v_mfma_f32_16x16x32_bf16 v[10:13], v[168:171], v[208:211], v[10:13]
	v_mfma_f32_16x16x32_bf16 v[4:7], v[176:179], v[208:211], v[4:7]
	s_setprio 0
	s_barrier
; #define PG8_KSETUP() const bool last = (t == nt - 2); const char* a1 = cA + (size_t)(t + 1) * kstep; \
;             const char* a2 = last ? nA : cA + (size_t)(t + 2) * kstep; const char* b2 = last ? nB : cB + (size_t)(t + 2) * kstep; const char* a3 = a2 + kstep; const char* b3 = b2 + kstep; \
;             if (last && has_next) S.a_ready(nxt)
; template <class Epi, class Sched, bool ALIGN_EPI = false, bool SP2 = false>
; __device__ __forceinline__ void gemm_phase(PG8_LAS unsigned char* lds, const Gemm g, const Sched& S, const Epi& E) {
;     ...
;         int t0 = 0;
;         if constexpr (SP2 && Epi::NVM == 16) { if (ui > 0) { const int t = 0; PG8_KSETUP(); PG8_KITER_SP2(24, 24); t0 = 2; } }
;         if constexpr (SP2 && Epi::NVM == 8) { if (ui > 0) { const int t = 0; PG8_KSETUP(); PG8_KITER_SP2(16, 16); t0 = 2; } }
;         for (int t = t0; t < nt; t += 2) {
;             PG8_KSETUP();
;             if constexpr (SP2) {
;             PG8_KITER_SP2(8, 8);
	ds_read_b128 v[138:141], v150
	ds_read_b128 v[152:155], v150 offset:1024
	ds_read_b128 v[156:159], v150 offset:2048
	ds_read_b128 v[160:163], v150 offset:3072
	ds_read_b128 v[164:167], v151
	ds_read_b128 v[168:171], v151 offset:1024
	ds_read_b128 v[172:175], v151 offset:2048
	ds_read_b128 v[176:179], v151 offset:3072
	ds_read_b128 v[180:183], v149 offset:32768
	ds_read_b128 v[184:187], v149 offset:33792
	ds_read_b128 v[188:191], v149 offset:34816
	ds_read_b128 v[192:195], v149 offset:35840
	ds_read_b128 v[196:199], v149 offset:36864
	ds_read_b128 v[200:203], v149 offset:37888
	ds_read_b128 v[204:207], v149 offset:38912
	ds_read_b128 v[208:211], v149 offset:39936
	s_add_u32 s30, s44, 0x160000
	s_addc_u32 s31, s45, 0
	s_mov_b32 m0, s57
	s_nop 0
	global_load_lds_dwordx4 v1, s[30:31] offset:0
	s_nop 0
	s_mov_b32 m0, s58
	s_nop 0
	global_load_lds_dwordx4 v143, s[30:31] offset:0
	s_waitcnt vmcnt(8)
	s_waitcnt lgkmcnt(0)
	s_barrier
	s_setprio 1
	v_mfma_f32_16x16x32_bf16 v[130:133], v[138:141], v[180:183], v[130:133]
	v_mfma_f32_16x16x32_bf16 v[130:133], v[152:155], v[184:187], v[130:133]
	v_mfma_f32_16x16x32_bf16 v[126:129], v[156:159], v[180:183], v[126:129]
	v_mfma_f32_16x16x32_bf16 v[126:129], v[160:163], v[184:187], v[126:129]
	v_mfma_f32_16x16x32_bf16 v[114:117], v[138:141], v[188:191], v[114:117]
	v_mfma_f32_16x16x32_bf16 v[114:117], v[152:155], v[192:195], v[114:117]
	v_mfma_f32_16x16x32_bf16 v[110:113], v[156:159], v[188:191], v[110:113]
	v_mfma_f32_16x16x32_bf16 v[110:113], v[160:163], v[192:195], v[110:113]
	v_mfma_f32_16x16x32_bf16 v[98:101], v[138:141], v[196:199], v[98:101]
	v_mfma_f32_16x16x32_bf16 v[98:101], v[152:155], v[200:203], v[98:101]
	v_mfma_f32_16x16x32_bf16 v[94:97], v[156:159], v[196:199], v[94:97]
	v_mfma_f32_16x16x32_bf16 v[94:97], v[160:163], v[200:203], v[94:97]
	v_mfma_f32_16x16x32_bf16 v[82:85], v[138:141], v[204:207], v[82:85]
	v_mfma_f32_16x16x32_bf16 v[82:85], v[152:155], v[208:211], v[82:85]
	v_mfma_f32_16x16x32_bf16 v[78:81], v[156:159], v[204:207], v[78:81]
	v_mfma_f32_16x16x32_bf16 v[78:81], v[160:163], v[208:211], v[78:81]
	s_setprio 0
	s_setprio 1
	v_mfma_f32_16x16x32_bf16 v[122:125], v[164:167], v[180:183], v[122:125]
	v_mfma_f32_16x16x32_bf16 v[122:125], v[168:171], v[184:187], v[122:125]
	v_mfma_f32_16x16x32_bf16 v[118:121], v[172:175], v[180:183], v[118:121]
	v_mfma_f32_16x16x32_bf16 v[118:121], v[176:179], v[184:187], v[118:121]
	v_mfma_f32_16x16x32_bf16 v[106:109], v[164:167], v[188:191], v[106:109]
	v_mfma_f32_16x16x32_bf16 v[106:109], v[168:171], v[192:195], v[106:109]
	v_mfma_f32_16x16x32_bf16 v[102:105], v[172:175], v[188:191], v[102:105]
	v_mfma_f32_16x16x32_bf16 v[102:105], v[176:179], v[192:195], v[102:105]
	v_mfma_f32_16x16x32_bf16 v[90:93], v[164:167], v[196:199], v[90:93]
	v_mfma_f32_16x16x32_bf16 v[90:93], v[168:171], v[200:203], v[90:93]
	v_mfma_f32_16x16x32_bf16 v[86:89], v[172:175], v[196:199], v[86:89]
	v_mfma_f32_16x16x32_bf16 v[86:89], v[176:179], v[200:203], v[86:89]
	v_mfma_f32_16x16x32_bf16 v[74:77], v[164:167], v[204:207], v[74:77]
	v_mfma_f32_16x16x32_bf16 v[74:77], v[168:171], v[208:211], v[74:77]
	v_mfma_f32_16x16x32_bf16 v[70:73], v[172:175], v[204:207], v[70:73]
	v_mfma_f32_16x16x32_bf16 v[70:73], v[176:179], v[208:211], v[70:73]
	s_setprio 0
	s_barrier
	ds_read_b128 v[180:183], v149 offset:49152
	ds_read_b128 v[184:187], v149 offset:50176
	ds_read_b128 v[188:191], v149 offset:51200
	ds_read_b128 v[192:195], v149 offset:52224
	ds_read_b128 v[196:199], v149 offset:53248
	ds_read_b128 v[200:203], v149 offset:54272
	ds_read_b128 v[204:207], v149 offset:55296
	ds_read_b128 v[208:211], v149 offset:56320
	s_add_u32 s30, s40, 0x80
	s_addc_u32 s31, s41, 0
	s_mov_b32 m0, s66
	s_nop 0
	global_load_lds_dwordx4 v142, s[30:31] offset:0
	s_nop 0
	s_mov_b32 m0, s67
	s_nop 0
	global_load_lds_dwordx4 v144, s[30:31] offset:0
	s_add_u32 s30, s40, 0x160080
	s_addc_u32 s31, s41, 0
	s_mov_b32 m0, s70
	s_nop 0
	global_load_lds_dwordx4 v142, s[30:31] offset:0
	s_nop 0
	s_mov_b32 m0, s71
	s_nop 0
	global_load_lds_dwordx4 v144, s[30:31] offset:0
	s_nop 0
	s_mov_b32 m0, s68
	s_nop 0
	global_load_lds_dwordx4 v1, s[38:39] offset:0
	s_nop 0
	s_mov_b32 m0, s69
	s_nop 0
	global_load_lds_dwordx4 v143, s[38:39] offset:0
	s_waitcnt vmcnt(8)
	s_waitcnt lgkmcnt(0)
	s_barrier
	s_setprio 1
	v_mfma_f32_16x16x32_bf16 v[66:69], v[138:141], v[180:183], v[66:69]
	v_mfma_f32_16x16x32_bf16 v[66:69], v[152:155], v[184:187], v[66:69]
	v_mfma_f32_16x16x32_bf16 v[62:65], v[156:159], v[180:183], v[62:65]
	v_mfma_f32_16x16x32_bf16 v[62:65], v[160:163], v[184:187], v[62:65]
	v_mfma_f32_16x16x32_bf16 v[50:53], v[138:141], v[188:191], v[50:53]
	v_mfma_f32_16x16x32_bf16 v[50:53], v[152:155], v[192:195], v[50:53]
	v_mfma_f32_16x16x32_bf16 v[46:49], v[156:159], v[188:191], v[46:49]
	v_mfma_f32_16x16x32_bf16 v[46:49], v[160:163], v[192:195], v[46:49]
	v_mfma_f32_16x16x32_bf16 v[34:37], v[138:141], v[196:199], v[34:37]
	v_mfma_f32_16x16x32_bf16 v[34:37], v[152:155], v[200:203], v[34:37]
	v_mfma_f32_16x16x32_bf16 v[30:33], v[156:159], v[196:199], v[30:33]
	v_mfma_f32_16x16x32_bf16 v[30:33], v[160:163], v[200:203], v[30:33]
	v_mfma_f32_16x16x32_bf16 v[18:21], v[138:141], v[204:207], v[18:21]
	v_mfma_f32_16x16x32_bf16 v[18:21], v[152:155], v[208:211], v[18:21]
	v_mfma_f32_16x16x32_bf16 v[14:17], v[156:159], v[204:207], v[14:17]
	v_mfma_f32_16x16x32_bf16 v[14:17], v[160:163], v[208:211], v[14:17]
	s_setprio 0
	s_setprio 1
	v_mfma_f32_16x16x32_bf16 v[58:61], v[164:167], v[180:183], v[58:61]
	v_mfma_f32_16x16x32_bf16 v[54:57], v[172:175], v[180:183], v[54:57]
	v_mfma_f32_16x16x32_bf16 v[42:45], v[164:167], v[188:191], v[42:45]
	v_mfma_f32_16x16x32_bf16 v[38:41], v[172:175], v[188:191], v[38:41]
	v_mfma_f32_16x16x32_bf16 v[26:29], v[164:167], v[196:199], v[26:29]
	v_mfma_f32_16x16x32_bf16 v[22:25], v[172:175], v[196:199], v[22:25]
	v_mfma_f32_16x16x32_bf16 v[8:11], v[164:167], v[204:207], v[10:13]
	v_mfma_f32_16x16x32_bf16 v[4:7], v[172:175], v[204:207], v[4:7]
	v_mfma_f32_16x16x32_bf16 v[58:61], v[168:171], v[184:187], v[58:61]
	v_mfma_f32_16x16x32_bf16 v[54:57], v[176:179], v[184:187], v[54:57]
	v_mfma_f32_16x16x32_bf16 v[42:45], v[168:171], v[192:195], v[42:45]
	v_mfma_f32_16x16x32_bf16 v[38:41], v[176:179], v[192:195], v[38:41]
	v_mfma_f32_16x16x32_bf16 v[26:29], v[168:171], v[200:203], v[26:29]
	v_mfma_f32_16x16x32_bf16 v[22:25], v[176:179], v[200:203], v[22:25]
	v_mfma_f32_16x16x32_bf16 v[10:13], v[168:171], v[208:211], v[8:11]
	v_mfma_f32_16x16x32_bf16 v[6:9], v[176:179], v[208:211], v[4:7]
	s_setprio 0
	s_barrier
	s_add_i32 s82, s82, 2
	s_add_u32 s83, s83, 0x100
	s_addc_u32 s84, s84, 0
	s_add_u32 s85, s85, 0x100
	s_addc_u32 s86, s86, 0
	s_add_u32 s36, s36, 0x100
	s_addc_u32 s37, s37, 0
	s_cmpk_gt_u32 s82, 0x55
	s_cbranch_scc0 .LBB0_2378
	s_and_b64 vcc, exec, s[16:17]
	s_cbranch_vccz .LBB0_2381
	s_barrier

.LBB0_2536:
	ds_read_b128 v[160:163], v155
	ds_read_b128 v[168:171], v155 offset:1024
	ds_read_b128 v[172:175], v155 offset:2048
	ds_read_b128 v[176:179], v155 offset:3072
	ds_read_b128 v[180:183], v159
	ds_read_b128 v[184:187], v159 offset:1024
	ds_read_b128 v[188:191], v159 offset:2048
	ds_read_b128 v[192:195], v159 offset:3072
	s_cmp_eq_u32 s91, 28
	s_cselect_b32 s56, s45, s89
	s_cselect_b32 s57, s37, s90
	s_cselect_b32 s54, s86, s87
	s_cselect_b32 s55, s29, s88
	s_add_u32 s46, s56, 0x80
	s_addc_u32 s47, s57, 0
	ds_read_b128 v[196:199], v164
	ds_read_b128 v[200:203], v164 offset:1024
	ds_read_b128 v[204:207], v164 offset:2048
	ds_read_b128 v[208:211], v164 offset:3072
	ds_read_b128 v[212:215], v164 offset:4096
	ds_read_b128 v[216:219], v164 offset:5120
	ds_read_b128 v[220:223], v164 offset:6144
	ds_read_b128 v[224:227], v164 offset:7168
	s_add_u32 s30, s89, 0x7ff80
	s_addc_u32 s31, s90, 0
	s_mov_b32 m0, s78
	s_nop 0
	global_load_lds_dwordx4 v1, s[30:31] offset:0
	s_nop 0
	s_mov_b32 m0, s79
	s_nop 0
	global_load_lds_dwordx4 v139, s[30:31] offset:0
	s_waitcnt vmcnt(8)
	s_waitcnt lgkmcnt(0)
	s_barrier
	s_setprio 1
	v_mfma_f32_16x16x32_bf16 v[126:129], v[160:163], v[196:199], v[126:129]
	v_mfma_f32_16x16x32_bf16 v[126:129], v[168:171], v[200:203], v[126:129]
	v_mfma_f32_16x16x32_bf16 v[122:125], v[172:175], v[196:199], v[122:125]
	v_mfma_f32_16x16x32_bf16 v[122:125], v[176:179], v[200:203], v[122:125]
	v_mfma_f32_16x16x32_bf16 v[114:117], v[160:163], v[204:207], v[114:117]
	v_mfma_f32_16x16x32_bf16 v[114:117], v[168:171], v[208:211], v[114:117]
	v_mfma_f32_16x16x32_bf16 v[106:109], v[172:175], v[204:207], v[106:109]
	v_mfma_f32_16x16x32_bf16 v[106:109], v[176:179], v[208:211], v[106:109]
	v_mfma_f32_16x16x32_bf16 v[98:101], v[160:163], v[212:215], v[98:101]
	v_mfma_f32_16x16x32_bf16 v[98:101], v[168:171], v[216:219], v[98:101]
	v_mfma_f32_16x16x32_bf16 v[90:93], v[172:175], v[212:215], v[90:93]
	v_mfma_f32_16x16x32_bf16 v[90:93], v[176:179], v[216:219], v[90:93]
	v_mfma_f32_16x16x32_bf16 v[82:85], v[160:163], v[220:223], v[82:85]
	v_mfma_f32_16x16x32_bf16 v[82:85], v[168:171], v[224:227], v[82:85]
	v_mfma_f32_16x16x32_bf16 v[74:77], v[172:175], v[220:223], v[74:77]
	v_mfma_f32_16x16x32_bf16 v[74:77], v[176:179], v[224:227], v[74:77]
	s_setprio 0
	s_setprio 1
	v_mfma_f32_16x16x32_bf16 v[118:121], v[180:183], v[196:199], v[118:121]
	v_mfma_f32_16x16x32_bf16 v[118:121], v[184:187], v[200:203], v[118:121]
	v_mfma_f32_16x16x32_bf16 v[110:113], v[188:191], v[196:199], v[110:113]
	v_mfma_f32_16x16x32_bf16 v[110:113], v[192:195], v[200:203], v[110:113]
	v_mfma_f32_16x16x32_bf16 v[102:105], v[180:183], v[204:207], v[102:105]
	v_mfma_f32_16x16x32_bf16 v[102:105], v[184:187], v[208:211], v[102:105]
	v_mfma_f32_16x16x32_bf16 v[94:97], v[188:191], v[204:207], v[94:97]
	v_mfma_f32_16x16x32_bf16 v[94:97], v[192:195], v[208:211], v[94:97]
	v_mfma_f32_16x16x32_bf16 v[86:89], v[180:183], v[212:215], v[86:89]
	v_mfma_f32_16x16x32_bf16 v[86:89], v[184:187], v[216:219], v[86:89]
	v_mfma_f32_16x16x32_bf16 v[78:81], v[188:191], v[212:215], v[78:81]
	v_mfma_f32_16x16x32_bf16 v[78:81], v[192:195], v[216:219], v[78:81]
	v_mfma_f32_16x16x32_bf16 v[70:73], v[180:183], v[220:223], v[70:73]
	v_mfma_f32_16x16x32_bf16 v[70:73], v[184:187], v[224:227], v[70:73]
	v_mfma_f32_16x16x32_bf16 v[66:69], v[188:191], v[220:223], v[66:69]
	v_mfma_f32_16x16x32_bf16 v[66:69], v[192:195], v[224:227], v[66:69]
	s_setprio 0
	s_barrier
	ds_read_b128 v[196:199], v164 offset:16384
	ds_read_b128 v[200:203], v164 offset:17408
	ds_read_b128 v[204:207], v164 offset:18432
	ds_read_b128 v[208:211], v164 offset:19456
	ds_read_b128 v[212:215], v164 offset:20480
	ds_read_b128 v[216:219], v164 offset:21504
	ds_read_b128 v[220:223], v164 offset:22528
	ds_read_b128 v[224:227], v164 offset:23552
	s_mov_b32 m0, s64
	s_nop 0
	global_load_lds_dwordx4 v137, s[54:55] offset:0
	s_add_u32 s30, s54, 0x80000
	s_mov_b32 m0, s65
	s_nop 0
	global_load_lds_dwordx4 v141, s[54:55] offset:0
	s_addc_u32 s31, s55, 0
	s_mov_b32 m0, s66
	s_nop 0
	global_load_lds_dwordx4 v137, s[30:31] offset:0
	s_nop 0
	s_mov_b32 m0, s67
	s_nop 0
	global_load_lds_dwordx4 v141, s[30:31] offset:0
	s_nop 0
	s_mov_b32 m0, s53
	s_nop 0
	global_load_lds_dwordx4 v1, s[56:57] offset:0
	s_nop 0
	s_mov_b32 m0, s68
	s_nop 0
	global_load_lds_dwordx4 v139, s[56:57] offset:0
	s_waitcnt vmcnt(8)
	s_waitcnt lgkmcnt(0)
	s_barrier
	s_setprio 1
	v_mfma_f32_16x16x32_bf16 v[62:65], v[160:163], v[196:199], v[62:65]
	v_mfma_f32_16x16x32_bf16 v[62:65], v[168:171], v[200:203], v[62:65]
	v_mfma_f32_16x16x32_bf16 v[58:61], v[172:175], v[196:199], v[58:61]
	v_mfma_f32_16x16x32_bf16 v[58:61], v[176:179], v[200:203], v[58:61]
	v_mfma_f32_16x16x32_bf16 v[50:53], v[160:163], v[204:207], v[50:53]
	v_mfma_f32_16x16x32_bf16 v[50:53], v[168:171], v[208:211], v[50:53]
	v_mfma_f32_16x16x32_bf16 v[42:45], v[172:175], v[204:207], v[42:45]
	v_mfma_f32_16x16x32_bf16 v[42:45], v[176:179], v[208:211], v[42:45]
	v_mfma_f32_16x16x32_bf16 v[34:37], v[160:163], v[212:215], v[34:37]
	v_mfma_f32_16x16x32_bf16 v[34:37], v[168:171], v[216:219], v[34:37]
	v_mfma_f32_16x16x32_bf16 v[26:29], v[172:175], v[212:215], v[26:29]
	v_mfma_f32_16x16x32_bf16 v[26:29], v[176:179], v[216:219], v[26:29]
	v_mfma_f32_16x16x32_bf16 v[18:21], v[160:163], v[220:223], v[18:21]
	v_mfma_f32_16x16x32_bf16 v[18:21], v[168:171], v[224:227], v[18:21]
	v_mfma_f32_16x16x32_bf16 v[10:13], v[172:175], v[220:223], v[10:13]
	v_mfma_f32_16x16x32_bf16 v[10:13], v[176:179], v[224:227], v[10:13]
	s_setprio 0
	s_setprio 1
	v_mfma_f32_16x16x32_bf16 v[54:57], v[180:183], v[196:199], v[54:57]
	v_mfma_f32_16x16x32_bf16 v[54:57], v[184:187], v[200:203], v[54:57]
	v_mfma_f32_16x16x32_bf16 v[46:49], v[188:191], v[196:199], v[46:49]
	v_mfma_f32_16x16x32_bf16 v[46:49], v[192:195], v[200:203], v[46:49]
	v_mfma_f32_16x16x32_bf16 v[38:41], v[180:183], v[204:207], v[38:41]
	v_mfma_f32_16x16x32_bf16 v[38:41], v[184:187], v[208:211], v[38:41]
	v_mfma_f32_16x16x32_bf16 v[30:33], v[188:191], v[204:207], v[30:33]
	v_mfma_f32_16x16x32_bf16 v[30:33], v[192:195], v[208:211], v[30:33]
	v_mfma_f32_16x16x32_bf16 v[22:25], v[180:183], v[212:215], v[22:25]
	v_mfma_f32_16x16x32_bf16 v[22:25], v[184:187], v[216:219], v[22:25]
	v_mfma_f32_16x16x32_bf16 v[14:17], v[188:191], v[212:215], v[14:17]
	v_mfma_f32_16x16x32_bf16 v[14:17], v[192:195], v[216:219], v[14:17]
	v_mfma_f32_16x16x32_bf16 v[6:9], v[180:183], v[220:223], v[6:9]
	v_mfma_f32_16x16x32_bf16 v[6:9], v[184:187], v[224:227], v[6:9]
	v_mfma_f32_16x16x32_bf16 v[2:5], v[188:191], v[220:223], v[2:5]
	v_mfma_f32_16x16x32_bf16 v[2:5], v[192:195], v[224:227], v[2:5]
	s_setprio 0
	s_barrier
; #define PG8_BAR __builtin_amdgcn_s_barrier()
; #define PG8_KSETUP() const bool last = (t == nt - 2); const char* a1 = cA + (size_t)(t + 1) * kstep; \
;             const char* a2 = last ? nA : cA + (size_t)(t + 2) * kstep; const char* b2 = last ? nB : cB + (size_t)(t + 2) * kstep; const char* a3 = a2 + kstep; const char* b3 = b2 + kstep; \
;             if (last && has_next) S.a_ready(nxt)
; template <class Epi, class Sched, bool ALIGN_EPI = false, bool SP2 = false>
; __device__ __forceinline__ void gemm_phase(PG8_LAS unsigned char* lds, const Gemm g, const Sched& S, const Epi& E) {
;     ...
;         int t0 = 0;
;         if constexpr (SP2 && Epi::NVM == 16) { if (ui > 0) { const int t = 0; PG8_KSETUP(); PG8_KITER_SP2(24, 24); t0 = 2; } }
;         if constexpr (SP2 && Epi::NVM == 8) { if (ui > 0) { const int t = 0; PG8_KSETUP(); PG8_KITER_SP2(16, 16); t0 = 2; } }
;         for (int t = t0; t < nt; t += 2) {
;     ...
;         if constexpr (ALIGN_EPI) { if (wr == 0) PG8_BAR; }
	ds_read_b128 v[160:163], v165
	ds_read_b128 v[168:171], v165 offset:1024
	ds_read_b128 v[172:175], v165 offset:2048
	ds_read_b128 v[176:179], v165 offset:3072
	ds_read_b128 v[180:183], v166
	ds_read_b128 v[184:187], v166 offset:1024
	ds_read_b128 v[188:191], v166 offset:2048
	ds_read_b128 v[192:195], v166 offset:3072
	ds_read_b128 v[196:199], v164 offset:32768
	ds_read_b128 v[200:203], v164 offset:33792
	ds_read_b128 v[204:207], v164 offset:34816
	ds_read_b128 v[208:211], v164 offset:35840
	ds_read_b128 v[212:215], v164 offset:36864
	ds_read_b128 v[216:219], v164 offset:37888
	ds_read_b128 v[220:223], v164 offset:38912
	ds_read_b128 v[224:227], v164 offset:39936
	s_add_u32 s30, s56, 0x80000
	s_addc_u32 s31, s57, 0
	s_mov_b32 m0, s69
	s_nop 0
	global_load_lds_dwordx4 v1, s[30:31] offset:0
	s_nop 0
	s_mov_b32 m0, s70
	s_nop 0
	global_load_lds_dwordx4 v139, s[30:31] offset:0
	s_waitcnt vmcnt(8)
	s_waitcnt lgkmcnt(0)
	s_barrier
	s_setprio 1
	v_mfma_f32_16x16x32_bf16 v[126:129], v[160:163], v[196:199], v[126:129]
	v_mfma_f32_16x16x32_bf16 v[126:129], v[168:171], v[200:203], v[126:129]
	v_mfma_f32_16x16x32_bf16 v[122:125], v[172:175], v[196:199], v[122:125]
	v_mfma_f32_16x16x32_bf16 v[122:125], v[176:179], v[200:203], v[122:125]
	v_mfma_f32_16x16x32_bf16 v[114:117], v[160:163], v[204:207], v[114:117]
	v_mfma_f32_16x16x32_bf16 v[114:117], v[168:171], v[208:211], v[114:117]
	v_mfma_f32_16x16x32_bf16 v[106:109], v[172:175], v[204:207], v[106:109]
	v_mfma_f32_16x16x32_bf16 v[106:109], v[176:179], v[208:211], v[106:109]
	v_mfma_f32_16x16x32_bf16 v[98:101], v[160:163], v[212:215], v[98:101]
	v_mfma_f32_16x16x32_bf16 v[98:101], v[168:171], v[216:219], v[98:101]
	v_mfma_f32_16x16x32_bf16 v[90:93], v[172:175], v[212:215], v[90:93]
	v_mfma_f32_16x16x32_bf16 v[90:93], v[176:179], v[216:219], v[90:93]
	v_mfma_f32_16x16x32_bf16 v[82:85], v[160:163], v[220:223], v[82:85]
	v_mfma_f32_16x16x32_bf16 v[82:85], v[168:171], v[224:227], v[82:85]
	v_mfma_f32_16x16x32_bf16 v[74:77], v[172:175], v[220:223], v[74:77]
	v_mfma_f32_16x16x32_bf16 v[74:77], v[176:179], v[224:227], v[74:77]
	s_setprio 0
	s_setprio 1
	v_mfma_f32_16x16x32_bf16 v[118:121], v[180:183], v[196:199], v[118:121]
	v_mfma_f32_16x16x32_bf16 v[118:121], v[184:187], v[200:203], v[118:121]
	v_mfma_f32_16x16x32_bf16 v[110:113], v[188:191], v[196:199], v[110:113]
	v_mfma_f32_16x16x32_bf16 v[110:113], v[192:195], v[200:203], v[110:113]
	v_mfma_f32_16x16x32_bf16 v[102:105], v[180:183], v[204:207], v[102:105]
	v_mfma_f32_16x16x32_bf16 v[102:105], v[184:187], v[208:211], v[102:105]
	v_mfma_f32_16x16x32_bf16 v[94:97], v[188:191], v[204:207], v[94:97]
	v_mfma_f32_16x16x32_bf16 v[94:97], v[192:195], v[208:211], v[94:97]
	v_mfma_f32_16x16x32_bf16 v[86:89], v[180:183], v[212:215], v[86:89]
	v_mfma_f32_16x16x32_bf16 v[86:89], v[184:187], v[216:219], v[86:89]
	v_mfma_f32_16x16x32_bf16 v[78:81], v[188:191], v[212:215], v[78:81]
	v_mfma_f32_16x16x32_bf16 v[78:81], v[192:195], v[216:219], v[78:81]
	v_mfma_f32_16x16x32_bf16 v[70:73], v[180:183], v[220:223], v[70:73]
	v_mfma_f32_16x16x32_bf16 v[70:73], v[184:187], v[224:227], v[70:73]
	v_mfma_f32_16x16x32_bf16 v[66:69], v[188:191], v[220:223], v[66:69]
	v_mfma_f32_16x16x32_bf16 v[66:69], v[192:195], v[224:227], v[66:69]
	s_setprio 0
	s_barrier
	ds_read_b128 v[196:199], v164 offset:49152
	ds_read_b128 v[200:203], v164 offset:50176
	ds_read_b128 v[204:207], v164 offset:51200
	ds_read_b128 v[208:211], v164 offset:52224
	ds_read_b128 v[212:215], v164 offset:53248
	ds_read_b128 v[216:219], v164 offset:54272
	ds_read_b128 v[220:223], v164 offset:55296
	ds_read_b128 v[224:227], v164 offset:56320
	s_add_u32 s30, s54, 0x80
	s_addc_u32 s31, s55, 0
	s_mov_b32 m0, s72
	s_nop 0
	global_load_lds_dwordx4 v137, s[30:31] offset:0
	s_nop 0
	s_mov_b32 m0, s73
	s_nop 0
	global_load_lds_dwordx4 v141, s[30:31] offset:0
	s_add_u32 s30, s54, 0x80080
	s_addc_u32 s31, s55, 0
	s_mov_b32 m0, s76
	s_nop 0
	global_load_lds_dwordx4 v137, s[30:31] offset:0
	s_nop 0
	s_mov_b32 m0, s77
	s_nop 0
	global_load_lds_dwordx4 v141, s[30:31] offset:0
	s_nop 0
	s_mov_b32 m0, s74
	s_nop 0
	global_load_lds_dwordx4 v1, s[46:47] offset:0
	s_nop 0
	s_mov_b32 m0, s75
	s_nop 0
	global_load_lds_dwordx4 v139, s[46:47] offset:0
	s_waitcnt vmcnt(8)
	s_waitcnt lgkmcnt(0)
	s_barrier
	s_setprio 1
	v_mfma_f32_16x16x32_bf16 v[62:65], v[160:163], v[196:199], v[62:65]
	v_mfma_f32_16x16x32_bf16 v[62:65], v[168:171], v[200:203], v[62:65]
	v_mfma_f32_16x16x32_bf16 v[58:61], v[172:175], v[196:199], v[58:61]
	v_mfma_f32_16x16x32_bf16 v[58:61], v[176:179], v[200:203], v[58:61]
	v_mfma_f32_16x16x32_bf16 v[50:53], v[160:163], v[204:207], v[50:53]
	v_mfma_f32_16x16x32_bf16 v[50:53], v[168:171], v[208:211], v[50:53]
	v_mfma_f32_16x16x32_bf16 v[42:45], v[172:175], v[204:207], v[42:45]
	v_mfma_f32_16x16x32_bf16 v[42:45], v[176:179], v[208:211], v[42:45]
	v_mfma_f32_16x16x32_bf16 v[34:37], v[160:163], v[212:215], v[34:37]
	v_mfma_f32_16x16x32_bf16 v[34:37], v[168:171], v[216:219], v[34:37]
	v_mfma_f32_16x16x32_bf16 v[26:29], v[172:175], v[212:215], v[26:29]
	v_mfma_f32_16x16x32_bf16 v[26:29], v[176:179], v[216:219], v[26:29]
	v_mfma_f32_16x16x32_bf16 v[18:21], v[160:163], v[220:223], v[18:21]
	v_mfma_f32_16x16x32_bf16 v[18:21], v[168:171], v[224:227], v[18:21]
	v_mfma_f32_16x16x32_bf16 v[10:13], v[172:175], v[220:223], v[10:13]
	v_mfma_f32_16x16x32_bf16 v[10:13], v[176:179], v[224:227], v[10:13]
	s_setprio 0
	s_setprio 1
	v_mfma_f32_16x16x32_bf16 v[54:57], v[180:183], v[196:199], v[54:57]
	v_mfma_f32_16x16x32_bf16 v[54:57], v[184:187], v[200:203], v[54:57]
	v_mfma_f32_16x16x32_bf16 v[46:49], v[188:191], v[196:199], v[46:49]
	v_mfma_f32_16x16x32_bf16 v[46:49], v[192:195], v[200:203], v[46:49]
	v_mfma_f32_16x16x32_bf16 v[38:41], v[180:183], v[204:207], v[38:41]
	v_mfma_f32_16x16x32_bf16 v[38:41], v[184:187], v[208:211], v[38:41]
	v_mfma_f32_16x16x32_bf16 v[30:33], v[188:191], v[204:207], v[30:33]
	v_mfma_f32_16x16x32_bf16 v[30:33], v[192:195], v[208:211], v[30:33]
	v_mfma_f32_16x16x32_bf16 v[22:25], v[180:183], v[212:215], v[22:25]
	v_mfma_f32_16x16x32_bf16 v[22:25], v[184:187], v[216:219], v[22:25]
	v_mfma_f32_16x16x32_bf16 v[14:17], v[188:191], v[212:215], v[14:17]
	v_mfma_f32_16x16x32_bf16 v[14:17], v[192:195], v[216:219], v[14:17]
	v_mfma_f32_16x16x32_bf16 v[6:9], v[180:183], v[220:223], v[6:9]
	v_mfma_f32_16x16x32_bf16 v[6:9], v[184:187], v[224:227], v[6:9]
	v_mfma_f32_16x16x32_bf16 v[2:5], v[188:191], v[220:223], v[2:5]
	v_mfma_f32_16x16x32_bf16 v[2:5], v[192:195], v[224:227], v[2:5]
	s_setprio 0
	s_barrier
	s_add_i32 s91, s91, 2
	s_add_u32 s87, s87, 0x100
	s_addc_u32 s88, s88, 0
	s_add_u32 s89, s89, 0x100
	s_addc_u32 s90, s90, 0
	s_cmp_gt_u32 s91, 29
	s_cbranch_scc0 .LBB0_2536
	s_and_b64 vcc, exec, s[18:19]
	s_cbranch_vccz .LBB0_2539
	s_barrier

; #define PG8_KSETUP() const bool last = (t == nt - 2); const char* a1 = cA + (size_t)(t + 1) * kstep; \
;             const char* a2 = last ? nA : cA + (size_t)(t + 2) * kstep; const char* b2 = last ? nB : cB + (size_t)(t + 2) * kstep; const char* a3 = a2 + kstep; const char* b3 = b2 + kstep; \
;             if (last && has_next) S.a_ready(nxt)
; template <class Epi, class Sched, bool ALIGN_EPI = false, bool SP2 = false>
; __device__ __forceinline__ void gemm_phase(PG8_LAS unsigned char* lds, const Gemm g, const Sched& S, const Epi& E) {
;     ...
;         int t0 = 0;
;         if constexpr (SP2 && Epi::NVM == 16) { if (ui > 0) { const int t = 0; PG8_KSETUP(); PG8_KITER_SP2(24, 24); t0 = 2; } }
.LBB0_2710:
	s_cmp_eq_u32 s29, 0
	s_mov_b32 s56, 0
	s_cbranch_scc1 .LBB0_2712
	ds_read_b128 v[4:7], v147
	ds_read_b128 v[8:11], v147 offset:1024
	ds_read_b128 v[12:15], v147 offset:2048
	ds_read_b128 v[16:19], v147 offset:3072
	ds_read_b128 v[20:23], v148
	ds_read_b128 v[24:27], v148 offset:1024
	ds_read_b128 v[28:31], v148 offset:2048
	ds_read_b128 v[32:35], v148 offset:3072
	s_add_u32 s40, s46, 0x100
	s_addc_u32 s41, s47, 0
	s_add_u32 s30, s54, 0x100
	s_addc_u32 s31, s55, 0
	s_add_u32 s38, s46, 0x180
	s_addc_u32 s39, s47, 0
	ds_read_b128 v[36:39], v149
	ds_read_b128 v[40:43], v149 offset:1024
	ds_read_b128 v[44:47], v149 offset:2048
	ds_read_b128 v[48:51], v149 offset:3072
	ds_read_b128 v[52:55], v149 offset:4096
	ds_read_b128 v[56:59], v149 offset:5120
	ds_read_b128 v[60:63], v149 offset:6144
	ds_read_b128 v[64:67], v149 offset:7168
	s_add_u32 s48, s46, 0x80080
	s_addc_u32 s49, s47, 0
	s_mov_b32 m0, s77
	s_nop 0
	global_load_lds_dwordx4 v1, s[48:49] offset:0
	s_nop 0
	s_mov_b32 m0, s78
	s_nop 0
	global_load_lds_dwordx4 v143, s[48:49] offset:0
	s_waitcnt vmcnt(24)
	s_waitcnt lgkmcnt(0)
	s_barrier
	s_setprio 1
	v_mfma_f32_16x16x32_bf16 v[92:95], v[4:7], v[60:63], 0
	v_mfma_f32_16x16x32_bf16 v[68:71], v[4:7], v[36:39], 0
	v_mfma_f32_16x16x32_bf16 v[72:75], v[12:15], v[36:39], 0
	v_mfma_f32_16x16x32_bf16 v[76:79], v[4:7], v[44:47], 0
	v_mfma_f32_16x16x32_bf16 v[80:83], v[12:15], v[44:47], 0
	v_mfma_f32_16x16x32_bf16 v[84:87], v[4:7], v[52:55], 0
	v_mfma_f32_16x16x32_bf16 v[88:91], v[12:15], v[52:55], 0
	v_mfma_f32_16x16x32_bf16 v[102:105], v[8:11], v[64:67], v[92:95]
	v_mfma_f32_16x16x32_bf16 v[92:95], v[12:15], v[60:63], 0
	v_mfma_f32_16x16x32_bf16 v[68:71], v[8:11], v[40:43], v[68:71]
	v_mfma_f32_16x16x32_bf16 v[72:75], v[16:19], v[40:43], v[72:75]
	v_mfma_f32_16x16x32_bf16 v[76:79], v[8:11], v[48:51], v[76:79]
	v_mfma_f32_16x16x32_bf16 v[80:83], v[16:19], v[48:51], v[80:83]
	v_mfma_f32_16x16x32_bf16 v[84:87], v[8:11], v[56:59], v[84:87]
	v_mfma_f32_16x16x32_bf16 v[88:91], v[16:19], v[56:59], v[88:91]
	v_mfma_f32_16x16x32_bf16 v[106:109], v[16:19], v[64:67], v[92:95]
	s_setprio 0
	s_setprio 1
	v_mfma_f32_16x16x32_bf16 v[92:95], v[20:23], v[36:39], 0
	v_mfma_f32_16x16x32_bf16 v[36:39], v[28:31], v[36:39], 0
	v_mfma_f32_16x16x32_bf16 v[118:121], v[24:27], v[40:43], v[92:95]
	v_mfma_f32_16x16x32_bf16 v[36:39], v[32:35], v[40:43], v[36:39]
	v_mfma_f32_16x16x32_bf16 v[40:43], v[20:23], v[44:47], 0
	v_mfma_f32_16x16x32_bf16 v[44:47], v[28:31], v[44:47], 0
	v_mfma_f32_16x16x32_bf16 v[40:43], v[24:27], v[48:51], v[40:43]
	v_mfma_f32_16x16x32_bf16 v[44:47], v[32:35], v[48:51], v[44:47]
	v_mfma_f32_16x16x32_bf16 v[48:51], v[20:23], v[52:55], 0
	v_mfma_f32_16x16x32_bf16 v[52:55], v[28:31], v[52:55], 0
	v_mfma_f32_16x16x32_bf16 v[48:51], v[24:27], v[56:59], v[48:51]
	v_mfma_f32_16x16x32_bf16 v[52:55], v[32:35], v[56:59], v[52:55]
	v_mfma_f32_16x16x32_bf16 v[56:59], v[20:23], v[60:63], 0
	v_mfma_f32_16x16x32_bf16 v[60:63], v[28:31], v[60:63], 0
	v_mfma_f32_16x16x32_bf16 v[56:59], v[24:27], v[64:67], v[56:59]
	v_mfma_f32_16x16x32_bf16 v[60:63], v[32:35], v[64:67], v[60:63]
	s_setprio 0
	s_barrier
	ds_read_b128 v[64:67], v149 offset:16384
	ds_read_b128 v[92:95], v149 offset:17408
	ds_read_b128 v[96:99], v149 offset:18432
	ds_read_b128 v[110:113], v149 offset:19456
	ds_read_b128 v[114:117], v149 offset:20480
	ds_read_b128 v[122:125], v149 offset:21504
	ds_read_b128 v[126:129], v149 offset:22528
	ds_read_b128 v[130:133], v149 offset:23552
	s_mov_b32 m0, s45
	s_nop 0
	global_load_lds_dwordx4 v142, s[30:31] offset:0
	s_nop 0
	s_mov_b32 m0, s52
	s_nop 0
	global_load_lds_dwordx4 v144, s[30:31] offset:0
	s_add_u32 s30, s54, 0x80100
	s_addc_u32 s31, s55, 0
	s_mov_b32 m0, s53
	s_nop 0
	global_load_lds_dwordx4 v142, s[30:31] offset:0
	s_nop 0
	s_mov_b32 m0, s64
	s_nop 0
	global_load_lds_dwordx4 v144, s[30:31] offset:0
	s_nop 0
	s_mov_b32 m0, s33
	s_nop 0
	global_load_lds_dwordx4 v1, s[40:41] offset:0
	s_nop 0
	s_mov_b32 m0, s65
	s_nop 0
	global_load_lds_dwordx4 v143, s[40:41] offset:0
	s_waitcnt vmcnt(24)
	s_waitcnt lgkmcnt(0)
	s_barrier
	s_setprio 1
	v_mfma_f32_16x16x32_bf16 v[138:141], v[4:7], v[64:67], 0
	v_mfma_f32_16x16x32_bf16 v[156:159], v[4:7], v[96:99], 0
	v_mfma_f32_16x16x32_bf16 v[164:167], v[4:7], v[114:117], 0
	v_mfma_f32_16x16x32_bf16 v[4:7], v[4:7], v[126:129], 0
	v_mfma_f32_16x16x32_bf16 v[138:141], v[8:11], v[92:95], v[138:141]
	v_mfma_f32_16x16x32_bf16 v[156:159], v[8:11], v[110:113], v[156:159]
	v_mfma_f32_16x16x32_bf16 v[164:167], v[8:11], v[122:125], v[164:167]
	v_mfma_f32_16x16x32_bf16 v[4:7], v[8:11], v[130:133], v[4:7]
	v_mfma_f32_16x16x32_bf16 v[8:11], v[12:15], v[126:129], 0
	v_mfma_f32_16x16x32_bf16 v[152:155], v[12:15], v[64:67], 0
	v_mfma_f32_16x16x32_bf16 v[160:163], v[12:15], v[96:99], 0
	v_mfma_f32_16x16x32_bf16 v[168:171], v[12:15], v[114:117], 0
	v_mfma_f32_16x16x32_bf16 v[8:11], v[16:19], v[130:133], v[8:11]
	v_mfma_f32_16x16x32_bf16 v[152:155], v[16:19], v[92:95], v[152:155]
	v_mfma_f32_16x16x32_bf16 v[160:163], v[16:19], v[110:113], v[160:163]
	v_mfma_f32_16x16x32_bf16 v[168:171], v[16:19], v[122:125], v[168:171]
	s_setprio 0
	s_setprio 1
	v_mfma_f32_16x16x32_bf16 v[12:15], v[20:23], v[64:67], 0
	v_mfma_f32_16x16x32_bf16 v[172:175], v[24:27], v[92:95], v[12:15]
	v_mfma_f32_16x16x32_bf16 v[12:15], v[28:31], v[64:67], 0
	v_mfma_f32_16x16x32_bf16 v[176:179], v[32:35], v[92:95], v[12:15]
	v_mfma_f32_16x16x32_bf16 v[12:15], v[20:23], v[96:99], 0
	v_mfma_f32_16x16x32_bf16 v[180:183], v[24:27], v[110:113], v[12:15]
	v_mfma_f32_16x16x32_bf16 v[12:15], v[28:31], v[96:99], 0
	v_mfma_f32_16x16x32_bf16 v[184:187], v[32:35], v[110:113], v[12:15]
	v_mfma_f32_16x16x32_bf16 v[12:15], v[20:23], v[114:117], 0
	v_mfma_f32_16x16x32_bf16 v[188:191], v[24:27], v[122:125], v[12:15]
	v_mfma_f32_16x16x32_bf16 v[12:15], v[28:31], v[114:117], 0
	v_mfma_f32_16x16x32_bf16 v[192:195], v[32:35], v[122:125], v[12:15]
	v_mfma_f32_16x16x32_bf16 v[12:15], v[20:23], v[126:129], 0
	v_mfma_f32_16x16x32_bf16 v[196:199], v[24:27], v[130:133], v[12:15]
	v_mfma_f32_16x16x32_bf16 v[12:15], v[28:31], v[126:129], 0
	v_mfma_f32_16x16x32_bf16 v[200:203], v[32:35], v[130:133], v[12:15]
	s_setprio 0
	s_barrier
; #define PG8_KSETUP() const bool last = (t == nt - 2); const char* a1 = cA + (size_t)(t + 1) * kstep; \
;             const char* a2 = last ? nA : cA + (size_t)(t + 2) * kstep; const char* b2 = last ? nB : cB + (size_t)(t + 2) * kstep; const char* a3 = a2 + kstep; const char* b3 = b2 + kstep; \
;             if (last && has_next) S.a_ready(nxt)
; template <class Epi, class Sched, bool ALIGN_EPI = false, bool SP2 = false>
; __device__ __forceinline__ void gemm_phase(PG8_LAS unsigned char* lds, const Gemm g, const Sched& S, const Epi& E) {
;     ...
;         int t0 = 0;
;         if constexpr (SP2 && Epi::NVM == 16) { if (ui > 0) { const int t = 0; PG8_KSETUP(); PG8_KITER_SP2(24, 24); t0 = 2; } }
	s_nop 4
	ds_read_b128 v[12:15], v150
	ds_read_b128 v[16:19], v150 offset:1024
	ds_read_b128 v[22:25], v150 offset:2048
	ds_read_b128 v[26:29], v150 offset:3072
	ds_read_b128 v[204:207], v151
	ds_read_b128 v[208:211], v151 offset:1024
	ds_read_b128 v[212:215], v151 offset:2048
	ds_read_b128 v[216:219], v151 offset:3072
	ds_read_b128 v[30:33], v149 offset:32768
	ds_read_b128 v[64:67], v149 offset:33792
	ds_read_b128 v[220:223], v149 offset:34816
	ds_read_b128 v[224:227], v149 offset:35840
	ds_read_b128 v[228:231], v149 offset:36864
	ds_read_b128 v[232:235], v149 offset:37888
	ds_read_b128 v[236:239], v149 offset:38912
	ds_read_b128 v[240:243], v149 offset:39936
	s_add_u32 s30, s46, 0x80100
	s_addc_u32 s31, s47, 0
	s_mov_b32 m0, s66
	s_nop 0
	global_load_lds_dwordx4 v1, s[30:31] offset:0
	s_nop 0
	s_mov_b32 m0, s67
	s_nop 0
	global_load_lds_dwordx4 v143, s[30:31] offset:0
	s_waitcnt vmcnt(8)
	s_waitcnt lgkmcnt(0)
	s_barrier
	s_setprio 1
	v_mfma_f32_16x16x32_bf16 v[68:71], v[12:15], v[30:33], v[68:71]
	v_mfma_f32_16x16x32_bf16 v[130:133], v[16:19], v[64:67], v[68:71]
	v_mfma_f32_16x16x32_bf16 v[68:71], v[22:25], v[30:33], v[72:75]
	v_mfma_f32_16x16x32_bf16 v[126:129], v[26:29], v[64:67], v[68:71]
	v_mfma_f32_16x16x32_bf16 v[68:71], v[12:15], v[220:223], v[76:79]
	v_mfma_f32_16x16x32_bf16 v[114:117], v[16:19], v[224:227], v[68:71]
	v_mfma_f32_16x16x32_bf16 v[68:71], v[22:25], v[220:223], v[80:83]
	v_mfma_f32_16x16x32_bf16 v[110:113], v[26:29], v[224:227], v[68:71]
	v_mfma_f32_16x16x32_bf16 v[68:71], v[12:15], v[228:231], v[84:87]
	v_mfma_f32_16x16x32_bf16 v[98:101], v[16:19], v[232:235], v[68:71]
	v_mfma_f32_16x16x32_bf16 v[68:71], v[22:25], v[228:231], v[88:91]
	v_mfma_f32_16x16x32_bf16 v[94:97], v[26:29], v[232:235], v[68:71]
	v_mfma_f32_16x16x32_bf16 v[68:71], v[12:15], v[236:239], v[102:105]
	v_mfma_f32_16x16x32_bf16 v[82:85], v[16:19], v[240:243], v[68:71]
	v_mfma_f32_16x16x32_bf16 v[68:71], v[22:25], v[236:239], v[106:109]
	v_mfma_f32_16x16x32_bf16 v[78:81], v[26:29], v[240:243], v[68:71]
	s_setprio 0
	s_setprio 1
	v_mfma_f32_16x16x32_bf16 v[68:71], v[204:207], v[30:33], v[118:121]
	v_mfma_f32_16x16x32_bf16 v[30:33], v[212:215], v[30:33], v[36:39]
	v_mfma_f32_16x16x32_bf16 v[118:121], v[216:219], v[64:67], v[30:33]
	v_mfma_f32_16x16x32_bf16 v[30:33], v[204:207], v[220:223], v[40:43]
	v_mfma_f32_16x16x32_bf16 v[106:109], v[208:211], v[224:227], v[30:33]
	v_mfma_f32_16x16x32_bf16 v[30:33], v[212:215], v[220:223], v[44:47]
	v_mfma_f32_16x16x32_bf16 v[102:105], v[216:219], v[224:227], v[30:33]
	v_mfma_f32_16x16x32_bf16 v[30:33], v[204:207], v[228:231], v[48:51]
	v_mfma_f32_16x16x32_bf16 v[90:93], v[208:211], v[232:235], v[30:33]
	v_mfma_f32_16x16x32_bf16 v[30:33], v[212:215], v[228:231], v[52:55]
	v_mfma_f32_16x16x32_bf16 v[86:89], v[216:219], v[232:235], v[30:33]
	v_mfma_f32_16x16x32_bf16 v[30:33], v[204:207], v[236:239], v[56:59]
	v_mfma_f32_16x16x32_bf16 v[74:77], v[208:211], v[240:243], v[30:33]
	v_mfma_f32_16x16x32_bf16 v[30:33], v[212:215], v[236:239], v[60:63]
	v_mfma_f32_16x16x32_bf16 v[122:125], v[208:211], v[64:67], v[68:71]
	v_mfma_f32_16x16x32_bf16 v[70:73], v[216:219], v[240:243], v[30:33]
	s_setprio 0
	s_barrier
	ds_read_b128 v[38:41], v149 offset:49152
	ds_read_b128 v[42:45], v149 offset:50176
	ds_read_b128 v[220:223], v149 offset:51200
	ds_read_b128 v[224:227], v149 offset:52224
	ds_read_b128 v[228:231], v149 offset:53248
	ds_read_b128 v[232:235], v149 offset:54272
	ds_read_b128 v[236:239], v149 offset:55296
	ds_read_b128 v[240:243], v149 offset:56320
	s_add_u32 s30, s54, 0x180
	s_addc_u32 s31, s55, 0
	s_mov_b32 m0, s71
	s_nop 0
	global_load_lds_dwordx4 v142, s[30:31] offset:0
	s_nop 0
	s_mov_b32 m0, s72
	s_nop 0
	global_load_lds_dwordx4 v144, s[30:31] offset:0
	s_add_u32 s30, s54, 0x80180
	s_addc_u32 s31, s55, 0
	s_mov_b32 m0, s75
	s_nop 0
	global_load_lds_dwordx4 v142, s[30:31] offset:0
	s_nop 0
	s_mov_b32 m0, s76
	s_nop 0
	global_load_lds_dwordx4 v144, s[30:31] offset:0
	s_nop 0
	s_mov_b32 m0, s73
	s_nop 0
	global_load_lds_dwordx4 v1, s[38:39] offset:0
	s_nop 0
	s_mov_b32 m0, s74
	s_nop 0
	global_load_lds_dwordx4 v143, s[38:39] offset:0
	s_waitcnt vmcnt(8)
	s_waitcnt lgkmcnt(0)
	s_barrier
	s_setprio 1
	v_mfma_f32_16x16x32_bf16 v[30:33], v[12:15], v[38:41], v[138:141]
	v_mfma_f32_16x16x32_bf16 v[66:69], v[16:19], v[42:45], v[30:33]
	v_mfma_f32_16x16x32_bf16 v[30:33], v[22:25], v[38:41], v[152:155]
	v_mfma_f32_16x16x32_bf16 v[62:65], v[26:29], v[42:45], v[30:33]
	v_mfma_f32_16x16x32_bf16 v[30:33], v[12:15], v[220:223], v[156:159]
	v_mfma_f32_16x16x32_bf16 v[50:53], v[16:19], v[224:227], v[30:33]
	v_mfma_f32_16x16x32_bf16 v[30:33], v[22:25], v[220:223], v[160:163]
	v_mfma_f32_16x16x32_bf16 v[46:49], v[26:29], v[224:227], v[30:33]
	v_mfma_f32_16x16x32_bf16 v[30:33], v[12:15], v[228:231], v[164:167]
	v_mfma_f32_16x16x32_bf16 v[4:7], v[12:15], v[236:239], v[4:7]
	v_mfma_f32_16x16x32_bf16 v[34:37], v[16:19], v[232:235], v[30:33]
	v_mfma_f32_16x16x32_bf16 v[30:33], v[22:25], v[228:231], v[168:171]
	v_mfma_f32_16x16x32_bf16 v[18:21], v[16:19], v[240:243], v[4:7]
	v_mfma_f32_16x16x32_bf16 v[4:7], v[22:25], v[236:239], v[8:11]
	v_mfma_f32_16x16x32_bf16 v[30:33], v[26:29], v[232:235], v[30:33]
	v_mfma_f32_16x16x32_bf16 v[14:17], v[26:29], v[240:243], v[4:7]
	s_setprio 0
	s_setprio 1
	v_mfma_f32_16x16x32_bf16 v[4:7], v[204:207], v[38:41], v[172:175]
	v_mfma_f32_16x16x32_bf16 v[58:61], v[208:211], v[42:45], v[4:7]
	v_mfma_f32_16x16x32_bf16 v[4:7], v[212:215], v[38:41], v[176:179]
	v_mfma_f32_16x16x32_bf16 v[54:57], v[216:219], v[42:45], v[4:7]
	v_mfma_f32_16x16x32_bf16 v[4:7], v[204:207], v[220:223], v[180:183]
	v_mfma_f32_16x16x32_bf16 v[42:45], v[208:211], v[224:227], v[4:7]
	v_mfma_f32_16x16x32_bf16 v[4:7], v[212:215], v[220:223], v[184:187]
	v_mfma_f32_16x16x32_bf16 v[38:41], v[216:219], v[224:227], v[4:7]
	v_mfma_f32_16x16x32_bf16 v[4:7], v[204:207], v[228:231], v[188:191]
	v_mfma_f32_16x16x32_bf16 v[26:29], v[208:211], v[232:235], v[4:7]
	v_mfma_f32_16x16x32_bf16 v[4:7], v[212:215], v[228:231], v[192:195]
	v_mfma_f32_16x16x32_bf16 v[22:25], v[216:219], v[232:235], v[4:7]
	v_mfma_f32_16x16x32_bf16 v[4:7], v[204:207], v[236:239], v[196:199]
	v_mfma_f32_16x16x32_bf16 v[10:13], v[208:211], v[240:243], v[4:7]
	v_mfma_f32_16x16x32_bf16 v[4:7], v[212:215], v[236:239], v[200:203]
	v_mfma_f32_16x16x32_bf16 v[6:9], v[216:219], v[240:243], v[4:7]
	s_setprio 0
	s_barrier
	s_mov_b32 s56, 2
	s_branch .LBB0_2713

; #define PG8_KSETUP() const bool last = (t == nt - 2); const char* a1 = cA + (size_t)(t + 1) * kstep; \
;             const char* a2 = last ? nA : cA + (size_t)(t + 2) * kstep; const char* b2 = last ? nB : cB + (size_t)(t + 2) * kstep; const char* a3 = a2 + kstep; const char* b3 = b2 + kstep; \
;             if (last && has_next) S.a_ready(nxt)
; template <class Epi, class Sched, bool ALIGN_EPI = false, bool SP2 = false>
; __device__ __forceinline__ void gemm_phase(PG8_LAS unsigned char* lds, const Gemm g, const Sched& S, const Epi& E) {
;     ...
;         int t0 = 0;
;         if constexpr (SP2 && Epi::NVM == 16) { if (ui > 0) { const int t = 0; PG8_KSETUP(); PG8_KITER_SP2(24, 24); t0 = 2; } }
;         if constexpr (SP2 && Epi::NVM == 8) { if (ui > 0) { const int t = 0; PG8_KSETUP(); PG8_KITER_SP2(16, 16); t0 = 2; } }
;         for (int t = t0; t < nt; t += 2) {
.LBB0_2714:
	ds_read_b128 v[138:141], v147
	ds_read_b128 v[152:155], v147 offset:1024
	ds_read_b128 v[156:159], v147 offset:2048
	ds_read_b128 v[160:163], v147 offset:3072
	ds_read_b128 v[164:167], v148
	ds_read_b128 v[168:171], v148 offset:1024
	ds_read_b128 v[172:175], v148 offset:2048
	ds_read_b128 v[176:179], v148 offset:3072
	s_cmp_eq_u32 s84, 28
	s_cselect_b32 s58, s43, s87
	s_cselect_b32 s59, s37, s88
	s_cselect_b32 s56, s83, s85
	s_cselect_b32 s57, s29, s86
	s_add_u32 s54, s58, 0x80
	s_addc_u32 s55, s59, 0
	ds_read_b128 v[180:183], v149
	ds_read_b128 v[184:187], v149 offset:1024
	ds_read_b128 v[188:191], v149 offset:2048
	ds_read_b128 v[192:195], v149 offset:3072
	ds_read_b128 v[196:199], v149 offset:4096
	ds_read_b128 v[200:203], v149 offset:5120
	ds_read_b128 v[204:207], v149 offset:6144
	ds_read_b128 v[208:211], v149 offset:7168
	s_mov_b32 m0, s77
	s_nop 0
	global_load_lds_dwordx4 v1, s[46:47] offset:0
	s_nop 0
	s_mov_b32 m0, s78
	s_nop 0
	global_load_lds_dwordx4 v143, s[46:47] offset:0
	s_waitcnt vmcnt(8)
	s_waitcnt lgkmcnt(0)
	s_barrier
	s_setprio 1
	v_mfma_f32_16x16x32_bf16 v[130:133], v[138:141], v[180:183], v[130:133]
	v_mfma_f32_16x16x32_bf16 v[130:133], v[152:155], v[184:187], v[130:133]
	v_mfma_f32_16x16x32_bf16 v[126:129], v[156:159], v[180:183], v[126:129]
	v_mfma_f32_16x16x32_bf16 v[126:129], v[160:163], v[184:187], v[126:129]
	v_mfma_f32_16x16x32_bf16 v[114:117], v[138:141], v[188:191], v[114:117]
	v_mfma_f32_16x16x32_bf16 v[114:117], v[152:155], v[192:195], v[114:117]
	v_mfma_f32_16x16x32_bf16 v[110:113], v[156:159], v[188:191], v[110:113]
	v_mfma_f32_16x16x32_bf16 v[110:113], v[160:163], v[192:195], v[110:113]
	v_mfma_f32_16x16x32_bf16 v[98:101], v[138:141], v[196:199], v[98:101]
	v_mfma_f32_16x16x32_bf16 v[98:101], v[152:155], v[200:203], v[98:101]
	v_mfma_f32_16x16x32_bf16 v[94:97], v[156:159], v[196:199], v[94:97]
	v_mfma_f32_16x16x32_bf16 v[94:97], v[160:163], v[200:203], v[94:97]
	v_mfma_f32_16x16x32_bf16 v[82:85], v[138:141], v[204:207], v[82:85]
	v_mfma_f32_16x16x32_bf16 v[82:85], v[152:155], v[208:211], v[82:85]
	v_mfma_f32_16x16x32_bf16 v[78:81], v[156:159], v[204:207], v[78:81]
	v_mfma_f32_16x16x32_bf16 v[78:81], v[160:163], v[208:211], v[78:81]
	s_setprio 0
	s_setprio 1
	v_mfma_f32_16x16x32_bf16 v[122:125], v[164:167], v[180:183], v[122:125]
	v_mfma_f32_16x16x32_bf16 v[122:125], v[168:171], v[184:187], v[122:125]
	v_mfma_f32_16x16x32_bf16 v[118:121], v[172:175], v[180:183], v[118:121]
	v_mfma_f32_16x16x32_bf16 v[118:121], v[176:179], v[184:187], v[118:121]
	v_mfma_f32_16x16x32_bf16 v[106:109], v[164:167], v[188:191], v[106:109]
	v_mfma_f32_16x16x32_bf16 v[106:109], v[168:171], v[192:195], v[106:109]
	v_mfma_f32_16x16x32_bf16 v[102:105], v[172:175], v[188:191], v[102:105]
	v_mfma_f32_16x16x32_bf16 v[102:105], v[176:179], v[192:195], v[102:105]
	v_mfma_f32_16x16x32_bf16 v[90:93], v[164:167], v[196:199], v[90:93]
	v_mfma_f32_16x16x32_bf16 v[90:93], v[168:171], v[200:203], v[90:93]
	v_mfma_f32_16x16x32_bf16 v[86:89], v[172:175], v[196:199], v[86:89]
	v_mfma_f32_16x16x32_bf16 v[86:89], v[176:179], v[200:203], v[86:89]
	v_mfma_f32_16x16x32_bf16 v[74:77], v[164:167], v[204:207], v[74:77]
	v_mfma_f32_16x16x32_bf16 v[74:77], v[168:171], v[208:211], v[74:77]
	v_mfma_f32_16x16x32_bf16 v[70:73], v[172:175], v[204:207], v[70:73]
	v_mfma_f32_16x16x32_bf16 v[70:73], v[176:179], v[208:211], v[70:73]
	s_setprio 0
	s_barrier
	ds_read_b128 v[180:183], v149 offset:16384
	ds_read_b128 v[184:187], v149 offset:17408
	ds_read_b128 v[188:191], v149 offset:18432
	ds_read_b128 v[192:195], v149 offset:19456
	ds_read_b128 v[196:199], v149 offset:20480
	ds_read_b128 v[200:203], v149 offset:21504
	ds_read_b128 v[204:207], v149 offset:22528
	ds_read_b128 v[208:211], v149 offset:23552
	s_mov_b32 m0, s45
	s_nop 0
	global_load_lds_dwordx4 v142, s[56:57] offset:0
	s_add_u32 s30, s56, 0x80000
	s_mov_b32 m0, s52
	s_nop 0
	global_load_lds_dwordx4 v144, s[56:57] offset:0
	s_addc_u32 s31, s57, 0
	s_mov_b32 m0, s53
	s_nop 0
	global_load_lds_dwordx4 v142, s[30:31] offset:0
	s_nop 0
	s_mov_b32 m0, s64
	s_nop 0
	global_load_lds_dwordx4 v144, s[30:31] offset:0
	s_nop 0
	s_mov_b32 m0, s33
	s_nop 0
	global_load_lds_dwordx4 v1, s[58:59] offset:0
	s_nop 0
	s_mov_b32 m0, s65
	s_nop 0
	global_load_lds_dwordx4 v143, s[58:59] offset:0
	s_waitcnt vmcnt(8)
	s_waitcnt lgkmcnt(0)
	s_barrier
	s_setprio 1
	v_mfma_f32_16x16x32_bf16 v[66:69], v[138:141], v[180:183], v[66:69]
	v_mfma_f32_16x16x32_bf16 v[66:69], v[152:155], v[184:187], v[66:69]
	v_mfma_f32_16x16x32_bf16 v[62:65], v[156:159], v[180:183], v[62:65]
	v_mfma_f32_16x16x32_bf16 v[62:65], v[160:163], v[184:187], v[62:65]
	v_mfma_f32_16x16x32_bf16 v[50:53], v[138:141], v[188:191], v[50:53]
	v_mfma_f32_16x16x32_bf16 v[50:53], v[152:155], v[192:195], v[50:53]
	v_mfma_f32_16x16x32_bf16 v[46:49], v[156:159], v[188:191], v[46:49]
	v_mfma_f32_16x16x32_bf16 v[46:49], v[160:163], v[192:195], v[46:49]
	v_mfma_f32_16x16x32_bf16 v[34:37], v[138:141], v[196:199], v[34:37]
	v_mfma_f32_16x16x32_bf16 v[34:37], v[152:155], v[200:203], v[34:37]
	v_mfma_f32_16x16x32_bf16 v[30:33], v[156:159], v[196:199], v[30:33]
	v_mfma_f32_16x16x32_bf16 v[30:33], v[160:163], v[200:203], v[30:33]
	v_mfma_f32_16x16x32_bf16 v[18:21], v[138:141], v[204:207], v[18:21]
	v_mfma_f32_16x16x32_bf16 v[18:21], v[152:155], v[208:211], v[18:21]
	v_mfma_f32_16x16x32_bf16 v[14:17], v[156:159], v[204:207], v[14:17]
	v_mfma_f32_16x16x32_bf16 v[14:17], v[160:163], v[208:211], v[14:17]
	s_setprio 0
	s_setprio 1
	v_mfma_f32_16x16x32_bf16 v[58:61], v[164:167], v[180:183], v[58:61]
	v_mfma_f32_16x16x32_bf16 v[54:57], v[172:175], v[180:183], v[54:57]
	v_mfma_f32_16x16x32_bf16 v[42:45], v[164:167], v[188:191], v[42:45]
	v_mfma_f32_16x16x32_bf16 v[38:41], v[172:175], v[188:191], v[38:41]
	v_mfma_f32_16x16x32_bf16 v[26:29], v[164:167], v[196:199], v[26:29]
	v_mfma_f32_16x16x32_bf16 v[22:25], v[172:175], v[196:199], v[22:25]
	v_mfma_f32_16x16x32_bf16 v[10:13], v[164:167], v[204:207], v[10:13]
	v_mfma_f32_16x16x32_bf16 v[4:7], v[172:175], v[204:207], v[6:9]
	v_mfma_f32_16x16x32_bf16 v[58:61], v[168:171], v[184:187], v[58:61]
	v_mfma_f32_16x16x32_bf16 v[54:57], v[176:179], v[184:187], v[54:57]
	v_mfma_f32_16x16x32_bf16 v[42:45], v[168:171], v[192:195], v[42:45]
	v_mfma_f32_16x16x32_bf16 v[38:41], v[176:179], v[192:195], v[38:41]
	v_mfma_f32_16x16x32_bf16 v[26:29], v[168:171], v[200:203], v[26:29]
	v_mfma_f32_16x16x32_bf16 v[22:25], v[176:179], v[200:203], v[22:25]
	v_mfma_f32_16x16x32_bf16 v[10:13], v[168:171], v[208:211], v[10:13]
	v_mfma_f32_16x16x32_bf16 v[4:7], v[176:179], v[208:211], v[4:7]
	s_setprio 0
	s_barrier
; #define PG8_BAR __builtin_amdgcn_s_barrier()
; #define PG8_KSETUP() const bool last = (t == nt - 2); const char* a1 = cA + (size_t)(t + 1) * kstep; \
;             const char* a2 = last ? nA : cA + (size_t)(t + 2) * kstep; const char* b2 = last ? nB : cB + (size_t)(t + 2) * kstep; const char* a3 = a2 + kstep; const char* b3 = b2 + kstep; \
;             if (last && has_next) S.a_ready(nxt)
; template <class Epi, class Sched, bool ALIGN_EPI = false, bool SP2 = false>
; __device__ __forceinline__ void gemm_phase(PG8_LAS unsigned char* lds, const Gemm g, const Sched& S, const Epi& E) {
;     ...
;         int t0 = 0;
;         if constexpr (SP2 && Epi::NVM == 16) { if (ui > 0) { const int t = 0; PG8_KSETUP(); PG8_KITER_SP2(24, 24); t0 = 2; } }
;         if constexpr (SP2 && Epi::NVM == 8) { if (ui > 0) { const int t = 0; PG8_KSETUP(); PG8_KITER_SP2(16, 16); t0 = 2; } }
;         for (int t = t0; t < nt; t += 2) {
;     ...
;         if constexpr (ALIGN_EPI) { if (wr == 0) PG8_BAR; }
	ds_read_b128 v[138:141], v150
	ds_read_b128 v[152:155], v150 offset:1024
	ds_read_b128 v[156:159], v150 offset:2048
	ds_read_b128 v[160:163], v150 offset:3072
	ds_read_b128 v[164:167], v151
	ds_read_b128 v[168:171], v151 offset:1024
	ds_read_b128 v[172:175], v151 offset:2048
	ds_read_b128 v[176:179], v151 offset:3072
	ds_read_b128 v[180:183], v149 offset:32768
	ds_read_b128 v[184:187], v149 offset:33792
	ds_read_b128 v[188:191], v149 offset:34816
	ds_read_b128 v[192:195], v149 offset:35840
	ds_read_b128 v[196:199], v149 offset:36864
	ds_read_b128 v[200:203], v149 offset:37888
	ds_read_b128 v[204:207], v149 offset:38912
	ds_read_b128 v[208:211], v149 offset:39936
	s_add_u32 s30, s58, 0x80000
	s_addc_u32 s31, s59, 0
	s_mov_b32 m0, s66
	s_nop 0
	global_load_lds_dwordx4 v1, s[30:31] offset:0
	s_nop 0
	s_mov_b32 m0, s67
	s_nop 0
	global_load_lds_dwordx4 v143, s[30:31] offset:0
	s_waitcnt vmcnt(8)
	s_waitcnt lgkmcnt(0)
	s_barrier
	s_setprio 1
	v_mfma_f32_16x16x32_bf16 v[130:133], v[138:141], v[180:183], v[130:133]
	v_mfma_f32_16x16x32_bf16 v[130:133], v[152:155], v[184:187], v[130:133]
	v_mfma_f32_16x16x32_bf16 v[126:129], v[156:159], v[180:183], v[126:129]
	v_mfma_f32_16x16x32_bf16 v[126:129], v[160:163], v[184:187], v[126:129]
	v_mfma_f32_16x16x32_bf16 v[114:117], v[138:141], v[188:191], v[114:117]
	v_mfma_f32_16x16x32_bf16 v[114:117], v[152:155], v[192:195], v[114:117]
	v_mfma_f32_16x16x32_bf16 v[110:113], v[156:159], v[188:191], v[110:113]
	v_mfma_f32_16x16x32_bf16 v[110:113], v[160:163], v[192:195], v[110:113]
	v_mfma_f32_16x16x32_bf16 v[98:101], v[138:141], v[196:199], v[98:101]
	v_mfma_f32_16x16x32_bf16 v[98:101], v[152:155], v[200:203], v[98:101]
	v_mfma_f32_16x16x32_bf16 v[94:97], v[156:159], v[196:199], v[94:97]
	v_mfma_f32_16x16x32_bf16 v[94:97], v[160:163], v[200:203], v[94:97]
	v_mfma_f32_16x16x32_bf16 v[82:85], v[138:141], v[204:207], v[82:85]
	v_mfma_f32_16x16x32_bf16 v[82:85], v[152:155], v[208:211], v[82:85]
	v_mfma_f32_16x16x32_bf16 v[78:81], v[156:159], v[204:207], v[78:81]
	v_mfma_f32_16x16x32_bf16 v[78:81], v[160:163], v[208:211], v[78:81]
	s_setprio 0
	s_setprio 1
	v_mfma_f32_16x16x32_bf16 v[122:125], v[164:167], v[180:183], v[122:125]
	v_mfma_f32_16x16x32_bf16 v[122:125], v[168:171], v[184:187], v[122:125]
	v_mfma_f32_16x16x32_bf16 v[118:121], v[172:175], v[180:183], v[118:121]
	v_mfma_f32_16x16x32_bf16 v[118:121], v[176:179], v[184:187], v[118:121]
	v_mfma_f32_16x16x32_bf16 v[106:109], v[164:167], v[188:191], v[106:109]
	v_mfma_f32_16x16x32_bf16 v[106:109], v[168:171], v[192:195], v[106:109]
	v_mfma_f32_16x16x32_bf16 v[102:105], v[172:175], v[188:191], v[102:105]
	v_mfma_f32_16x16x32_bf16 v[102:105], v[176:179], v[192:195], v[102:105]
	v_mfma_f32_16x16x32_bf16 v[90:93], v[164:167], v[196:199], v[90:93]
	v_mfma_f32_16x16x32_bf16 v[90:93], v[168:171], v[200:203], v[90:93]
	v_mfma_f32_16x16x32_bf16 v[86:89], v[172:175], v[196:199], v[86:89]
	v_mfma_f32_16x16x32_bf16 v[86:89], v[176:179], v[200:203], v[86:89]
	v_mfma_f32_16x16x32_bf16 v[74:77], v[164:167], v[204:207], v[74:77]
	v_mfma_f32_16x16x32_bf16 v[74:77], v[168:171], v[208:211], v[74:77]
	v_mfma_f32_16x16x32_bf16 v[70:73], v[172:175], v[204:207], v[70:73]
	v_mfma_f32_16x16x32_bf16 v[70:73], v[176:179], v[208:211], v[70:73]
	s_setprio 0
	s_barrier
	ds_read_b128 v[180:183], v149 offset:49152
	ds_read_b128 v[184:187], v149 offset:50176
	ds_read_b128 v[188:191], v149 offset:51200
	ds_read_b128 v[192:195], v149 offset:52224
	ds_read_b128 v[196:199], v149 offset:53248
	ds_read_b128 v[200:203], v149 offset:54272
	ds_read_b128 v[204:207], v149 offset:55296
	ds_read_b128 v[208:211], v149 offset:56320
	s_add_u32 s30, s56, 0x80
	s_addc_u32 s31, s57, 0
	s_mov_b32 m0, s71
	s_nop 0
	global_load_lds_dwordx4 v142, s[30:31] offset:0
	s_nop 0
	s_mov_b32 m0, s72
	s_nop 0
	global_load_lds_dwordx4 v144, s[30:31] offset:0
	s_add_u32 s30, s56, 0x80080
	s_addc_u32 s31, s57, 0
	s_mov_b32 m0, s75
	s_nop 0
	global_load_lds_dwordx4 v142, s[30:31] offset:0
	s_nop 0
	s_mov_b32 m0, s76
	s_nop 0
	global_load_lds_dwordx4 v144, s[30:31] offset:0
	s_nop 0
	s_mov_b32 m0, s73
	s_nop 0
	global_load_lds_dwordx4 v1, s[54:55] offset:0
	s_nop 0
	s_mov_b32 m0, s74
	s_nop 0
	global_load_lds_dwordx4 v143, s[54:55] offset:0
	s_waitcnt vmcnt(8)
	s_waitcnt lgkmcnt(0)
	s_barrier
	s_setprio 1
	v_mfma_f32_16x16x32_bf16 v[66:69], v[138:141], v[180:183], v[66:69]
	v_mfma_f32_16x16x32_bf16 v[66:69], v[152:155], v[184:187], v[66:69]
	v_mfma_f32_16x16x32_bf16 v[62:65], v[156:159], v[180:183], v[62:65]
	v_mfma_f32_16x16x32_bf16 v[62:65], v[160:163], v[184:187], v[62:65]
	v_mfma_f32_16x16x32_bf16 v[50:53], v[138:141], v[188:191], v[50:53]
	v_mfma_f32_16x16x32_bf16 v[50:53], v[152:155], v[192:195], v[50:53]
	v_mfma_f32_16x16x32_bf16 v[46:49], v[156:159], v[188:191], v[46:49]
	v_mfma_f32_16x16x32_bf16 v[46:49], v[160:163], v[192:195], v[46:49]
	v_mfma_f32_16x16x32_bf16 v[34:37], v[138:141], v[196:199], v[34:37]
	v_mfma_f32_16x16x32_bf16 v[34:37], v[152:155], v[200:203], v[34:37]
	v_mfma_f32_16x16x32_bf16 v[30:33], v[156:159], v[196:199], v[30:33]
	v_mfma_f32_16x16x32_bf16 v[30:33], v[160:163], v[200:203], v[30:33]
	v_mfma_f32_16x16x32_bf16 v[18:21], v[138:141], v[204:207], v[18:21]
	v_mfma_f32_16x16x32_bf16 v[18:21], v[152:155], v[208:211], v[18:21]
	v_mfma_f32_16x16x32_bf16 v[14:17], v[156:159], v[204:207], v[14:17]
	v_mfma_f32_16x16x32_bf16 v[14:17], v[160:163], v[208:211], v[14:17]
	s_setprio 0
	s_setprio 1
	v_mfma_f32_16x16x32_bf16 v[58:61], v[164:167], v[180:183], v[58:61]
	v_mfma_f32_16x16x32_bf16 v[54:57], v[172:175], v[180:183], v[54:57]
	v_mfma_f32_16x16x32_bf16 v[42:45], v[164:167], v[188:191], v[42:45]
	v_mfma_f32_16x16x32_bf16 v[38:41], v[172:175], v[188:191], v[38:41]
	v_mfma_f32_16x16x32_bf16 v[26:29], v[164:167], v[196:199], v[26:29]
	v_mfma_f32_16x16x32_bf16 v[22:25], v[172:175], v[196:199], v[22:25]
	v_mfma_f32_16x16x32_bf16 v[8:11], v[164:167], v[204:207], v[10:13]
	v_mfma_f32_16x16x32_bf16 v[4:7], v[172:175], v[204:207], v[4:7]
	v_mfma_f32_16x16x32_bf16 v[58:61], v[168:171], v[184:187], v[58:61]
	v_mfma_f32_16x16x32_bf16 v[54:57], v[176:179], v[184:187], v[54:57]
	v_mfma_f32_16x16x32_bf16 v[42:45], v[168:171], v[192:195], v[42:45]
	v_mfma_f32_16x16x32_bf16 v[38:41], v[176:179], v[192:195], v[38:41]
	v_mfma_f32_16x16x32_bf16 v[26:29], v[168:171], v[200:203], v[26:29]
	v_mfma_f32_16x16x32_bf16 v[22:25], v[176:179], v[200:203], v[22:25]
	v_mfma_f32_16x16x32_bf16 v[10:13], v[168:171], v[208:211], v[8:11]
	v_mfma_f32_16x16x32_bf16 v[6:9], v[176:179], v[208:211], v[4:7]
	s_setprio 0
	s_barrier
	s_add_i32 s84, s84, 2
	s_add_u32 s85, s85, 0x100
	s_addc_u32 s86, s86, 0
	s_add_u32 s87, s87, 0x100
	s_addc_u32 s88, s88, 0
	s_add_u32 s46, s46, 0x100
	s_addc_u32 s47, s47, 0
	s_cmp_gt_u32 s84, 29
	s_cbranch_scc0 .LBB0_2714
	s_and_b64 vcc, exec, s[18:19]
	s_cbranch_vccz .LBB0_2717
	s_barrier

; #define PG8_KSETUP() const bool last = (t == nt - 2); const char* a1 = cA + (size_t)(t + 1) * kstep; \
;             const char* a2 = last ? nA : cA + (size_t)(t + 2) * kstep; const char* b2 = last ? nB : cB + (size_t)(t + 2) * kstep; const char* a3 = a2 + kstep; const char* b3 = b2 + kstep; \
;             if (last && has_next) S.a_ready(nxt)
; template <class Epi, class Sched, bool ALIGN_EPI = false, bool SP2 = false>
; __device__ __forceinline__ void gemm_phase(PG8_LAS unsigned char* lds, const Gemm g, const Sched& S, const Epi& E) {
;     ...
;         int t0 = 0;
;         if constexpr (SP2 && Epi::NVM == 16) { if (ui > 0) { const int t = 0; PG8_KSETUP(); PG8_KITER_SP2(24, 24); t0 = 2; } }
.LBB0_2869:
	s_cmp_lg_u32 s73, 0
	s_mov_b32 s40, 0
	s_cbranch_scc0 .LBB0_2871
	ds_read_b128 v[4:7], v152
	ds_read_b128 v[8:11], v152 offset:1024
	ds_read_b128 v[12:15], v152 offset:2048
	ds_read_b128 v[16:19], v152 offset:3072
	ds_read_b128 v[20:23], v153
	ds_read_b128 v[24:27], v153 offset:1024
	ds_read_b128 v[28:31], v153 offset:2048
	ds_read_b128 v[32:35], v153 offset:3072
	s_add_u32 s24, s36, 0x100
	s_addc_u32 s25, s37, 0
	s_add_u32 s30, s38, 0x100
	s_addc_u32 s31, s39, 0
	s_add_u32 s22, s36, 0x180
	s_addc_u32 s23, s37, 0
	ds_read_b128 v[36:39], v154
	ds_read_b128 v[40:43], v154 offset:1024
	ds_read_b128 v[44:47], v154 offset:2048
	ds_read_b128 v[48:51], v154 offset:3072
	ds_read_b128 v[52:55], v154 offset:4096
	ds_read_b128 v[56:59], v154 offset:5120
	ds_read_b128 v[60:63], v154 offset:6144
	ds_read_b128 v[64:67], v154 offset:7168
	s_add_u32 s40, s36, 0x80080
	s_addc_u32 s41, s37, 0
	s_mov_b32 m0, s64
	s_nop 0
	global_load_lds_dwordx4 v1, s[40:41] offset:0
	s_nop 0
	s_mov_b32 m0, s65
	s_nop 0
	global_load_lds_dwordx4 v147, s[40:41] offset:0
	s_waitcnt vmcnt(16)
	s_waitcnt lgkmcnt(0)
	s_barrier
	s_setprio 1
	v_mfma_f32_16x16x32_bf16 v[92:95], v[4:7], v[60:63], 0
	v_mfma_f32_16x16x32_bf16 v[68:71], v[4:7], v[36:39], 0
	v_mfma_f32_16x16x32_bf16 v[72:75], v[12:15], v[36:39], 0
	v_mfma_f32_16x16x32_bf16 v[76:79], v[4:7], v[44:47], 0
	v_mfma_f32_16x16x32_bf16 v[80:83], v[12:15], v[44:47], 0
	v_mfma_f32_16x16x32_bf16 v[84:87], v[4:7], v[52:55], 0
	v_mfma_f32_16x16x32_bf16 v[88:91], v[12:15], v[52:55], 0
	v_mfma_f32_16x16x32_bf16 v[102:105], v[8:11], v[64:67], v[92:95]
	v_mfma_f32_16x16x32_bf16 v[92:95], v[12:15], v[60:63], 0
	v_mfma_f32_16x16x32_bf16 v[68:71], v[8:11], v[40:43], v[68:71]
	v_mfma_f32_16x16x32_bf16 v[72:75], v[16:19], v[40:43], v[72:75]
	v_mfma_f32_16x16x32_bf16 v[76:79], v[8:11], v[48:51], v[76:79]
	v_mfma_f32_16x16x32_bf16 v[80:83], v[16:19], v[48:51], v[80:83]
	v_mfma_f32_16x16x32_bf16 v[84:87], v[8:11], v[56:59], v[84:87]
	v_mfma_f32_16x16x32_bf16 v[88:91], v[16:19], v[56:59], v[88:91]
	v_mfma_f32_16x16x32_bf16 v[106:109], v[16:19], v[64:67], v[92:95]
	s_setprio 0
	s_setprio 1
	v_mfma_f32_16x16x32_bf16 v[92:95], v[20:23], v[36:39], 0
	v_mfma_f32_16x16x32_bf16 v[36:39], v[28:31], v[36:39], 0
	v_mfma_f32_16x16x32_bf16 v[118:121], v[24:27], v[40:43], v[92:95]
	v_mfma_f32_16x16x32_bf16 v[36:39], v[32:35], v[40:43], v[36:39]
	v_mfma_f32_16x16x32_bf16 v[40:43], v[20:23], v[44:47], 0
	v_mfma_f32_16x16x32_bf16 v[44:47], v[28:31], v[44:47], 0
	v_mfma_f32_16x16x32_bf16 v[40:43], v[24:27], v[48:51], v[40:43]
	v_mfma_f32_16x16x32_bf16 v[44:47], v[32:35], v[48:51], v[44:47]
	v_mfma_f32_16x16x32_bf16 v[48:51], v[20:23], v[52:55], 0
	v_mfma_f32_16x16x32_bf16 v[52:55], v[28:31], v[52:55], 0
	v_mfma_f32_16x16x32_bf16 v[48:51], v[24:27], v[56:59], v[48:51]
	v_mfma_f32_16x16x32_bf16 v[52:55], v[32:35], v[56:59], v[52:55]
	v_mfma_f32_16x16x32_bf16 v[56:59], v[20:23], v[60:63], 0
	v_mfma_f32_16x16x32_bf16 v[60:63], v[28:31], v[60:63], 0
	v_mfma_f32_16x16x32_bf16 v[56:59], v[24:27], v[64:67], v[56:59]
	v_mfma_f32_16x16x32_bf16 v[60:63], v[32:35], v[64:67], v[60:63]
	s_setprio 0
	s_barrier
	ds_read_b128 v[64:67], v154 offset:16384
	ds_read_b128 v[92:95], v154 offset:17408
	ds_read_b128 v[96:99], v154 offset:18432
	ds_read_b128 v[110:113], v154 offset:19456
	ds_read_b128 v[114:117], v154 offset:20480
	ds_read_b128 v[122:125], v154 offset:21504
	ds_read_b128 v[126:129], v154 offset:22528
	ds_read_b128 v[130:133], v154 offset:23552
	s_mov_b32 m0, s29
	s_nop 0
	global_load_lds_dwordx4 v146, s[30:31] offset:0
	s_nop 0
	s_mov_b32 m0, s44
	s_nop 0
	global_load_lds_dwordx4 v148, s[30:31] offset:0
	s_add_u32 s30, s38, 0x80100
	s_addc_u32 s31, s39, 0
	s_mov_b32 m0, s45
	s_nop 0
	global_load_lds_dwordx4 v146, s[30:31] offset:0
	s_nop 0
	s_mov_b32 m0, s46
	s_nop 0
	global_load_lds_dwordx4 v148, s[30:31] offset:0
	s_nop 0
	s_mov_b32 m0, s21
	s_nop 0
	global_load_lds_dwordx4 v1, s[24:25] offset:0
	s_nop 0
	s_mov_b32 m0, s47
	s_nop 0
	global_load_lds_dwordx4 v147, s[24:25] offset:0
	s_waitcnt vmcnt(16)
	s_waitcnt lgkmcnt(0)
	s_barrier
	s_setprio 1
	v_mfma_f32_16x16x32_bf16 v[138:141], v[4:7], v[64:67], 0
	v_mfma_f32_16x16x32_bf16 v[158:161], v[4:7], v[96:99], 0
	v_mfma_f32_16x16x32_bf16 v[166:169], v[4:7], v[114:117], 0
	v_mfma_f32_16x16x32_bf16 v[4:7], v[4:7], v[126:129], 0
	v_mfma_f32_16x16x32_bf16 v[138:141], v[8:11], v[92:95], v[138:141]
	v_mfma_f32_16x16x32_bf16 v[158:161], v[8:11], v[110:113], v[158:161]
	v_mfma_f32_16x16x32_bf16 v[166:169], v[8:11], v[122:125], v[166:169]
	v_mfma_f32_16x16x32_bf16 v[4:7], v[8:11], v[130:133], v[4:7]
	v_mfma_f32_16x16x32_bf16 v[8:11], v[12:15], v[126:129], 0
	v_mfma_f32_16x16x32_bf16 v[142:145], v[12:15], v[64:67], 0
	v_mfma_f32_16x16x32_bf16 v[162:165], v[12:15], v[96:99], 0
	v_mfma_f32_16x16x32_bf16 v[170:173], v[12:15], v[114:117], 0
	v_mfma_f32_16x16x32_bf16 v[8:11], v[16:19], v[130:133], v[8:11]
	v_mfma_f32_16x16x32_bf16 v[142:145], v[16:19], v[92:95], v[142:145]
	v_mfma_f32_16x16x32_bf16 v[162:165], v[16:19], v[110:113], v[162:165]
	v_mfma_f32_16x16x32_bf16 v[170:173], v[16:19], v[122:125], v[170:173]
	s_setprio 0
	s_setprio 1
	v_mfma_f32_16x16x32_bf16 v[12:15], v[20:23], v[64:67], 0
	v_mfma_f32_16x16x32_bf16 v[174:177], v[24:27], v[92:95], v[12:15]
	v_mfma_f32_16x16x32_bf16 v[12:15], v[28:31], v[64:67], 0
	v_mfma_f32_16x16x32_bf16 v[178:181], v[32:35], v[92:95], v[12:15]
	v_mfma_f32_16x16x32_bf16 v[12:15], v[20:23], v[96:99], 0
	v_mfma_f32_16x16x32_bf16 v[182:185], v[24:27], v[110:113], v[12:15]
	v_mfma_f32_16x16x32_bf16 v[12:15], v[28:31], v[96:99], 0
	v_mfma_f32_16x16x32_bf16 v[186:189], v[32:35], v[110:113], v[12:15]
	v_mfma_f32_16x16x32_bf16 v[12:15], v[20:23], v[114:117], 0
	v_mfma_f32_16x16x32_bf16 v[190:193], v[24:27], v[122:125], v[12:15]
	v_mfma_f32_16x16x32_bf16 v[12:15], v[28:31], v[114:117], 0
	v_mfma_f32_16x16x32_bf16 v[194:197], v[32:35], v[122:125], v[12:15]
	v_mfma_f32_16x16x32_bf16 v[12:15], v[20:23], v[126:129], 0
	v_mfma_f32_16x16x32_bf16 v[198:201], v[24:27], v[130:133], v[12:15]
	v_mfma_f32_16x16x32_bf16 v[12:15], v[28:31], v[126:129], 0
	v_mfma_f32_16x16x32_bf16 v[202:205], v[32:35], v[130:133], v[12:15]
	s_setprio 0
	s_barrier
; #define PG8_KSETUP() const bool last = (t == nt - 2); const char* a1 = cA + (size_t)(t + 1) * kstep; \
;             const char* a2 = last ? nA : cA + (size_t)(t + 2) * kstep; const char* b2 = last ? nB : cB + (size_t)(t + 2) * kstep; const char* a3 = a2 + kstep; const char* b3 = b2 + kstep; \
;             if (last && has_next) S.a_ready(nxt)
; template <class Epi, class Sched, bool ALIGN_EPI = false, bool SP2 = false>
; __device__ __forceinline__ void gemm_phase(PG8_LAS unsigned char* lds, const Gemm g, const Sched& S, const Epi& E) {
;     ...
;         int t0 = 0;
;         if constexpr (SP2 && Epi::NVM == 16) { if (ui > 0) { const int t = 0; PG8_KSETUP(); PG8_KITER_SP2(24, 24); t0 = 2; } }
	s_nop 4
	ds_read_b128 v[12:15], v155
	ds_read_b128 v[16:19], v155 offset:1024
	ds_read_b128 v[22:25], v155 offset:2048
	ds_read_b128 v[26:29], v155 offset:3072
	ds_read_b128 v[206:209], v156
	ds_read_b128 v[210:213], v156 offset:1024
	ds_read_b128 v[214:217], v156 offset:2048
	ds_read_b128 v[218:221], v156 offset:3072
	ds_read_b128 v[30:33], v154 offset:32768
	ds_read_b128 v[64:67], v154 offset:33792
	ds_read_b128 v[222:225], v154 offset:34816
	ds_read_b128 v[226:229], v154 offset:35840
	ds_read_b128 v[230:233], v154 offset:36864
	ds_read_b128 v[234:237], v154 offset:37888
	ds_read_b128 v[238:241], v154 offset:38912
	ds_read_b128 v[242:245], v154 offset:39936
	s_add_u32 s24, s36, 0x80100
	s_addc_u32 s25, s37, 0
	s_mov_b32 m0, s52
	s_nop 0
	global_load_lds_dwordx4 v1, s[24:25] offset:0
	s_nop 0
	s_mov_b32 m0, s53
	s_nop 0
	global_load_lds_dwordx4 v147, s[24:25] offset:0
	s_waitcnt vmcnt(8)
	s_waitcnt lgkmcnt(0)
	s_barrier
	s_setprio 1
	v_mfma_f32_16x16x32_bf16 v[68:71], v[12:15], v[30:33], v[68:71]
	v_mfma_f32_16x16x32_bf16 v[130:133], v[16:19], v[64:67], v[68:71]
	v_mfma_f32_16x16x32_bf16 v[68:71], v[22:25], v[30:33], v[72:75]
	v_mfma_f32_16x16x32_bf16 v[126:129], v[26:29], v[64:67], v[68:71]
	v_mfma_f32_16x16x32_bf16 v[68:71], v[12:15], v[222:225], v[76:79]
	v_mfma_f32_16x16x32_bf16 v[114:117], v[16:19], v[226:229], v[68:71]
	v_mfma_f32_16x16x32_bf16 v[68:71], v[22:25], v[222:225], v[80:83]
	v_mfma_f32_16x16x32_bf16 v[110:113], v[26:29], v[226:229], v[68:71]
	v_mfma_f32_16x16x32_bf16 v[68:71], v[12:15], v[230:233], v[84:87]
	v_mfma_f32_16x16x32_bf16 v[98:101], v[16:19], v[234:237], v[68:71]
	v_mfma_f32_16x16x32_bf16 v[68:71], v[22:25], v[230:233], v[88:91]
	v_mfma_f32_16x16x32_bf16 v[94:97], v[26:29], v[234:237], v[68:71]
	v_mfma_f32_16x16x32_bf16 v[68:71], v[12:15], v[238:241], v[102:105]
	v_mfma_f32_16x16x32_bf16 v[82:85], v[16:19], v[242:245], v[68:71]
	v_mfma_f32_16x16x32_bf16 v[68:71], v[22:25], v[238:241], v[106:109]
	v_mfma_f32_16x16x32_bf16 v[78:81], v[26:29], v[242:245], v[68:71]
	s_setprio 0
	s_setprio 1
	v_mfma_f32_16x16x32_bf16 v[68:71], v[206:209], v[30:33], v[118:121]
	v_mfma_f32_16x16x32_bf16 v[30:33], v[214:217], v[30:33], v[36:39]
	v_mfma_f32_16x16x32_bf16 v[118:121], v[218:221], v[64:67], v[30:33]
	v_mfma_f32_16x16x32_bf16 v[30:33], v[206:209], v[222:225], v[40:43]
	v_mfma_f32_16x16x32_bf16 v[106:109], v[210:213], v[226:229], v[30:33]
	v_mfma_f32_16x16x32_bf16 v[30:33], v[214:217], v[222:225], v[44:47]
	v_mfma_f32_16x16x32_bf16 v[102:105], v[218:221], v[226:229], v[30:33]
	v_mfma_f32_16x16x32_bf16 v[30:33], v[206:209], v[230:233], v[48:51]
	v_mfma_f32_16x16x32_bf16 v[90:93], v[210:213], v[234:237], v[30:33]
	v_mfma_f32_16x16x32_bf16 v[30:33], v[214:217], v[230:233], v[52:55]
	v_mfma_f32_16x16x32_bf16 v[86:89], v[218:221], v[234:237], v[30:33]
	v_mfma_f32_16x16x32_bf16 v[30:33], v[206:209], v[238:241], v[56:59]
	v_mfma_f32_16x16x32_bf16 v[74:77], v[210:213], v[242:245], v[30:33]
	v_mfma_f32_16x16x32_bf16 v[30:33], v[214:217], v[238:241], v[60:63]
	v_mfma_f32_16x16x32_bf16 v[122:125], v[210:213], v[64:67], v[68:71]
	v_mfma_f32_16x16x32_bf16 v[66:69], v[218:221], v[242:245], v[30:33]
	s_setprio 0
	s_barrier
	ds_read_b128 v[38:41], v154 offset:49152
	ds_read_b128 v[42:45], v154 offset:50176
	ds_read_b128 v[222:225], v154 offset:51200
	ds_read_b128 v[226:229], v154 offset:52224
	ds_read_b128 v[230:233], v154 offset:53248
	ds_read_b128 v[234:237], v154 offset:54272
	ds_read_b128 v[238:241], v154 offset:55296
	ds_read_b128 v[242:245], v154 offset:56320
	s_add_u32 s24, s38, 0x180
	s_addc_u32 s25, s39, 0
	s_mov_b32 m0, s54
	s_nop 0
	global_load_lds_dwordx4 v146, s[24:25] offset:0
	s_nop 0
	s_mov_b32 m0, s55
	s_nop 0
	global_load_lds_dwordx4 v148, s[24:25] offset:0
	s_add_u32 s24, s38, 0x80180
	s_addc_u32 s25, s39, 0
	s_mov_b32 m0, s58
	s_nop 0
	global_load_lds_dwordx4 v146, s[24:25] offset:0
	s_nop 0
	s_mov_b32 m0, s59
	s_nop 0
	global_load_lds_dwordx4 v148, s[24:25] offset:0
	s_nop 0
	s_mov_b32 m0, s56
	s_nop 0
	global_load_lds_dwordx4 v1, s[22:23] offset:0
	s_nop 0
	s_mov_b32 m0, s57
	s_nop 0
	global_load_lds_dwordx4 v147, s[22:23] offset:0
	s_waitcnt vmcnt(8)
	s_waitcnt lgkmcnt(0)
	s_barrier
	s_setprio 1
	v_mfma_f32_16x16x32_bf16 v[30:33], v[12:15], v[38:41], v[138:141]
	v_mfma_f32_16x16x32_bf16 v[70:73], v[16:19], v[42:45], v[30:33]
	v_mfma_f32_16x16x32_bf16 v[30:33], v[22:25], v[38:41], v[142:145]
	v_mfma_f32_16x16x32_bf16 v[62:65], v[26:29], v[42:45], v[30:33]
	v_mfma_f32_16x16x32_bf16 v[30:33], v[12:15], v[222:225], v[158:161]
	v_mfma_f32_16x16x32_bf16 v[50:53], v[16:19], v[226:229], v[30:33]
	v_mfma_f32_16x16x32_bf16 v[30:33], v[22:25], v[222:225], v[162:165]
	v_mfma_f32_16x16x32_bf16 v[46:49], v[26:29], v[226:229], v[30:33]
	v_mfma_f32_16x16x32_bf16 v[30:33], v[12:15], v[230:233], v[166:169]
	v_mfma_f32_16x16x32_bf16 v[4:7], v[12:15], v[238:241], v[4:7]
	v_mfma_f32_16x16x32_bf16 v[34:37], v[16:19], v[234:237], v[30:33]
	v_mfma_f32_16x16x32_bf16 v[30:33], v[22:25], v[230:233], v[170:173]
	v_mfma_f32_16x16x32_bf16 v[18:21], v[16:19], v[242:245], v[4:7]
	v_mfma_f32_16x16x32_bf16 v[4:7], v[22:25], v[238:241], v[8:11]
	v_mfma_f32_16x16x32_bf16 v[30:33], v[26:29], v[234:237], v[30:33]
	v_mfma_f32_16x16x32_bf16 v[14:17], v[26:29], v[242:245], v[4:7]
	s_setprio 0
	s_setprio 1
	v_mfma_f32_16x16x32_bf16 v[4:7], v[206:209], v[38:41], v[174:177]
	v_mfma_f32_16x16x32_bf16 v[58:61], v[210:213], v[42:45], v[4:7]
	v_mfma_f32_16x16x32_bf16 v[4:7], v[214:217], v[38:41], v[178:181]
	v_mfma_f32_16x16x32_bf16 v[54:57], v[218:221], v[42:45], v[4:7]
	v_mfma_f32_16x16x32_bf16 v[4:7], v[206:209], v[222:225], v[182:185]
	v_mfma_f32_16x16x32_bf16 v[42:45], v[210:213], v[226:229], v[4:7]
	v_mfma_f32_16x16x32_bf16 v[4:7], v[214:217], v[222:225], v[186:189]
	v_mfma_f32_16x16x32_bf16 v[38:41], v[218:221], v[226:229], v[4:7]
	v_mfma_f32_16x16x32_bf16 v[4:7], v[206:209], v[230:233], v[190:193]
	v_mfma_f32_16x16x32_bf16 v[26:29], v[210:213], v[234:237], v[4:7]
	v_mfma_f32_16x16x32_bf16 v[4:7], v[214:217], v[230:233], v[194:197]
	v_mfma_f32_16x16x32_bf16 v[22:25], v[218:221], v[234:237], v[4:7]
	v_mfma_f32_16x16x32_bf16 v[4:7], v[206:209], v[238:241], v[198:201]
	v_mfma_f32_16x16x32_bf16 v[10:13], v[210:213], v[242:245], v[4:7]
	v_mfma_f32_16x16x32_bf16 v[4:7], v[214:217], v[238:241], v[202:205]
	v_mfma_f32_16x16x32_bf16 v[6:9], v[218:221], v[242:245], v[4:7]
	s_setprio 0
	s_barrier
	s_mov_b32 s40, 2
	s_branch .LBB0_2872

; #define PG8_KSETUP() const bool last = (t == nt - 2); const char* a1 = cA + (size_t)(t + 1) * kstep; \
;             const char* a2 = last ? nA : cA + (size_t)(t + 2) * kstep; const char* b2 = last ? nB : cB + (size_t)(t + 2) * kstep; const char* a3 = a2 + kstep; const char* b3 = b2 + kstep; \
;             if (last && has_next) S.a_ready(nxt)
; template <class Epi, class Sched, bool ALIGN_EPI = false, bool SP2 = false>
; __device__ __forceinline__ void gemm_phase(PG8_LAS unsigned char* lds, const Gemm g, const Sched& S, const Epi& E) {
;     ...
;         int t0 = 0;
;         if constexpr (SP2 && Epi::NVM == 16) { if (ui > 0) { const int t = 0; PG8_KSETUP(); PG8_KITER_SP2(24, 24); t0 = 2; } }
;         if constexpr (SP2 && Epi::NVM == 8) { if (ui > 0) { const int t = 0; PG8_KSETUP(); PG8_KITER_SP2(16, 16); t0 = 2; } }
;         for (int t = t0; t < nt; t += 2) {
.LBB0_2873:
	ds_read_b128 v[138:141], v152
	ds_read_b128 v[142:145], v152 offset:1024
	ds_read_b128 v[158:161], v152 offset:2048
	ds_read_b128 v[162:165], v152 offset:3072
	ds_read_b128 v[166:169], v153
	ds_read_b128 v[170:173], v153 offset:1024
	ds_read_b128 v[174:177], v153 offset:2048
	ds_read_b128 v[178:181], v153 offset:3072
	s_cmp_eq_u32 s76, 28
	s_cselect_b32 s40, s74, s79
	s_cselect_b32 s41, s19, s80
	s_cselect_b32 s38, s75, s77
	s_cselect_b32 s39, s17, s78
	s_add_u32 s36, s40, 0x80
	s_addc_u32 s37, s41, 0
	ds_read_b128 v[182:185], v154
	ds_read_b128 v[186:189], v154 offset:1024
	ds_read_b128 v[190:193], v154 offset:2048
	ds_read_b128 v[194:197], v154 offset:3072
	ds_read_b128 v[198:201], v154 offset:4096
	ds_read_b128 v[202:205], v154 offset:5120
	ds_read_b128 v[206:209], v154 offset:6144
	ds_read_b128 v[210:213], v154 offset:7168
	s_add_u32 s30, s79, 0x7ff80
	s_addc_u32 s31, s80, 0
	s_mov_b32 m0, s64
	s_nop 0
	global_load_lds_dwordx4 v1, s[30:31] offset:0
	s_nop 0
	s_mov_b32 m0, s65
	s_nop 0
	global_load_lds_dwordx4 v147, s[30:31] offset:0
	s_waitcnt vmcnt(8)
	s_waitcnt lgkmcnt(0)
	s_barrier
	s_setprio 1
	v_mfma_f32_16x16x32_bf16 v[130:133], v[138:141], v[182:185], v[130:133]
	v_mfma_f32_16x16x32_bf16 v[130:133], v[142:145], v[186:189], v[130:133]
	v_mfma_f32_16x16x32_bf16 v[126:129], v[158:161], v[182:185], v[126:129]
	v_mfma_f32_16x16x32_bf16 v[126:129], v[162:165], v[186:189], v[126:129]
	v_mfma_f32_16x16x32_bf16 v[114:117], v[138:141], v[190:193], v[114:117]
	v_mfma_f32_16x16x32_bf16 v[114:117], v[142:145], v[194:197], v[114:117]
	v_mfma_f32_16x16x32_bf16 v[110:113], v[158:161], v[190:193], v[110:113]
	v_mfma_f32_16x16x32_bf16 v[110:113], v[162:165], v[194:197], v[110:113]
	v_mfma_f32_16x16x32_bf16 v[98:101], v[138:141], v[198:201], v[98:101]
	v_mfma_f32_16x16x32_bf16 v[98:101], v[142:145], v[202:205], v[98:101]
	v_mfma_f32_16x16x32_bf16 v[94:97], v[158:161], v[198:201], v[94:97]
	v_mfma_f32_16x16x32_bf16 v[94:97], v[162:165], v[202:205], v[94:97]
	v_mfma_f32_16x16x32_bf16 v[82:85], v[138:141], v[206:209], v[82:85]
	v_mfma_f32_16x16x32_bf16 v[82:85], v[142:145], v[210:213], v[82:85]
	v_mfma_f32_16x16x32_bf16 v[78:81], v[158:161], v[206:209], v[78:81]
	v_mfma_f32_16x16x32_bf16 v[78:81], v[162:165], v[210:213], v[78:81]
	s_setprio 0
	s_setprio 1
	v_mfma_f32_16x16x32_bf16 v[122:125], v[166:169], v[182:185], v[122:125]
	v_mfma_f32_16x16x32_bf16 v[122:125], v[170:173], v[186:189], v[122:125]
	v_mfma_f32_16x16x32_bf16 v[118:121], v[174:177], v[182:185], v[118:121]
	v_mfma_f32_16x16x32_bf16 v[118:121], v[178:181], v[186:189], v[118:121]
	v_mfma_f32_16x16x32_bf16 v[106:109], v[166:169], v[190:193], v[106:109]
	v_mfma_f32_16x16x32_bf16 v[106:109], v[170:173], v[194:197], v[106:109]
	v_mfma_f32_16x16x32_bf16 v[102:105], v[174:177], v[190:193], v[102:105]
	v_mfma_f32_16x16x32_bf16 v[102:105], v[178:181], v[194:197], v[102:105]
	v_mfma_f32_16x16x32_bf16 v[90:93], v[166:169], v[198:201], v[90:93]
	v_mfma_f32_16x16x32_bf16 v[90:93], v[170:173], v[202:205], v[90:93]
	v_mfma_f32_16x16x32_bf16 v[86:89], v[174:177], v[198:201], v[86:89]
	v_mfma_f32_16x16x32_bf16 v[86:89], v[178:181], v[202:205], v[86:89]
	v_mfma_f32_16x16x32_bf16 v[74:77], v[166:169], v[206:209], v[74:77]
	v_mfma_f32_16x16x32_bf16 v[74:77], v[170:173], v[210:213], v[74:77]
	v_mfma_f32_16x16x32_bf16 v[66:69], v[174:177], v[206:209], v[66:69]
	v_mfma_f32_16x16x32_bf16 v[66:69], v[178:181], v[210:213], v[66:69]
	s_setprio 0
	s_barrier
	ds_read_b128 v[182:185], v154 offset:16384
	ds_read_b128 v[186:189], v154 offset:17408
	ds_read_b128 v[190:193], v154 offset:18432
	ds_read_b128 v[194:197], v154 offset:19456
	ds_read_b128 v[198:201], v154 offset:20480
	ds_read_b128 v[202:205], v154 offset:21504
	ds_read_b128 v[206:209], v154 offset:22528
	ds_read_b128 v[210:213], v154 offset:23552
	s_mov_b32 m0, s29
	s_nop 0
	global_load_lds_dwordx4 v146, s[38:39] offset:0
	s_add_u32 s30, s38, 0x80000
	s_mov_b32 m0, s44
	s_nop 0
	global_load_lds_dwordx4 v148, s[38:39] offset:0
	s_addc_u32 s31, s39, 0
	s_mov_b32 m0, s45
	s_nop 0
	global_load_lds_dwordx4 v146, s[30:31] offset:0
	s_nop 0
	s_mov_b32 m0, s46
	s_nop 0
	global_load_lds_dwordx4 v148, s[30:31] offset:0
	s_nop 0
	s_mov_b32 m0, s21
	s_nop 0
	global_load_lds_dwordx4 v1, s[40:41] offset:0
	s_nop 0
	s_mov_b32 m0, s47
	s_nop 0
	global_load_lds_dwordx4 v147, s[40:41] offset:0
	s_waitcnt vmcnt(8)
	s_waitcnt lgkmcnt(0)
	s_barrier
	s_setprio 1
	v_mfma_f32_16x16x32_bf16 v[70:73], v[138:141], v[182:185], v[70:73]
	v_mfma_f32_16x16x32_bf16 v[70:73], v[142:145], v[186:189], v[70:73]
	v_mfma_f32_16x16x32_bf16 v[62:65], v[158:161], v[182:185], v[62:65]
	v_mfma_f32_16x16x32_bf16 v[62:65], v[162:165], v[186:189], v[62:65]
	v_mfma_f32_16x16x32_bf16 v[50:53], v[138:141], v[190:193], v[50:53]
	v_mfma_f32_16x16x32_bf16 v[50:53], v[142:145], v[194:197], v[50:53]
	v_mfma_f32_16x16x32_bf16 v[46:49], v[158:161], v[190:193], v[46:49]
	v_mfma_f32_16x16x32_bf16 v[46:49], v[162:165], v[194:197], v[46:49]
	v_mfma_f32_16x16x32_bf16 v[34:37], v[138:141], v[198:201], v[34:37]
	v_mfma_f32_16x16x32_bf16 v[34:37], v[142:145], v[202:205], v[34:37]
	v_mfma_f32_16x16x32_bf16 v[30:33], v[158:161], v[198:201], v[30:33]
	v_mfma_f32_16x16x32_bf16 v[30:33], v[162:165], v[202:205], v[30:33]
	v_mfma_f32_16x16x32_bf16 v[18:21], v[138:141], v[206:209], v[18:21]
	v_mfma_f32_16x16x32_bf16 v[18:21], v[142:145], v[210:213], v[18:21]
	v_mfma_f32_16x16x32_bf16 v[14:17], v[158:161], v[206:209], v[14:17]
	v_mfma_f32_16x16x32_bf16 v[14:17], v[162:165], v[210:213], v[14:17]
	s_setprio 0
	s_setprio 1
	v_mfma_f32_16x16x32_bf16 v[58:61], v[166:169], v[182:185], v[58:61]
	v_mfma_f32_16x16x32_bf16 v[54:57], v[174:177], v[182:185], v[54:57]
	v_mfma_f32_16x16x32_bf16 v[42:45], v[166:169], v[190:193], v[42:45]
	v_mfma_f32_16x16x32_bf16 v[38:41], v[174:177], v[190:193], v[38:41]
	v_mfma_f32_16x16x32_bf16 v[26:29], v[166:169], v[198:201], v[26:29]
	v_mfma_f32_16x16x32_bf16 v[22:25], v[174:177], v[198:201], v[22:25]
	v_mfma_f32_16x16x32_bf16 v[10:13], v[166:169], v[206:209], v[10:13]
	v_mfma_f32_16x16x32_bf16 v[4:7], v[174:177], v[206:209], v[6:9]
	v_mfma_f32_16x16x32_bf16 v[58:61], v[170:173], v[186:189], v[58:61]
	v_mfma_f32_16x16x32_bf16 v[54:57], v[178:181], v[186:189], v[54:57]
	v_mfma_f32_16x16x32_bf16 v[42:45], v[170:173], v[194:197], v[42:45]
	v_mfma_f32_16x16x32_bf16 v[38:41], v[178:181], v[194:197], v[38:41]
	v_mfma_f32_16x16x32_bf16 v[26:29], v[170:173], v[202:205], v[26:29]
	v_mfma_f32_16x16x32_bf16 v[22:25], v[178:181], v[202:205], v[22:25]
	v_mfma_f32_16x16x32_bf16 v[10:13], v[170:173], v[210:213], v[10:13]
	v_mfma_f32_16x16x32_bf16 v[4:7], v[178:181], v[210:213], v[4:7]
	s_setprio 0
	s_barrier
; #define PG8_BAR __builtin_amdgcn_s_barrier()
; #define PG8_KSETUP() const bool last = (t == nt - 2); const char* a1 = cA + (size_t)(t + 1) * kstep; \
;             const char* a2 = last ? nA : cA + (size_t)(t + 2) * kstep; const char* b2 = last ? nB : cB + (size_t)(t + 2) * kstep; const char* a3 = a2 + kstep; const char* b3 = b2 + kstep; \
;             if (last && has_next) S.a_ready(nxt)
; template <class Epi, class Sched, bool ALIGN_EPI = false, bool SP2 = false>
; __device__ __forceinline__ void gemm_phase(PG8_LAS unsigned char* lds, const Gemm g, const Sched& S, const Epi& E) {
;     ...
;         int t0 = 0;
;         if constexpr (SP2 && Epi::NVM == 16) { if (ui > 0) { const int t = 0; PG8_KSETUP(); PG8_KITER_SP2(24, 24); t0 = 2; } }
;         if constexpr (SP2 && Epi::NVM == 8) { if (ui > 0) { const int t = 0; PG8_KSETUP(); PG8_KITER_SP2(16, 16); t0 = 2; } }
;         for (int t = t0; t < nt; t += 2) {
;     ...
;         if constexpr (ALIGN_EPI) { if (wr == 0) PG8_BAR; }
	ds_read_b128 v[138:141], v155
	ds_read_b128 v[142:145], v155 offset:1024
	ds_read_b128 v[158:161], v155 offset:2048
	ds_read_b128 v[162:165], v155 offset:3072
	ds_read_b128 v[166:169], v156
	ds_read_b128 v[170:173], v156 offset:1024
	ds_read_b128 v[174:177], v156 offset:2048
	ds_read_b128 v[178:181], v156 offset:3072
	ds_read_b128 v[182:185], v154 offset:32768
	ds_read_b128 v[186:189], v154 offset:33792
	ds_read_b128 v[190:193], v154 offset:34816
	ds_read_b128 v[194:197], v154 offset:35840
	ds_read_b128 v[198:201], v154 offset:36864
	ds_read_b128 v[202:205], v154 offset:37888
	ds_read_b128 v[206:209], v154 offset:38912
	ds_read_b128 v[210:213], v154 offset:39936
	s_add_u32 s30, s40, 0x80000
	s_addc_u32 s31, s41, 0
	s_mov_b32 m0, s52
	s_nop 0
	global_load_lds_dwordx4 v1, s[30:31] offset:0
	s_nop 0
	s_mov_b32 m0, s53
	s_nop 0
	global_load_lds_dwordx4 v147, s[30:31] offset:0
	s_waitcnt vmcnt(8)
	s_waitcnt lgkmcnt(0)
	s_barrier
	s_setprio 1
	v_mfma_f32_16x16x32_bf16 v[130:133], v[138:141], v[182:185], v[130:133]
	v_mfma_f32_16x16x32_bf16 v[130:133], v[142:145], v[186:189], v[130:133]
	v_mfma_f32_16x16x32_bf16 v[126:129], v[158:161], v[182:185], v[126:129]
	v_mfma_f32_16x16x32_bf16 v[126:129], v[162:165], v[186:189], v[126:129]
	v_mfma_f32_16x16x32_bf16 v[114:117], v[138:141], v[190:193], v[114:117]
	v_mfma_f32_16x16x32_bf16 v[114:117], v[142:145], v[194:197], v[114:117]
	v_mfma_f32_16x16x32_bf16 v[110:113], v[158:161], v[190:193], v[110:113]
	v_mfma_f32_16x16x32_bf16 v[110:113], v[162:165], v[194:197], v[110:113]
	v_mfma_f32_16x16x32_bf16 v[98:101], v[138:141], v[198:201], v[98:101]
	v_mfma_f32_16x16x32_bf16 v[98:101], v[142:145], v[202:205], v[98:101]
	v_mfma_f32_16x16x32_bf16 v[94:97], v[158:161], v[198:201], v[94:97]
	v_mfma_f32_16x16x32_bf16 v[94:97], v[162:165], v[202:205], v[94:97]
	v_mfma_f32_16x16x32_bf16 v[82:85], v[138:141], v[206:209], v[82:85]
	v_mfma_f32_16x16x32_bf16 v[82:85], v[142:145], v[210:213], v[82:85]
	v_mfma_f32_16x16x32_bf16 v[78:81], v[158:161], v[206:209], v[78:81]
	v_mfma_f32_16x16x32_bf16 v[78:81], v[162:165], v[210:213], v[78:81]
	s_setprio 0
	s_setprio 1
	v_mfma_f32_16x16x32_bf16 v[122:125], v[166:169], v[182:185], v[122:125]
	v_mfma_f32_16x16x32_bf16 v[122:125], v[170:173], v[186:189], v[122:125]
	v_mfma_f32_16x16x32_bf16 v[118:121], v[174:177], v[182:185], v[118:121]
	v_mfma_f32_16x16x32_bf16 v[118:121], v[178:181], v[186:189], v[118:121]
	v_mfma_f32_16x16x32_bf16 v[106:109], v[166:169], v[190:193], v[106:109]
	v_mfma_f32_16x16x32_bf16 v[106:109], v[170:173], v[194:197], v[106:109]
	v_mfma_f32_16x16x32_bf16 v[102:105], v[174:177], v[190:193], v[102:105]
	v_mfma_f32_16x16x32_bf16 v[102:105], v[178:181], v[194:197], v[102:105]
	v_mfma_f32_16x16x32_bf16 v[90:93], v[166:169], v[198:201], v[90:93]
	v_mfma_f32_16x16x32_bf16 v[90:93], v[170:173], v[202:205], v[90:93]
	v_mfma_f32_16x16x32_bf16 v[86:89], v[174:177], v[198:201], v[86:89]
	v_mfma_f32_16x16x32_bf16 v[86:89], v[178:181], v[202:205], v[86:89]
	v_mfma_f32_16x16x32_bf16 v[74:77], v[166:169], v[206:209], v[74:77]
	v_mfma_f32_16x16x32_bf16 v[74:77], v[170:173], v[210:213], v[74:77]
	v_mfma_f32_16x16x32_bf16 v[66:69], v[174:177], v[206:209], v[66:69]
	v_mfma_f32_16x16x32_bf16 v[66:69], v[178:181], v[210:213], v[66:69]
	s_setprio 0
	s_barrier
	ds_read_b128 v[182:185], v154 offset:49152
	ds_read_b128 v[186:189], v154 offset:50176
	ds_read_b128 v[190:193], v154 offset:51200
	ds_read_b128 v[194:197], v154 offset:52224
	ds_read_b128 v[198:201], v154 offset:53248
	ds_read_b128 v[202:205], v154 offset:54272
	ds_read_b128 v[206:209], v154 offset:55296
	ds_read_b128 v[210:213], v154 offset:56320
	s_add_u32 s30, s38, 0x80
	s_addc_u32 s31, s39, 0
	s_mov_b32 m0, s54
	s_nop 0
	global_load_lds_dwordx4 v146, s[30:31] offset:0
	s_nop 0
	s_mov_b32 m0, s55
	s_nop 0
	global_load_lds_dwordx4 v148, s[30:31] offset:0
	s_add_u32 s30, s38, 0x80080
	s_addc_u32 s31, s39, 0
	s_mov_b32 m0, s58
	s_nop 0
	global_load_lds_dwordx4 v146, s[30:31] offset:0
	s_nop 0
	s_mov_b32 m0, s59
	s_nop 0
	global_load_lds_dwordx4 v148, s[30:31] offset:0
	s_nop 0
	s_mov_b32 m0, s56
	s_nop 0
	global_load_lds_dwordx4 v1, s[36:37] offset:0
	s_nop 0
	s_mov_b32 m0, s57
	s_nop 0
	global_load_lds_dwordx4 v147, s[36:37] offset:0
	s_waitcnt vmcnt(8)
	s_waitcnt lgkmcnt(0)
	s_barrier
	s_setprio 1
	v_mfma_f32_16x16x32_bf16 v[70:73], v[138:141], v[182:185], v[70:73]
	v_mfma_f32_16x16x32_bf16 v[70:73], v[142:145], v[186:189], v[70:73]
	v_mfma_f32_16x16x32_bf16 v[62:65], v[158:161], v[182:185], v[62:65]
	v_mfma_f32_16x16x32_bf16 v[62:65], v[162:165], v[186:189], v[62:65]
	v_mfma_f32_16x16x32_bf16 v[50:53], v[138:141], v[190:193], v[50:53]
	v_mfma_f32_16x16x32_bf16 v[50:53], v[142:145], v[194:197], v[50:53]
	v_mfma_f32_16x16x32_bf16 v[46:49], v[158:161], v[190:193], v[46:49]
	v_mfma_f32_16x16x32_bf16 v[46:49], v[162:165], v[194:197], v[46:49]
	v_mfma_f32_16x16x32_bf16 v[34:37], v[138:141], v[198:201], v[34:37]
	v_mfma_f32_16x16x32_bf16 v[34:37], v[142:145], v[202:205], v[34:37]
	v_mfma_f32_16x16x32_bf16 v[30:33], v[158:161], v[198:201], v[30:33]
	v_mfma_f32_16x16x32_bf16 v[30:33], v[162:165], v[202:205], v[30:33]
	v_mfma_f32_16x16x32_bf16 v[18:21], v[138:141], v[206:209], v[18:21]
	v_mfma_f32_16x16x32_bf16 v[18:21], v[142:145], v[210:213], v[18:21]
	v_mfma_f32_16x16x32_bf16 v[14:17], v[158:161], v[206:209], v[14:17]
	v_mfma_f32_16x16x32_bf16 v[14:17], v[162:165], v[210:213], v[14:17]
	s_setprio 0
	s_setprio 1
	v_mfma_f32_16x16x32_bf16 v[58:61], v[166:169], v[182:185], v[58:61]
	v_mfma_f32_16x16x32_bf16 v[54:57], v[174:177], v[182:185], v[54:57]
	v_mfma_f32_16x16x32_bf16 v[42:45], v[166:169], v[190:193], v[42:45]
	v_mfma_f32_16x16x32_bf16 v[38:41], v[174:177], v[190:193], v[38:41]
	v_mfma_f32_16x16x32_bf16 v[26:29], v[166:169], v[198:201], v[26:29]
	v_mfma_f32_16x16x32_bf16 v[22:25], v[174:177], v[198:201], v[22:25]
	v_mfma_f32_16x16x32_bf16 v[8:11], v[166:169], v[206:209], v[10:13]
	v_mfma_f32_16x16x32_bf16 v[4:7], v[174:177], v[206:209], v[4:7]
	v_mfma_f32_16x16x32_bf16 v[58:61], v[170:173], v[186:189], v[58:61]
	v_mfma_f32_16x16x32_bf16 v[54:57], v[178:181], v[186:189], v[54:57]
	v_mfma_f32_16x16x32_bf16 v[42:45], v[170:173], v[194:197], v[42:45]
	v_mfma_f32_16x16x32_bf16 v[38:41], v[178:181], v[194:197], v[38:41]
	v_mfma_f32_16x16x32_bf16 v[26:29], v[170:173], v[202:205], v[26:29]
	v_mfma_f32_16x16x32_bf16 v[22:25], v[178:181], v[202:205], v[22:25]
	v_mfma_f32_16x16x32_bf16 v[10:13], v[170:173], v[210:213], v[8:11]
	v_mfma_f32_16x16x32_bf16 v[6:9], v[178:181], v[210:213], v[4:7]
	s_setprio 0
	s_barrier
	s_add_i32 s76, s76, 2
	s_add_u32 s77, s77, 0x100
	s_addc_u32 s78, s78, 0
	s_add_u32 s79, s79, 0x100
	s_addc_u32 s80, s80, 0
	s_cmp_gt_u32 s76, 29
	s_cbranch_scc0 .LBB0_2873
	s_and_b64 vcc, exec, s[14:15]
	s_cbranch_vccz .LBB0_2876
	s_barrier

; #define PG8_KSETUP() const bool last = (t == nt - 2); const char* a1 = cA + (size_t)(t + 1) * kstep; \
;             const char* a2 = last ? nA : cA + (size_t)(t + 2) * kstep; const char* b2 = last ? nB : cB + (size_t)(t + 2) * kstep; const char* a3 = a2 + kstep; const char* b3 = b2 + kstep; \
;             if (last && has_next) S.a_ready(nxt)
; template <class Epi, class Sched, bool ALIGN_EPI = false, bool SP2 = false>
; __device__ __forceinline__ void gemm_phase(PG8_LAS unsigned char* lds, const Gemm g, const Sched& S, const Epi& E) {
;     ...
;         int t0 = 0;
;         if constexpr (SP2 && Epi::NVM == 16) { if (ui > 0) { const int t = 0; PG8_KSETUP(); PG8_KITER_SP2(24, 24); t0 = 2; } }
.LBB0_2955:
	ds_read_b128 v[4:7], v147
	ds_read_b128 v[8:11], v147 offset:1024
	ds_read_b128 v[12:15], v147 offset:2048
	ds_read_b128 v[16:19], v147 offset:3072
	ds_read_b128 v[20:23], v148
	ds_read_b128 v[24:27], v148 offset:1024
	ds_read_b128 v[28:31], v148 offset:2048
	ds_read_b128 v[32:35], v148 offset:3072
	s_add_u32 s42, s36, 0x100
	s_addc_u32 s43, s37, 0
	s_add_u32 s30, s38, 0x100
	s_addc_u32 s31, s39, 0
	s_add_u32 s40, s36, 0x180
	s_addc_u32 s41, s37, 0
	ds_read_b128 v[36:39], v149
	ds_read_b128 v[40:43], v149 offset:1024
	ds_read_b128 v[44:47], v149 offset:2048
	ds_read_b128 v[48:51], v149 offset:3072
	ds_read_b128 v[52:55], v149 offset:4096
	ds_read_b128 v[56:59], v149 offset:5120
	ds_read_b128 v[60:63], v149 offset:6144
	ds_read_b128 v[64:67], v149 offset:7168
	s_add_u32 s48, s36, 0x160080
	s_addc_u32 s49, s37, 0
	s_mov_b32 m0, s70
	s_nop 0
	global_load_lds_dwordx4 v1, s[48:49] offset:0
	s_nop 0
	s_mov_b32 m0, s71
	s_nop 0
	global_load_lds_dwordx4 v143, s[48:49] offset:0
	s_waitcnt vmcnt(24)
	s_waitcnt lgkmcnt(0)
	s_barrier
	s_setprio 1
	v_mfma_f32_16x16x32_bf16 v[92:95], v[4:7], v[60:63], 0
	v_mfma_f32_16x16x32_bf16 v[68:71], v[4:7], v[36:39], 0
	v_mfma_f32_16x16x32_bf16 v[72:75], v[12:15], v[36:39], 0
	v_mfma_f32_16x16x32_bf16 v[76:79], v[4:7], v[44:47], 0
	v_mfma_f32_16x16x32_bf16 v[80:83], v[12:15], v[44:47], 0
	v_mfma_f32_16x16x32_bf16 v[84:87], v[4:7], v[52:55], 0
	v_mfma_f32_16x16x32_bf16 v[88:91], v[12:15], v[52:55], 0
	v_mfma_f32_16x16x32_bf16 v[102:105], v[8:11], v[64:67], v[92:95]
	v_mfma_f32_16x16x32_bf16 v[92:95], v[12:15], v[60:63], 0
	v_mfma_f32_16x16x32_bf16 v[68:71], v[8:11], v[40:43], v[68:71]
	v_mfma_f32_16x16x32_bf16 v[72:75], v[16:19], v[40:43], v[72:75]
	v_mfma_f32_16x16x32_bf16 v[76:79], v[8:11], v[48:51], v[76:79]
	v_mfma_f32_16x16x32_bf16 v[80:83], v[16:19], v[48:51], v[80:83]
	v_mfma_f32_16x16x32_bf16 v[84:87], v[8:11], v[56:59], v[84:87]
	v_mfma_f32_16x16x32_bf16 v[88:91], v[16:19], v[56:59], v[88:91]
	v_mfma_f32_16x16x32_bf16 v[106:109], v[16:19], v[64:67], v[92:95]
	s_setprio 0
	s_setprio 1
	v_mfma_f32_16x16x32_bf16 v[92:95], v[20:23], v[36:39], 0
	v_mfma_f32_16x16x32_bf16 v[36:39], v[28:31], v[36:39], 0
	v_mfma_f32_16x16x32_bf16 v[118:121], v[24:27], v[40:43], v[92:95]
	v_mfma_f32_16x16x32_bf16 v[36:39], v[32:35], v[40:43], v[36:39]
	v_mfma_f32_16x16x32_bf16 v[40:43], v[20:23], v[44:47], 0
	v_mfma_f32_16x16x32_bf16 v[44:47], v[28:31], v[44:47], 0
	v_mfma_f32_16x16x32_bf16 v[40:43], v[24:27], v[48:51], v[40:43]
	v_mfma_f32_16x16x32_bf16 v[44:47], v[32:35], v[48:51], v[44:47]
	v_mfma_f32_16x16x32_bf16 v[48:51], v[20:23], v[52:55], 0
	v_mfma_f32_16x16x32_bf16 v[52:55], v[28:31], v[52:55], 0
	v_mfma_f32_16x16x32_bf16 v[48:51], v[24:27], v[56:59], v[48:51]
	v_mfma_f32_16x16x32_bf16 v[52:55], v[32:35], v[56:59], v[52:55]
	v_mfma_f32_16x16x32_bf16 v[56:59], v[20:23], v[60:63], 0
	v_mfma_f32_16x16x32_bf16 v[60:63], v[28:31], v[60:63], 0
	v_mfma_f32_16x16x32_bf16 v[56:59], v[24:27], v[64:67], v[56:59]
	v_mfma_f32_16x16x32_bf16 v[60:63], v[32:35], v[64:67], v[60:63]
	s_setprio 0
	s_barrier
	ds_read_b128 v[64:67], v149 offset:16384
	ds_read_b128 v[92:95], v149 offset:17408
	ds_read_b128 v[96:99], v149 offset:18432
	ds_read_b128 v[110:113], v149 offset:19456
	ds_read_b128 v[114:117], v149 offset:20480
	ds_read_b128 v[122:125], v149 offset:21504
	ds_read_b128 v[126:129], v149 offset:22528
	ds_read_b128 v[130:133], v149 offset:23552
	s_mov_b32 m0, s46
	s_nop 0
	global_load_lds_dwordx4 v142, s[30:31] offset:0
	s_nop 0
	s_mov_b32 m0, s47
	s_nop 0
	global_load_lds_dwordx4 v144, s[30:31] offset:0
	s_add_u32 s30, s38, 0x160100
	s_addc_u32 s31, s39, 0
	s_mov_b32 m0, s52
	s_nop 0
	global_load_lds_dwordx4 v142, s[30:31] offset:0
	s_nop 0
	s_mov_b32 m0, s53
	s_nop 0
	global_load_lds_dwordx4 v144, s[30:31] offset:0
	s_nop 0
	s_mov_b32 m0, s45
	s_nop 0
	global_load_lds_dwordx4 v1, s[42:43] offset:0
	s_nop 0
	s_mov_b32 m0, s54
	s_nop 0
	global_load_lds_dwordx4 v143, s[42:43] offset:0
	s_waitcnt vmcnt(24)
	s_waitcnt lgkmcnt(0)
	s_barrier
	s_setprio 1
	v_mfma_f32_16x16x32_bf16 v[138:141], v[4:7], v[64:67], 0
	v_mfma_f32_16x16x32_bf16 v[156:159], v[4:7], v[96:99], 0
	v_mfma_f32_16x16x32_bf16 v[164:167], v[4:7], v[114:117], 0
	v_mfma_f32_16x16x32_bf16 v[4:7], v[4:7], v[126:129], 0
	v_mfma_f32_16x16x32_bf16 v[138:141], v[8:11], v[92:95], v[138:141]
	v_mfma_f32_16x16x32_bf16 v[156:159], v[8:11], v[110:113], v[156:159]
	v_mfma_f32_16x16x32_bf16 v[164:167], v[8:11], v[122:125], v[164:167]
	v_mfma_f32_16x16x32_bf16 v[4:7], v[8:11], v[130:133], v[4:7]
	v_mfma_f32_16x16x32_bf16 v[8:11], v[12:15], v[126:129], 0
	v_mfma_f32_16x16x32_bf16 v[152:155], v[12:15], v[64:67], 0
	v_mfma_f32_16x16x32_bf16 v[160:163], v[12:15], v[96:99], 0
	v_mfma_f32_16x16x32_bf16 v[168:171], v[12:15], v[114:117], 0
	v_mfma_f32_16x16x32_bf16 v[8:11], v[16:19], v[130:133], v[8:11]
	v_mfma_f32_16x16x32_bf16 v[152:155], v[16:19], v[92:95], v[152:155]
	v_mfma_f32_16x16x32_bf16 v[160:163], v[16:19], v[110:113], v[160:163]
	v_mfma_f32_16x16x32_bf16 v[168:171], v[16:19], v[122:125], v[168:171]
	s_setprio 0
	s_setprio 1
	v_mfma_f32_16x16x32_bf16 v[12:15], v[20:23], v[64:67], 0
	v_mfma_f32_16x16x32_bf16 v[172:175], v[24:27], v[92:95], v[12:15]
	v_mfma_f32_16x16x32_bf16 v[12:15], v[28:31], v[64:67], 0
	v_mfma_f32_16x16x32_bf16 v[176:179], v[32:35], v[92:95], v[12:15]
	v_mfma_f32_16x16x32_bf16 v[12:15], v[20:23], v[96:99], 0
	v_mfma_f32_16x16x32_bf16 v[180:183], v[24:27], v[110:113], v[12:15]
	v_mfma_f32_16x16x32_bf16 v[12:15], v[28:31], v[96:99], 0
	v_mfma_f32_16x16x32_bf16 v[184:187], v[32:35], v[110:113], v[12:15]
	v_mfma_f32_16x16x32_bf16 v[12:15], v[20:23], v[114:117], 0
	v_mfma_f32_16x16x32_bf16 v[188:191], v[24:27], v[122:125], v[12:15]
	v_mfma_f32_16x16x32_bf16 v[12:15], v[28:31], v[114:117], 0
	v_mfma_f32_16x16x32_bf16 v[192:195], v[32:35], v[122:125], v[12:15]
	v_mfma_f32_16x16x32_bf16 v[12:15], v[20:23], v[126:129], 0
	v_mfma_f32_16x16x32_bf16 v[196:199], v[24:27], v[130:133], v[12:15]
	v_mfma_f32_16x16x32_bf16 v[12:15], v[28:31], v[126:129], 0
	v_mfma_f32_16x16x32_bf16 v[200:203], v[32:35], v[130:133], v[12:15]
	s_setprio 0
	s_barrier
; #define PG8_KSETUP() const bool last = (t == nt - 2); const char* a1 = cA + (size_t)(t + 1) * kstep; \
;             const char* a2 = last ? nA : cA + (size_t)(t + 2) * kstep; const char* b2 = last ? nB : cB + (size_t)(t + 2) * kstep; const char* a3 = a2 + kstep; const char* b3 = b2 + kstep; \
;             if (last && has_next) S.a_ready(nxt)
; template <class Epi, class Sched, bool ALIGN_EPI = false, bool SP2 = false>
; __device__ __forceinline__ void gemm_phase(PG8_LAS unsigned char* lds, const Gemm g, const Sched& S, const Epi& E) {
;     ...
;         int t0 = 0;
;         if constexpr (SP2 && Epi::NVM == 16) { if (ui > 0) { const int t = 0; PG8_KSETUP(); PG8_KITER_SP2(24, 24); t0 = 2; } }
	s_nop 4
	ds_read_b128 v[12:15], v150
	ds_read_b128 v[16:19], v150 offset:1024
	ds_read_b128 v[22:25], v150 offset:2048
	ds_read_b128 v[26:29], v150 offset:3072
	ds_read_b128 v[204:207], v151
	ds_read_b128 v[208:211], v151 offset:1024
	ds_read_b128 v[212:215], v151 offset:2048
	ds_read_b128 v[216:219], v151 offset:3072
	ds_read_b128 v[30:33], v149 offset:32768
	ds_read_b128 v[64:67], v149 offset:33792
	ds_read_b128 v[220:223], v149 offset:34816
	ds_read_b128 v[224:227], v149 offset:35840
	ds_read_b128 v[228:231], v149 offset:36864
	ds_read_b128 v[232:235], v149 offset:37888
	ds_read_b128 v[236:239], v149 offset:38912
	ds_read_b128 v[240:243], v149 offset:39936
	s_add_u32 s30, s36, 0x160100
	s_addc_u32 s31, s37, 0
	s_mov_b32 m0, s55
	s_nop 0
	global_load_lds_dwordx4 v1, s[30:31] offset:0
	s_nop 0
	s_mov_b32 m0, s56
	s_nop 0
	global_load_lds_dwordx4 v143, s[30:31] offset:0
	s_waitcnt vmcnt(8)
	s_waitcnt lgkmcnt(0)
	s_barrier
	s_setprio 1
	v_mfma_f32_16x16x32_bf16 v[68:71], v[12:15], v[30:33], v[68:71]
	v_mfma_f32_16x16x32_bf16 v[130:133], v[16:19], v[64:67], v[68:71]
	v_mfma_f32_16x16x32_bf16 v[68:71], v[22:25], v[30:33], v[72:75]
	v_mfma_f32_16x16x32_bf16 v[126:129], v[26:29], v[64:67], v[68:71]
	v_mfma_f32_16x16x32_bf16 v[68:71], v[12:15], v[220:223], v[76:79]
	v_mfma_f32_16x16x32_bf16 v[114:117], v[16:19], v[224:227], v[68:71]
	v_mfma_f32_16x16x32_bf16 v[68:71], v[22:25], v[220:223], v[80:83]
	v_mfma_f32_16x16x32_bf16 v[110:113], v[26:29], v[224:227], v[68:71]
	v_mfma_f32_16x16x32_bf16 v[68:71], v[12:15], v[228:231], v[84:87]
	v_mfma_f32_16x16x32_bf16 v[98:101], v[16:19], v[232:235], v[68:71]
	v_mfma_f32_16x16x32_bf16 v[68:71], v[22:25], v[228:231], v[88:91]
	v_mfma_f32_16x16x32_bf16 v[94:97], v[26:29], v[232:235], v[68:71]
	v_mfma_f32_16x16x32_bf16 v[68:71], v[12:15], v[236:239], v[102:105]
	v_mfma_f32_16x16x32_bf16 v[82:85], v[16:19], v[240:243], v[68:71]
	v_mfma_f32_16x16x32_bf16 v[68:71], v[22:25], v[236:239], v[106:109]
	v_mfma_f32_16x16x32_bf16 v[78:81], v[26:29], v[240:243], v[68:71]
	s_setprio 0
	s_setprio 1
	v_mfma_f32_16x16x32_bf16 v[68:71], v[204:207], v[30:33], v[118:121]
	v_mfma_f32_16x16x32_bf16 v[30:33], v[212:215], v[30:33], v[36:39]
	v_mfma_f32_16x16x32_bf16 v[118:121], v[216:219], v[64:67], v[30:33]
	v_mfma_f32_16x16x32_bf16 v[30:33], v[204:207], v[220:223], v[40:43]
	v_mfma_f32_16x16x32_bf16 v[106:109], v[208:211], v[224:227], v[30:33]
	v_mfma_f32_16x16x32_bf16 v[30:33], v[212:215], v[220:223], v[44:47]
	v_mfma_f32_16x16x32_bf16 v[102:105], v[216:219], v[224:227], v[30:33]
	v_mfma_f32_16x16x32_bf16 v[30:33], v[204:207], v[228:231], v[48:51]
	v_mfma_f32_16x16x32_bf16 v[90:93], v[208:211], v[232:235], v[30:33]
	v_mfma_f32_16x16x32_bf16 v[30:33], v[212:215], v[228:231], v[52:55]
	v_mfma_f32_16x16x32_bf16 v[86:89], v[216:219], v[232:235], v[30:33]
	v_mfma_f32_16x16x32_bf16 v[30:33], v[204:207], v[236:239], v[56:59]
	v_mfma_f32_16x16x32_bf16 v[74:77], v[208:211], v[240:243], v[30:33]
	v_mfma_f32_16x16x32_bf16 v[30:33], v[212:215], v[236:239], v[60:63]
	v_mfma_f32_16x16x32_bf16 v[122:125], v[208:211], v[64:67], v[68:71]
	v_mfma_f32_16x16x32_bf16 v[70:73], v[216:219], v[240:243], v[30:33]
	s_setprio 0
	s_barrier
	ds_read_b128 v[38:41], v149 offset:49152
	ds_read_b128 v[42:45], v149 offset:50176
	ds_read_b128 v[220:223], v149 offset:51200
	ds_read_b128 v[224:227], v149 offset:52224
	ds_read_b128 v[228:231], v149 offset:53248
	ds_read_b128 v[232:235], v149 offset:54272
	ds_read_b128 v[236:239], v149 offset:55296
	ds_read_b128 v[240:243], v149 offset:56320
	s_add_u32 s30, s38, 0x180
	s_addc_u32 s31, s39, 0
	s_mov_b32 m0, s64
	s_nop 0
	global_load_lds_dwordx4 v142, s[30:31] offset:0
	s_nop 0
	s_mov_b32 m0, s65
	s_nop 0
	global_load_lds_dwordx4 v144, s[30:31] offset:0
	s_add_u32 s30, s38, 0x160180
	s_addc_u32 s31, s39, 0
	s_mov_b32 m0, s68
	s_nop 0
	global_load_lds_dwordx4 v142, s[30:31] offset:0
	s_nop 0
	s_mov_b32 m0, s69
	s_nop 0
	global_load_lds_dwordx4 v144, s[30:31] offset:0
	s_nop 0
	s_mov_b32 m0, s66
	s_nop 0
	global_load_lds_dwordx4 v1, s[40:41] offset:0
	s_nop 0
	s_mov_b32 m0, s67
	s_nop 0
	global_load_lds_dwordx4 v143, s[40:41] offset:0
	s_waitcnt vmcnt(8)
	s_waitcnt lgkmcnt(0)
	s_barrier
	s_setprio 1
	v_mfma_f32_16x16x32_bf16 v[30:33], v[12:15], v[38:41], v[138:141]
	v_mfma_f32_16x16x32_bf16 v[66:69], v[16:19], v[42:45], v[30:33]
	v_mfma_f32_16x16x32_bf16 v[30:33], v[22:25], v[38:41], v[152:155]
	v_mfma_f32_16x16x32_bf16 v[62:65], v[26:29], v[42:45], v[30:33]
	v_mfma_f32_16x16x32_bf16 v[30:33], v[12:15], v[220:223], v[156:159]
	v_mfma_f32_16x16x32_bf16 v[50:53], v[16:19], v[224:227], v[30:33]
	v_mfma_f32_16x16x32_bf16 v[30:33], v[22:25], v[220:223], v[160:163]
	v_mfma_f32_16x16x32_bf16 v[46:49], v[26:29], v[224:227], v[30:33]
	v_mfma_f32_16x16x32_bf16 v[30:33], v[12:15], v[228:231], v[164:167]
	v_mfma_f32_16x16x32_bf16 v[4:7], v[12:15], v[236:239], v[4:7]
	v_mfma_f32_16x16x32_bf16 v[34:37], v[16:19], v[232:235], v[30:33]
	v_mfma_f32_16x16x32_bf16 v[30:33], v[22:25], v[228:231], v[168:171]
	v_mfma_f32_16x16x32_bf16 v[18:21], v[16:19], v[240:243], v[4:7]
	v_mfma_f32_16x16x32_bf16 v[4:7], v[22:25], v[236:239], v[8:11]
	v_mfma_f32_16x16x32_bf16 v[30:33], v[26:29], v[232:235], v[30:33]
	v_mfma_f32_16x16x32_bf16 v[14:17], v[26:29], v[240:243], v[4:7]
	s_setprio 0
	s_setprio 1
	v_mfma_f32_16x16x32_bf16 v[4:7], v[204:207], v[38:41], v[172:175]
	v_mfma_f32_16x16x32_bf16 v[58:61], v[208:211], v[42:45], v[4:7]
	v_mfma_f32_16x16x32_bf16 v[4:7], v[212:215], v[38:41], v[176:179]
	v_mfma_f32_16x16x32_bf16 v[54:57], v[216:219], v[42:45], v[4:7]
	v_mfma_f32_16x16x32_bf16 v[4:7], v[204:207], v[220:223], v[180:183]
	v_mfma_f32_16x16x32_bf16 v[42:45], v[208:211], v[224:227], v[4:7]
	v_mfma_f32_16x16x32_bf16 v[4:7], v[212:215], v[220:223], v[184:187]
	v_mfma_f32_16x16x32_bf16 v[38:41], v[216:219], v[224:227], v[4:7]
	v_mfma_f32_16x16x32_bf16 v[4:7], v[204:207], v[228:231], v[188:191]
	v_mfma_f32_16x16x32_bf16 v[26:29], v[208:211], v[232:235], v[4:7]
	v_mfma_f32_16x16x32_bf16 v[4:7], v[212:215], v[228:231], v[192:195]
	v_mfma_f32_16x16x32_bf16 v[22:25], v[216:219], v[232:235], v[4:7]
	v_mfma_f32_16x16x32_bf16 v[4:7], v[204:207], v[236:239], v[196:199]
	v_mfma_f32_16x16x32_bf16 v[10:13], v[208:211], v[240:243], v[4:7]
	v_mfma_f32_16x16x32_bf16 v[4:7], v[212:215], v[236:239], v[200:203]
	v_mfma_f32_16x16x32_bf16 v[6:9], v[216:219], v[240:243], v[4:7]
	s_setprio 0
	s_barrier
	s_mov_b32 s40, 2
	s_branch .LBB0_2959

; #define PG8_KSETUP() const bool last = (t == nt - 2); const char* a1 = cA + (size_t)(t + 1) * kstep; \
;             const char* a2 = last ? nA : cA + (size_t)(t + 2) * kstep; const char* b2 = last ? nB : cB + (size_t)(t + 2) * kstep; const char* a3 = a2 + kstep; const char* b3 = b2 + kstep; \
;             if (last && has_next) S.a_ready(nxt)
; template <class Epi, class Sched, bool ALIGN_EPI = false, bool SP2 = false>
; __device__ __forceinline__ void gemm_phase(PG8_LAS unsigned char* lds, const Gemm g, const Sched& S, const Epi& E) {
;     ...
;         int t0 = 0;
;         if constexpr (SP2 && Epi::NVM == 16) { if (ui > 0) { const int t = 0; PG8_KSETUP(); PG8_KITER_SP2(24, 24); t0 = 2; } }
;         if constexpr (SP2 && Epi::NVM == 8) { if (ui > 0) { const int t = 0; PG8_KSETUP(); PG8_KITER_SP2(16, 16); t0 = 2; } }
;         for (int t = t0; t < nt; t += 2) {
.LBB0_2960:
	ds_read_b128 v[138:141], v147
	ds_read_b128 v[152:155], v147 offset:1024
	ds_read_b128 v[156:159], v147 offset:2048
	ds_read_b128 v[160:163], v147 offset:3072
	ds_read_b128 v[164:167], v148
	ds_read_b128 v[168:171], v148 offset:1024
	ds_read_b128 v[172:175], v148 offset:2048
	ds_read_b128 v[176:179], v148 offset:3072
	s_cmpk_eq_i32 s80, 0x54
	s_cselect_b32 s42, s8, s83
	s_cselect_b32 s43, s9, s84
	s_cselect_b32 s40, s28, s81
	s_cselect_b32 s41, s29, s82
	s_add_u32 s38, s42, 0x80
	s_addc_u32 s39, s43, 0
	ds_read_b128 v[180:183], v149
	ds_read_b128 v[184:187], v149 offset:1024
	ds_read_b128 v[188:191], v149 offset:2048
	ds_read_b128 v[192:195], v149 offset:3072
	ds_read_b128 v[196:199], v149 offset:4096
	ds_read_b128 v[200:203], v149 offset:5120
	ds_read_b128 v[204:207], v149 offset:6144
	ds_read_b128 v[208:211], v149 offset:7168
	s_mov_b32 m0, s70
	s_nop 0
	global_load_lds_dwordx4 v1, s[36:37] offset:0
	s_nop 0
	s_mov_b32 m0, s71
	s_nop 0
	global_load_lds_dwordx4 v143, s[36:37] offset:0
	s_waitcnt vmcnt(8)
	s_waitcnt lgkmcnt(0)
	s_barrier
	s_setprio 1
	v_mfma_f32_16x16x32_bf16 v[130:133], v[138:141], v[180:183], v[130:133]
	v_mfma_f32_16x16x32_bf16 v[130:133], v[152:155], v[184:187], v[130:133]
	v_mfma_f32_16x16x32_bf16 v[126:129], v[156:159], v[180:183], v[126:129]
	v_mfma_f32_16x16x32_bf16 v[126:129], v[160:163], v[184:187], v[126:129]
	v_mfma_f32_16x16x32_bf16 v[114:117], v[138:141], v[188:191], v[114:117]
	v_mfma_f32_16x16x32_bf16 v[114:117], v[152:155], v[192:195], v[114:117]
	v_mfma_f32_16x16x32_bf16 v[110:113], v[156:159], v[188:191], v[110:113]
	v_mfma_f32_16x16x32_bf16 v[110:113], v[160:163], v[192:195], v[110:113]
	v_mfma_f32_16x16x32_bf16 v[98:101], v[138:141], v[196:199], v[98:101]
	v_mfma_f32_16x16x32_bf16 v[98:101], v[152:155], v[200:203], v[98:101]
	v_mfma_f32_16x16x32_bf16 v[94:97], v[156:159], v[196:199], v[94:97]
	v_mfma_f32_16x16x32_bf16 v[94:97], v[160:163], v[200:203], v[94:97]
	v_mfma_f32_16x16x32_bf16 v[82:85], v[138:141], v[204:207], v[82:85]
	v_mfma_f32_16x16x32_bf16 v[82:85], v[152:155], v[208:211], v[82:85]
	v_mfma_f32_16x16x32_bf16 v[78:81], v[156:159], v[204:207], v[78:81]
	v_mfma_f32_16x16x32_bf16 v[78:81], v[160:163], v[208:211], v[78:81]
	s_setprio 0
	s_setprio 1
	v_mfma_f32_16x16x32_bf16 v[122:125], v[164:167], v[180:183], v[122:125]
	v_mfma_f32_16x16x32_bf16 v[122:125], v[168:171], v[184:187], v[122:125]
	v_mfma_f32_16x16x32_bf16 v[118:121], v[172:175], v[180:183], v[118:121]
	v_mfma_f32_16x16x32_bf16 v[118:121], v[176:179], v[184:187], v[118:121]
	v_mfma_f32_16x16x32_bf16 v[106:109], v[164:167], v[188:191], v[106:109]
	v_mfma_f32_16x16x32_bf16 v[106:109], v[168:171], v[192:195], v[106:109]
	v_mfma_f32_16x16x32_bf16 v[102:105], v[172:175], v[188:191], v[102:105]
	v_mfma_f32_16x16x32_bf16 v[102:105], v[176:179], v[192:195], v[102:105]
	v_mfma_f32_16x16x32_bf16 v[90:93], v[164:167], v[196:199], v[90:93]
	v_mfma_f32_16x16x32_bf16 v[90:93], v[168:171], v[200:203], v[90:93]
	v_mfma_f32_16x16x32_bf16 v[86:89], v[172:175], v[196:199], v[86:89]
	v_mfma_f32_16x16x32_bf16 v[86:89], v[176:179], v[200:203], v[86:89]
	v_mfma_f32_16x16x32_bf16 v[74:77], v[164:167], v[204:207], v[74:77]
	v_mfma_f32_16x16x32_bf16 v[74:77], v[168:171], v[208:211], v[74:77]
	v_mfma_f32_16x16x32_bf16 v[70:73], v[172:175], v[204:207], v[70:73]
	v_mfma_f32_16x16x32_bf16 v[70:73], v[176:179], v[208:211], v[70:73]
	s_setprio 0
	s_barrier
	ds_read_b128 v[180:183], v149 offset:16384
	ds_read_b128 v[184:187], v149 offset:17408
	ds_read_b128 v[188:191], v149 offset:18432
	ds_read_b128 v[192:195], v149 offset:19456
	ds_read_b128 v[196:199], v149 offset:20480
	ds_read_b128 v[200:203], v149 offset:21504
	ds_read_b128 v[204:207], v149 offset:22528
	ds_read_b128 v[208:211], v149 offset:23552
	s_mov_b32 m0, s46
	s_nop 0
	global_load_lds_dwordx4 v142, s[40:41] offset:0
	s_add_u32 s30, s40, 0x160000
	s_mov_b32 m0, s47
	s_nop 0
	global_load_lds_dwordx4 v144, s[40:41] offset:0
	s_addc_u32 s31, s41, 0
	s_mov_b32 m0, s52
	s_nop 0
	global_load_lds_dwordx4 v142, s[30:31] offset:0
	s_nop 0
	s_mov_b32 m0, s53
	s_nop 0
	global_load_lds_dwordx4 v144, s[30:31] offset:0
	s_nop 0
	s_mov_b32 m0, s45
	s_nop 0
	global_load_lds_dwordx4 v1, s[42:43] offset:0
	s_nop 0
	s_mov_b32 m0, s54
	s_nop 0
	global_load_lds_dwordx4 v143, s[42:43] offset:0
	s_waitcnt vmcnt(8)
	s_waitcnt lgkmcnt(0)
	s_barrier
	s_setprio 1
	v_mfma_f32_16x16x32_bf16 v[66:69], v[138:141], v[180:183], v[66:69]
	v_mfma_f32_16x16x32_bf16 v[66:69], v[152:155], v[184:187], v[66:69]
	v_mfma_f32_16x16x32_bf16 v[62:65], v[156:159], v[180:183], v[62:65]
	v_mfma_f32_16x16x32_bf16 v[62:65], v[160:163], v[184:187], v[62:65]
	v_mfma_f32_16x16x32_bf16 v[50:53], v[138:141], v[188:191], v[50:53]
	v_mfma_f32_16x16x32_bf16 v[50:53], v[152:155], v[192:195], v[50:53]
	v_mfma_f32_16x16x32_bf16 v[46:49], v[156:159], v[188:191], v[46:49]
	v_mfma_f32_16x16x32_bf16 v[46:49], v[160:163], v[192:195], v[46:49]
	v_mfma_f32_16x16x32_bf16 v[34:37], v[138:141], v[196:199], v[34:37]
	v_mfma_f32_16x16x32_bf16 v[34:37], v[152:155], v[200:203], v[34:37]
	v_mfma_f32_16x16x32_bf16 v[30:33], v[156:159], v[196:199], v[30:33]
	v_mfma_f32_16x16x32_bf16 v[30:33], v[160:163], v[200:203], v[30:33]
	v_mfma_f32_16x16x32_bf16 v[18:21], v[138:141], v[204:207], v[18:21]
	v_mfma_f32_16x16x32_bf16 v[18:21], v[152:155], v[208:211], v[18:21]
	v_mfma_f32_16x16x32_bf16 v[14:17], v[156:159], v[204:207], v[14:17]
	v_mfma_f32_16x16x32_bf16 v[14:17], v[160:163], v[208:211], v[14:17]
	s_setprio 0
	s_setprio 1
	v_mfma_f32_16x16x32_bf16 v[58:61], v[164:167], v[180:183], v[58:61]
	v_mfma_f32_16x16x32_bf16 v[54:57], v[172:175], v[180:183], v[54:57]
	v_mfma_f32_16x16x32_bf16 v[42:45], v[164:167], v[188:191], v[42:45]
	v_mfma_f32_16x16x32_bf16 v[38:41], v[172:175], v[188:191], v[38:41]
	v_mfma_f32_16x16x32_bf16 v[26:29], v[164:167], v[196:199], v[26:29]
	v_mfma_f32_16x16x32_bf16 v[22:25], v[172:175], v[196:199], v[22:25]
	v_mfma_f32_16x16x32_bf16 v[10:13], v[164:167], v[204:207], v[10:13]
	v_mfma_f32_16x16x32_bf16 v[4:7], v[172:175], v[204:207], v[6:9]
	v_mfma_f32_16x16x32_bf16 v[58:61], v[168:171], v[184:187], v[58:61]
	v_mfma_f32_16x16x32_bf16 v[54:57], v[176:179], v[184:187], v[54:57]
	v_mfma_f32_16x16x32_bf16 v[42:45], v[168:171], v[192:195], v[42:45]
	v_mfma_f32_16x16x32_bf16 v[38:41], v[176:179], v[192:195], v[38:41]
	v_mfma_f32_16x16x32_bf16 v[26:29], v[168:171], v[200:203], v[26:29]
	v_mfma_f32_16x16x32_bf16 v[22:25], v[176:179], v[200:203], v[22:25]
	v_mfma_f32_16x16x32_bf16 v[10:13], v[168:171], v[208:211], v[10:13]
	v_mfma_f32_16x16x32_bf16 v[4:7], v[176:179], v[208:211], v[4:7]
	s_setprio 0
	s_barrier
; #define PG8_BAR __builtin_amdgcn_s_barrier()
; #define PG8_KSETUP() const bool last = (t == nt - 2); const char* a1 = cA + (size_t)(t + 1) * kstep; \
;             const char* a2 = last ? nA : cA + (size_t)(t + 2) * kstep; const char* b2 = last ? nB : cB + (size_t)(t + 2) * kstep; const char* a3 = a2 + kstep; const char* b3 = b2 + kstep; \
;             if (last && has_next) S.a_ready(nxt)
; template <class Epi, class Sched, bool ALIGN_EPI = false, bool SP2 = false>
; __device__ __forceinline__ void gemm_phase(PG8_LAS unsigned char* lds, const Gemm g, const Sched& S, const Epi& E) {
;     ...
;         int t0 = 0;
;         if constexpr (SP2 && Epi::NVM == 16) { if (ui > 0) { const int t = 0; PG8_KSETUP(); PG8_KITER_SP2(24, 24); t0 = 2; } }
;         if constexpr (SP2 && Epi::NVM == 8) { if (ui > 0) { const int t = 0; PG8_KSETUP(); PG8_KITER_SP2(16, 16); t0 = 2; } }
;         for (int t = t0; t < nt; t += 2) {
;     ...
;         if constexpr (ALIGN_EPI) { if (wr == 0) PG8_BAR; }
	ds_read_b128 v[138:141], v150
	ds_read_b128 v[152:155], v150 offset:1024
	ds_read_b128 v[156:159], v150 offset:2048
	ds_read_b128 v[160:163], v150 offset:3072
	ds_read_b128 v[164:167], v151
	ds_read_b128 v[168:171], v151 offset:1024
	ds_read_b128 v[172:175], v151 offset:2048
	ds_read_b128 v[176:179], v151 offset:3072
	ds_read_b128 v[180:183], v149 offset:32768
	ds_read_b128 v[184:187], v149 offset:33792
	ds_read_b128 v[188:191], v149 offset:34816
	ds_read_b128 v[192:195], v149 offset:35840
	ds_read_b128 v[196:199], v149 offset:36864
	ds_read_b128 v[200:203], v149 offset:37888
	ds_read_b128 v[204:207], v149 offset:38912
	ds_read_b128 v[208:211], v149 offset:39936
	s_add_u32 s30, s42, 0x160000
	s_addc_u32 s31, s43, 0
	s_mov_b32 m0, s55
	s_nop 0
	global_load_lds_dwordx4 v1, s[30:31] offset:0
	s_nop 0
	s_mov_b32 m0, s56
	s_nop 0
	global_load_lds_dwordx4 v143, s[30:31] offset:0
	s_waitcnt vmcnt(8)
	s_waitcnt lgkmcnt(0)
	s_barrier
	s_setprio 1
	v_mfma_f32_16x16x32_bf16 v[130:133], v[138:141], v[180:183], v[130:133]
	v_mfma_f32_16x16x32_bf16 v[130:133], v[152:155], v[184:187], v[130:133]
	v_mfma_f32_16x16x32_bf16 v[126:129], v[156:159], v[180:183], v[126:129]
	v_mfma_f32_16x16x32_bf16 v[126:129], v[160:163], v[184:187], v[126:129]
	v_mfma_f32_16x16x32_bf16 v[114:117], v[138:141], v[188:191], v[114:117]
	v_mfma_f32_16x16x32_bf16 v[114:117], v[152:155], v[192:195], v[114:117]
	v_mfma_f32_16x16x32_bf16 v[110:113], v[156:159], v[188:191], v[110:113]
	v_mfma_f32_16x16x32_bf16 v[110:113], v[160:163], v[192:195], v[110:113]
	v_mfma_f32_16x16x32_bf16 v[98:101], v[138:141], v[196:199], v[98:101]
	v_mfma_f32_16x16x32_bf16 v[98:101], v[152:155], v[200:203], v[98:101]
	v_mfma_f32_16x16x32_bf16 v[94:97], v[156:159], v[196:199], v[94:97]
	v_mfma_f32_16x16x32_bf16 v[94:97], v[160:163], v[200:203], v[94:97]
	v_mfma_f32_16x16x32_bf16 v[82:85], v[138:141], v[204:207], v[82:85]
	v_mfma_f32_16x16x32_bf16 v[82:85], v[152:155], v[208:211], v[82:85]
	v_mfma_f32_16x16x32_bf16 v[78:81], v[156:159], v[204:207], v[78:81]
	v_mfma_f32_16x16x32_bf16 v[78:81], v[160:163], v[208:211], v[78:81]
	s_setprio 0
	s_setprio 1
	v_mfma_f32_16x16x32_bf16 v[122:125], v[164:167], v[180:183], v[122:125]
	v_mfma_f32_16x16x32_bf16 v[122:125], v[168:171], v[184:187], v[122:125]
	v_mfma_f32_16x16x32_bf16 v[118:121], v[172:175], v[180:183], v[118:121]
	v_mfma_f32_16x16x32_bf16 v[118:121], v[176:179], v[184:187], v[118:121]
	v_mfma_f32_16x16x32_bf16 v[106:109], v[164:167], v[188:191], v[106:109]
	v_mfma_f32_16x16x32_bf16 v[106:109], v[168:171], v[192:195], v[106:109]
	v_mfma_f32_16x16x32_bf16 v[102:105], v[172:175], v[188:191], v[102:105]
	v_mfma_f32_16x16x32_bf16 v[102:105], v[176:179], v[192:195], v[102:105]
	v_mfma_f32_16x16x32_bf16 v[90:93], v[164:167], v[196:199], v[90:93]
	v_mfma_f32_16x16x32_bf16 v[90:93], v[168:171], v[200:203], v[90:93]
	v_mfma_f32_16x16x32_bf16 v[86:89], v[172:175], v[196:199], v[86:89]
	v_mfma_f32_16x16x32_bf16 v[86:89], v[176:179], v[200:203], v[86:89]
	v_mfma_f32_16x16x32_bf16 v[74:77], v[164:167], v[204:207], v[74:77]
	v_mfma_f32_16x16x32_bf16 v[74:77], v[168:171], v[208:211], v[74:77]
	v_mfma_f32_16x16x32_bf16 v[70:73], v[172:175], v[204:207], v[70:73]
	v_mfma_f32_16x16x32_bf16 v[70:73], v[176:179], v[208:211], v[70:73]
	s_setprio 0
	s_barrier
	ds_read_b128 v[180:183], v149 offset:49152
	ds_read_b128 v[184:187], v149 offset:50176
	ds_read_b128 v[188:191], v149 offset:51200
	ds_read_b128 v[192:195], v149 offset:52224
	ds_read_b128 v[196:199], v149 offset:53248
	ds_read_b128 v[200:203], v149 offset:54272
	ds_read_b128 v[204:207], v149 offset:55296
	ds_read_b128 v[208:211], v149 offset:56320
	s_add_u32 s30, s40, 0x80
	s_addc_u32 s31, s41, 0
	s_mov_b32 m0, s64
	s_nop 0
	global_load_lds_dwordx4 v142, s[30:31] offset:0
	s_nop 0
	s_mov_b32 m0, s65
	s_nop 0
	global_load_lds_dwordx4 v144, s[30:31] offset:0
	s_add_u32 s30, s40, 0x160080
	s_addc_u32 s31, s41, 0
	s_mov_b32 m0, s68
	s_nop 0
	global_load_lds_dwordx4 v142, s[30:31] offset:0
	s_nop 0
	s_mov_b32 m0, s69
	s_nop 0
	global_load_lds_dwordx4 v144, s[30:31] offset:0
	s_nop 0
	s_mov_b32 m0, s66
	s_nop 0
	global_load_lds_dwordx4 v1, s[38:39] offset:0
	s_nop 0
	s_mov_b32 m0, s67
	s_nop 0
	global_load_lds_dwordx4 v143, s[38:39] offset:0
	s_waitcnt vmcnt(8)
	s_waitcnt lgkmcnt(0)
	s_barrier
	s_setprio 1
	v_mfma_f32_16x16x32_bf16 v[66:69], v[138:141], v[180:183], v[66:69]
	v_mfma_f32_16x16x32_bf16 v[66:69], v[152:155], v[184:187], v[66:69]
	v_mfma_f32_16x16x32_bf16 v[62:65], v[156:159], v[180:183], v[62:65]
	v_mfma_f32_16x16x32_bf16 v[62:65], v[160:163], v[184:187], v[62:65]
	v_mfma_f32_16x16x32_bf16 v[50:53], v[138:141], v[188:191], v[50:53]
	v_mfma_f32_16x16x32_bf16 v[50:53], v[152:155], v[192:195], v[50:53]
	v_mfma_f32_16x16x32_bf16 v[46:49], v[156:159], v[188:191], v[46:49]
	v_mfma_f32_16x16x32_bf16 v[46:49], v[160:163], v[192:195], v[46:49]
	v_mfma_f32_16x16x32_bf16 v[34:37], v[138:141], v[196:199], v[34:37]
	v_mfma_f32_16x16x32_bf16 v[34:37], v[152:155], v[200:203], v[34:37]
	v_mfma_f32_16x16x32_bf16 v[30:33], v[156:159], v[196:199], v[30:33]
	v_mfma_f32_16x16x32_bf16 v[30:33], v[160:163], v[200:203], v[30:33]
	v_mfma_f32_16x16x32_bf16 v[18:21], v[138:141], v[204:207], v[18:21]
	v_mfma_f32_16x16x32_bf16 v[18:21], v[152:155], v[208:211], v[18:21]
	v_mfma_f32_16x16x32_bf16 v[14:17], v[156:159], v[204:207], v[14:17]
	v_mfma_f32_16x16x32_bf16 v[14:17], v[160:163], v[208:211], v[14:17]
	s_setprio 0
	s_setprio 1
	v_mfma_f32_16x16x32_bf16 v[58:61], v[164:167], v[180:183], v[58:61]
	v_mfma_f32_16x16x32_bf16 v[54:57], v[172:175], v[180:183], v[54:57]
	v_mfma_f32_16x16x32_bf16 v[42:45], v[164:167], v[188:191], v[42:45]
	v_mfma_f32_16x16x32_bf16 v[38:41], v[172:175], v[188:191], v[38:41]
	v_mfma_f32_16x16x32_bf16 v[26:29], v[164:167], v[196:199], v[26:29]
	v_mfma_f32_16x16x32_bf16 v[22:25], v[172:175], v[196:199], v[22:25]
	v_mfma_f32_16x16x32_bf16 v[8:11], v[164:167], v[204:207], v[10:13]
	v_mfma_f32_16x16x32_bf16 v[4:7], v[172:175], v[204:207], v[4:7]
	v_mfma_f32_16x16x32_bf16 v[58:61], v[168:171], v[184:187], v[58:61]
	v_mfma_f32_16x16x32_bf16 v[54:57], v[176:179], v[184:187], v[54:57]
	v_mfma_f32_16x16x32_bf16 v[42:45], v[168:171], v[192:195], v[42:45]
	v_mfma_f32_16x16x32_bf16 v[38:41], v[176:179], v[192:195], v[38:41]
	v_mfma_f32_16x16x32_bf16 v[26:29], v[168:171], v[200:203], v[26:29]
	v_mfma_f32_16x16x32_bf16 v[22:25], v[176:179], v[200:203], v[22:25]
	v_mfma_f32_16x16x32_bf16 v[10:13], v[168:171], v[208:211], v[8:11]
	v_mfma_f32_16x16x32_bf16 v[6:9], v[176:179], v[208:211], v[4:7]
	s_setprio 0
	s_barrier
	s_add_i32 s80, s80, 2
	s_add_u32 s81, s81, 0x100
	s_addc_u32 s82, s82, 0
	s_add_u32 s83, s83, 0x100
	s_addc_u32 s84, s84, 0
	s_add_u32 s36, s36, 0x100
	s_addc_u32 s37, s37, 0
	s_cmpk_gt_u32 s80, 0x55
	s_cbranch_scc0 .LBB0_2960
	s_and_b64 vcc, exec, s[16:17]
	s_cbranch_vccz .LBB0_2963
	s_barrier

; #define PG8_KSETUP() const bool last = (t == nt - 2); const char* a1 = cA + (size_t)(t + 1) * kstep; \
;             const char* a2 = last ? nA : cA + (size_t)(t + 2) * kstep; const char* b2 = last ? nB : cB + (size_t)(t + 2) * kstep; const char* a3 = a2 + kstep; const char* b3 = b2 + kstep; \
;             if (last && has_next) S.a_ready(nxt)
; template <class Epi, class Sched, bool ALIGN_EPI = false, bool SP2 = false>
; __device__ __forceinline__ void gemm_phase(PG8_LAS unsigned char* lds, const Gemm g, const Sched& S, const Epi& E) {
;     ...
;         int t0 = 0;
;         if constexpr (SP2 && Epi::NVM == 16) { if (ui > 0) { const int t = 0; PG8_KSETUP(); PG8_KITER_SP2(24, 24); t0 = 2; } }
;         if constexpr (SP2 && Epi::NVM == 8) { if (ui > 0) { const int t = 0; PG8_KSETUP(); PG8_KITER_SP2(16, 16); t0 = 2; } }
;         for (int t = t0; t < nt; t += 2) {
.LBB0_3114:
	ds_read_b128 v[136:139], v149
	ds_read_b128 v[154:157], v149 offset:1024
	ds_read_b128 v[158:161], v149 offset:2048
	ds_read_b128 v[162:165], v149 offset:3072
	ds_read_b128 v[166:169], v150
	ds_read_b128 v[170:173], v150 offset:1024
	ds_read_b128 v[174:177], v150 offset:2048
	ds_read_b128 v[178:181], v150 offset:3072
	s_cmp_eq_u32 s78, 28
	s_cselect_b32 s40, s72, s76
	s_cselect_b32 s41, s19, s77
	s_cselect_b32 s38, s73, s74
	s_cselect_b32 s39, s17, s75
	s_add_u32 s36, s40, 0x80
	s_addc_u32 s37, s41, 0
	ds_read_b128 v[182:185], v151
	ds_read_b128 v[186:189], v151 offset:1024
	ds_read_b128 v[190:193], v151 offset:2048
	ds_read_b128 v[194:197], v151 offset:3072
	ds_read_b128 v[198:201], v151 offset:4096
	ds_read_b128 v[202:205], v151 offset:5120
	ds_read_b128 v[206:209], v151 offset:6144
	ds_read_b128 v[210:213], v151 offset:7168
	s_mov_b32 m0, s67
	s_nop 0
	global_load_lds_dwordx4 v1, s[28:29] offset:0
	s_nop 0
	s_mov_b32 m0, s68
	s_nop 0
	global_load_lds_dwordx4 v143, s[28:29] offset:0
	s_waitcnt vmcnt(8)
	s_waitcnt lgkmcnt(0)
	s_barrier
	s_setprio 1
	v_mfma_f32_16x16x32_bf16 v[126:129], v[136:139], v[182:185], v[126:129]
	v_mfma_f32_16x16x32_bf16 v[126:129], v[154:157], v[186:189], v[126:129]
	v_mfma_f32_16x16x32_bf16 v[122:125], v[158:161], v[182:185], v[122:125]
	v_mfma_f32_16x16x32_bf16 v[122:125], v[162:165], v[186:189], v[122:125]
	v_mfma_f32_16x16x32_bf16 v[114:117], v[136:139], v[190:193], v[114:117]
	v_mfma_f32_16x16x32_bf16 v[114:117], v[154:157], v[194:197], v[114:117]
	v_mfma_f32_16x16x32_bf16 v[106:109], v[158:161], v[190:193], v[106:109]
	v_mfma_f32_16x16x32_bf16 v[106:109], v[162:165], v[194:197], v[106:109]
	v_mfma_f32_16x16x32_bf16 v[98:101], v[136:139], v[198:201], v[98:101]
	v_mfma_f32_16x16x32_bf16 v[98:101], v[154:157], v[202:205], v[98:101]
	v_mfma_f32_16x16x32_bf16 v[90:93], v[158:161], v[198:201], v[90:93]
	v_mfma_f32_16x16x32_bf16 v[90:93], v[162:165], v[202:205], v[90:93]
	v_mfma_f32_16x16x32_bf16 v[82:85], v[136:139], v[206:209], v[82:85]
	v_mfma_f32_16x16x32_bf16 v[82:85], v[154:157], v[210:213], v[82:85]
	v_mfma_f32_16x16x32_bf16 v[74:77], v[158:161], v[206:209], v[74:77]
	v_mfma_f32_16x16x32_bf16 v[74:77], v[162:165], v[210:213], v[74:77]
	s_setprio 0
	s_setprio 1
	v_mfma_f32_16x16x32_bf16 v[118:121], v[166:169], v[182:185], v[118:121]
	v_mfma_f32_16x16x32_bf16 v[118:121], v[170:173], v[186:189], v[118:121]
	v_mfma_f32_16x16x32_bf16 v[110:113], v[174:177], v[182:185], v[110:113]
	v_mfma_f32_16x16x32_bf16 v[110:113], v[178:181], v[186:189], v[110:113]
	v_mfma_f32_16x16x32_bf16 v[102:105], v[166:169], v[190:193], v[102:105]
	v_mfma_f32_16x16x32_bf16 v[102:105], v[170:173], v[194:197], v[102:105]
	v_mfma_f32_16x16x32_bf16 v[94:97], v[174:177], v[190:193], v[94:97]
	v_mfma_f32_16x16x32_bf16 v[94:97], v[178:181], v[194:197], v[94:97]
	v_mfma_f32_16x16x32_bf16 v[86:89], v[166:169], v[198:201], v[86:89]
	v_mfma_f32_16x16x32_bf16 v[86:89], v[170:173], v[202:205], v[86:89]
	v_mfma_f32_16x16x32_bf16 v[78:81], v[174:177], v[198:201], v[78:81]
	v_mfma_f32_16x16x32_bf16 v[78:81], v[178:181], v[202:205], v[78:81]
	v_mfma_f32_16x16x32_bf16 v[70:73], v[166:169], v[206:209], v[70:73]
	v_mfma_f32_16x16x32_bf16 v[70:73], v[170:173], v[210:213], v[70:73]
	v_mfma_f32_16x16x32_bf16 v[66:69], v[174:177], v[206:209], v[66:69]
	v_mfma_f32_16x16x32_bf16 v[66:69], v[178:181], v[210:213], v[66:69]
	s_setprio 0
	s_barrier
	ds_read_b128 v[182:185], v151 offset:16384
	ds_read_b128 v[186:189], v151 offset:17408
	ds_read_b128 v[190:193], v151 offset:18432
	ds_read_b128 v[194:197], v151 offset:19456
	ds_read_b128 v[198:201], v151 offset:20480
	ds_read_b128 v[202:205], v151 offset:21504
	ds_read_b128 v[206:209], v151 offset:22528
	ds_read_b128 v[210:213], v151 offset:23552
	s_mov_b32 m0, s25
	s_nop 0
	global_load_lds_dwordx4 v135, s[38:39] offset:0
	s_add_u32 s30, s38, 0x80000
	s_mov_b32 m0, s46
	s_nop 0
	global_load_lds_dwordx4 v145, s[38:39] offset:0
	s_addc_u32 s31, s39, 0
	s_mov_b32 m0, s47
	s_nop 0
	global_load_lds_dwordx4 v135, s[30:31] offset:0
	s_nop 0
	s_mov_b32 m0, s52
	s_nop 0
	global_load_lds_dwordx4 v145, s[30:31] offset:0
	s_nop 0
	s_mov_b32 m0, s43
	s_nop 0
	global_load_lds_dwordx4 v1, s[40:41] offset:0
	s_nop 0
	s_mov_b32 m0, s53
	s_nop 0
	global_load_lds_dwordx4 v143, s[40:41] offset:0
	s_waitcnt vmcnt(8)
	s_waitcnt lgkmcnt(0)
	s_barrier
	s_setprio 1
	v_mfma_f32_16x16x32_bf16 v[62:65], v[136:139], v[182:185], v[62:65]
	v_mfma_f32_16x16x32_bf16 v[62:65], v[154:157], v[186:189], v[62:65]
	v_mfma_f32_16x16x32_bf16 v[58:61], v[158:161], v[182:185], v[58:61]
	v_mfma_f32_16x16x32_bf16 v[58:61], v[162:165], v[186:189], v[58:61]
	v_mfma_f32_16x16x32_bf16 v[50:53], v[136:139], v[190:193], v[50:53]
	v_mfma_f32_16x16x32_bf16 v[50:53], v[154:157], v[194:197], v[50:53]
	v_mfma_f32_16x16x32_bf16 v[42:45], v[158:161], v[190:193], v[42:45]
	v_mfma_f32_16x16x32_bf16 v[42:45], v[162:165], v[194:197], v[42:45]
	v_mfma_f32_16x16x32_bf16 v[34:37], v[136:139], v[198:201], v[34:37]
	v_mfma_f32_16x16x32_bf16 v[34:37], v[154:157], v[202:205], v[34:37]
	v_mfma_f32_16x16x32_bf16 v[26:29], v[158:161], v[198:201], v[26:29]
	v_mfma_f32_16x16x32_bf16 v[26:29], v[162:165], v[202:205], v[26:29]
	v_mfma_f32_16x16x32_bf16 v[18:21], v[136:139], v[206:209], v[18:21]
	v_mfma_f32_16x16x32_bf16 v[18:21], v[154:157], v[210:213], v[18:21]
	v_mfma_f32_16x16x32_bf16 v[10:13], v[158:161], v[206:209], v[10:13]
	v_mfma_f32_16x16x32_bf16 v[10:13], v[162:165], v[210:213], v[10:13]
	s_setprio 0
	s_setprio 1
	v_mfma_f32_16x16x32_bf16 v[54:57], v[166:169], v[182:185], v[54:57]
	v_mfma_f32_16x16x32_bf16 v[54:57], v[170:173], v[186:189], v[54:57]
	v_mfma_f32_16x16x32_bf16 v[46:49], v[174:177], v[182:185], v[46:49]
	v_mfma_f32_16x16x32_bf16 v[46:49], v[178:181], v[186:189], v[46:49]
	v_mfma_f32_16x16x32_bf16 v[38:41], v[166:169], v[190:193], v[38:41]
	v_mfma_f32_16x16x32_bf16 v[38:41], v[170:173], v[194:197], v[38:41]
	v_mfma_f32_16x16x32_bf16 v[30:33], v[174:177], v[190:193], v[30:33]
	v_mfma_f32_16x16x32_bf16 v[30:33], v[178:181], v[194:197], v[30:33]
	v_mfma_f32_16x16x32_bf16 v[22:25], v[166:169], v[198:201], v[22:25]
	v_mfma_f32_16x16x32_bf16 v[22:25], v[170:173], v[202:205], v[22:25]
	v_mfma_f32_16x16x32_bf16 v[14:17], v[174:177], v[198:201], v[14:17]
	v_mfma_f32_16x16x32_bf16 v[14:17], v[178:181], v[202:205], v[14:17]
	v_mfma_f32_16x16x32_bf16 v[6:9], v[166:169], v[206:209], v[6:9]
	v_mfma_f32_16x16x32_bf16 v[6:9], v[170:173], v[210:213], v[6:9]
	v_mfma_f32_16x16x32_bf16 v[2:5], v[174:177], v[206:209], v[2:5]
	v_mfma_f32_16x16x32_bf16 v[2:5], v[178:181], v[210:213], v[2:5]
	s_setprio 0
	s_barrier
; #define PG8_BAR __builtin_amdgcn_s_barrier()
; #define PG8_KSETUP() const bool last = (t == nt - 2); const char* a1 = cA + (size_t)(t + 1) * kstep; \
;             const char* a2 = last ? nA : cA + (size_t)(t + 2) * kstep; const char* b2 = last ? nB : cB + (size_t)(t + 2) * kstep; const char* a3 = a2 + kstep; const char* b3 = b2 + kstep; \
;             if (last && has_next) S.a_ready(nxt)
; template <class Epi, class Sched, bool ALIGN_EPI = false, bool SP2 = false>
; __device__ __forceinline__ void gemm_phase(PG8_LAS unsigned char* lds, const Gemm g, const Sched& S, const Epi& E) {
;     ...
;         int t0 = 0;
;         if constexpr (SP2 && Epi::NVM == 16) { if (ui > 0) { const int t = 0; PG8_KSETUP(); PG8_KITER_SP2(24, 24); t0 = 2; } }
;         if constexpr (SP2 && Epi::NVM == 8) { if (ui > 0) { const int t = 0; PG8_KSETUP(); PG8_KITER_SP2(16, 16); t0 = 2; } }
;         for (int t = t0; t < nt; t += 2) {
;     ...
;         if constexpr (ALIGN_EPI) { if (wr == 0) PG8_BAR; }
	ds_read_b128 v[136:139], v152
	ds_read_b128 v[154:157], v152 offset:1024
	ds_read_b128 v[158:161], v152 offset:2048
	ds_read_b128 v[162:165], v152 offset:3072
	ds_read_b128 v[166:169], v153
	ds_read_b128 v[170:173], v153 offset:1024
	ds_read_b128 v[174:177], v153 offset:2048
	ds_read_b128 v[178:181], v153 offset:3072
	ds_read_b128 v[182:185], v151 offset:32768
	ds_read_b128 v[186:189], v151 offset:33792
	ds_read_b128 v[190:193], v151 offset:34816
	ds_read_b128 v[194:197], v151 offset:35840
	ds_read_b128 v[198:201], v151 offset:36864
	ds_read_b128 v[202:205], v151 offset:37888
	ds_read_b128 v[206:209], v151 offset:38912
	ds_read_b128 v[210:213], v151 offset:39936
	s_add_u32 s30, s40, 0x80000
	s_addc_u32 s31, s41, 0
	s_mov_b32 m0, s54
	s_nop 0
	global_load_lds_dwordx4 v1, s[30:31] offset:0
	s_nop 0
	s_mov_b32 m0, s55
	s_nop 0
	global_load_lds_dwordx4 v143, s[30:31] offset:0
	s_waitcnt vmcnt(8)
	s_waitcnt lgkmcnt(0)
	s_barrier
	s_setprio 1
	v_mfma_f32_16x16x32_bf16 v[126:129], v[136:139], v[182:185], v[126:129]
	v_mfma_f32_16x16x32_bf16 v[126:129], v[154:157], v[186:189], v[126:129]
	v_mfma_f32_16x16x32_bf16 v[122:125], v[158:161], v[182:185], v[122:125]
	v_mfma_f32_16x16x32_bf16 v[122:125], v[162:165], v[186:189], v[122:125]
	v_mfma_f32_16x16x32_bf16 v[114:117], v[136:139], v[190:193], v[114:117]
	v_mfma_f32_16x16x32_bf16 v[114:117], v[154:157], v[194:197], v[114:117]
	v_mfma_f32_16x16x32_bf16 v[106:109], v[158:161], v[190:193], v[106:109]
	v_mfma_f32_16x16x32_bf16 v[106:109], v[162:165], v[194:197], v[106:109]
	v_mfma_f32_16x16x32_bf16 v[98:101], v[136:139], v[198:201], v[98:101]
	v_mfma_f32_16x16x32_bf16 v[98:101], v[154:157], v[202:205], v[98:101]
	v_mfma_f32_16x16x32_bf16 v[90:93], v[158:161], v[198:201], v[90:93]
	v_mfma_f32_16x16x32_bf16 v[90:93], v[162:165], v[202:205], v[90:93]
	v_mfma_f32_16x16x32_bf16 v[82:85], v[136:139], v[206:209], v[82:85]
	v_mfma_f32_16x16x32_bf16 v[82:85], v[154:157], v[210:213], v[82:85]
	v_mfma_f32_16x16x32_bf16 v[74:77], v[158:161], v[206:209], v[74:77]
	v_mfma_f32_16x16x32_bf16 v[74:77], v[162:165], v[210:213], v[74:77]
	s_setprio 0
	s_setprio 1
	v_mfma_f32_16x16x32_bf16 v[118:121], v[166:169], v[182:185], v[118:121]
	v_mfma_f32_16x16x32_bf16 v[118:121], v[170:173], v[186:189], v[118:121]
	v_mfma_f32_16x16x32_bf16 v[110:113], v[174:177], v[182:185], v[110:113]
	v_mfma_f32_16x16x32_bf16 v[110:113], v[178:181], v[186:189], v[110:113]
	v_mfma_f32_16x16x32_bf16 v[102:105], v[166:169], v[190:193], v[102:105]
	v_mfma_f32_16x16x32_bf16 v[102:105], v[170:173], v[194:197], v[102:105]
	v_mfma_f32_16x16x32_bf16 v[94:97], v[174:177], v[190:193], v[94:97]
	v_mfma_f32_16x16x32_bf16 v[94:97], v[178:181], v[194:197], v[94:97]
	v_mfma_f32_16x16x32_bf16 v[86:89], v[166:169], v[198:201], v[86:89]
	v_mfma_f32_16x16x32_bf16 v[86:89], v[170:173], v[202:205], v[86:89]
	v_mfma_f32_16x16x32_bf16 v[78:81], v[174:177], v[198:201], v[78:81]
	v_mfma_f32_16x16x32_bf16 v[78:81], v[178:181], v[202:205], v[78:81]
	v_mfma_f32_16x16x32_bf16 v[70:73], v[166:169], v[206:209], v[70:73]
	v_mfma_f32_16x16x32_bf16 v[70:73], v[170:173], v[210:213], v[70:73]
	v_mfma_f32_16x16x32_bf16 v[66:69], v[174:177], v[206:209], v[66:69]
	v_mfma_f32_16x16x32_bf16 v[66:69], v[178:181], v[210:213], v[66:69]
	s_setprio 0
	s_barrier
	ds_read_b128 v[182:185], v151 offset:49152
	ds_read_b128 v[186:189], v151 offset:50176
	ds_read_b128 v[190:193], v151 offset:51200
	ds_read_b128 v[194:197], v151 offset:52224
	ds_read_b128 v[198:201], v151 offset:53248
	ds_read_b128 v[202:205], v151 offset:54272
	ds_read_b128 v[206:209], v151 offset:55296
	ds_read_b128 v[210:213], v151 offset:56320
	s_add_u32 s30, s38, 0x80
	s_addc_u32 s31, s39, 0
	s_mov_b32 m0, s57
	s_nop 0
	global_load_lds_dwordx4 v135, s[30:31] offset:0
	s_nop 0
	s_mov_b32 m0, s58
	s_nop 0
	global_load_lds_dwordx4 v145, s[30:31] offset:0
	s_add_u32 s30, s38, 0x80080
	s_addc_u32 s31, s39, 0
	s_mov_b32 m0, s65
	s_nop 0
	global_load_lds_dwordx4 v135, s[30:31] offset:0
	s_nop 0
	s_mov_b32 m0, s66
	s_nop 0
	global_load_lds_dwordx4 v145, s[30:31] offset:0
	s_nop 0
	s_mov_b32 m0, s59
	s_nop 0
	global_load_lds_dwordx4 v1, s[36:37] offset:0
	s_nop 0
	s_mov_b32 m0, s64
	s_nop 0
	global_load_lds_dwordx4 v143, s[36:37] offset:0
	s_waitcnt vmcnt(8)
	s_waitcnt lgkmcnt(0)
	s_barrier
	s_setprio 1
	v_mfma_f32_16x16x32_bf16 v[62:65], v[136:139], v[182:185], v[62:65]
	v_mfma_f32_16x16x32_bf16 v[62:65], v[154:157], v[186:189], v[62:65]
	v_mfma_f32_16x16x32_bf16 v[58:61], v[158:161], v[182:185], v[58:61]
	v_mfma_f32_16x16x32_bf16 v[58:61], v[162:165], v[186:189], v[58:61]
	v_mfma_f32_16x16x32_bf16 v[50:53], v[136:139], v[190:193], v[50:53]
	v_mfma_f32_16x16x32_bf16 v[50:53], v[154:157], v[194:197], v[50:53]
	v_mfma_f32_16x16x32_bf16 v[42:45], v[158:161], v[190:193], v[42:45]
	v_mfma_f32_16x16x32_bf16 v[42:45], v[162:165], v[194:197], v[42:45]
	v_mfma_f32_16x16x32_bf16 v[34:37], v[136:139], v[198:201], v[34:37]
	v_mfma_f32_16x16x32_bf16 v[34:37], v[154:157], v[202:205], v[34:37]
	v_mfma_f32_16x16x32_bf16 v[26:29], v[158:161], v[198:201], v[26:29]
	v_mfma_f32_16x16x32_bf16 v[26:29], v[162:165], v[202:205], v[26:29]
	v_mfma_f32_16x16x32_bf16 v[18:21], v[136:139], v[206:209], v[18:21]
	v_mfma_f32_16x16x32_bf16 v[18:21], v[154:157], v[210:213], v[18:21]
	v_mfma_f32_16x16x32_bf16 v[10:13], v[158:161], v[206:209], v[10:13]
	v_mfma_f32_16x16x32_bf16 v[10:13], v[162:165], v[210:213], v[10:13]
	s_setprio 0
	s_setprio 1
	v_mfma_f32_16x16x32_bf16 v[54:57], v[166:169], v[182:185], v[54:57]
	v_mfma_f32_16x16x32_bf16 v[54:57], v[170:173], v[186:189], v[54:57]
	v_mfma_f32_16x16x32_bf16 v[46:49], v[174:177], v[182:185], v[46:49]
	v_mfma_f32_16x16x32_bf16 v[46:49], v[178:181], v[186:189], v[46:49]
	v_mfma_f32_16x16x32_bf16 v[38:41], v[166:169], v[190:193], v[38:41]
	v_mfma_f32_16x16x32_bf16 v[38:41], v[170:173], v[194:197], v[38:41]
	v_mfma_f32_16x16x32_bf16 v[30:33], v[174:177], v[190:193], v[30:33]
	v_mfma_f32_16x16x32_bf16 v[30:33], v[178:181], v[194:197], v[30:33]
	v_mfma_f32_16x16x32_bf16 v[22:25], v[166:169], v[198:201], v[22:25]
	v_mfma_f32_16x16x32_bf16 v[22:25], v[170:173], v[202:205], v[22:25]
	v_mfma_f32_16x16x32_bf16 v[14:17], v[174:177], v[198:201], v[14:17]
	v_mfma_f32_16x16x32_bf16 v[14:17], v[178:181], v[202:205], v[14:17]
	v_mfma_f32_16x16x32_bf16 v[6:9], v[166:169], v[206:209], v[6:9]
	v_mfma_f32_16x16x32_bf16 v[6:9], v[170:173], v[210:213], v[6:9]
	v_mfma_f32_16x16x32_bf16 v[2:5], v[174:177], v[206:209], v[2:5]
	v_mfma_f32_16x16x32_bf16 v[2:5], v[178:181], v[210:213], v[2:5]
	s_setprio 0
	s_barrier
	s_add_i32 s78, s78, 2
	s_add_u32 s74, s74, 0x100
	s_addc_u32 s75, s75, 0
	s_add_u32 s76, s76, 0x100
	s_addc_u32 s77, s77, 0
	s_add_u32 s28, s28, 0x100
	s_addc_u32 s29, s29, 0
	s_cmp_gt_u32 s78, 29
	s_cbranch_scc0 .LBB0_3114
	s_and_b64 vcc, exec, s[14:15]
	s_cbranch_vccz .LBB0_3117
	s_barrier

; #define PG8_KSETUP() const bool last = (t == nt - 2); const char* a1 = cA + (size_t)(t + 1) * kstep; \
;             const char* a2 = last ? nA : cA + (size_t)(t + 2) * kstep; const char* b2 = last ? nB : cB + (size_t)(t + 2) * kstep; const char* a3 = a2 + kstep; const char* b3 = b2 + kstep; \
;             if (last && has_next) S.a_ready(nxt)
; template <class Epi, class Sched, bool ALIGN_EPI = false, bool SP2 = false>
; __device__ __forceinline__ void gemm_phase(PG8_LAS unsigned char* lds, const Gemm g, const Sched& S, const Epi& E) {
;     ...
;         int t0 = 0;
;         if constexpr (SP2 && Epi::NVM == 16) { if (ui > 0) { const int t = 0; PG8_KSETUP(); PG8_KITER_SP2(24, 24); t0 = 2; } }
.LBB0_3464:
	s_cmp_eq_u32 s29, 0
	s_mov_b32 s50, 0
	s_cbranch_scc1 .LBB0_3466
	ds_read_b128 v[4:7], v147
	ds_read_b128 v[8:11], v147 offset:1024
	ds_read_b128 v[12:15], v147 offset:2048
	ds_read_b128 v[16:19], v147 offset:3072
	ds_read_b128 v[20:23], v148
	ds_read_b128 v[24:27], v148 offset:1024
	ds_read_b128 v[28:31], v148 offset:2048
	ds_read_b128 v[32:35], v148 offset:3072
	s_add_u32 s40, s46, 0x100
	s_addc_u32 s41, s47, 0
	s_add_u32 s30, s48, 0x100
	s_addc_u32 s31, s49, 0
	s_add_u32 s38, s46, 0x180
	s_addc_u32 s39, s47, 0
	ds_read_b128 v[36:39], v149
	ds_read_b128 v[40:43], v149 offset:1024
	ds_read_b128 v[44:47], v149 offset:2048
	ds_read_b128 v[48:51], v149 offset:3072
	ds_read_b128 v[52:55], v149 offset:4096
	ds_read_b128 v[56:59], v149 offset:5120
	ds_read_b128 v[60:63], v149 offset:6144
	ds_read_b128 v[64:67], v149 offset:7168
	s_add_u32 s50, s46, 0x80080
	s_addc_u32 s51, s47, 0
	s_mov_b32 m0, s73
	s_nop 0
	global_load_lds_dwordx4 v1, s[50:51] offset:0
	s_nop 0
	s_mov_b32 m0, s74
	s_nop 0
	global_load_lds_dwordx4 v143, s[50:51] offset:0
	s_waitcnt vmcnt(24)
	s_waitcnt lgkmcnt(0)
	s_barrier
	s_setprio 1
	v_mfma_f32_16x16x32_bf16 v[92:95], v[4:7], v[60:63], 0
	v_mfma_f32_16x16x32_bf16 v[68:71], v[4:7], v[36:39], 0
	v_mfma_f32_16x16x32_bf16 v[72:75], v[12:15], v[36:39], 0
	v_mfma_f32_16x16x32_bf16 v[76:79], v[4:7], v[44:47], 0
	v_mfma_f32_16x16x32_bf16 v[80:83], v[12:15], v[44:47], 0
	v_mfma_f32_16x16x32_bf16 v[84:87], v[4:7], v[52:55], 0
	v_mfma_f32_16x16x32_bf16 v[88:91], v[12:15], v[52:55], 0
	v_mfma_f32_16x16x32_bf16 v[102:105], v[8:11], v[64:67], v[92:95]
	v_mfma_f32_16x16x32_bf16 v[92:95], v[12:15], v[60:63], 0
	v_mfma_f32_16x16x32_bf16 v[68:71], v[8:11], v[40:43], v[68:71]
	v_mfma_f32_16x16x32_bf16 v[72:75], v[16:19], v[40:43], v[72:75]
	v_mfma_f32_16x16x32_bf16 v[76:79], v[8:11], v[48:51], v[76:79]
	v_mfma_f32_16x16x32_bf16 v[80:83], v[16:19], v[48:51], v[80:83]
	v_mfma_f32_16x16x32_bf16 v[84:87], v[8:11], v[56:59], v[84:87]
	v_mfma_f32_16x16x32_bf16 v[88:91], v[16:19], v[56:59], v[88:91]
	v_mfma_f32_16x16x32_bf16 v[106:109], v[16:19], v[64:67], v[92:95]
	s_setprio 0
	s_setprio 1
	v_mfma_f32_16x16x32_bf16 v[92:95], v[20:23], v[36:39], 0
	v_mfma_f32_16x16x32_bf16 v[36:39], v[28:31], v[36:39], 0
	v_mfma_f32_16x16x32_bf16 v[118:121], v[24:27], v[40:43], v[92:95]
	v_mfma_f32_16x16x32_bf16 v[36:39], v[32:35], v[40:43], v[36:39]
	v_mfma_f32_16x16x32_bf16 v[40:43], v[20:23], v[44:47], 0
	v_mfma_f32_16x16x32_bf16 v[44:47], v[28:31], v[44:47], 0
	v_mfma_f32_16x16x32_bf16 v[40:43], v[24:27], v[48:51], v[40:43]
	v_mfma_f32_16x16x32_bf16 v[44:47], v[32:35], v[48:51], v[44:47]
	v_mfma_f32_16x16x32_bf16 v[48:51], v[20:23], v[52:55], 0
	v_mfma_f32_16x16x32_bf16 v[52:55], v[28:31], v[52:55], 0
	v_mfma_f32_16x16x32_bf16 v[48:51], v[24:27], v[56:59], v[48:51]
	v_mfma_f32_16x16x32_bf16 v[52:55], v[32:35], v[56:59], v[52:55]
	v_mfma_f32_16x16x32_bf16 v[56:59], v[20:23], v[60:63], 0
	v_mfma_f32_16x16x32_bf16 v[60:63], v[28:31], v[60:63], 0
	v_mfma_f32_16x16x32_bf16 v[56:59], v[24:27], v[64:67], v[56:59]
	v_mfma_f32_16x16x32_bf16 v[60:63], v[32:35], v[64:67], v[60:63]
	s_setprio 0
	s_barrier
	ds_read_b128 v[64:67], v149 offset:16384
	ds_read_b128 v[92:95], v149 offset:17408
	ds_read_b128 v[96:99], v149 offset:18432
	ds_read_b128 v[110:113], v149 offset:19456
	ds_read_b128 v[114:117], v149 offset:20480
	ds_read_b128 v[122:125], v149 offset:21504
	ds_read_b128 v[126:129], v149 offset:22528
	ds_read_b128 v[130:133], v149 offset:23552
	s_mov_b32 m0, s45
	s_nop 0
	global_load_lds_dwordx4 v142, s[30:31] offset:0
	s_nop 0
	s_mov_b32 m0, s54
	s_nop 0
	global_load_lds_dwordx4 v144, s[30:31] offset:0
	s_add_u32 s30, s48, 0x80100
	s_addc_u32 s31, s49, 0
	s_mov_b32 m0, s55
	s_nop 0
	global_load_lds_dwordx4 v142, s[30:31] offset:0
	s_nop 0
	s_mov_b32 m0, s56
	s_nop 0
	global_load_lds_dwordx4 v144, s[30:31] offset:0
	s_nop 0
	s_mov_b32 m0, s33
	s_nop 0
	global_load_lds_dwordx4 v1, s[40:41] offset:0
	s_nop 0
	s_mov_b32 m0, s57
	s_nop 0
	global_load_lds_dwordx4 v143, s[40:41] offset:0
	s_waitcnt vmcnt(24)
	s_waitcnt lgkmcnt(0)
	s_barrier
	s_setprio 1
	v_mfma_f32_16x16x32_bf16 v[138:141], v[4:7], v[64:67], 0
	v_mfma_f32_16x16x32_bf16 v[156:159], v[4:7], v[96:99], 0
	v_mfma_f32_16x16x32_bf16 v[164:167], v[4:7], v[114:117], 0
	v_mfma_f32_16x16x32_bf16 v[4:7], v[4:7], v[126:129], 0
	v_mfma_f32_16x16x32_bf16 v[138:141], v[8:11], v[92:95], v[138:141]
	v_mfma_f32_16x16x32_bf16 v[156:159], v[8:11], v[110:113], v[156:159]
	v_mfma_f32_16x16x32_bf16 v[164:167], v[8:11], v[122:125], v[164:167]
	v_mfma_f32_16x16x32_bf16 v[4:7], v[8:11], v[130:133], v[4:7]
	v_mfma_f32_16x16x32_bf16 v[8:11], v[12:15], v[126:129], 0
	v_mfma_f32_16x16x32_bf16 v[152:155], v[12:15], v[64:67], 0
	v_mfma_f32_16x16x32_bf16 v[160:163], v[12:15], v[96:99], 0
	v_mfma_f32_16x16x32_bf16 v[168:171], v[12:15], v[114:117], 0
	v_mfma_f32_16x16x32_bf16 v[8:11], v[16:19], v[130:133], v[8:11]
	v_mfma_f32_16x16x32_bf16 v[152:155], v[16:19], v[92:95], v[152:155]
	v_mfma_f32_16x16x32_bf16 v[160:163], v[16:19], v[110:113], v[160:163]
	v_mfma_f32_16x16x32_bf16 v[168:171], v[16:19], v[122:125], v[168:171]
	s_setprio 0
	s_setprio 1
	v_mfma_f32_16x16x32_bf16 v[12:15], v[20:23], v[64:67], 0
	v_mfma_f32_16x16x32_bf16 v[172:175], v[24:27], v[92:95], v[12:15]
	v_mfma_f32_16x16x32_bf16 v[12:15], v[28:31], v[64:67], 0
	v_mfma_f32_16x16x32_bf16 v[176:179], v[32:35], v[92:95], v[12:15]
	v_mfma_f32_16x16x32_bf16 v[12:15], v[20:23], v[96:99], 0
	v_mfma_f32_16x16x32_bf16 v[180:183], v[24:27], v[110:113], v[12:15]
	v_mfma_f32_16x16x32_bf16 v[12:15], v[28:31], v[96:99], 0
	v_mfma_f32_16x16x32_bf16 v[184:187], v[32:35], v[110:113], v[12:15]
	v_mfma_f32_16x16x32_bf16 v[12:15], v[20:23], v[114:117], 0
	v_mfma_f32_16x16x32_bf16 v[188:191], v[24:27], v[122:125], v[12:15]
	v_mfma_f32_16x16x32_bf16 v[12:15], v[28:31], v[114:117], 0
	v_mfma_f32_16x16x32_bf16 v[192:195], v[32:35], v[122:125], v[12:15]
	v_mfma_f32_16x16x32_bf16 v[12:15], v[20:23], v[126:129], 0
	v_mfma_f32_16x16x32_bf16 v[196:199], v[24:27], v[130:133], v[12:15]
	v_mfma_f32_16x16x32_bf16 v[12:15], v[28:31], v[126:129], 0
	v_mfma_f32_16x16x32_bf16 v[200:203], v[32:35], v[130:133], v[12:15]
	s_setprio 0
	s_barrier
; #define PG8_KSETUP() const bool last = (t == nt - 2); const char* a1 = cA + (size_t)(t + 1) * kstep; \
;             const char* a2 = last ? nA : cA + (size_t)(t + 2) * kstep; const char* b2 = last ? nB : cB + (size_t)(t + 2) * kstep; const char* a3 = a2 + kstep; const char* b3 = b2 + kstep; \
;             if (last && has_next) S.a_ready(nxt)
; template <class Epi, class Sched, bool ALIGN_EPI = false, bool SP2 = false>
; __device__ __forceinline__ void gemm_phase(PG8_LAS unsigned char* lds, const Gemm g, const Sched& S, const Epi& E) {
;     ...
;         int t0 = 0;
;         if constexpr (SP2 && Epi::NVM == 16) { if (ui > 0) { const int t = 0; PG8_KSETUP(); PG8_KITER_SP2(24, 24); t0 = 2; } }
	s_nop 4
	ds_read_b128 v[12:15], v150
	ds_read_b128 v[16:19], v150 offset:1024
	ds_read_b128 v[22:25], v150 offset:2048
	ds_read_b128 v[26:29], v150 offset:3072
	ds_read_b128 v[204:207], v151
	ds_read_b128 v[208:211], v151 offset:1024
	ds_read_b128 v[212:215], v151 offset:2048
	ds_read_b128 v[216:219], v151 offset:3072
	ds_read_b128 v[30:33], v149 offset:32768
	ds_read_b128 v[64:67], v149 offset:33792
	ds_read_b128 v[220:223], v149 offset:34816
	ds_read_b128 v[224:227], v149 offset:35840
	ds_read_b128 v[228:231], v149 offset:36864
	ds_read_b128 v[232:235], v149 offset:37888
	ds_read_b128 v[236:239], v149 offset:38912
	ds_read_b128 v[240:243], v149 offset:39936
	s_add_u32 s30, s46, 0x80100
	s_addc_u32 s31, s47, 0
	s_mov_b32 m0, s58
	s_nop 0
	global_load_lds_dwordx4 v1, s[30:31] offset:0
	s_nop 0
	s_mov_b32 m0, s59
	s_nop 0
	global_load_lds_dwordx4 v143, s[30:31] offset:0
	s_waitcnt vmcnt(8)
	s_waitcnt lgkmcnt(0)
	s_barrier
	s_setprio 1
	v_mfma_f32_16x16x32_bf16 v[68:71], v[12:15], v[30:33], v[68:71]
	v_mfma_f32_16x16x32_bf16 v[130:133], v[16:19], v[64:67], v[68:71]
	v_mfma_f32_16x16x32_bf16 v[68:71], v[22:25], v[30:33], v[72:75]
	v_mfma_f32_16x16x32_bf16 v[126:129], v[26:29], v[64:67], v[68:71]
	v_mfma_f32_16x16x32_bf16 v[68:71], v[12:15], v[220:223], v[76:79]
	v_mfma_f32_16x16x32_bf16 v[114:117], v[16:19], v[224:227], v[68:71]
	v_mfma_f32_16x16x32_bf16 v[68:71], v[22:25], v[220:223], v[80:83]
	v_mfma_f32_16x16x32_bf16 v[110:113], v[26:29], v[224:227], v[68:71]
	v_mfma_f32_16x16x32_bf16 v[68:71], v[12:15], v[228:231], v[84:87]
	v_mfma_f32_16x16x32_bf16 v[98:101], v[16:19], v[232:235], v[68:71]
	v_mfma_f32_16x16x32_bf16 v[68:71], v[22:25], v[228:231], v[88:91]
	v_mfma_f32_16x16x32_bf16 v[94:97], v[26:29], v[232:235], v[68:71]
	v_mfma_f32_16x16x32_bf16 v[68:71], v[12:15], v[236:239], v[102:105]
	v_mfma_f32_16x16x32_bf16 v[82:85], v[16:19], v[240:243], v[68:71]
	v_mfma_f32_16x16x32_bf16 v[68:71], v[22:25], v[236:239], v[106:109]
	v_mfma_f32_16x16x32_bf16 v[78:81], v[26:29], v[240:243], v[68:71]
	s_setprio 0
	s_setprio 1
	v_mfma_f32_16x16x32_bf16 v[68:71], v[204:207], v[30:33], v[118:121]
	v_mfma_f32_16x16x32_bf16 v[30:33], v[212:215], v[30:33], v[36:39]
	v_mfma_f32_16x16x32_bf16 v[118:121], v[216:219], v[64:67], v[30:33]
	v_mfma_f32_16x16x32_bf16 v[30:33], v[204:207], v[220:223], v[40:43]
	v_mfma_f32_16x16x32_bf16 v[106:109], v[208:211], v[224:227], v[30:33]
	v_mfma_f32_16x16x32_bf16 v[30:33], v[212:215], v[220:223], v[44:47]
	v_mfma_f32_16x16x32_bf16 v[102:105], v[216:219], v[224:227], v[30:33]
	v_mfma_f32_16x16x32_bf16 v[30:33], v[204:207], v[228:231], v[48:51]
	v_mfma_f32_16x16x32_bf16 v[90:93], v[208:211], v[232:235], v[30:33]
	v_mfma_f32_16x16x32_bf16 v[30:33], v[212:215], v[228:231], v[52:55]
	v_mfma_f32_16x16x32_bf16 v[86:89], v[216:219], v[232:235], v[30:33]
	v_mfma_f32_16x16x32_bf16 v[30:33], v[204:207], v[236:239], v[56:59]
	v_mfma_f32_16x16x32_bf16 v[74:77], v[208:211], v[240:243], v[30:33]
	v_mfma_f32_16x16x32_bf16 v[30:33], v[212:215], v[236:239], v[60:63]
	v_mfma_f32_16x16x32_bf16 v[122:125], v[208:211], v[64:67], v[68:71]
	v_mfma_f32_16x16x32_bf16 v[70:73], v[216:219], v[240:243], v[30:33]
	s_setprio 0
	s_barrier
	ds_read_b128 v[38:41], v149 offset:49152
	ds_read_b128 v[42:45], v149 offset:50176
	ds_read_b128 v[220:223], v149 offset:51200
	ds_read_b128 v[224:227], v149 offset:52224
	ds_read_b128 v[228:231], v149 offset:53248
	ds_read_b128 v[232:235], v149 offset:54272
	ds_read_b128 v[236:239], v149 offset:55296
	ds_read_b128 v[240:243], v149 offset:56320
	s_add_u32 s30, s48, 0x180
	s_addc_u32 s31, s49, 0
	s_mov_b32 m0, s67
	s_nop 0
	global_load_lds_dwordx4 v142, s[30:31] offset:0
	s_nop 0
	s_mov_b32 m0, s68
	s_nop 0
	global_load_lds_dwordx4 v144, s[30:31] offset:0
	s_add_u32 s30, s48, 0x80180
	s_addc_u32 s31, s49, 0
	s_mov_b32 m0, s71
	s_nop 0
	global_load_lds_dwordx4 v142, s[30:31] offset:0
	s_nop 0
	s_mov_b32 m0, s72
	s_nop 0
	global_load_lds_dwordx4 v144, s[30:31] offset:0
	s_nop 0
	s_mov_b32 m0, s69
	s_nop 0
	global_load_lds_dwordx4 v1, s[38:39] offset:0
	s_nop 0
	s_mov_b32 m0, s70
	s_nop 0
	global_load_lds_dwordx4 v143, s[38:39] offset:0
	s_waitcnt vmcnt(8)
	s_waitcnt lgkmcnt(0)
	s_barrier
	s_setprio 1
	v_mfma_f32_16x16x32_bf16 v[30:33], v[12:15], v[38:41], v[138:141]
	v_mfma_f32_16x16x32_bf16 v[66:69], v[16:19], v[42:45], v[30:33]
	v_mfma_f32_16x16x32_bf16 v[30:33], v[22:25], v[38:41], v[152:155]
	v_mfma_f32_16x16x32_bf16 v[62:65], v[26:29], v[42:45], v[30:33]
	v_mfma_f32_16x16x32_bf16 v[30:33], v[12:15], v[220:223], v[156:159]
	v_mfma_f32_16x16x32_bf16 v[50:53], v[16:19], v[224:227], v[30:33]
	v_mfma_f32_16x16x32_bf16 v[30:33], v[22:25], v[220:223], v[160:163]
	v_mfma_f32_16x16x32_bf16 v[46:49], v[26:29], v[224:227], v[30:33]
	v_mfma_f32_16x16x32_bf16 v[30:33], v[12:15], v[228:231], v[164:167]
	v_mfma_f32_16x16x32_bf16 v[4:7], v[12:15], v[236:239], v[4:7]
	v_mfma_f32_16x16x32_bf16 v[34:37], v[16:19], v[232:235], v[30:33]
	v_mfma_f32_16x16x32_bf16 v[30:33], v[22:25], v[228:231], v[168:171]
	v_mfma_f32_16x16x32_bf16 v[18:21], v[16:19], v[240:243], v[4:7]
	v_mfma_f32_16x16x32_bf16 v[4:7], v[22:25], v[236:239], v[8:11]
	v_mfma_f32_16x16x32_bf16 v[30:33], v[26:29], v[232:235], v[30:33]
	v_mfma_f32_16x16x32_bf16 v[14:17], v[26:29], v[240:243], v[4:7]
	s_setprio 0
	s_setprio 1
	v_mfma_f32_16x16x32_bf16 v[4:7], v[204:207], v[38:41], v[172:175]
	v_mfma_f32_16x16x32_bf16 v[58:61], v[208:211], v[42:45], v[4:7]
	v_mfma_f32_16x16x32_bf16 v[4:7], v[212:215], v[38:41], v[176:179]
	v_mfma_f32_16x16x32_bf16 v[54:57], v[216:219], v[42:45], v[4:7]
	v_mfma_f32_16x16x32_bf16 v[4:7], v[204:207], v[220:223], v[180:183]
	v_mfma_f32_16x16x32_bf16 v[42:45], v[208:211], v[224:227], v[4:7]
	v_mfma_f32_16x16x32_bf16 v[4:7], v[212:215], v[220:223], v[184:187]
	v_mfma_f32_16x16x32_bf16 v[38:41], v[216:219], v[224:227], v[4:7]
	v_mfma_f32_16x16x32_bf16 v[4:7], v[204:207], v[228:231], v[188:191]
	v_mfma_f32_16x16x32_bf16 v[26:29], v[208:211], v[232:235], v[4:7]
	v_mfma_f32_16x16x32_bf16 v[4:7], v[212:215], v[228:231], v[192:195]
	v_mfma_f32_16x16x32_bf16 v[22:25], v[216:219], v[232:235], v[4:7]
	v_mfma_f32_16x16x32_bf16 v[4:7], v[204:207], v[236:239], v[196:199]
	v_mfma_f32_16x16x32_bf16 v[10:13], v[208:211], v[240:243], v[4:7]
	v_mfma_f32_16x16x32_bf16 v[4:7], v[212:215], v[236:239], v[200:203]
	v_mfma_f32_16x16x32_bf16 v[6:9], v[216:219], v[240:243], v[4:7]
	s_setprio 0
	s_barrier
	s_mov_b32 s50, 2
	s_branch .LBB0_3467

.LBB0_3468:
	ds_read_b128 v[138:141], v147
	ds_read_b128 v[152:155], v147 offset:1024
	ds_read_b128 v[156:159], v147 offset:2048
	ds_read_b128 v[160:163], v147 offset:3072
	ds_read_b128 v[164:167], v148
	ds_read_b128 v[168:171], v148 offset:1024
	ds_read_b128 v[172:175], v148 offset:2048
	ds_read_b128 v[176:179], v148 offset:3072
	s_cmp_eq_u32 s80, 28
	s_cselect_b32 s52, s43, s83
	s_cselect_b32 s53, s37, s84
	s_cselect_b32 s50, s79, s81
	s_cselect_b32 s51, s29, s82
	s_add_u32 s48, s52, 0x80
	s_addc_u32 s49, s53, 0
	ds_read_b128 v[180:183], v149
	ds_read_b128 v[184:187], v149 offset:1024
	ds_read_b128 v[188:191], v149 offset:2048
	ds_read_b128 v[192:195], v149 offset:3072
	ds_read_b128 v[196:199], v149 offset:4096
	ds_read_b128 v[200:203], v149 offset:5120
	ds_read_b128 v[204:207], v149 offset:6144
	ds_read_b128 v[208:211], v149 offset:7168
	s_mov_b32 m0, s73
	s_nop 0
	global_load_lds_dwordx4 v1, s[46:47] offset:0
	s_nop 0
	s_mov_b32 m0, s74
	s_nop 0
	global_load_lds_dwordx4 v143, s[46:47] offset:0
	s_waitcnt vmcnt(8)
	s_waitcnt lgkmcnt(0)
	s_barrier
	s_setprio 1
	v_mfma_f32_16x16x32_bf16 v[130:133], v[138:141], v[180:183], v[130:133]
	v_mfma_f32_16x16x32_bf16 v[130:133], v[152:155], v[184:187], v[130:133]
	v_mfma_f32_16x16x32_bf16 v[126:129], v[156:159], v[180:183], v[126:129]
	v_mfma_f32_16x16x32_bf16 v[126:129], v[160:163], v[184:187], v[126:129]
	v_mfma_f32_16x16x32_bf16 v[114:117], v[138:141], v[188:191], v[114:117]
	v_mfma_f32_16x16x32_bf16 v[114:117], v[152:155], v[192:195], v[114:117]
	v_mfma_f32_16x16x32_bf16 v[110:113], v[156:159], v[188:191], v[110:113]
	v_mfma_f32_16x16x32_bf16 v[110:113], v[160:163], v[192:195], v[110:113]
	v_mfma_f32_16x16x32_bf16 v[98:101], v[138:141], v[196:199], v[98:101]
	v_mfma_f32_16x16x32_bf16 v[98:101], v[152:155], v[200:203], v[98:101]
	v_mfma_f32_16x16x32_bf16 v[94:97], v[156:159], v[196:199], v[94:97]
	v_mfma_f32_16x16x32_bf16 v[94:97], v[160:163], v[200:203], v[94:97]
	v_mfma_f32_16x16x32_bf16 v[82:85], v[138:141], v[204:207], v[82:85]
	v_mfma_f32_16x16x32_bf16 v[82:85], v[152:155], v[208:211], v[82:85]
	v_mfma_f32_16x16x32_bf16 v[78:81], v[156:159], v[204:207], v[78:81]
	v_mfma_f32_16x16x32_bf16 v[78:81], v[160:163], v[208:211], v[78:81]
	s_setprio 0
	s_setprio 1
	v_mfma_f32_16x16x32_bf16 v[122:125], v[164:167], v[180:183], v[122:125]
	v_mfma_f32_16x16x32_bf16 v[122:125], v[168:171], v[184:187], v[122:125]
	v_mfma_f32_16x16x32_bf16 v[118:121], v[172:175], v[180:183], v[118:121]
	v_mfma_f32_16x16x32_bf16 v[118:121], v[176:179], v[184:187], v[118:121]
	v_mfma_f32_16x16x32_bf16 v[106:109], v[164:167], v[188:191], v[106:109]
	v_mfma_f32_16x16x32_bf16 v[106:109], v[168:171], v[192:195], v[106:109]
	v_mfma_f32_16x16x32_bf16 v[102:105], v[172:175], v[188:191], v[102:105]
	v_mfma_f32_16x16x32_bf16 v[102:105], v[176:179], v[192:195], v[102:105]
	v_mfma_f32_16x16x32_bf16 v[90:93], v[164:167], v[196:199], v[90:93]
	v_mfma_f32_16x16x32_bf16 v[90:93], v[168:171], v[200:203], v[90:93]
	v_mfma_f32_16x16x32_bf16 v[86:89], v[172:175], v[196:199], v[86:89]
	v_mfma_f32_16x16x32_bf16 v[86:89], v[176:179], v[200:203], v[86:89]
	v_mfma_f32_16x16x32_bf16 v[74:77], v[164:167], v[204:207], v[74:77]
	v_mfma_f32_16x16x32_bf16 v[74:77], v[168:171], v[208:211], v[74:77]
	v_mfma_f32_16x16x32_bf16 v[70:73], v[172:175], v[204:207], v[70:73]
	v_mfma_f32_16x16x32_bf16 v[70:73], v[176:179], v[208:211], v[70:73]
	s_setprio 0
	s_barrier
	ds_read_b128 v[180:183], v149 offset:16384
	ds_read_b128 v[184:187], v149 offset:17408
	ds_read_b128 v[188:191], v149 offset:18432
	ds_read_b128 v[192:195], v149 offset:19456
	ds_read_b128 v[196:199], v149 offset:20480
	ds_read_b128 v[200:203], v149 offset:21504
	ds_read_b128 v[204:207], v149 offset:22528
	ds_read_b128 v[208:211], v149 offset:23552
	s_mov_b32 m0, s45
	s_nop 0
	global_load_lds_dwordx4 v142, s[50:51] offset:0
	s_add_u32 s30, s50, 0x80000
	s_mov_b32 m0, s54
	s_nop 0
	global_load_lds_dwordx4 v144, s[50:51] offset:0
	s_addc_u32 s31, s51, 0
	s_mov_b32 m0, s55
	s_nop 0
	global_load_lds_dwordx4 v142, s[30:31] offset:0
	s_nop 0
	s_mov_b32 m0, s56
	s_nop 0
	global_load_lds_dwordx4 v144, s[30:31] offset:0
	s_nop 0
	s_mov_b32 m0, s33
	s_nop 0
	global_load_lds_dwordx4 v1, s[52:53] offset:0
	s_nop 0
	s_mov_b32 m0, s57
	s_nop 0
	global_load_lds_dwordx4 v143, s[52:53] offset:0
	s_waitcnt vmcnt(8)
	s_waitcnt lgkmcnt(0)
	s_barrier
	s_setprio 1
	v_mfma_f32_16x16x32_bf16 v[66:69], v[138:141], v[180:183], v[66:69]
	v_mfma_f32_16x16x32_bf16 v[66:69], v[152:155], v[184:187], v[66:69]
	v_mfma_f32_16x16x32_bf16 v[62:65], v[156:159], v[180:183], v[62:65]
	v_mfma_f32_16x16x32_bf16 v[62:65], v[160:163], v[184:187], v[62:65]
	v_mfma_f32_16x16x32_bf16 v[50:53], v[138:141], v[188:191], v[50:53]
	v_mfma_f32_16x16x32_bf16 v[50:53], v[152:155], v[192:195], v[50:53]
	v_mfma_f32_16x16x32_bf16 v[46:49], v[156:159], v[188:191], v[46:49]
	v_mfma_f32_16x16x32_bf16 v[46:49], v[160:163], v[192:195], v[46:49]
	v_mfma_f32_16x16x32_bf16 v[34:37], v[138:141], v[196:199], v[34:37]
	v_mfma_f32_16x16x32_bf16 v[34:37], v[152:155], v[200:203], v[34:37]
	v_mfma_f32_16x16x32_bf16 v[30:33], v[156:159], v[196:199], v[30:33]
	v_mfma_f32_16x16x32_bf16 v[30:33], v[160:163], v[200:203], v[30:33]
	v_mfma_f32_16x16x32_bf16 v[18:21], v[138:141], v[204:207], v[18:21]
	v_mfma_f32_16x16x32_bf16 v[18:21], v[152:155], v[208:211], v[18:21]
	v_mfma_f32_16x16x32_bf16 v[14:17], v[156:159], v[204:207], v[14:17]
	v_mfma_f32_16x16x32_bf16 v[14:17], v[160:163], v[208:211], v[14:17]
	s_setprio 0
	s_setprio 1
	v_mfma_f32_16x16x32_bf16 v[58:61], v[164:167], v[180:183], v[58:61]
	v_mfma_f32_16x16x32_bf16 v[54:57], v[172:175], v[180:183], v[54:57]
	v_mfma_f32_16x16x32_bf16 v[42:45], v[164:167], v[188:191], v[42:45]
	v_mfma_f32_16x16x32_bf16 v[38:41], v[172:175], v[188:191], v[38:41]
	v_mfma_f32_16x16x32_bf16 v[26:29], v[164:167], v[196:199], v[26:29]
	v_mfma_f32_16x16x32_bf16 v[22:25], v[172:175], v[196:199], v[22:25]
	v_mfma_f32_16x16x32_bf16 v[10:13], v[164:167], v[204:207], v[10:13]
	v_mfma_f32_16x16x32_bf16 v[4:7], v[172:175], v[204:207], v[6:9]
	v_mfma_f32_16x16x32_bf16 v[58:61], v[168:171], v[184:187], v[58:61]
	v_mfma_f32_16x16x32_bf16 v[54:57], v[176:179], v[184:187], v[54:57]
	v_mfma_f32_16x16x32_bf16 v[42:45], v[168:171], v[192:195], v[42:45]
	v_mfma_f32_16x16x32_bf16 v[38:41], v[176:179], v[192:195], v[38:41]
	v_mfma_f32_16x16x32_bf16 v[26:29], v[168:171], v[200:203], v[26:29]
	v_mfma_f32_16x16x32_bf16 v[22:25], v[176:179], v[200:203], v[22:25]
	v_mfma_f32_16x16x32_bf16 v[10:13], v[168:171], v[208:211], v[10:13]
	v_mfma_f32_16x16x32_bf16 v[4:7], v[176:179], v[208:211], v[4:7]
	s_setprio 0
	s_barrier
; #define PG8_KSETUP() const bool last = (t == nt - 2); const char* a1 = cA + (size_t)(t + 1) * kstep; \
;             const char* a2 = last ? nA : cA + (size_t)(t + 2) * kstep; const char* b2 = last ? nB : cB + (size_t)(t + 2) * kstep; const char* a3 = a2 + kstep; const char* b3 = b2 + kstep; \
;             if (last && has_next) S.a_ready(nxt)
; template <class Epi, class Sched, bool ALIGN_EPI = false, bool SP2 = false>
; __device__ __forceinline__ void gemm_phase(PG8_LAS unsigned char* lds, const Gemm g, const Sched& S, const Epi& E) {
;     ...
;         int t0 = 0;
;         if constexpr (SP2 && Epi::NVM == 16) { if (ui > 0) { const int t = 0; PG8_KSETUP(); PG8_KITER_SP2(24, 24); t0 = 2; } }
;         if constexpr (SP2 && Epi::NVM == 8) { if (ui > 0) { const int t = 0; PG8_KSETUP(); PG8_KITER_SP2(16, 16); t0 = 2; } }
;         for (int t = t0; t < nt; t += 2) {
;             PG8_KSETUP();
;             if constexpr (SP2) {
;             PG8_KITER_SP2(8, 8);
	ds_read_b128 v[138:141], v150
	ds_read_b128 v[152:155], v150 offset:1024
	ds_read_b128 v[156:159], v150 offset:2048
	ds_read_b128 v[160:163], v150 offset:3072
	ds_read_b128 v[164:167], v151
	ds_read_b128 v[168:171], v151 offset:1024
	ds_read_b128 v[172:175], v151 offset:2048
	ds_read_b128 v[176:179], v151 offset:3072
	ds_read_b128 v[180:183], v149 offset:32768
	ds_read_b128 v[184:187], v149 offset:33792
	ds_read_b128 v[188:191], v149 offset:34816
	ds_read_b128 v[192:195], v149 offset:35840
	ds_read_b128 v[196:199], v149 offset:36864
	ds_read_b128 v[200:203], v149 offset:37888
	ds_read_b128 v[204:207], v149 offset:38912
	ds_read_b128 v[208:211], v149 offset:39936
	s_add_u32 s30, s52, 0x80000
	s_addc_u32 s31, s53, 0
	s_mov_b32 m0, s58
	s_nop 0
	global_load_lds_dwordx4 v1, s[30:31] offset:0
	s_nop 0
	s_mov_b32 m0, s59
	s_nop 0
	global_load_lds_dwordx4 v143, s[30:31] offset:0
	s_waitcnt vmcnt(8)
	s_waitcnt lgkmcnt(0)
	s_barrier
	s_setprio 1
	v_mfma_f32_16x16x32_bf16 v[130:133], v[138:141], v[180:183], v[130:133]
	v_mfma_f32_16x16x32_bf16 v[130:133], v[152:155], v[184:187], v[130:133]
	v_mfma_f32_16x16x32_bf16 v[126:129], v[156:159], v[180:183], v[126:129]
	v_mfma_f32_16x16x32_bf16 v[126:129], v[160:163], v[184:187], v[126:129]
	v_mfma_f32_16x16x32_bf16 v[114:117], v[138:141], v[188:191], v[114:117]
	v_mfma_f32_16x16x32_bf16 v[114:117], v[152:155], v[192:195], v[114:117]
	v_mfma_f32_16x16x32_bf16 v[110:113], v[156:159], v[188:191], v[110:113]
	v_mfma_f32_16x16x32_bf16 v[110:113], v[160:163], v[192:195], v[110:113]
	v_mfma_f32_16x16x32_bf16 v[98:101], v[138:141], v[196:199], v[98:101]
	v_mfma_f32_16x16x32_bf16 v[98:101], v[152:155], v[200:203], v[98:101]
	v_mfma_f32_16x16x32_bf16 v[94:97], v[156:159], v[196:199], v[94:97]
	v_mfma_f32_16x16x32_bf16 v[94:97], v[160:163], v[200:203], v[94:97]
	v_mfma_f32_16x16x32_bf16 v[82:85], v[138:141], v[204:207], v[82:85]
	v_mfma_f32_16x16x32_bf16 v[82:85], v[152:155], v[208:211], v[82:85]
	v_mfma_f32_16x16x32_bf16 v[78:81], v[156:159], v[204:207], v[78:81]
	v_mfma_f32_16x16x32_bf16 v[78:81], v[160:163], v[208:211], v[78:81]
	s_setprio 0
	s_setprio 1
	v_mfma_f32_16x16x32_bf16 v[122:125], v[164:167], v[180:183], v[122:125]
	v_mfma_f32_16x16x32_bf16 v[122:125], v[168:171], v[184:187], v[122:125]
	v_mfma_f32_16x16x32_bf16 v[118:121], v[172:175], v[180:183], v[118:121]
	v_mfma_f32_16x16x32_bf16 v[118:121], v[176:179], v[184:187], v[118:121]
	v_mfma_f32_16x16x32_bf16 v[106:109], v[164:167], v[188:191], v[106:109]
	v_mfma_f32_16x16x32_bf16 v[106:109], v[168:171], v[192:195], v[106:109]
	v_mfma_f32_16x16x32_bf16 v[102:105], v[172:175], v[188:191], v[102:105]
	v_mfma_f32_16x16x32_bf16 v[102:105], v[176:179], v[192:195], v[102:105]
	v_mfma_f32_16x16x32_bf16 v[90:93], v[164:167], v[196:199], v[90:93]
	v_mfma_f32_16x16x32_bf16 v[90:93], v[168:171], v[200:203], v[90:93]
	v_mfma_f32_16x16x32_bf16 v[86:89], v[172:175], v[196:199], v[86:89]
	v_mfma_f32_16x16x32_bf16 v[86:89], v[176:179], v[200:203], v[86:89]
	v_mfma_f32_16x16x32_bf16 v[74:77], v[164:167], v[204:207], v[74:77]
	v_mfma_f32_16x16x32_bf16 v[74:77], v[168:171], v[208:211], v[74:77]
	v_mfma_f32_16x16x32_bf16 v[70:73], v[172:175], v[204:207], v[70:73]
	v_mfma_f32_16x16x32_bf16 v[70:73], v[176:179], v[208:211], v[70:73]
	s_setprio 0
	s_barrier
	ds_read_b128 v[180:183], v149 offset:49152
	ds_read_b128 v[184:187], v149 offset:50176
	ds_read_b128 v[188:191], v149 offset:51200
	ds_read_b128 v[192:195], v149 offset:52224
	ds_read_b128 v[196:199], v149 offset:53248
	ds_read_b128 v[200:203], v149 offset:54272
	ds_read_b128 v[204:207], v149 offset:55296
	ds_read_b128 v[208:211], v149 offset:56320
	s_add_u32 s30, s50, 0x80
	s_addc_u32 s31, s51, 0
	s_mov_b32 m0, s67
	s_nop 0
	global_load_lds_dwordx4 v142, s[30:31] offset:0
	s_nop 0
	s_mov_b32 m0, s68
	s_nop 0
	global_load_lds_dwordx4 v144, s[30:31] offset:0
	s_add_u32 s30, s50, 0x80080
	s_addc_u32 s31, s51, 0
	s_mov_b32 m0, s71
	s_nop 0
	global_load_lds_dwordx4 v142, s[30:31] offset:0
	s_nop 0
	s_mov_b32 m0, s72
	s_nop 0
	global_load_lds_dwordx4 v144, s[30:31] offset:0
	s_nop 0
	s_mov_b32 m0, s69
	s_nop 0
	global_load_lds_dwordx4 v1, s[48:49] offset:0
	s_nop 0
	s_mov_b32 m0, s70
	s_nop 0
	global_load_lds_dwordx4 v143, s[48:49] offset:0
	s_waitcnt vmcnt(8)
	s_waitcnt lgkmcnt(0)
	s_barrier
	s_setprio 1
	v_mfma_f32_16x16x32_bf16 v[66:69], v[138:141], v[180:183], v[66:69]
	v_mfma_f32_16x16x32_bf16 v[66:69], v[152:155], v[184:187], v[66:69]
	v_mfma_f32_16x16x32_bf16 v[62:65], v[156:159], v[180:183], v[62:65]
	v_mfma_f32_16x16x32_bf16 v[62:65], v[160:163], v[184:187], v[62:65]
	v_mfma_f32_16x16x32_bf16 v[50:53], v[138:141], v[188:191], v[50:53]
	v_mfma_f32_16x16x32_bf16 v[50:53], v[152:155], v[192:195], v[50:53]
	v_mfma_f32_16x16x32_bf16 v[46:49], v[156:159], v[188:191], v[46:49]
	v_mfma_f32_16x16x32_bf16 v[46:49], v[160:163], v[192:195], v[46:49]
	v_mfma_f32_16x16x32_bf16 v[34:37], v[138:141], v[196:199], v[34:37]
	v_mfma_f32_16x16x32_bf16 v[34:37], v[152:155], v[200:203], v[34:37]
	v_mfma_f32_16x16x32_bf16 v[30:33], v[156:159], v[196:199], v[30:33]
	v_mfma_f32_16x16x32_bf16 v[30:33], v[160:163], v[200:203], v[30:33]
	v_mfma_f32_16x16x32_bf16 v[18:21], v[138:141], v[204:207], v[18:21]
	v_mfma_f32_16x16x32_bf16 v[18:21], v[152:155], v[208:211], v[18:21]
	v_mfma_f32_16x16x32_bf16 v[14:17], v[156:159], v[204:207], v[14:17]
	v_mfma_f32_16x16x32_bf16 v[14:17], v[160:163], v[208:211], v[14:17]
	s_setprio 0
	s_setprio 1
	v_mfma_f32_16x16x32_bf16 v[58:61], v[164:167], v[180:183], v[58:61]
	v_mfma_f32_16x16x32_bf16 v[54:57], v[172:175], v[180:183], v[54:57]
	v_mfma_f32_16x16x32_bf16 v[42:45], v[164:167], v[188:191], v[42:45]
	v_mfma_f32_16x16x32_bf16 v[38:41], v[172:175], v[188:191], v[38:41]
	v_mfma_f32_16x16x32_bf16 v[26:29], v[164:167], v[196:199], v[26:29]
	v_mfma_f32_16x16x32_bf16 v[22:25], v[172:175], v[196:199], v[22:25]
	v_mfma_f32_16x16x32_bf16 v[8:11], v[164:167], v[204:207], v[10:13]
	v_mfma_f32_16x16x32_bf16 v[4:7], v[172:175], v[204:207], v[4:7]
	v_mfma_f32_16x16x32_bf16 v[58:61], v[168:171], v[184:187], v[58:61]
	v_mfma_f32_16x16x32_bf16 v[54:57], v[176:179], v[184:187], v[54:57]
	v_mfma_f32_16x16x32_bf16 v[42:45], v[168:171], v[192:195], v[42:45]
	v_mfma_f32_16x16x32_bf16 v[38:41], v[176:179], v[192:195], v[38:41]
	v_mfma_f32_16x16x32_bf16 v[26:29], v[168:171], v[200:203], v[26:29]
	v_mfma_f32_16x16x32_bf16 v[22:25], v[176:179], v[200:203], v[22:25]
	v_mfma_f32_16x16x32_bf16 v[10:13], v[168:171], v[208:211], v[8:11]
	v_mfma_f32_16x16x32_bf16 v[6:9], v[176:179], v[208:211], v[4:7]
	s_setprio 0
	s_barrier
	s_add_i32 s80, s80, 2
	s_add_u32 s81, s81, 0x100
	s_addc_u32 s82, s82, 0
	s_add_u32 s83, s83, 0x100
	s_addc_u32 s84, s84, 0
	s_add_u32 s46, s46, 0x100
	s_addc_u32 s47, s47, 0
	s_cmp_gt_u32 s80, 29
	s_cbranch_scc0 .LBB0_3468
	s_and_b64 vcc, exec, s[18:19]
	s_cbranch_vccz .LBB0_3471
	s_barrier

; #define PG8_KSETUP() const bool last = (t == nt - 2); const char* a1 = cA + (size_t)(t + 1) * kstep; \
;             const char* a2 = last ? nA : cA + (size_t)(t + 2) * kstep; const char* b2 = last ? nB : cB + (size_t)(t + 2) * kstep; const char* a3 = a2 + kstep; const char* b3 = b2 + kstep; \
;             if (last && has_next) S.a_ready(nxt)
; template <class Epi, class Sched, bool ALIGN_EPI = false, bool SP2 = false>
; __device__ __forceinline__ void gemm_phase(PG8_LAS unsigned char* lds, const Gemm g, const Sched& S, const Epi& E) {
;     ...
;         if constexpr (SP2 && Epi::NVM == 16) { if (ui > 0) { const int t = 0; PG8_KSETUP(); PG8_KITER_SP2(24, 24); t0 = 2; } }
;         if constexpr (SP2 && Epi::NVM == 8) { if (ui > 0) { const int t = 0; PG8_KSETUP(); PG8_KITER_SP2(16, 16); t0 = 2; } }
.LBB0_3617:
	s_cmp_lg_u32 s69, 0
	s_mov_b32 s40, 0
	s_cbranch_scc0 .LBB0_3619
	ds_read_b128 v[4:7], v152
	ds_read_b128 v[8:11], v152 offset:1024
	ds_read_b128 v[12:15], v152 offset:2048
	ds_read_b128 v[16:19], v152 offset:3072
	ds_read_b128 v[20:23], v153
	ds_read_b128 v[24:27], v153 offset:1024
	ds_read_b128 v[28:31], v153 offset:2048
	ds_read_b128 v[32:35], v153 offset:3072
	s_add_u32 s24, s36, 0x100
	s_addc_u32 s25, s37, 0
	s_add_u32 s30, s38, 0x100
	s_addc_u32 s31, s39, 0
	s_add_u32 s22, s36, 0x180
	s_addc_u32 s23, s37, 0
	ds_read_b128 v[36:39], v154
	ds_read_b128 v[40:43], v154 offset:1024
	ds_read_b128 v[44:47], v154 offset:2048
	ds_read_b128 v[48:51], v154 offset:3072
	ds_read_b128 v[52:55], v154 offset:4096
	ds_read_b128 v[56:59], v154 offset:5120
	ds_read_b128 v[60:63], v154 offset:6144
	ds_read_b128 v[64:67], v154 offset:7168
	s_add_u32 s40, s36, 0x80080
	s_addc_u32 s41, s37, 0
	s_mov_b32 m0, s56
	s_nop 0
	global_load_lds_dwordx4 v1, s[40:41] offset:0
	s_nop 0
	s_mov_b32 m0, s57
	s_nop 0
	global_load_lds_dwordx4 v147, s[40:41] offset:0
	s_waitcnt vmcnt(16)
	s_waitcnt lgkmcnt(0)
	s_barrier
	s_setprio 1
	v_mfma_f32_16x16x32_bf16 v[92:95], v[4:7], v[60:63], 0
	v_mfma_f32_16x16x32_bf16 v[68:71], v[4:7], v[36:39], 0
	v_mfma_f32_16x16x32_bf16 v[72:75], v[12:15], v[36:39], 0
	v_mfma_f32_16x16x32_bf16 v[76:79], v[4:7], v[44:47], 0
	v_mfma_f32_16x16x32_bf16 v[80:83], v[12:15], v[44:47], 0
	v_mfma_f32_16x16x32_bf16 v[84:87], v[4:7], v[52:55], 0
	v_mfma_f32_16x16x32_bf16 v[88:91], v[12:15], v[52:55], 0
	v_mfma_f32_16x16x32_bf16 v[102:105], v[8:11], v[64:67], v[92:95]
	v_mfma_f32_16x16x32_bf16 v[92:95], v[12:15], v[60:63], 0
	v_mfma_f32_16x16x32_bf16 v[68:71], v[8:11], v[40:43], v[68:71]
	v_mfma_f32_16x16x32_bf16 v[72:75], v[16:19], v[40:43], v[72:75]
	v_mfma_f32_16x16x32_bf16 v[76:79], v[8:11], v[48:51], v[76:79]
	v_mfma_f32_16x16x32_bf16 v[80:83], v[16:19], v[48:51], v[80:83]
	v_mfma_f32_16x16x32_bf16 v[84:87], v[8:11], v[56:59], v[84:87]
	v_mfma_f32_16x16x32_bf16 v[88:91], v[16:19], v[56:59], v[88:91]
	v_mfma_f32_16x16x32_bf16 v[106:109], v[16:19], v[64:67], v[92:95]
	s_setprio 0
	s_setprio 1
	v_mfma_f32_16x16x32_bf16 v[92:95], v[20:23], v[36:39], 0
	v_mfma_f32_16x16x32_bf16 v[36:39], v[28:31], v[36:39], 0
	v_mfma_f32_16x16x32_bf16 v[118:121], v[24:27], v[40:43], v[92:95]
	v_mfma_f32_16x16x32_bf16 v[36:39], v[32:35], v[40:43], v[36:39]
	v_mfma_f32_16x16x32_bf16 v[40:43], v[20:23], v[44:47], 0
	v_mfma_f32_16x16x32_bf16 v[44:47], v[28:31], v[44:47], 0
	v_mfma_f32_16x16x32_bf16 v[40:43], v[24:27], v[48:51], v[40:43]
	v_mfma_f32_16x16x32_bf16 v[44:47], v[32:35], v[48:51], v[44:47]
	v_mfma_f32_16x16x32_bf16 v[48:51], v[20:23], v[52:55], 0
	v_mfma_f32_16x16x32_bf16 v[52:55], v[28:31], v[52:55], 0
	v_mfma_f32_16x16x32_bf16 v[48:51], v[24:27], v[56:59], v[48:51]
	v_mfma_f32_16x16x32_bf16 v[52:55], v[32:35], v[56:59], v[52:55]
	v_mfma_f32_16x16x32_bf16 v[56:59], v[20:23], v[60:63], 0
	v_mfma_f32_16x16x32_bf16 v[60:63], v[28:31], v[60:63], 0
	v_mfma_f32_16x16x32_bf16 v[56:59], v[24:27], v[64:67], v[56:59]
	v_mfma_f32_16x16x32_bf16 v[60:63], v[32:35], v[64:67], v[60:63]
	s_setprio 0
	s_barrier
	ds_read_b128 v[64:67], v154 offset:16384
	ds_read_b128 v[92:95], v154 offset:17408
	ds_read_b128 v[96:99], v154 offset:18432
	ds_read_b128 v[110:113], v154 offset:19456
	ds_read_b128 v[114:117], v154 offset:20480
	ds_read_b128 v[122:125], v154 offset:21504
	ds_read_b128 v[126:129], v154 offset:22528
	ds_read_b128 v[130:133], v154 offset:23552
	s_mov_b32 m0, s29
	s_nop 0
	global_load_lds_dwordx4 v146, s[30:31] offset:0
	s_nop 0
	s_mov_b32 m0, s44
	s_nop 0
	global_load_lds_dwordx4 v148, s[30:31] offset:0
	s_add_u32 s30, s38, 0x80100
	s_addc_u32 s31, s39, 0
	s_mov_b32 m0, s45
	s_nop 0
	global_load_lds_dwordx4 v146, s[30:31] offset:0
	s_nop 0
	s_mov_b32 m0, s46
	s_nop 0
	global_load_lds_dwordx4 v148, s[30:31] offset:0
	s_nop 0
	s_mov_b32 m0, s21
	s_nop 0
	global_load_lds_dwordx4 v1, s[24:25] offset:0
	s_nop 0
	s_mov_b32 m0, s47
	s_nop 0
	global_load_lds_dwordx4 v147, s[24:25] offset:0
	s_waitcnt vmcnt(16)
	s_waitcnt lgkmcnt(0)
	s_barrier
	s_setprio 1
	v_mfma_f32_16x16x32_bf16 v[138:141], v[4:7], v[64:67], 0
	v_mfma_f32_16x16x32_bf16 v[158:161], v[4:7], v[96:99], 0
	v_mfma_f32_16x16x32_bf16 v[166:169], v[4:7], v[114:117], 0
	v_mfma_f32_16x16x32_bf16 v[4:7], v[4:7], v[126:129], 0
	v_mfma_f32_16x16x32_bf16 v[138:141], v[8:11], v[92:95], v[138:141]
	v_mfma_f32_16x16x32_bf16 v[158:161], v[8:11], v[110:113], v[158:161]
	v_mfma_f32_16x16x32_bf16 v[166:169], v[8:11], v[122:125], v[166:169]
	v_mfma_f32_16x16x32_bf16 v[4:7], v[8:11], v[130:133], v[4:7]
	v_mfma_f32_16x16x32_bf16 v[8:11], v[12:15], v[126:129], 0
	v_mfma_f32_16x16x32_bf16 v[142:145], v[12:15], v[64:67], 0
	v_mfma_f32_16x16x32_bf16 v[162:165], v[12:15], v[96:99], 0
	v_mfma_f32_16x16x32_bf16 v[170:173], v[12:15], v[114:117], 0
	v_mfma_f32_16x16x32_bf16 v[8:11], v[16:19], v[130:133], v[8:11]
	v_mfma_f32_16x16x32_bf16 v[142:145], v[16:19], v[92:95], v[142:145]
	v_mfma_f32_16x16x32_bf16 v[162:165], v[16:19], v[110:113], v[162:165]
	v_mfma_f32_16x16x32_bf16 v[170:173], v[16:19], v[122:125], v[170:173]
	s_setprio 0
	s_setprio 1
	v_mfma_f32_16x16x32_bf16 v[12:15], v[20:23], v[64:67], 0
	v_mfma_f32_16x16x32_bf16 v[174:177], v[24:27], v[92:95], v[12:15]
	v_mfma_f32_16x16x32_bf16 v[12:15], v[28:31], v[64:67], 0
	v_mfma_f32_16x16x32_bf16 v[178:181], v[32:35], v[92:95], v[12:15]
	v_mfma_f32_16x16x32_bf16 v[12:15], v[20:23], v[96:99], 0
	v_mfma_f32_16x16x32_bf16 v[182:185], v[24:27], v[110:113], v[12:15]
	v_mfma_f32_16x16x32_bf16 v[12:15], v[28:31], v[96:99], 0
	v_mfma_f32_16x16x32_bf16 v[186:189], v[32:35], v[110:113], v[12:15]
	v_mfma_f32_16x16x32_bf16 v[12:15], v[20:23], v[114:117], 0
	v_mfma_f32_16x16x32_bf16 v[190:193], v[24:27], v[122:125], v[12:15]
	v_mfma_f32_16x16x32_bf16 v[12:15], v[28:31], v[114:117], 0
	v_mfma_f32_16x16x32_bf16 v[194:197], v[32:35], v[122:125], v[12:15]
	v_mfma_f32_16x16x32_bf16 v[12:15], v[20:23], v[126:129], 0
	v_mfma_f32_16x16x32_bf16 v[198:201], v[24:27], v[130:133], v[12:15]
	v_mfma_f32_16x16x32_bf16 v[12:15], v[28:31], v[126:129], 0
	v_mfma_f32_16x16x32_bf16 v[202:205], v[32:35], v[130:133], v[12:15]
	s_setprio 0
	s_barrier
; #define PG8_KSETUP() const bool last = (t == nt - 2); const char* a1 = cA + (size_t)(t + 1) * kstep; \
;             const char* a2 = last ? nA : cA + (size_t)(t + 2) * kstep; const char* b2 = last ? nB : cB + (size_t)(t + 2) * kstep; const char* a3 = a2 + kstep; const char* b3 = b2 + kstep; \
;             if (last && has_next) S.a_ready(nxt)
; template <class Epi, class Sched, bool ALIGN_EPI = false, bool SP2 = false>
; __device__ __forceinline__ void gemm_phase(PG8_LAS unsigned char* lds, const Gemm g, const Sched& S, const Epi& E) {
;     ...
;         int t0 = 0;
;         if constexpr (SP2 && Epi::NVM == 16) { if (ui > 0) { const int t = 0; PG8_KSETUP(); PG8_KITER_SP2(24, 24); t0 = 2; } }
;         if constexpr (SP2 && Epi::NVM == 8) { if (ui > 0) { const int t = 0; PG8_KSETUP(); PG8_KITER_SP2(16, 16); t0 = 2; } }
	s_nop 4
	ds_read_b128 v[12:15], v155
	ds_read_b128 v[16:19], v155 offset:1024
	ds_read_b128 v[22:25], v155 offset:2048
	ds_read_b128 v[26:29], v155 offset:3072
	ds_read_b128 v[206:209], v156
	ds_read_b128 v[210:213], v156 offset:1024
	ds_read_b128 v[214:217], v156 offset:2048
	ds_read_b128 v[218:221], v156 offset:3072
	ds_read_b128 v[30:33], v154 offset:32768
	ds_read_b128 v[64:67], v154 offset:33792
	ds_read_b128 v[222:225], v154 offset:34816
	ds_read_b128 v[226:229], v154 offset:35840
	ds_read_b128 v[230:233], v154 offset:36864
	ds_read_b128 v[234:237], v154 offset:37888
	ds_read_b128 v[238:241], v154 offset:38912
	ds_read_b128 v[242:245], v154 offset:39936
	s_add_u32 s24, s36, 0x80100
	s_addc_u32 s25, s37, 0
	s_mov_b32 m0, s48
	s_nop 0
	global_load_lds_dwordx4 v1, s[24:25] offset:0
	s_nop 0
	s_mov_b32 m0, s49
	s_nop 0
	global_load_lds_dwordx4 v147, s[24:25] offset:0
	s_waitcnt vmcnt(8)
	s_waitcnt lgkmcnt(0)
	s_barrier
	s_setprio 1
	v_mfma_f32_16x16x32_bf16 v[68:71], v[12:15], v[30:33], v[68:71]
	v_mfma_f32_16x16x32_bf16 v[130:133], v[16:19], v[64:67], v[68:71]
	v_mfma_f32_16x16x32_bf16 v[68:71], v[22:25], v[30:33], v[72:75]
	v_mfma_f32_16x16x32_bf16 v[126:129], v[26:29], v[64:67], v[68:71]
	v_mfma_f32_16x16x32_bf16 v[68:71], v[12:15], v[222:225], v[76:79]
	v_mfma_f32_16x16x32_bf16 v[114:117], v[16:19], v[226:229], v[68:71]
	v_mfma_f32_16x16x32_bf16 v[68:71], v[22:25], v[222:225], v[80:83]
	v_mfma_f32_16x16x32_bf16 v[110:113], v[26:29], v[226:229], v[68:71]
	v_mfma_f32_16x16x32_bf16 v[68:71], v[12:15], v[230:233], v[84:87]
	v_mfma_f32_16x16x32_bf16 v[98:101], v[16:19], v[234:237], v[68:71]
	v_mfma_f32_16x16x32_bf16 v[68:71], v[22:25], v[230:233], v[88:91]
	v_mfma_f32_16x16x32_bf16 v[94:97], v[26:29], v[234:237], v[68:71]
	v_mfma_f32_16x16x32_bf16 v[68:71], v[12:15], v[238:241], v[102:105]
	v_mfma_f32_16x16x32_bf16 v[82:85], v[16:19], v[242:245], v[68:71]
	v_mfma_f32_16x16x32_bf16 v[68:71], v[22:25], v[238:241], v[106:109]
	v_mfma_f32_16x16x32_bf16 v[78:81], v[26:29], v[242:245], v[68:71]
	s_setprio 0
	s_setprio 1
	v_mfma_f32_16x16x32_bf16 v[68:71], v[206:209], v[30:33], v[118:121]
	v_mfma_f32_16x16x32_bf16 v[30:33], v[214:217], v[30:33], v[36:39]
	v_mfma_f32_16x16x32_bf16 v[118:121], v[218:221], v[64:67], v[30:33]
	v_mfma_f32_16x16x32_bf16 v[30:33], v[206:209], v[222:225], v[40:43]
	v_mfma_f32_16x16x32_bf16 v[106:109], v[210:213], v[226:229], v[30:33]
	v_mfma_f32_16x16x32_bf16 v[30:33], v[214:217], v[222:225], v[44:47]
	v_mfma_f32_16x16x32_bf16 v[102:105], v[218:221], v[226:229], v[30:33]
	v_mfma_f32_16x16x32_bf16 v[30:33], v[206:209], v[230:233], v[48:51]
	v_mfma_f32_16x16x32_bf16 v[90:93], v[210:213], v[234:237], v[30:33]
	v_mfma_f32_16x16x32_bf16 v[30:33], v[214:217], v[230:233], v[52:55]
	v_mfma_f32_16x16x32_bf16 v[86:89], v[218:221], v[234:237], v[30:33]
	v_mfma_f32_16x16x32_bf16 v[30:33], v[206:209], v[238:241], v[56:59]
	v_mfma_f32_16x16x32_bf16 v[74:77], v[210:213], v[242:245], v[30:33]
	v_mfma_f32_16x16x32_bf16 v[30:33], v[214:217], v[238:241], v[60:63]
	v_mfma_f32_16x16x32_bf16 v[122:125], v[210:213], v[64:67], v[68:71]
	v_mfma_f32_16x16x32_bf16 v[66:69], v[218:221], v[242:245], v[30:33]
	s_setprio 0
	s_barrier
	ds_read_b128 v[38:41], v154 offset:49152
	ds_read_b128 v[42:45], v154 offset:50176
	ds_read_b128 v[222:225], v154 offset:51200
	ds_read_b128 v[226:229], v154 offset:52224
	ds_read_b128 v[230:233], v154 offset:53248
	ds_read_b128 v[234:237], v154 offset:54272
	ds_read_b128 v[238:241], v154 offset:55296
	ds_read_b128 v[242:245], v154 offset:56320
	s_add_u32 s24, s38, 0x180
	s_addc_u32 s25, s39, 0
	s_mov_b32 m0, s50
	s_nop 0
	global_load_lds_dwordx4 v146, s[24:25] offset:0
	s_nop 0
	s_mov_b32 m0, s51
	s_nop 0
	global_load_lds_dwordx4 v148, s[24:25] offset:0
	s_add_u32 s24, s38, 0x80180
	s_addc_u32 s25, s39, 0
	s_mov_b32 m0, s54
	s_nop 0
	global_load_lds_dwordx4 v146, s[24:25] offset:0
	s_nop 0
	s_mov_b32 m0, s55
	s_nop 0
	global_load_lds_dwordx4 v148, s[24:25] offset:0
	s_nop 0
	s_mov_b32 m0, s52
	s_nop 0
	global_load_lds_dwordx4 v1, s[22:23] offset:0
	s_nop 0
	s_mov_b32 m0, s53
	s_nop 0
	global_load_lds_dwordx4 v147, s[22:23] offset:0
	s_waitcnt vmcnt(8)
	s_waitcnt lgkmcnt(0)
	s_barrier
	s_setprio 1
	v_mfma_f32_16x16x32_bf16 v[30:33], v[12:15], v[38:41], v[138:141]
	v_mfma_f32_16x16x32_bf16 v[70:73], v[16:19], v[42:45], v[30:33]
	v_mfma_f32_16x16x32_bf16 v[30:33], v[22:25], v[38:41], v[142:145]
	v_mfma_f32_16x16x32_bf16 v[62:65], v[26:29], v[42:45], v[30:33]
	v_mfma_f32_16x16x32_bf16 v[30:33], v[12:15], v[222:225], v[158:161]
	v_mfma_f32_16x16x32_bf16 v[50:53], v[16:19], v[226:229], v[30:33]
	v_mfma_f32_16x16x32_bf16 v[30:33], v[22:25], v[222:225], v[162:165]
	v_mfma_f32_16x16x32_bf16 v[46:49], v[26:29], v[226:229], v[30:33]
	v_mfma_f32_16x16x32_bf16 v[30:33], v[12:15], v[230:233], v[166:169]
	v_mfma_f32_16x16x32_bf16 v[4:7], v[12:15], v[238:241], v[4:7]
	v_mfma_f32_16x16x32_bf16 v[34:37], v[16:19], v[234:237], v[30:33]
	v_mfma_f32_16x16x32_bf16 v[30:33], v[22:25], v[230:233], v[170:173]
	v_mfma_f32_16x16x32_bf16 v[18:21], v[16:19], v[242:245], v[4:7]
	v_mfma_f32_16x16x32_bf16 v[4:7], v[22:25], v[238:241], v[8:11]
	v_mfma_f32_16x16x32_bf16 v[30:33], v[26:29], v[234:237], v[30:33]
	v_mfma_f32_16x16x32_bf16 v[14:17], v[26:29], v[242:245], v[4:7]
	s_setprio 0
	s_setprio 1
	v_mfma_f32_16x16x32_bf16 v[4:7], v[206:209], v[38:41], v[174:177]
	v_mfma_f32_16x16x32_bf16 v[58:61], v[210:213], v[42:45], v[4:7]
	v_mfma_f32_16x16x32_bf16 v[4:7], v[214:217], v[38:41], v[178:181]
	v_mfma_f32_16x16x32_bf16 v[54:57], v[218:221], v[42:45], v[4:7]
	v_mfma_f32_16x16x32_bf16 v[4:7], v[206:209], v[222:225], v[182:185]
	v_mfma_f32_16x16x32_bf16 v[42:45], v[210:213], v[226:229], v[4:7]
	v_mfma_f32_16x16x32_bf16 v[4:7], v[214:217], v[222:225], v[186:189]
	v_mfma_f32_16x16x32_bf16 v[38:41], v[218:221], v[226:229], v[4:7]
	v_mfma_f32_16x16x32_bf16 v[4:7], v[206:209], v[230:233], v[190:193]
	v_mfma_f32_16x16x32_bf16 v[26:29], v[210:213], v[234:237], v[4:7]
	v_mfma_f32_16x16x32_bf16 v[4:7], v[214:217], v[230:233], v[194:197]
	v_mfma_f32_16x16x32_bf16 v[22:25], v[218:221], v[234:237], v[4:7]
	v_mfma_f32_16x16x32_bf16 v[4:7], v[206:209], v[238:241], v[198:201]
	v_mfma_f32_16x16x32_bf16 v[10:13], v[210:213], v[242:245], v[4:7]
	v_mfma_f32_16x16x32_bf16 v[4:7], v[214:217], v[238:241], v[202:205]
	v_mfma_f32_16x16x32_bf16 v[6:9], v[218:221], v[242:245], v[4:7]
	s_setprio 0
	s_barrier
	s_mov_b32 s40, 2
	s_branch .LBB0_3620

.LBB0_3621:
	ds_read_b128 v[138:141], v152
	ds_read_b128 v[142:145], v152 offset:1024
	ds_read_b128 v[158:161], v152 offset:2048
	ds_read_b128 v[162:165], v152 offset:3072
	ds_read_b128 v[166:169], v153
	ds_read_b128 v[170:173], v153 offset:1024
	ds_read_b128 v[174:177], v153 offset:2048
	ds_read_b128 v[178:181], v153 offset:3072
	s_cmp_eq_u32 s72, 28
	s_cselect_b32 s40, s70, s75
	s_cselect_b32 s41, s19, s76
	s_cselect_b32 s38, s71, s73
	s_cselect_b32 s39, s17, s74
	s_add_u32 s36, s40, 0x80
	s_addc_u32 s37, s41, 0
	ds_read_b128 v[182:185], v154
	ds_read_b128 v[186:189], v154 offset:1024
	ds_read_b128 v[190:193], v154 offset:2048
	ds_read_b128 v[194:197], v154 offset:3072
	ds_read_b128 v[198:201], v154 offset:4096
	ds_read_b128 v[202:205], v154 offset:5120
	ds_read_b128 v[206:209], v154 offset:6144
	ds_read_b128 v[210:213], v154 offset:7168
	s_add_u32 s30, s75, 0x7ff80
	s_addc_u32 s31, s76, 0
	s_mov_b32 m0, s56
	s_nop 0
	global_load_lds_dwordx4 v1, s[30:31] offset:0
	s_nop 0
	s_mov_b32 m0, s57
	s_nop 0
	global_load_lds_dwordx4 v147, s[30:31] offset:0
	s_waitcnt vmcnt(8)
	s_waitcnt lgkmcnt(0)
	s_barrier
	s_setprio 1
	v_mfma_f32_16x16x32_bf16 v[130:133], v[138:141], v[182:185], v[130:133]
	v_mfma_f32_16x16x32_bf16 v[130:133], v[142:145], v[186:189], v[130:133]
	v_mfma_f32_16x16x32_bf16 v[126:129], v[158:161], v[182:185], v[126:129]
	v_mfma_f32_16x16x32_bf16 v[126:129], v[162:165], v[186:189], v[126:129]
	v_mfma_f32_16x16x32_bf16 v[114:117], v[138:141], v[190:193], v[114:117]
	v_mfma_f32_16x16x32_bf16 v[114:117], v[142:145], v[194:197], v[114:117]
	v_mfma_f32_16x16x32_bf16 v[110:113], v[158:161], v[190:193], v[110:113]
	v_mfma_f32_16x16x32_bf16 v[110:113], v[162:165], v[194:197], v[110:113]
	v_mfma_f32_16x16x32_bf16 v[98:101], v[138:141], v[198:201], v[98:101]
	v_mfma_f32_16x16x32_bf16 v[98:101], v[142:145], v[202:205], v[98:101]
	v_mfma_f32_16x16x32_bf16 v[94:97], v[158:161], v[198:201], v[94:97]
	v_mfma_f32_16x16x32_bf16 v[94:97], v[162:165], v[202:205], v[94:97]
	v_mfma_f32_16x16x32_bf16 v[82:85], v[138:141], v[206:209], v[82:85]
	v_mfma_f32_16x16x32_bf16 v[82:85], v[142:145], v[210:213], v[82:85]
	v_mfma_f32_16x16x32_bf16 v[78:81], v[158:161], v[206:209], v[78:81]
	v_mfma_f32_16x16x32_bf16 v[78:81], v[162:165], v[210:213], v[78:81]
	s_setprio 0
	s_setprio 1
	v_mfma_f32_16x16x32_bf16 v[122:125], v[166:169], v[182:185], v[122:125]
	v_mfma_f32_16x16x32_bf16 v[122:125], v[170:173], v[186:189], v[122:125]
	v_mfma_f32_16x16x32_bf16 v[118:121], v[174:177], v[182:185], v[118:121]
	v_mfma_f32_16x16x32_bf16 v[118:121], v[178:181], v[186:189], v[118:121]
	v_mfma_f32_16x16x32_bf16 v[106:109], v[166:169], v[190:193], v[106:109]
	v_mfma_f32_16x16x32_bf16 v[106:109], v[170:173], v[194:197], v[106:109]
	v_mfma_f32_16x16x32_bf16 v[102:105], v[174:177], v[190:193], v[102:105]
	v_mfma_f32_16x16x32_bf16 v[102:105], v[178:181], v[194:197], v[102:105]
	v_mfma_f32_16x16x32_bf16 v[90:93], v[166:169], v[198:201], v[90:93]
	v_mfma_f32_16x16x32_bf16 v[90:93], v[170:173], v[202:205], v[90:93]
	v_mfma_f32_16x16x32_bf16 v[86:89], v[174:177], v[198:201], v[86:89]
	v_mfma_f32_16x16x32_bf16 v[86:89], v[178:181], v[202:205], v[86:89]
	v_mfma_f32_16x16x32_bf16 v[74:77], v[166:169], v[206:209], v[74:77]
	v_mfma_f32_16x16x32_bf16 v[74:77], v[170:173], v[210:213], v[74:77]
	v_mfma_f32_16x16x32_bf16 v[66:69], v[174:177], v[206:209], v[66:69]
	v_mfma_f32_16x16x32_bf16 v[66:69], v[178:181], v[210:213], v[66:69]
	s_setprio 0
	s_barrier
	ds_read_b128 v[182:185], v154 offset:16384
	ds_read_b128 v[186:189], v154 offset:17408
	ds_read_b128 v[190:193], v154 offset:18432
	ds_read_b128 v[194:197], v154 offset:19456
	ds_read_b128 v[198:201], v154 offset:20480
	ds_read_b128 v[202:205], v154 offset:21504
	ds_read_b128 v[206:209], v154 offset:22528
	ds_read_b128 v[210:213], v154 offset:23552
	s_mov_b32 m0, s29
	s_nop 0
	global_load_lds_dwordx4 v146, s[38:39] offset:0
	s_add_u32 s30, s38, 0x80000
	s_mov_b32 m0, s44
	s_nop 0
	global_load_lds_dwordx4 v148, s[38:39] offset:0
	s_addc_u32 s31, s39, 0
	s_mov_b32 m0, s45
	s_nop 0
	global_load_lds_dwordx4 v146, s[30:31] offset:0
	s_nop 0
	s_mov_b32 m0, s46
	s_nop 0
	global_load_lds_dwordx4 v148, s[30:31] offset:0
	s_nop 0
	s_mov_b32 m0, s21
	s_nop 0
	global_load_lds_dwordx4 v1, s[40:41] offset:0
	s_nop 0
	s_mov_b32 m0, s47
	s_nop 0
	global_load_lds_dwordx4 v147, s[40:41] offset:0
	s_waitcnt vmcnt(8)
	s_waitcnt lgkmcnt(0)
	s_barrier
	s_setprio 1
	v_mfma_f32_16x16x32_bf16 v[70:73], v[138:141], v[182:185], v[70:73]
	v_mfma_f32_16x16x32_bf16 v[70:73], v[142:145], v[186:189], v[70:73]
	v_mfma_f32_16x16x32_bf16 v[62:65], v[158:161], v[182:185], v[62:65]
	v_mfma_f32_16x16x32_bf16 v[62:65], v[162:165], v[186:189], v[62:65]
	v_mfma_f32_16x16x32_bf16 v[50:53], v[138:141], v[190:193], v[50:53]
	v_mfma_f32_16x16x32_bf16 v[50:53], v[142:145], v[194:197], v[50:53]
	v_mfma_f32_16x16x32_bf16 v[46:49], v[158:161], v[190:193], v[46:49]
	v_mfma_f32_16x16x32_bf16 v[46:49], v[162:165], v[194:197], v[46:49]
	v_mfma_f32_16x16x32_bf16 v[34:37], v[138:141], v[198:201], v[34:37]
	v_mfma_f32_16x16x32_bf16 v[34:37], v[142:145], v[202:205], v[34:37]
	v_mfma_f32_16x16x32_bf16 v[30:33], v[158:161], v[198:201], v[30:33]
	v_mfma_f32_16x16x32_bf16 v[30:33], v[162:165], v[202:205], v[30:33]
	v_mfma_f32_16x16x32_bf16 v[18:21], v[138:141], v[206:209], v[18:21]
	v_mfma_f32_16x16x32_bf16 v[18:21], v[142:145], v[210:213], v[18:21]
	v_mfma_f32_16x16x32_bf16 v[14:17], v[158:161], v[206:209], v[14:17]
	v_mfma_f32_16x16x32_bf16 v[14:17], v[162:165], v[210:213], v[14:17]
	s_setprio 0
	s_setprio 1
	v_mfma_f32_16x16x32_bf16 v[58:61], v[166:169], v[182:185], v[58:61]
	v_mfma_f32_16x16x32_bf16 v[54:57], v[174:177], v[182:185], v[54:57]
	v_mfma_f32_16x16x32_bf16 v[42:45], v[166:169], v[190:193], v[42:45]
	v_mfma_f32_16x16x32_bf16 v[38:41], v[174:177], v[190:193], v[38:41]
	v_mfma_f32_16x16x32_bf16 v[26:29], v[166:169], v[198:201], v[26:29]
	v_mfma_f32_16x16x32_bf16 v[22:25], v[174:177], v[198:201], v[22:25]
	v_mfma_f32_16x16x32_bf16 v[10:13], v[166:169], v[206:209], v[10:13]
	v_mfma_f32_16x16x32_bf16 v[4:7], v[174:177], v[206:209], v[6:9]
	v_mfma_f32_16x16x32_bf16 v[58:61], v[170:173], v[186:189], v[58:61]
	v_mfma_f32_16x16x32_bf16 v[54:57], v[178:181], v[186:189], v[54:57]
	v_mfma_f32_16x16x32_bf16 v[42:45], v[170:173], v[194:197], v[42:45]
	v_mfma_f32_16x16x32_bf16 v[38:41], v[178:181], v[194:197], v[38:41]
	v_mfma_f32_16x16x32_bf16 v[26:29], v[170:173], v[202:205], v[26:29]
	v_mfma_f32_16x16x32_bf16 v[22:25], v[178:181], v[202:205], v[22:25]
	v_mfma_f32_16x16x32_bf16 v[10:13], v[170:173], v[210:213], v[10:13]
	v_mfma_f32_16x16x32_bf16 v[4:7], v[178:181], v[210:213], v[4:7]
	s_setprio 0
	s_barrier
; #define PG8_KSETUP() const bool last = (t == nt - 2); const char* a1 = cA + (size_t)(t + 1) * kstep; \
;             const char* a2 = last ? nA : cA + (size_t)(t + 2) * kstep; const char* b2 = last ? nB : cB + (size_t)(t + 2) * kstep; const char* a3 = a2 + kstep; const char* b3 = b2 + kstep; \
;             if (last && has_next) S.a_ready(nxt)
; template <class Epi, class Sched, bool ALIGN_EPI = false, bool SP2 = false>
; __device__ __forceinline__ void gemm_phase(PG8_LAS unsigned char* lds, const Gemm g, const Sched& S, const Epi& E) {
;     ...
;         int t0 = 0;
;         if constexpr (SP2 && Epi::NVM == 16) { if (ui > 0) { const int t = 0; PG8_KSETUP(); PG8_KITER_SP2(24, 24); t0 = 2; } }
;         if constexpr (SP2 && Epi::NVM == 8) { if (ui > 0) { const int t = 0; PG8_KSETUP(); PG8_KITER_SP2(16, 16); t0 = 2; } }
;         for (int t = t0; t < nt; t += 2) {
;             PG8_KSETUP();
;             if constexpr (SP2) {
;             PG8_KITER_SP2(8, 8);
	ds_read_b128 v[138:141], v155
	ds_read_b128 v[142:145], v155 offset:1024
	ds_read_b128 v[158:161], v155 offset:2048
	ds_read_b128 v[162:165], v155 offset:3072
	ds_read_b128 v[166:169], v156
	ds_read_b128 v[170:173], v156 offset:1024
	ds_read_b128 v[174:177], v156 offset:2048
	ds_read_b128 v[178:181], v156 offset:3072
	ds_read_b128 v[182:185], v154 offset:32768
	ds_read_b128 v[186:189], v154 offset:33792
	ds_read_b128 v[190:193], v154 offset:34816
	ds_read_b128 v[194:197], v154 offset:35840
	ds_read_b128 v[198:201], v154 offset:36864
	ds_read_b128 v[202:205], v154 offset:37888
	ds_read_b128 v[206:209], v154 offset:38912
	ds_read_b128 v[210:213], v154 offset:39936
	s_add_u32 s30, s40, 0x80000
	s_addc_u32 s31, s41, 0
	s_mov_b32 m0, s48
	s_nop 0
	global_load_lds_dwordx4 v1, s[30:31] offset:0
	s_nop 0
	s_mov_b32 m0, s49
	s_nop 0
	global_load_lds_dwordx4 v147, s[30:31] offset:0
	s_waitcnt vmcnt(8)
	s_waitcnt lgkmcnt(0)
	s_barrier
	s_setprio 1
	v_mfma_f32_16x16x32_bf16 v[130:133], v[138:141], v[182:185], v[130:133]
	v_mfma_f32_16x16x32_bf16 v[130:133], v[142:145], v[186:189], v[130:133]
	v_mfma_f32_16x16x32_bf16 v[126:129], v[158:161], v[182:185], v[126:129]
	v_mfma_f32_16x16x32_bf16 v[126:129], v[162:165], v[186:189], v[126:129]
	v_mfma_f32_16x16x32_bf16 v[114:117], v[138:141], v[190:193], v[114:117]
	v_mfma_f32_16x16x32_bf16 v[114:117], v[142:145], v[194:197], v[114:117]
	v_mfma_f32_16x16x32_bf16 v[110:113], v[158:161], v[190:193], v[110:113]
	v_mfma_f32_16x16x32_bf16 v[110:113], v[162:165], v[194:197], v[110:113]
	v_mfma_f32_16x16x32_bf16 v[98:101], v[138:141], v[198:201], v[98:101]
	v_mfma_f32_16x16x32_bf16 v[98:101], v[142:145], v[202:205], v[98:101]
	v_mfma_f32_16x16x32_bf16 v[94:97], v[158:161], v[198:201], v[94:97]
	v_mfma_f32_16x16x32_bf16 v[94:97], v[162:165], v[202:205], v[94:97]
	v_mfma_f32_16x16x32_bf16 v[82:85], v[138:141], v[206:209], v[82:85]
	v_mfma_f32_16x16x32_bf16 v[82:85], v[142:145], v[210:213], v[82:85]
	v_mfma_f32_16x16x32_bf16 v[78:81], v[158:161], v[206:209], v[78:81]
	v_mfma_f32_16x16x32_bf16 v[78:81], v[162:165], v[210:213], v[78:81]
	s_setprio 0
	s_setprio 1
	v_mfma_f32_16x16x32_bf16 v[122:125], v[166:169], v[182:185], v[122:125]
	v_mfma_f32_16x16x32_bf16 v[122:125], v[170:173], v[186:189], v[122:125]
	v_mfma_f32_16x16x32_bf16 v[118:121], v[174:177], v[182:185], v[118:121]
	v_mfma_f32_16x16x32_bf16 v[118:121], v[178:181], v[186:189], v[118:121]
	v_mfma_f32_16x16x32_bf16 v[106:109], v[166:169], v[190:193], v[106:109]
	v_mfma_f32_16x16x32_bf16 v[106:109], v[170:173], v[194:197], v[106:109]
	v_mfma_f32_16x16x32_bf16 v[102:105], v[174:177], v[190:193], v[102:105]
	v_mfma_f32_16x16x32_bf16 v[102:105], v[178:181], v[194:197], v[102:105]
	v_mfma_f32_16x16x32_bf16 v[90:93], v[166:169], v[198:201], v[90:93]
	v_mfma_f32_16x16x32_bf16 v[90:93], v[170:173], v[202:205], v[90:93]
	v_mfma_f32_16x16x32_bf16 v[86:89], v[174:177], v[198:201], v[86:89]
	v_mfma_f32_16x16x32_bf16 v[86:89], v[178:181], v[202:205], v[86:89]
	v_mfma_f32_16x16x32_bf16 v[74:77], v[166:169], v[206:209], v[74:77]
	v_mfma_f32_16x16x32_bf16 v[74:77], v[170:173], v[210:213], v[74:77]
	v_mfma_f32_16x16x32_bf16 v[66:69], v[174:177], v[206:209], v[66:69]
	v_mfma_f32_16x16x32_bf16 v[66:69], v[178:181], v[210:213], v[66:69]
	s_setprio 0
	s_barrier
	ds_read_b128 v[182:185], v154 offset:49152
	ds_read_b128 v[186:189], v154 offset:50176
	ds_read_b128 v[190:193], v154 offset:51200
	ds_read_b128 v[194:197], v154 offset:52224
	ds_read_b128 v[198:201], v154 offset:53248
	ds_read_b128 v[202:205], v154 offset:54272
	ds_read_b128 v[206:209], v154 offset:55296
	ds_read_b128 v[210:213], v154 offset:56320
	s_add_u32 s30, s38, 0x80
	s_addc_u32 s31, s39, 0
	s_mov_b32 m0, s50
	s_nop 0
	global_load_lds_dwordx4 v146, s[30:31] offset:0
	s_nop 0
	s_mov_b32 m0, s51
	s_nop 0
	global_load_lds_dwordx4 v148, s[30:31] offset:0
	s_add_u32 s30, s38, 0x80080
	s_addc_u32 s31, s39, 0
	s_mov_b32 m0, s54
	s_nop 0
	global_load_lds_dwordx4 v146, s[30:31] offset:0
	s_nop 0
	s_mov_b32 m0, s55
	s_nop 0
	global_load_lds_dwordx4 v148, s[30:31] offset:0
	s_nop 0
	s_mov_b32 m0, s52
	s_nop 0
	global_load_lds_dwordx4 v1, s[36:37] offset:0
	s_nop 0
	s_mov_b32 m0, s53
	s_nop 0
	global_load_lds_dwordx4 v147, s[36:37] offset:0
	s_waitcnt vmcnt(8)
	s_waitcnt lgkmcnt(0)
	s_barrier
	s_setprio 1
	v_mfma_f32_16x16x32_bf16 v[70:73], v[138:141], v[182:185], v[70:73]
	v_mfma_f32_16x16x32_bf16 v[70:73], v[142:145], v[186:189], v[70:73]
	v_mfma_f32_16x16x32_bf16 v[62:65], v[158:161], v[182:185], v[62:65]
	v_mfma_f32_16x16x32_bf16 v[62:65], v[162:165], v[186:189], v[62:65]
	v_mfma_f32_16x16x32_bf16 v[50:53], v[138:141], v[190:193], v[50:53]
	v_mfma_f32_16x16x32_bf16 v[50:53], v[142:145], v[194:197], v[50:53]
	v_mfma_f32_16x16x32_bf16 v[46:49], v[158:161], v[190:193], v[46:49]
	v_mfma_f32_16x16x32_bf16 v[46:49], v[162:165], v[194:197], v[46:49]
	v_mfma_f32_16x16x32_bf16 v[34:37], v[138:141], v[198:201], v[34:37]
	v_mfma_f32_16x16x32_bf16 v[34:37], v[142:145], v[202:205], v[34:37]
	v_mfma_f32_16x16x32_bf16 v[30:33], v[158:161], v[198:201], v[30:33]
	v_mfma_f32_16x16x32_bf16 v[30:33], v[162:165], v[202:205], v[30:33]
	v_mfma_f32_16x16x32_bf16 v[18:21], v[138:141], v[206:209], v[18:21]
	v_mfma_f32_16x16x32_bf16 v[18:21], v[142:145], v[210:213], v[18:21]
	v_mfma_f32_16x16x32_bf16 v[14:17], v[158:161], v[206:209], v[14:17]
	v_mfma_f32_16x16x32_bf16 v[14:17], v[162:165], v[210:213], v[14:17]
	s_setprio 0
	s_setprio 1
	v_mfma_f32_16x16x32_bf16 v[58:61], v[166:169], v[182:185], v[58:61]
	v_mfma_f32_16x16x32_bf16 v[54:57], v[174:177], v[182:185], v[54:57]
	v_mfma_f32_16x16x32_bf16 v[42:45], v[166:169], v[190:193], v[42:45]
	v_mfma_f32_16x16x32_bf16 v[38:41], v[174:177], v[190:193], v[38:41]
	v_mfma_f32_16x16x32_bf16 v[26:29], v[166:169], v[198:201], v[26:29]
	v_mfma_f32_16x16x32_bf16 v[22:25], v[174:177], v[198:201], v[22:25]
	v_mfma_f32_16x16x32_bf16 v[8:11], v[166:169], v[206:209], v[10:13]
	v_mfma_f32_16x16x32_bf16 v[4:7], v[174:177], v[206:209], v[4:7]
	v_mfma_f32_16x16x32_bf16 v[58:61], v[170:173], v[186:189], v[58:61]
	v_mfma_f32_16x16x32_bf16 v[54:57], v[178:181], v[186:189], v[54:57]
	v_mfma_f32_16x16x32_bf16 v[42:45], v[170:173], v[194:197], v[42:45]
	v_mfma_f32_16x16x32_bf16 v[38:41], v[178:181], v[194:197], v[38:41]
	v_mfma_f32_16x16x32_bf16 v[26:29], v[170:173], v[202:205], v[26:29]
	v_mfma_f32_16x16x32_bf16 v[22:25], v[178:181], v[202:205], v[22:25]
	v_mfma_f32_16x16x32_bf16 v[10:13], v[170:173], v[210:213], v[8:11]
	v_mfma_f32_16x16x32_bf16 v[6:9], v[178:181], v[210:213], v[4:7]
	s_setprio 0
	s_barrier
	s_add_i32 s72, s72, 2
	s_add_u32 s73, s73, 0x100
	s_addc_u32 s74, s74, 0
	s_add_u32 s75, s75, 0x100
	s_addc_u32 s76, s76, 0
	s_cmp_gt_u32 s72, 29
	s_cbranch_scc0 .LBB0_3621
	s_and_b64 vcc, exec, s[14:15]
	s_cbranch_vccz .LBB0_3624
	s_barrier

; #define PG8_KSETUP() const bool last = (t == nt - 2); const char* a1 = cA + (size_t)(t + 1) * kstep; \
;             const char* a2 = last ? nA : cA + (size_t)(t + 2) * kstep; const char* b2 = last ? nB : cB + (size_t)(t + 2) * kstep; const char* a3 = a2 + kstep; const char* b3 = b2 + kstep; \
;             if (last && has_next) S.a_ready(nxt)
; template <class Epi, class Sched, bool ALIGN_EPI = false, bool SP2 = false>
; __device__ __forceinline__ void gemm_phase(PG8_LAS unsigned char* lds, const Gemm g, const Sched& S, const Epi& E) {
;     ...
;         if constexpr (SP2 && Epi::NVM == 16) { if (ui > 0) { const int t = 0; PG8_KSETUP(); PG8_KITER_SP2(24, 24); t0 = 2; } }
.LBB0_3696:
	ds_read_b128 v[2:5], v150
	ds_read_b128 v[6:9], v150 offset:1024
	ds_read_b128 v[10:13], v150 offset:2048
	ds_read_b128 v[14:17], v150 offset:3072
	ds_read_b128 v[18:21], v151
	ds_read_b128 v[22:25], v151 offset:1024
	ds_read_b128 v[26:29], v151 offset:2048
	ds_read_b128 v[30:33], v151 offset:3072
	s_add_u32 s22, s16, 0x100
	s_addc_u32 s23, s17, 0
	s_add_u32 s30, s18, 0x100
	s_addc_u32 s31, s19, 0
	s_add_u32 s20, s16, 0x180
	s_addc_u32 s21, s17, 0
	ds_read_b128 v[34:37], v152
	ds_read_b128 v[38:41], v152 offset:1024
	ds_read_b128 v[42:45], v152 offset:2048
	ds_read_b128 v[46:49], v152 offset:3072
	ds_read_b128 v[50:53], v152 offset:4096
	ds_read_b128 v[54:57], v152 offset:5120
	ds_read_b128 v[58:61], v152 offset:6144
	ds_read_b128 v[62:65], v152 offset:7168
	s_add_u32 s56, s16, 0x160080
	s_addc_u32 s57, s17, 0
	s_mov_b32 m0, s48
	s_nop 0
	global_load_lds_dwordx4 v144, s[56:57] offset:0
	s_nop 0
	s_mov_b32 m0, s49
	s_nop 0
	global_load_lds_dwordx4 v146, s[56:57] offset:0
	s_waitcnt vmcnt(24)
	s_waitcnt lgkmcnt(0)
	s_barrier
	s_setprio 1
	v_mfma_f32_16x16x32_bf16 v[90:93], v[2:5], v[58:61], 0
	v_mfma_f32_16x16x32_bf16 v[66:69], v[2:5], v[34:37], 0
	v_mfma_f32_16x16x32_bf16 v[70:73], v[10:13], v[34:37], 0
	v_mfma_f32_16x16x32_bf16 v[74:77], v[2:5], v[42:45], 0
	v_mfma_f32_16x16x32_bf16 v[78:81], v[10:13], v[42:45], 0
	v_mfma_f32_16x16x32_bf16 v[82:85], v[2:5], v[50:53], 0
	v_mfma_f32_16x16x32_bf16 v[86:89], v[10:13], v[50:53], 0
	v_mfma_f32_16x16x32_bf16 v[100:103], v[6:9], v[62:65], v[90:93]
	v_mfma_f32_16x16x32_bf16 v[90:93], v[10:13], v[58:61], 0
	v_mfma_f32_16x16x32_bf16 v[66:69], v[6:9], v[38:41], v[66:69]
	v_mfma_f32_16x16x32_bf16 v[70:73], v[14:17], v[38:41], v[70:73]
	v_mfma_f32_16x16x32_bf16 v[74:77], v[6:9], v[46:49], v[74:77]
	v_mfma_f32_16x16x32_bf16 v[78:81], v[14:17], v[46:49], v[78:81]
	v_mfma_f32_16x16x32_bf16 v[82:85], v[6:9], v[54:57], v[82:85]
	v_mfma_f32_16x16x32_bf16 v[86:89], v[14:17], v[54:57], v[86:89]
	v_mfma_f32_16x16x32_bf16 v[104:107], v[14:17], v[62:65], v[90:93]
	s_setprio 0
	s_setprio 1
	v_mfma_f32_16x16x32_bf16 v[90:93], v[18:21], v[34:37], 0
	v_mfma_f32_16x16x32_bf16 v[34:37], v[26:29], v[34:37], 0
	v_mfma_f32_16x16x32_bf16 v[116:119], v[22:25], v[38:41], v[90:93]
	v_mfma_f32_16x16x32_bf16 v[34:37], v[30:33], v[38:41], v[34:37]
	v_mfma_f32_16x16x32_bf16 v[38:41], v[18:21], v[42:45], 0
	v_mfma_f32_16x16x32_bf16 v[42:45], v[26:29], v[42:45], 0
	v_mfma_f32_16x16x32_bf16 v[38:41], v[22:25], v[46:49], v[38:41]
	v_mfma_f32_16x16x32_bf16 v[42:45], v[30:33], v[46:49], v[42:45]
	v_mfma_f32_16x16x32_bf16 v[46:49], v[18:21], v[50:53], 0
	v_mfma_f32_16x16x32_bf16 v[50:53], v[26:29], v[50:53], 0
	v_mfma_f32_16x16x32_bf16 v[46:49], v[22:25], v[54:57], v[46:49]
	v_mfma_f32_16x16x32_bf16 v[50:53], v[30:33], v[54:57], v[50:53]
	v_mfma_f32_16x16x32_bf16 v[54:57], v[18:21], v[58:61], 0
	v_mfma_f32_16x16x32_bf16 v[58:61], v[26:29], v[58:61], 0
	v_mfma_f32_16x16x32_bf16 v[54:57], v[22:25], v[62:65], v[54:57]
	v_mfma_f32_16x16x32_bf16 v[58:61], v[30:33], v[62:65], v[58:61]
	s_setprio 0
	s_barrier
	ds_read_b128 v[62:65], v152 offset:16384
	ds_read_b128 v[90:93], v152 offset:17408
	ds_read_b128 v[94:97], v152 offset:18432
	ds_read_b128 v[108:111], v152 offset:19456
	ds_read_b128 v[112:115], v152 offset:20480
	ds_read_b128 v[120:123], v152 offset:21504
	ds_read_b128 v[124:127], v152 offset:22528
	ds_read_b128 v[128:131], v152 offset:23552
	s_mov_b32 m0, s34
	s_nop 0
	global_load_lds_dwordx4 v145, s[30:31] offset:0
	s_nop 0
	s_mov_b32 m0, s36
	s_nop 0
	global_load_lds_dwordx4 v147, s[30:31] offset:0
	s_add_u32 s30, s18, 0x160100
	s_addc_u32 s31, s19, 0
	s_mov_b32 m0, s37
	s_nop 0
	global_load_lds_dwordx4 v145, s[30:31] offset:0
	s_nop 0
	s_mov_b32 m0, s38
	s_nop 0
	global_load_lds_dwordx4 v147, s[30:31] offset:0
	s_nop 0
	s_mov_b32 m0, s28
	s_nop 0
	global_load_lds_dwordx4 v144, s[22:23] offset:0
	s_nop 0
	s_mov_b32 m0, s39
	s_nop 0
	global_load_lds_dwordx4 v146, s[22:23] offset:0
	s_waitcnt vmcnt(24)
	s_waitcnt lgkmcnt(0)
	s_barrier
	s_setprio 1
	v_mfma_f32_16x16x32_bf16 v[132:135], v[2:5], v[62:65], 0
	v_mfma_f32_16x16x32_bf16 v[156:159], v[2:5], v[94:97], 0
	v_mfma_f32_16x16x32_bf16 v[164:167], v[2:5], v[112:115], 0
	v_mfma_f32_16x16x32_bf16 v[2:5], v[2:5], v[124:127], 0
	v_mfma_f32_16x16x32_bf16 v[132:135], v[6:9], v[90:93], v[132:135]
	v_mfma_f32_16x16x32_bf16 v[156:159], v[6:9], v[108:111], v[156:159]
	v_mfma_f32_16x16x32_bf16 v[164:167], v[6:9], v[120:123], v[164:167]
	v_mfma_f32_16x16x32_bf16 v[2:5], v[6:9], v[128:131], v[2:5]
	v_mfma_f32_16x16x32_bf16 v[6:9], v[10:13], v[124:127], 0
	v_mfma_f32_16x16x32_bf16 v[140:143], v[10:13], v[62:65], 0
	v_mfma_f32_16x16x32_bf16 v[160:163], v[10:13], v[94:97], 0
	v_mfma_f32_16x16x32_bf16 v[168:171], v[10:13], v[112:115], 0
	v_mfma_f32_16x16x32_bf16 v[6:9], v[14:17], v[128:131], v[6:9]
	v_mfma_f32_16x16x32_bf16 v[140:143], v[14:17], v[90:93], v[140:143]
	v_mfma_f32_16x16x32_bf16 v[160:163], v[14:17], v[108:111], v[160:163]
	v_mfma_f32_16x16x32_bf16 v[168:171], v[14:17], v[120:123], v[168:171]
	s_setprio 0
	s_setprio 1
	v_mfma_f32_16x16x32_bf16 v[10:13], v[18:21], v[62:65], 0
	v_mfma_f32_16x16x32_bf16 v[172:175], v[22:25], v[90:93], v[10:13]
	v_mfma_f32_16x16x32_bf16 v[10:13], v[26:29], v[62:65], 0
	v_mfma_f32_16x16x32_bf16 v[176:179], v[30:33], v[90:93], v[10:13]
	v_mfma_f32_16x16x32_bf16 v[10:13], v[18:21], v[94:97], 0
	v_mfma_f32_16x16x32_bf16 v[180:183], v[22:25], v[108:111], v[10:13]
	v_mfma_f32_16x16x32_bf16 v[10:13], v[26:29], v[94:97], 0
	v_mfma_f32_16x16x32_bf16 v[184:187], v[30:33], v[108:111], v[10:13]
	v_mfma_f32_16x16x32_bf16 v[10:13], v[18:21], v[112:115], 0
	v_mfma_f32_16x16x32_bf16 v[188:191], v[22:25], v[120:123], v[10:13]
	v_mfma_f32_16x16x32_bf16 v[10:13], v[26:29], v[112:115], 0
	v_mfma_f32_16x16x32_bf16 v[192:195], v[30:33], v[120:123], v[10:13]
	v_mfma_f32_16x16x32_bf16 v[10:13], v[18:21], v[124:127], 0
	v_mfma_f32_16x16x32_bf16 v[196:199], v[22:25], v[128:131], v[10:13]
	v_mfma_f32_16x16x32_bf16 v[10:13], v[26:29], v[124:127], 0
	v_mfma_f32_16x16x32_bf16 v[200:203], v[30:33], v[128:131], v[10:13]
	s_setprio 0
	s_barrier
; #define PG8_KSETUP() const bool last = (t == nt - 2); const char* a1 = cA + (size_t)(t + 1) * kstep; \
;             const char* a2 = last ? nA : cA + (size_t)(t + 2) * kstep; const char* b2 = last ? nB : cB + (size_t)(t + 2) * kstep; const char* a3 = a2 + kstep; const char* b3 = b2 + kstep; \
;             if (last && has_next) S.a_ready(nxt)
; template <class Epi, class Sched, bool ALIGN_EPI = false, bool SP2 = false>
; __device__ __forceinline__ void gemm_phase(PG8_LAS unsigned char* lds, const Gemm g, const Sched& S, const Epi& E) {
;     ...
;         int t0 = 0;
;         if constexpr (SP2 && Epi::NVM == 16) { if (ui > 0) { const int t = 0; PG8_KSETUP(); PG8_KITER_SP2(24, 24); t0 = 2; } }
;         if constexpr (SP2 && Epi::NVM == 8) { if (ui > 0) { const int t = 0; PG8_KSETUP(); PG8_KITER_SP2(16, 16); t0 = 2; } }
	s_nop 4
	ds_read_b128 v[10:13], v153
	ds_read_b128 v[14:17], v153 offset:1024
	ds_read_b128 v[20:23], v153 offset:2048
	ds_read_b128 v[24:27], v153 offset:3072
	ds_read_b128 v[204:207], v154
	ds_read_b128 v[208:211], v154 offset:1024
	ds_read_b128 v[212:215], v154 offset:2048
	ds_read_b128 v[216:219], v154 offset:3072
	ds_read_b128 v[28:31], v152 offset:32768
	ds_read_b128 v[62:65], v152 offset:33792
	ds_read_b128 v[220:223], v152 offset:34816
	ds_read_b128 v[224:227], v152 offset:35840
	ds_read_b128 v[228:231], v152 offset:36864
	ds_read_b128 v[232:235], v152 offset:37888
	ds_read_b128 v[236:239], v152 offset:38912
	ds_read_b128 v[240:243], v152 offset:39936
	s_add_u32 s22, s16, 0x160100
	s_addc_u32 s23, s17, 0
	s_mov_b32 m0, s40
	s_nop 0
	global_load_lds_dwordx4 v144, s[22:23] offset:0
	s_nop 0
	s_mov_b32 m0, s41
	s_nop 0
	global_load_lds_dwordx4 v146, s[22:23] offset:0
	s_waitcnt vmcnt(8)
	s_waitcnt lgkmcnt(0)
	s_barrier
	s_setprio 1
	v_mfma_f32_16x16x32_bf16 v[66:69], v[10:13], v[28:31], v[66:69]
	v_mfma_f32_16x16x32_bf16 v[128:131], v[14:17], v[62:65], v[66:69]
	v_mfma_f32_16x16x32_bf16 v[66:69], v[20:23], v[28:31], v[70:73]
	v_mfma_f32_16x16x32_bf16 v[124:127], v[24:27], v[62:65], v[66:69]
	v_mfma_f32_16x16x32_bf16 v[66:69], v[10:13], v[220:223], v[74:77]
	v_mfma_f32_16x16x32_bf16 v[112:115], v[14:17], v[224:227], v[66:69]
	v_mfma_f32_16x16x32_bf16 v[66:69], v[20:23], v[220:223], v[78:81]
	v_mfma_f32_16x16x32_bf16 v[108:111], v[24:27], v[224:227], v[66:69]
	v_mfma_f32_16x16x32_bf16 v[66:69], v[10:13], v[228:231], v[82:85]
	v_mfma_f32_16x16x32_bf16 v[96:99], v[14:17], v[232:235], v[66:69]
	v_mfma_f32_16x16x32_bf16 v[66:69], v[20:23], v[228:231], v[86:89]
	v_mfma_f32_16x16x32_bf16 v[92:95], v[24:27], v[232:235], v[66:69]
	v_mfma_f32_16x16x32_bf16 v[66:69], v[10:13], v[236:239], v[100:103]
	v_mfma_f32_16x16x32_bf16 v[80:83], v[14:17], v[240:243], v[66:69]
	v_mfma_f32_16x16x32_bf16 v[66:69], v[20:23], v[236:239], v[104:107]
	v_mfma_f32_16x16x32_bf16 v[76:79], v[24:27], v[240:243], v[66:69]
	s_setprio 0
	s_setprio 1
	v_mfma_f32_16x16x32_bf16 v[66:69], v[204:207], v[28:31], v[116:119]
	v_mfma_f32_16x16x32_bf16 v[28:31], v[212:215], v[28:31], v[34:37]
	v_mfma_f32_16x16x32_bf16 v[116:119], v[216:219], v[62:65], v[28:31]
	v_mfma_f32_16x16x32_bf16 v[28:31], v[204:207], v[220:223], v[38:41]
	v_mfma_f32_16x16x32_bf16 v[104:107], v[208:211], v[224:227], v[28:31]
	v_mfma_f32_16x16x32_bf16 v[28:31], v[212:215], v[220:223], v[42:45]
	v_mfma_f32_16x16x32_bf16 v[100:103], v[216:219], v[224:227], v[28:31]
	v_mfma_f32_16x16x32_bf16 v[28:31], v[204:207], v[228:231], v[46:49]
	v_mfma_f32_16x16x32_bf16 v[88:91], v[208:211], v[232:235], v[28:31]
	v_mfma_f32_16x16x32_bf16 v[28:31], v[212:215], v[228:231], v[50:53]
	v_mfma_f32_16x16x32_bf16 v[84:87], v[216:219], v[232:235], v[28:31]
	v_mfma_f32_16x16x32_bf16 v[28:31], v[204:207], v[236:239], v[54:57]
	v_mfma_f32_16x16x32_bf16 v[72:75], v[208:211], v[240:243], v[28:31]
	v_mfma_f32_16x16x32_bf16 v[28:31], v[212:215], v[236:239], v[58:61]
	v_mfma_f32_16x16x32_bf16 v[120:123], v[208:211], v[62:65], v[66:69]
	v_mfma_f32_16x16x32_bf16 v[68:71], v[216:219], v[240:243], v[28:31]
	s_setprio 0
	s_barrier
	ds_read_b128 v[36:39], v152 offset:49152
	ds_read_b128 v[40:43], v152 offset:50176
	ds_read_b128 v[220:223], v152 offset:51200
	ds_read_b128 v[224:227], v152 offset:52224
	ds_read_b128 v[228:231], v152 offset:53248
	ds_read_b128 v[232:235], v152 offset:54272
	ds_read_b128 v[236:239], v152 offset:55296
	ds_read_b128 v[240:243], v152 offset:56320
	s_add_u32 s22, s18, 0x180
	s_addc_u32 s23, s19, 0
	s_mov_b32 m0, s42
	s_nop 0
	global_load_lds_dwordx4 v145, s[22:23] offset:0
	s_nop 0
	s_mov_b32 m0, s43
	s_nop 0
	global_load_lds_dwordx4 v147, s[22:23] offset:0
	s_add_u32 s22, s18, 0x160180
	s_addc_u32 s23, s19, 0
	s_mov_b32 m0, s46
	s_nop 0
	global_load_lds_dwordx4 v145, s[22:23] offset:0
	s_nop 0
	s_mov_b32 m0, s47
	s_nop 0
	global_load_lds_dwordx4 v147, s[22:23] offset:0
	s_nop 0
	s_mov_b32 m0, s44
	s_nop 0
	global_load_lds_dwordx4 v144, s[20:21] offset:0
	s_nop 0
	s_mov_b32 m0, s45
	s_nop 0
	global_load_lds_dwordx4 v146, s[20:21] offset:0
	s_waitcnt vmcnt(8)
	s_waitcnt lgkmcnt(0)
	s_barrier
	s_setprio 1
	v_mfma_f32_16x16x32_bf16 v[28:31], v[10:13], v[36:39], v[132:135]
	v_mfma_f32_16x16x32_bf16 v[64:67], v[14:17], v[40:43], v[28:31]
	v_mfma_f32_16x16x32_bf16 v[28:31], v[20:23], v[36:39], v[140:143]
	v_mfma_f32_16x16x32_bf16 v[60:63], v[24:27], v[40:43], v[28:31]
	v_mfma_f32_16x16x32_bf16 v[28:31], v[10:13], v[220:223], v[156:159]
	v_mfma_f32_16x16x32_bf16 v[48:51], v[14:17], v[224:227], v[28:31]
	v_mfma_f32_16x16x32_bf16 v[28:31], v[20:23], v[220:223], v[160:163]
	v_mfma_f32_16x16x32_bf16 v[44:47], v[24:27], v[224:227], v[28:31]
	v_mfma_f32_16x16x32_bf16 v[28:31], v[10:13], v[228:231], v[164:167]
	v_mfma_f32_16x16x32_bf16 v[2:5], v[10:13], v[236:239], v[2:5]
	v_mfma_f32_16x16x32_bf16 v[32:35], v[14:17], v[232:235], v[28:31]
	v_mfma_f32_16x16x32_bf16 v[28:31], v[20:23], v[228:231], v[168:171]
	v_mfma_f32_16x16x32_bf16 v[16:19], v[14:17], v[240:243], v[2:5]
	v_mfma_f32_16x16x32_bf16 v[2:5], v[20:23], v[236:239], v[6:9]
	v_mfma_f32_16x16x32_bf16 v[28:31], v[24:27], v[232:235], v[28:31]
	v_mfma_f32_16x16x32_bf16 v[12:15], v[24:27], v[240:243], v[2:5]
	s_setprio 0
	s_setprio 1
	v_mfma_f32_16x16x32_bf16 v[2:5], v[204:207], v[36:39], v[172:175]
	v_mfma_f32_16x16x32_bf16 v[56:59], v[208:211], v[40:43], v[2:5]
	v_mfma_f32_16x16x32_bf16 v[2:5], v[212:215], v[36:39], v[176:179]
	v_mfma_f32_16x16x32_bf16 v[52:55], v[216:219], v[40:43], v[2:5]
	v_mfma_f32_16x16x32_bf16 v[2:5], v[204:207], v[220:223], v[180:183]
	v_mfma_f32_16x16x32_bf16 v[40:43], v[208:211], v[224:227], v[2:5]
	v_mfma_f32_16x16x32_bf16 v[2:5], v[212:215], v[220:223], v[184:187]
	v_mfma_f32_16x16x32_bf16 v[36:39], v[216:219], v[224:227], v[2:5]
	v_mfma_f32_16x16x32_bf16 v[2:5], v[204:207], v[228:231], v[188:191]
	v_mfma_f32_16x16x32_bf16 v[24:27], v[208:211], v[232:235], v[2:5]
	v_mfma_f32_16x16x32_bf16 v[2:5], v[212:215], v[228:231], v[192:195]
	v_mfma_f32_16x16x32_bf16 v[20:23], v[216:219], v[232:235], v[2:5]
	v_mfma_f32_16x16x32_bf16 v[2:5], v[204:207], v[236:239], v[196:199]
	v_mfma_f32_16x16x32_bf16 v[8:11], v[208:211], v[240:243], v[2:5]
	v_mfma_f32_16x16x32_bf16 v[2:5], v[212:215], v[236:239], v[200:203]
	v_mfma_f32_16x16x32_bf16 v[4:7], v[216:219], v[240:243], v[2:5]
	s_setprio 0
	s_barrier
	s_mov_b32 s20, 2
	s_branch .LBB0_3700

.LBB0_3701:
	ds_read_b128 v[132:135], v150
	ds_read_b128 v[140:143], v150 offset:1024
	ds_read_b128 v[156:159], v150 offset:2048
	ds_read_b128 v[160:163], v150 offset:3072
	ds_read_b128 v[164:167], v151
	ds_read_b128 v[168:171], v151 offset:1024
	ds_read_b128 v[172:175], v151 offset:2048
	ds_read_b128 v[176:179], v151 offset:3072
	s_cmpk_eq_i32 s22, 0x54
	s_cselect_b32 s20, s4, s57
	s_cselect_b32 s21, s5, s58
	s_cselect_b32 s18, s14, s23
	s_cselect_b32 s19, s15, s56
	s_add_u32 s16, s20, 0x80
	s_addc_u32 s17, s21, 0
	ds_read_b128 v[180:183], v152
	ds_read_b128 v[184:187], v152 offset:1024
	ds_read_b128 v[188:191], v152 offset:2048
	ds_read_b128 v[192:195], v152 offset:3072
	ds_read_b128 v[196:199], v152 offset:4096
	ds_read_b128 v[200:203], v152 offset:5120
	ds_read_b128 v[204:207], v152 offset:6144
	ds_read_b128 v[208:211], v152 offset:7168
	s_add_u32 s30, s57, 0x15ff80
	s_addc_u32 s31, s58, 0
	s_mov_b32 m0, s48
	s_nop 0
	global_load_lds_dwordx4 v144, s[30:31] offset:0
	s_nop 0
	s_mov_b32 m0, s49
	s_nop 0
	global_load_lds_dwordx4 v146, s[30:31] offset:0
	s_waitcnt vmcnt(8)
	s_waitcnt lgkmcnt(0)
	s_barrier
	s_setprio 1
	v_mfma_f32_16x16x32_bf16 v[128:131], v[132:135], v[180:183], v[128:131]
	v_mfma_f32_16x16x32_bf16 v[128:131], v[140:143], v[184:187], v[128:131]
	v_mfma_f32_16x16x32_bf16 v[124:127], v[156:159], v[180:183], v[124:127]
	v_mfma_f32_16x16x32_bf16 v[124:127], v[160:163], v[184:187], v[124:127]
	v_mfma_f32_16x16x32_bf16 v[112:115], v[132:135], v[188:191], v[112:115]
	v_mfma_f32_16x16x32_bf16 v[112:115], v[140:143], v[192:195], v[112:115]
	v_mfma_f32_16x16x32_bf16 v[108:111], v[156:159], v[188:191], v[108:111]
	v_mfma_f32_16x16x32_bf16 v[108:111], v[160:163], v[192:195], v[108:111]
	v_mfma_f32_16x16x32_bf16 v[96:99], v[132:135], v[196:199], v[96:99]
	v_mfma_f32_16x16x32_bf16 v[96:99], v[140:143], v[200:203], v[96:99]
	v_mfma_f32_16x16x32_bf16 v[92:95], v[156:159], v[196:199], v[92:95]
	v_mfma_f32_16x16x32_bf16 v[92:95], v[160:163], v[200:203], v[92:95]
	v_mfma_f32_16x16x32_bf16 v[80:83], v[132:135], v[204:207], v[80:83]
	v_mfma_f32_16x16x32_bf16 v[80:83], v[140:143], v[208:211], v[80:83]
	v_mfma_f32_16x16x32_bf16 v[76:79], v[156:159], v[204:207], v[76:79]
	v_mfma_f32_16x16x32_bf16 v[76:79], v[160:163], v[208:211], v[76:79]
	s_setprio 0
	s_setprio 1
	v_mfma_f32_16x16x32_bf16 v[120:123], v[164:167], v[180:183], v[120:123]
	v_mfma_f32_16x16x32_bf16 v[120:123], v[168:171], v[184:187], v[120:123]
	v_mfma_f32_16x16x32_bf16 v[116:119], v[172:175], v[180:183], v[116:119]
	v_mfma_f32_16x16x32_bf16 v[116:119], v[176:179], v[184:187], v[116:119]
	v_mfma_f32_16x16x32_bf16 v[104:107], v[164:167], v[188:191], v[104:107]
	v_mfma_f32_16x16x32_bf16 v[104:107], v[168:171], v[192:195], v[104:107]
	v_mfma_f32_16x16x32_bf16 v[100:103], v[172:175], v[188:191], v[100:103]
	v_mfma_f32_16x16x32_bf16 v[100:103], v[176:179], v[192:195], v[100:103]
	v_mfma_f32_16x16x32_bf16 v[88:91], v[164:167], v[196:199], v[88:91]
	v_mfma_f32_16x16x32_bf16 v[88:91], v[168:171], v[200:203], v[88:91]
	v_mfma_f32_16x16x32_bf16 v[84:87], v[172:175], v[196:199], v[84:87]
	v_mfma_f32_16x16x32_bf16 v[84:87], v[176:179], v[200:203], v[84:87]
	v_mfma_f32_16x16x32_bf16 v[72:75], v[164:167], v[204:207], v[72:75]
	v_mfma_f32_16x16x32_bf16 v[72:75], v[168:171], v[208:211], v[72:75]
	v_mfma_f32_16x16x32_bf16 v[68:71], v[172:175], v[204:207], v[68:71]
	v_mfma_f32_16x16x32_bf16 v[68:71], v[176:179], v[208:211], v[68:71]
	s_setprio 0
	s_barrier
	ds_read_b128 v[180:183], v152 offset:16384
	ds_read_b128 v[184:187], v152 offset:17408
	ds_read_b128 v[188:191], v152 offset:18432
	ds_read_b128 v[192:195], v152 offset:19456
	ds_read_b128 v[196:199], v152 offset:20480
	ds_read_b128 v[200:203], v152 offset:21504
	ds_read_b128 v[204:207], v152 offset:22528
	ds_read_b128 v[208:211], v152 offset:23552
	s_mov_b32 m0, s34
	s_nop 0
	global_load_lds_dwordx4 v145, s[18:19] offset:0
	s_add_u32 s30, s18, 0x160000
	s_mov_b32 m0, s36
	s_nop 0
	global_load_lds_dwordx4 v147, s[18:19] offset:0
	s_addc_u32 s31, s19, 0
	s_mov_b32 m0, s37
	s_nop 0
	global_load_lds_dwordx4 v145, s[30:31] offset:0
	s_nop 0
	s_mov_b32 m0, s38
	s_nop 0
	global_load_lds_dwordx4 v147, s[30:31] offset:0
	s_nop 0
	s_mov_b32 m0, s28
	s_nop 0
	global_load_lds_dwordx4 v144, s[20:21] offset:0
	s_nop 0
	s_mov_b32 m0, s39
	s_nop 0
	global_load_lds_dwordx4 v146, s[20:21] offset:0
	s_waitcnt vmcnt(8)
	s_waitcnt lgkmcnt(0)
	s_barrier
	s_setprio 1
	v_mfma_f32_16x16x32_bf16 v[64:67], v[132:135], v[180:183], v[64:67]
	v_mfma_f32_16x16x32_bf16 v[64:67], v[140:143], v[184:187], v[64:67]
	v_mfma_f32_16x16x32_bf16 v[60:63], v[156:159], v[180:183], v[60:63]
	v_mfma_f32_16x16x32_bf16 v[60:63], v[160:163], v[184:187], v[60:63]
	v_mfma_f32_16x16x32_bf16 v[48:51], v[132:135], v[188:191], v[48:51]
	v_mfma_f32_16x16x32_bf16 v[48:51], v[140:143], v[192:195], v[48:51]
	v_mfma_f32_16x16x32_bf16 v[44:47], v[156:159], v[188:191], v[44:47]
	v_mfma_f32_16x16x32_bf16 v[44:47], v[160:163], v[192:195], v[44:47]
	v_mfma_f32_16x16x32_bf16 v[32:35], v[132:135], v[196:199], v[32:35]
	v_mfma_f32_16x16x32_bf16 v[32:35], v[140:143], v[200:203], v[32:35]
	v_mfma_f32_16x16x32_bf16 v[28:31], v[156:159], v[196:199], v[28:31]
	v_mfma_f32_16x16x32_bf16 v[28:31], v[160:163], v[200:203], v[28:31]
	v_mfma_f32_16x16x32_bf16 v[16:19], v[132:135], v[204:207], v[16:19]
	v_mfma_f32_16x16x32_bf16 v[16:19], v[140:143], v[208:211], v[16:19]
	v_mfma_f32_16x16x32_bf16 v[12:15], v[156:159], v[204:207], v[12:15]
	v_mfma_f32_16x16x32_bf16 v[12:15], v[160:163], v[208:211], v[12:15]
	s_setprio 0
	s_setprio 1
	v_mfma_f32_16x16x32_bf16 v[56:59], v[164:167], v[180:183], v[56:59]
	v_mfma_f32_16x16x32_bf16 v[52:55], v[172:175], v[180:183], v[52:55]
	v_mfma_f32_16x16x32_bf16 v[40:43], v[164:167], v[188:191], v[40:43]
	v_mfma_f32_16x16x32_bf16 v[36:39], v[172:175], v[188:191], v[36:39]
	v_mfma_f32_16x16x32_bf16 v[24:27], v[164:167], v[196:199], v[24:27]
	v_mfma_f32_16x16x32_bf16 v[20:23], v[172:175], v[196:199], v[20:23]
	v_mfma_f32_16x16x32_bf16 v[8:11], v[164:167], v[204:207], v[8:11]
	v_mfma_f32_16x16x32_bf16 v[2:5], v[172:175], v[204:207], v[4:7]
	v_mfma_f32_16x16x32_bf16 v[56:59], v[168:171], v[184:187], v[56:59]
	v_mfma_f32_16x16x32_bf16 v[52:55], v[176:179], v[184:187], v[52:55]
	v_mfma_f32_16x16x32_bf16 v[40:43], v[168:171], v[192:195], v[40:43]
	v_mfma_f32_16x16x32_bf16 v[36:39], v[176:179], v[192:195], v[36:39]
	v_mfma_f32_16x16x32_bf16 v[24:27], v[168:171], v[200:203], v[24:27]
	v_mfma_f32_16x16x32_bf16 v[20:23], v[176:179], v[200:203], v[20:23]
	v_mfma_f32_16x16x32_bf16 v[8:11], v[168:171], v[208:211], v[8:11]
	v_mfma_f32_16x16x32_bf16 v[2:5], v[176:179], v[208:211], v[2:5]
	s_setprio 0
	s_barrier
; #define PG8_KSETUP() const bool last = (t == nt - 2); const char* a1 = cA + (size_t)(t + 1) * kstep; \
;             const char* a2 = last ? nA : cA + (size_t)(t + 2) * kstep; const char* b2 = last ? nB : cB + (size_t)(t + 2) * kstep; const char* a3 = a2 + kstep; const char* b3 = b2 + kstep; \
;             if (last && has_next) S.a_ready(nxt)
; template <class Epi, class Sched, bool ALIGN_EPI = false, bool SP2 = false>
; __device__ __forceinline__ void gemm_phase(PG8_LAS unsigned char* lds, const Gemm g, const Sched& S, const Epi& E) {
;     ...
;         int t0 = 0;
;         if constexpr (SP2 && Epi::NVM == 16) { if (ui > 0) { const int t = 0; PG8_KSETUP(); PG8_KITER_SP2(24, 24); t0 = 2; } }
;         if constexpr (SP2 && Epi::NVM == 8) { if (ui > 0) { const int t = 0; PG8_KSETUP(); PG8_KITER_SP2(16, 16); t0 = 2; } }
;         for (int t = t0; t < nt; t += 2) {
;             PG8_KSETUP();
;             if constexpr (SP2) {
;             PG8_KITER_SP2(8, 8);
	ds_read_b128 v[132:135], v153
	ds_read_b128 v[140:143], v153 offset:1024
	ds_read_b128 v[156:159], v153 offset:2048
	ds_read_b128 v[160:163], v153 offset:3072
	ds_read_b128 v[164:167], v154
	ds_read_b128 v[168:171], v154 offset:1024
	ds_read_b128 v[172:175], v154 offset:2048
	ds_read_b128 v[176:179], v154 offset:3072
	ds_read_b128 v[180:183], v152 offset:32768
	ds_read_b128 v[184:187], v152 offset:33792
	ds_read_b128 v[188:191], v152 offset:34816
	ds_read_b128 v[192:195], v152 offset:35840
	ds_read_b128 v[196:199], v152 offset:36864
	ds_read_b128 v[200:203], v152 offset:37888
	ds_read_b128 v[204:207], v152 offset:38912
	ds_read_b128 v[208:211], v152 offset:39936
	s_add_u32 s20, s20, 0x160000
	s_addc_u32 s21, s21, 0
	s_mov_b32 m0, s40
	s_nop 0
	global_load_lds_dwordx4 v144, s[20:21] offset:0
	s_nop 0
	s_mov_b32 m0, s41
	s_nop 0
	global_load_lds_dwordx4 v146, s[20:21] offset:0
	s_waitcnt vmcnt(8)
	s_waitcnt lgkmcnt(0)
	s_barrier
	s_setprio 1
	v_mfma_f32_16x16x32_bf16 v[128:131], v[132:135], v[180:183], v[128:131]
	v_mfma_f32_16x16x32_bf16 v[128:131], v[140:143], v[184:187], v[128:131]
	v_mfma_f32_16x16x32_bf16 v[124:127], v[156:159], v[180:183], v[124:127]
	v_mfma_f32_16x16x32_bf16 v[124:127], v[160:163], v[184:187], v[124:127]
	v_mfma_f32_16x16x32_bf16 v[112:115], v[132:135], v[188:191], v[112:115]
	v_mfma_f32_16x16x32_bf16 v[112:115], v[140:143], v[192:195], v[112:115]
	v_mfma_f32_16x16x32_bf16 v[108:111], v[156:159], v[188:191], v[108:111]
	v_mfma_f32_16x16x32_bf16 v[108:111], v[160:163], v[192:195], v[108:111]
	v_mfma_f32_16x16x32_bf16 v[96:99], v[132:135], v[196:199], v[96:99]
	v_mfma_f32_16x16x32_bf16 v[96:99], v[140:143], v[200:203], v[96:99]
	v_mfma_f32_16x16x32_bf16 v[92:95], v[156:159], v[196:199], v[92:95]
	v_mfma_f32_16x16x32_bf16 v[92:95], v[160:163], v[200:203], v[92:95]
	v_mfma_f32_16x16x32_bf16 v[80:83], v[132:135], v[204:207], v[80:83]
	v_mfma_f32_16x16x32_bf16 v[80:83], v[140:143], v[208:211], v[80:83]
	v_mfma_f32_16x16x32_bf16 v[76:79], v[156:159], v[204:207], v[76:79]
	v_mfma_f32_16x16x32_bf16 v[76:79], v[160:163], v[208:211], v[76:79]
	s_setprio 0
	s_setprio 1
	v_mfma_f32_16x16x32_bf16 v[120:123], v[164:167], v[180:183], v[120:123]
	v_mfma_f32_16x16x32_bf16 v[120:123], v[168:171], v[184:187], v[120:123]
	v_mfma_f32_16x16x32_bf16 v[116:119], v[172:175], v[180:183], v[116:119]
	v_mfma_f32_16x16x32_bf16 v[116:119], v[176:179], v[184:187], v[116:119]
	v_mfma_f32_16x16x32_bf16 v[104:107], v[164:167], v[188:191], v[104:107]
	v_mfma_f32_16x16x32_bf16 v[104:107], v[168:171], v[192:195], v[104:107]
	v_mfma_f32_16x16x32_bf16 v[100:103], v[172:175], v[188:191], v[100:103]
	v_mfma_f32_16x16x32_bf16 v[100:103], v[176:179], v[192:195], v[100:103]
	v_mfma_f32_16x16x32_bf16 v[88:91], v[164:167], v[196:199], v[88:91]
	v_mfma_f32_16x16x32_bf16 v[88:91], v[168:171], v[200:203], v[88:91]
	v_mfma_f32_16x16x32_bf16 v[84:87], v[172:175], v[196:199], v[84:87]
	v_mfma_f32_16x16x32_bf16 v[84:87], v[176:179], v[200:203], v[84:87]
	v_mfma_f32_16x16x32_bf16 v[72:75], v[164:167], v[204:207], v[72:75]
	v_mfma_f32_16x16x32_bf16 v[72:75], v[168:171], v[208:211], v[72:75]
	v_mfma_f32_16x16x32_bf16 v[68:71], v[172:175], v[204:207], v[68:71]
	v_mfma_f32_16x16x32_bf16 v[68:71], v[176:179], v[208:211], v[68:71]
	s_setprio 0
	s_barrier
	ds_read_b128 v[180:183], v152 offset:49152
	ds_read_b128 v[184:187], v152 offset:50176
	ds_read_b128 v[188:191], v152 offset:51200
	ds_read_b128 v[192:195], v152 offset:52224
	ds_read_b128 v[196:199], v152 offset:53248
	ds_read_b128 v[200:203], v152 offset:54272
	ds_read_b128 v[204:207], v152 offset:55296
	ds_read_b128 v[208:211], v152 offset:56320
	s_add_u32 s20, s18, 0x80
	s_addc_u32 s21, s19, 0
	s_mov_b32 m0, s42
	s_nop 0
	global_load_lds_dwordx4 v145, s[20:21] offset:0
	s_add_u32 s18, s18, 0x160080
	s_mov_b32 m0, s43
	s_nop 0
	global_load_lds_dwordx4 v147, s[20:21] offset:0
	s_addc_u32 s19, s19, 0
	s_mov_b32 m0, s46
	s_nop 0
	global_load_lds_dwordx4 v145, s[18:19] offset:0
	s_nop 0
	s_mov_b32 m0, s47
	s_nop 0
	global_load_lds_dwordx4 v147, s[18:19] offset:0
	s_nop 0
	s_mov_b32 m0, s44
	s_nop 0
	global_load_lds_dwordx4 v144, s[16:17] offset:0
	s_nop 0
	s_mov_b32 m0, s45
	s_nop 0
	global_load_lds_dwordx4 v146, s[16:17] offset:0
	s_waitcnt vmcnt(8)
	s_waitcnt lgkmcnt(0)
	s_barrier
	s_setprio 1
	v_mfma_f32_16x16x32_bf16 v[64:67], v[132:135], v[180:183], v[64:67]
	v_mfma_f32_16x16x32_bf16 v[64:67], v[140:143], v[184:187], v[64:67]
	v_mfma_f32_16x16x32_bf16 v[60:63], v[156:159], v[180:183], v[60:63]
	v_mfma_f32_16x16x32_bf16 v[60:63], v[160:163], v[184:187], v[60:63]
	v_mfma_f32_16x16x32_bf16 v[48:51], v[132:135], v[188:191], v[48:51]
	v_mfma_f32_16x16x32_bf16 v[48:51], v[140:143], v[192:195], v[48:51]
	v_mfma_f32_16x16x32_bf16 v[44:47], v[156:159], v[188:191], v[44:47]
	v_mfma_f32_16x16x32_bf16 v[44:47], v[160:163], v[192:195], v[44:47]
	v_mfma_f32_16x16x32_bf16 v[32:35], v[132:135], v[196:199], v[32:35]
	v_mfma_f32_16x16x32_bf16 v[32:35], v[140:143], v[200:203], v[32:35]
	v_mfma_f32_16x16x32_bf16 v[28:31], v[156:159], v[196:199], v[28:31]
	v_mfma_f32_16x16x32_bf16 v[28:31], v[160:163], v[200:203], v[28:31]
	v_mfma_f32_16x16x32_bf16 v[16:19], v[132:135], v[204:207], v[16:19]
	v_mfma_f32_16x16x32_bf16 v[16:19], v[140:143], v[208:211], v[16:19]
	v_mfma_f32_16x16x32_bf16 v[12:15], v[156:159], v[204:207], v[12:15]
	v_mfma_f32_16x16x32_bf16 v[12:15], v[160:163], v[208:211], v[12:15]
	s_setprio 0
	s_setprio 1
	v_mfma_f32_16x16x32_bf16 v[56:59], v[164:167], v[180:183], v[56:59]
	v_mfma_f32_16x16x32_bf16 v[52:55], v[172:175], v[180:183], v[52:55]
	v_mfma_f32_16x16x32_bf16 v[40:43], v[164:167], v[188:191], v[40:43]
	v_mfma_f32_16x16x32_bf16 v[36:39], v[172:175], v[188:191], v[36:39]
	v_mfma_f32_16x16x32_bf16 v[24:27], v[164:167], v[196:199], v[24:27]
	v_mfma_f32_16x16x32_bf16 v[20:23], v[172:175], v[196:199], v[20:23]
	v_mfma_f32_16x16x32_bf16 v[6:9], v[164:167], v[204:207], v[8:11]
	v_mfma_f32_16x16x32_bf16 v[2:5], v[172:175], v[204:207], v[2:5]
	v_mfma_f32_16x16x32_bf16 v[56:59], v[168:171], v[184:187], v[56:59]
	v_mfma_f32_16x16x32_bf16 v[52:55], v[176:179], v[184:187], v[52:55]
	v_mfma_f32_16x16x32_bf16 v[40:43], v[168:171], v[192:195], v[40:43]
	v_mfma_f32_16x16x32_bf16 v[36:39], v[176:179], v[192:195], v[36:39]
	v_mfma_f32_16x16x32_bf16 v[24:27], v[168:171], v[200:203], v[24:27]
	v_mfma_f32_16x16x32_bf16 v[20:23], v[176:179], v[200:203], v[20:23]
	v_mfma_f32_16x16x32_bf16 v[8:11], v[168:171], v[208:211], v[6:9]
	v_mfma_f32_16x16x32_bf16 v[4:7], v[176:179], v[208:211], v[2:5]
	s_setprio 0
	s_barrier
	s_add_i32 s22, s22, 2
	s_add_u32 s23, s23, 0x100
	s_addc_u32 s56, s56, 0
	s_add_u32 s57, s57, 0x100
	s_addc_u32 s58, s58, 0
	s_cmpk_gt_u32 s22, 0x55
	s_cbranch_scc0 .LBB0_3701
	s_and_b64 vcc, exec, s[12:13]
	s_cbranch_vccz .LBB0_3704
	s_barrier
